# nt (streaming) policy on all GEMM epilogue output stores, on top of gelu+decay trims
# baseline (speedup 1.0000x reference)
; __device__ __forceinline__ u32x4 pack8(f32x4 v0, f32x4 v1) { u32x4 w; w.x = cvt_pk_bf16(v0[0], v0[1]); w.y = cvt_pk_bf16(v0[2], v0[3]); w.z = cvt_pk_bf16(v1[0], v1[1]); w.w = cvt_pk_bf16(v1[2], v1[3]); return w; }
; __device__ __forceinline__ f32x4 gelu4(f32x4 v) { f32x2 a = gelu_pk((f32x2){v[0], v[1]}), b = gelu_pk((f32x2){v[2], v[3]}); return (f32x4){a.x, a.y, b.x, b.y}; }
; __device__ __forceinline__ f32x2 gelu_pk(f32x2 v) {
;     const f32x2 av = __builtin_elementwise_abs(v), d = av * 0.2316418882f + 1.0f;
;     f32x2 t; t.x = __builtin_amdgcn_rcpf(d.x); t.y = __builtin_amdgcn_rcpf(d.y);
;     f32x2 q = t * 0.5307027145f + (-0.7265760135f); q = q * t + 0.7107068705f; q = q * t + (-0.142248368f); q = q * t + 0.127414796f; q = q * t;
;     const f32x2 s = (v * v) * (-0.72134752044f);
;     f32x2 e; e.x = __builtin_amdgcn_exp2f(s.x); e.y = __builtin_amdgcn_exp2f(s.y);
;     const f32x2 m = v * (q * e), r = v - m;
;     f32x2 o; o.x = v.x < 0.f ? m.x : r.x; o.y = v.y < 0.f ? m.y : r.y; return o;
; }
;     __device__ __forceinline__ void operator()(f32x4 (&acc)[2][2][4][2], const Unit& u, int wr, int wc, int fr_, int fq_) const {
;     ...
;             for (int m = 0; m < 4; ++m) { const int row = row0 + ai * HALF + m * 16; const float rs = rstd[row]; bf16_t* rowp = base + (size_t)row * ld + col0;
;                 float s1 = 0.f, s2 = 0.f;
; #pragma unroll
;                 for (int bj = 0; bj < 2; ++bj) { f32x4 v0 = acc[ai][bj][m][0] * rs, v1 = acc[ai][bj][m][1] * rs;
;                     if (act) { v0 = gelu4(v0); v1 = gelu4(v1); }
;                     s1 += ((v0[0] + v0[1]) + (v0[2] + v0[3])) + ((v1[0] + v1[1]) + (v1[2] + v1[3]));
;                     s2 += ((v0[0] * v0[0] + v0[1] * v0[1]) + (v0[2] * v0[2] + v0[3] * v0[3])) + ((v1[0] * v1[0] + v1[1] * v1[1]) + (v1[2] * v1[2] + v1[3] * v1[3]));
;                     *(u32x4*)(rowp + bj * HALF) = pack8(v0, v1); }
;                 if (pn >= 4 && pn < 8) { s1 += __shfl_xor(s1, 16); s1 += __shfl_xor(s1, 32); s2 += __shfl_xor(s2, 16); s2 += __shfl_xor(s2, 32);
;                     if (fq == 0) { lns[(size_t)row * 32 + (pn - 4) * 4 + wc] = s1; lns[(size_t)row * 32 + 16 + (pn - 4) * 4 + wc] = s2; } } }
.LBB0_356:
	s_lshl_b32 s9, s9, 8
	s_or_b32 s9, s9, s38
	v_lshl_add_u32 v120, v163, 3, s9
	v_ashrrev_i32_e32 v121, 31, v120
	v_lshl_add_u64 v[120:121], v[120:121], 1, s[10:11]
	v_mul_lo_u32 v164, s87, v146
	v_mul_lo_u32 v165, s86, v147
	v_mad_u64_u32 v[154:155], s[10:11], s86, v146, 0
	v_add3_u32 v155, v155, v165, v164
	v_lshl_add_u64 v[154:155], v[154:155], 1, v[120:121]
	v_cvt_pk_bf16_f32 v164, v150, v151
	v_cvt_pk_bf16_f32 v165, v126, v127
	v_cvt_pk_bf16_f32 v166, v124, v125
	v_cvt_pk_bf16_f32 v167, v122, v123
	v_mov_b32_e32 v153, v152
	global_store_dwordx4 v[154:155], v[164:167], off nt
	v_pk_mul_f32 v[116:117], v[116:117], v[152:153]
	s_and_b64 vcc, exec, s[6:7]
	v_mov_b32_e32 v164, v152
	v_mov_b32_e32 v165, v152
	v_pk_mul_f32 v[118:119], v[118:119], v[164:165]
	v_pk_mul_f32 v[114:115], v[114:115], v[164:165]
	v_pk_mul_f32 v[112:113], v[112:113], v[152:153]
	s_cbranch_vccnz .LBB0_358
	v_fma_f32 v152, |v116|, s90, 1.0
	v_fma_f32 v153, |v117|, s90, 1.0
	v_mov_b64_e32 v[164:165], s[94:95]
	v_rcp_f32_e32 v152, v152
	v_rcp_f32_e32 v153, v153
	v_pk_mul_f32 v[168:169], v[116:117], v[116:117]
	v_pk_mul_f32 v[168:169], v[168:169], s[18:19] op_sel_hi:[1,0]
	v_pk_fma_f32 v[166:167], v[152:153], s[92:93], v[164:165] op_sel_hi:[1,0,0]
	v_exp_f32_e32 v168, v168
	v_pk_fma_f32 v[166:167], v[152:153], v[166:167], s[96:97] op_sel_hi:[1,1,0]
	v_exp_f32_e32 v169, v169
	v_pk_fma_f32 v[166:167], v[152:153], v[166:167], s[16:17] op_sel_hi:[1,1,0]
	v_pk_fma_f32 v[166:167], v[152:153], v[166:167], s[84:85] op_sel_hi:[1,1,0]
	v_pk_mul_f32 v[152:153], v[152:153], v[166:167]
	v_pk_mul_f32 v[166:167], v[118:119], v[118:119]
	v_pk_mul_f32 v[152:153], v[168:169], v[152:153]
	v_pk_mul_f32 v[166:167], v[166:167], s[18:19] op_sel_hi:[1,0]
	v_max_f32_e32 v168, 0, v116
	v_max_f32_e32 v169, 0, v117
	v_exp_f32_e32 v166, v166
	v_fma_f32 v116, -|v116|, v152, v168
	v_fma_f32 v117, -|v117|, v153, v169
	v_exp_f32_e32 v167, v167
	v_fma_f32 v152, |v118|, s90, 1.0
	v_fma_f32 v153, |v119|, s90, 1.0
	v_rcp_f32_e32 v152, v152
	v_rcp_f32_e32 v153, v153
	s_nop 0
	v_pk_fma_f32 v[168:169], v[152:153], s[92:93], v[164:165] op_sel_hi:[1,0,0]
	v_pk_fma_f32 v[168:169], v[152:153], v[168:169], s[96:97] op_sel_hi:[1,1,0]
	v_pk_fma_f32 v[168:169], v[152:153], v[168:169], s[16:17] op_sel_hi:[1,1,0]
	v_pk_fma_f32 v[168:169], v[152:153], v[168:169], s[84:85] op_sel_hi:[1,1,0]
	v_pk_mul_f32 v[152:153], v[152:153], v[168:169]
	v_pk_mul_f32 v[168:169], v[112:113], v[112:113]
	v_pk_mul_f32 v[152:153], v[166:167], v[152:153]
	v_pk_mul_f32 v[168:169], v[168:169], s[18:19] op_sel_hi:[1,0]
	v_max_f32_e32 v166, 0, v118
	v_max_f32_e32 v167, 0, v119
	v_exp_f32_e32 v168, v168
	v_fma_f32 v118, -|v118|, v152, v166
	v_fma_f32 v119, -|v119|, v153, v167
	v_exp_f32_e32 v169, v169
	v_fma_f32 v152, |v112|, s90, 1.0
	v_fma_f32 v153, |v113|, s90, 1.0
	v_rcp_f32_e32 v152, v152
	v_rcp_f32_e32 v153, v153
	s_nop 0
	v_pk_fma_f32 v[166:167], v[152:153], s[92:93], v[164:165] op_sel_hi:[1,0,0]
	v_pk_fma_f32 v[166:167], v[152:153], v[166:167], s[96:97] op_sel_hi:[1,1,0]
	v_pk_fma_f32 v[166:167], v[152:153], v[166:167], s[16:17] op_sel_hi:[1,1,0]
	v_pk_fma_f32 v[166:167], v[152:153], v[166:167], s[84:85] op_sel_hi:[1,1,0]
	v_pk_mul_f32 v[152:153], v[152:153], v[166:167]
	v_pk_mul_f32 v[166:167], v[114:115], v[114:115]
	v_pk_mul_f32 v[152:153], v[168:169], v[152:153]
	v_max_f32_e32 v168, 0, v112
	v_max_f32_e32 v169, 0, v113
	v_fma_f32 v112, -|v112|, v152, v168
	v_fma_f32 v113, -|v113|, v153, v169
	s_nop 0
	v_fma_f32 v152, |v114|, s90, 1.0
	v_fma_f32 v153, |v115|, s90, 1.0
	v_rcp_f32_e32 v152, v152
	v_rcp_f32_e32 v153, v153
	s_nop 0
	v_pk_fma_f32 v[164:165], v[152:153], s[92:93], v[164:165] op_sel_hi:[1,0,0]
	v_pk_fma_f32 v[164:165], v[152:153], v[164:165], s[96:97] op_sel_hi:[1,1,0]
	v_pk_fma_f32 v[164:165], v[152:153], v[164:165], s[16:17] op_sel_hi:[1,1,0]
	v_pk_fma_f32 v[164:165], v[152:153], v[164:165], s[84:85] op_sel_hi:[1,1,0]
	v_pk_mul_f32 v[152:153], v[152:153], v[164:165]
	v_pk_mul_f32 v[164:165], v[166:167], s[18:19] op_sel_hi:[1,0]
	v_exp_f32_e32 v164, v164
	v_exp_f32_e32 v165, v165
	s_nop 0
	v_pk_mul_f32 v[152:153], v[164:165], v[152:153]
	v_max_f32_e32 v164, 0, v114
	v_max_f32_e32 v165, 0, v115
	v_fma_f32 v114, -|v114|, v152, v164
	v_fma_f32 v115, -|v115|, v153, v165
	s_nop 1
.LBB0_358:
	s_and_b32 s9, s8, -4
	s_cmp_eq_u32 s9, 4
	s_cselect_b64 s[14:15], -1, 0
	s_lshl_b32 s12, s8, 2
	s_cmp_lg_u32 s9, 4
	v_cmp_eq_u32_e64 s[8:9], 0, v163
	v_cvt_pk_bf16_f32 v164, v116, v117
	v_cvt_pk_bf16_f32 v165, v118, v119
	v_cvt_pk_bf16_f32 v166, v112, v113
	v_cvt_pk_bf16_f32 v167, v114, v115
	global_store_dwordx4 v[154:155], v[164:167], off offset:256 nt
	s_cbranch_scc1 .LBB0_362
	v_add_f32_e32 v152, v150, v151
	v_add_f32_e32 v153, v126, v127
	v_add_f32_e32 v152, v152, v153
	v_add_f32_e32 v153, v124, v125
	v_add_f32_e32 v154, v122, v123
	v_mul_f32_e32 v125, v125, v125
	v_mul_f32_e32 v123, v123, v123
	v_fmac_f32_e32 v125, v124, v124
	v_fmac_f32_e32 v123, v122, v122
	v_add_f32_e32 v122, v125, v123
	v_mul_f32_e32 v123, v117, v117
	v_mul_f32_e32 v124, v119, v119
	v_fmac_f32_e32 v123, v116, v116
	v_fmac_f32_e32 v124, v118, v118
	v_add_f32_e32 v123, v123, v124
	v_mul_f32_e32 v124, v113, v113
	v_fmac_f32_e32 v124, v112, v112
	v_mul_f32_e32 v125, v115, v115
	v_add_f32_e32 v112, v112, v113
	v_add_f32_e32 v113, v114, v115
	v_and_b32_e32 v115, 64, v162
	v_add_f32_e32 v153, v153, v154
	v_add_f32_e32 v116, v116, v117
	v_add_f32_e32 v117, v118, v119
	v_add_f32_e32 v112, v112, v113
	v_xor_b32_e32 v113, 16, v162
	v_add_u32_e32 v115, 64, v115
	v_add_f32_e32 v152, v152, v153
	v_add_f32_e32 v116, v116, v117
	v_cmp_lt_i32_e32 vcc, v113, v115
	v_add_f32_e32 v152, 0, v152
	v_mul_f32_e32 v151, v151, v151
	v_mul_f32_e32 v127, v127, v127
	v_add_f32_e32 v112, v116, v112
	v_cndmask_b32_e32 v113, v162, v113, vcc
	v_fmac_f32_e32 v151, v150, v150
	v_fmac_f32_e32 v127, v126, v126
	v_add_f32_e32 v112, v152, v112
	v_lshlrev_b32_e32 v113, 2, v113
	v_fmac_f32_e32 v125, v114, v114
	v_add_f32_e32 v126, v151, v127
	ds_bpermute_b32 v116, v113, v112
	v_add_f32_e32 v114, v124, v125
	v_add_f32_e32 v122, v126, v122
	v_add_f32_e32 v114, v123, v114
	v_add_f32_e32 v114, v122, v114
	ds_bpermute_b32 v117, v113, v114
	s_waitcnt lgkmcnt(1)
	v_add_f32_e32 v112, v112, v116
	v_xor_b32_e32 v116, 32, v162
	v_cmp_lt_i32_e32 vcc, v116, v115
	s_waitcnt lgkmcnt(0)
	v_add_f32_e32 v114, v114, v117
	v_cndmask_b32_e32 v113, v162, v116, vcc
	v_lshlrev_b32_e32 v115, 2, v113
	ds_bpermute_b32 v113, v115, v112
	ds_bpermute_b32 v115, v115, v114
	s_and_saveexec_b64 s[10:11], s[8:9]
	s_cbranch_execz .LBB0_361
	s_waitcnt lgkmcnt(0)
	v_add_f32_e32 v114, v114, v115
	v_add_f32_e32 v115, v112, v113
	v_lshlrev_b64 v[112:113], 7, v[146:147]
	v_lshl_add_u64 v[112:113], s[78:79], 0, v[112:113]
	v_lshl_add_u64 v[112:113], s[12:13], 2, v[112:113]
	s_lshl_b32 s46, s36, 2
	s_mov_b32 s47, s13
	v_lshl_add_u64 v[112:113], v[112:113], 0, s[46:47]
	global_store_dword v[112:113], v115, off offset:-64
	global_store_dword v[112:113], v114, off

; __device__ __forceinline__ u32x4 pack8(f32x4 v0, f32x4 v1) { u32x4 w; w.x = cvt_pk_bf16(v0[0], v0[1]); w.y = cvt_pk_bf16(v0[2], v0[3]); w.z = cvt_pk_bf16(v1[0], v1[1]); w.w = cvt_pk_bf16(v1[2], v1[3]); return w; }
; __device__ __forceinline__ f32x4 gelu4(f32x4 v) { f32x2 a = gelu_pk((f32x2){v[0], v[1]}), b = gelu_pk((f32x2){v[2], v[3]}); return (f32x4){a.x, a.y, b.x, b.y}; }
; __device__ __forceinline__ f32x2 gelu_pk(f32x2 v) {
;     const f32x2 av = __builtin_elementwise_abs(v), d = av * 0.2316418882f + 1.0f;
;     f32x2 t; t.x = __builtin_amdgcn_rcpf(d.x); t.y = __builtin_amdgcn_rcpf(d.y);
;     f32x2 q = t * 0.5307027145f + (-0.7265760135f); q = q * t + 0.7107068705f; q = q * t + (-0.142248368f); q = q * t + 0.127414796f; q = q * t;
;     const f32x2 s = (v * v) * (-0.72134752044f);
;     f32x2 e; e.x = __builtin_amdgcn_exp2f(s.x); e.y = __builtin_amdgcn_exp2f(s.y);
;     const f32x2 m = v * (q * e), r = v - m;
;     f32x2 o; o.x = v.x < 0.f ? m.x : r.x; o.y = v.y < 0.f ? m.y : r.y; return o;
; }
;     __device__ __forceinline__ void operator()(f32x4 (&acc)[2][2][4][2], const Unit& u, int wr, int wc, int fr_, int fq_) const {
;     ...
;             for (int m = 0; m < 4; ++m) { const int row = row0 + ai * HALF + m * 16; const float rs = rstd[row]; bf16_t* rowp = base + (size_t)row * ld + col0;
;                 float s1 = 0.f, s2 = 0.f;
; #pragma unroll
;                 for (int bj = 0; bj < 2; ++bj) { f32x4 v0 = acc[ai][bj][m][0] * rs, v1 = acc[ai][bj][m][1] * rs;
;                     if (act) { v0 = gelu4(v0); v1 = gelu4(v1); }
;                     s1 += ((v0[0] + v0[1]) + (v0[2] + v0[3])) + ((v1[0] + v1[1]) + (v1[2] + v1[3]));
;                     s2 += ((v0[0] * v0[0] + v0[1] * v0[1]) + (v0[2] * v0[2] + v0[3] * v0[3])) + ((v1[0] * v1[0] + v1[1] * v1[1]) + (v1[2] * v1[2] + v1[3] * v1[3]));
;                     *(u32x4*)(rowp + bj * HALF) = pack8(v0, v1); }
;                 if (pn >= 4 && pn < 8) { s1 += __shfl_xor(s1, 16); s1 += __shfl_xor(s1, 32); s2 += __shfl_xor(s2, 16); s2 += __shfl_xor(s2, 32);
;                     if (fq == 0) { lns[(size_t)row * 32 + (pn - 4) * 4 + wc] = s1; lns[(size_t)row * 32 + 16 + (pn - 4) * 4 + wc] = s2; } } }
.LBB0_364:
	v_add_u32_e32 v112, 16, v146
	v_ashrrev_i32_e32 v113, 31, v112
	v_mul_lo_u32 v118, s86, v113
	v_mul_lo_u32 v119, s87, v112
	v_mad_u64_u32 v[116:117], s[10:11], s86, v112, 0
	v_mov_b32_e32 v115, v114
	v_add3_u32 v117, v117, v118, v119
	v_mov_b32_e32 v118, v114
	v_mov_b32_e32 v119, v114
	v_lshl_add_u64 v[116:117], v[116:117], 1, v[120:121]
	v_cvt_pk_bf16_f32 v122, v108, v109
	v_cvt_pk_bf16_f32 v123, v110, v111
	v_cvt_pk_bf16_f32 v124, v104, v105
	v_cvt_pk_bf16_f32 v125, v106, v107
	v_pk_mul_f32 v[102:103], v[102:103], v[118:119]
	v_pk_mul_f32 v[100:101], v[100:101], v[114:115]
	v_pk_mul_f32 v[98:99], v[98:99], v[118:119]
	s_and_b64 vcc, exec, s[6:7]
	v_pk_mul_f32 v[96:97], v[96:97], v[114:115]
	global_store_dwordx4 v[116:117], v[122:125], off nt
	s_cbranch_vccnz .LBB0_366
	v_fma_f32 v114, |v100|, s90, 1.0
	v_fma_f32 v115, |v101|, s90, 1.0
	v_mov_b64_e32 v[118:119], s[94:95]
	v_rcp_f32_e32 v114, v114
	v_rcp_f32_e32 v115, v115
	v_pk_mul_f32 v[124:125], v[100:101], v[100:101]
	v_pk_mul_f32 v[124:125], v[124:125], s[18:19] op_sel_hi:[1,0]
	v_pk_fma_f32 v[122:123], v[114:115], s[92:93], v[118:119] op_sel_hi:[1,0,0]
	v_exp_f32_e32 v124, v124
	v_pk_fma_f32 v[122:123], v[114:115], v[122:123], s[96:97] op_sel_hi:[1,1,0]
	v_exp_f32_e32 v125, v125
	v_pk_fma_f32 v[122:123], v[114:115], v[122:123], s[16:17] op_sel_hi:[1,1,0]
	v_pk_fma_f32 v[122:123], v[114:115], v[122:123], s[84:85] op_sel_hi:[1,1,0]
	v_pk_mul_f32 v[114:115], v[114:115], v[122:123]
	v_pk_mul_f32 v[122:123], v[102:103], v[102:103]
	v_pk_mul_f32 v[114:115], v[124:125], v[114:115]
	v_pk_mul_f32 v[122:123], v[122:123], s[18:19] op_sel_hi:[1,0]
	v_max_f32_e32 v124, 0, v100
	v_max_f32_e32 v125, 0, v101
	v_exp_f32_e32 v122, v122
	v_fma_f32 v100, -|v100|, v114, v124
	v_fma_f32 v101, -|v101|, v115, v125
	v_exp_f32_e32 v123, v123
	v_fma_f32 v114, |v102|, s90, 1.0
	v_fma_f32 v115, |v103|, s90, 1.0
	v_rcp_f32_e32 v114, v114
	v_rcp_f32_e32 v115, v115
	s_nop 0
	v_pk_fma_f32 v[124:125], v[114:115], s[92:93], v[118:119] op_sel_hi:[1,0,0]
	v_pk_fma_f32 v[124:125], v[114:115], v[124:125], s[96:97] op_sel_hi:[1,1,0]
	v_pk_fma_f32 v[124:125], v[114:115], v[124:125], s[16:17] op_sel_hi:[1,1,0]
	v_pk_fma_f32 v[124:125], v[114:115], v[124:125], s[84:85] op_sel_hi:[1,1,0]
	v_pk_mul_f32 v[114:115], v[114:115], v[124:125]
	v_pk_mul_f32 v[124:125], v[96:97], v[96:97]
	v_pk_mul_f32 v[114:115], v[122:123], v[114:115]
	v_pk_mul_f32 v[124:125], v[124:125], s[18:19] op_sel_hi:[1,0]
	v_max_f32_e32 v122, 0, v102
	v_max_f32_e32 v123, 0, v103
	v_exp_f32_e32 v124, v124
	v_fma_f32 v102, -|v102|, v114, v122
	v_fma_f32 v103, -|v103|, v115, v123
	v_exp_f32_e32 v125, v125
	v_fma_f32 v114, |v96|, s90, 1.0
	v_fma_f32 v115, |v97|, s90, 1.0
	v_rcp_f32_e32 v114, v114
	v_rcp_f32_e32 v115, v115
	s_nop 0
	v_pk_fma_f32 v[122:123], v[114:115], s[92:93], v[118:119] op_sel_hi:[1,0,0]
	v_pk_fma_f32 v[122:123], v[114:115], v[122:123], s[96:97] op_sel_hi:[1,1,0]
	v_pk_fma_f32 v[122:123], v[114:115], v[122:123], s[16:17] op_sel_hi:[1,1,0]
	v_pk_fma_f32 v[122:123], v[114:115], v[122:123], s[84:85] op_sel_hi:[1,1,0]
	v_pk_mul_f32 v[114:115], v[114:115], v[122:123]
	v_pk_mul_f32 v[122:123], v[98:99], v[98:99]
	v_pk_mul_f32 v[114:115], v[124:125], v[114:115]
	v_max_f32_e32 v124, 0, v96
	v_max_f32_e32 v125, 0, v97
	v_fma_f32 v96, -|v96|, v114, v124
	v_fma_f32 v97, -|v97|, v115, v125
	s_nop 0
	v_fma_f32 v114, |v98|, s90, 1.0
	v_fma_f32 v115, |v99|, s90, 1.0
	v_rcp_f32_e32 v114, v114
	v_rcp_f32_e32 v115, v115
	s_nop 0
	v_pk_fma_f32 v[118:119], v[114:115], s[92:93], v[118:119] op_sel_hi:[1,0,0]
	v_pk_fma_f32 v[118:119], v[114:115], v[118:119], s[96:97] op_sel_hi:[1,1,0]
	v_pk_fma_f32 v[118:119], v[114:115], v[118:119], s[16:17] op_sel_hi:[1,1,0]
	v_pk_fma_f32 v[118:119], v[114:115], v[118:119], s[84:85] op_sel_hi:[1,1,0]
	v_pk_mul_f32 v[114:115], v[114:115], v[118:119]
	v_pk_mul_f32 v[118:119], v[122:123], s[18:19] op_sel_hi:[1,0]
	v_exp_f32_e32 v118, v118
	v_exp_f32_e32 v119, v119
	s_nop 0
	v_pk_mul_f32 v[114:115], v[118:119], v[114:115]
	v_max_f32_e32 v118, 0, v98
	v_max_f32_e32 v119, 0, v99
	v_fma_f32 v98, -|v98|, v114, v118
	v_fma_f32 v99, -|v99|, v115, v119
	s_nop 1
.LBB0_366:
	v_cndmask_b32_e64 v114, 0, 1, s[14:15]
	v_cvt_pk_bf16_f32 v122, v100, v101
	v_cvt_pk_bf16_f32 v123, v102, v103
	v_cvt_pk_bf16_f32 v124, v96, v97
	v_cvt_pk_bf16_f32 v125, v98, v99
	v_cmp_ne_u32_e64 s[10:11], 1, v114
	s_andn2_b64 vcc, exec, s[14:15]
	global_store_dwordx4 v[116:117], v[122:125], off offset:256 nt
	s_cbranch_vccnz .LBB0_370
	v_add_f32_e32 v114, v108, v109
	v_add_f32_e32 v115, v110, v111
	v_add_f32_e32 v114, v114, v115
	v_add_f32_e32 v115, v104, v105
	v_mul_f32_e32 v105, v105, v105
	v_fmac_f32_e32 v105, v104, v104
	v_mul_f32_e32 v104, v107, v107
	v_fmac_f32_e32 v104, v106, v106
	v_add_f32_e32 v116, v106, v107
	v_add_f32_e32 v104, v105, v104
	v_mul_f32_e32 v105, v101, v101
	v_mul_f32_e32 v106, v103, v103
	v_fmac_f32_e32 v105, v100, v100
	v_fmac_f32_e32 v106, v102, v102
	v_add_f32_e32 v105, v105, v106
	v_mul_f32_e32 v106, v97, v97
	v_fmac_f32_e32 v106, v96, v96
	v_mul_f32_e32 v107, v99, v99
	v_add_f32_e32 v96, v96, v97
	v_add_f32_e32 v97, v98, v99
	v_and_b32_e32 v99, 64, v162
	v_add_f32_e32 v115, v115, v116
	v_add_f32_e32 v100, v100, v101
	v_add_f32_e32 v101, v102, v103
	v_add_f32_e32 v96, v96, v97
	v_xor_b32_e32 v97, 16, v162
	v_add_u32_e32 v99, 64, v99
	v_add_f32_e32 v114, v114, v115
	v_mul_f32_e32 v109, v109, v109
	v_add_f32_e32 v100, v100, v101
	v_cmp_lt_i32_e32 vcc, v97, v99
	v_add_f32_e32 v114, 0, v114
	v_fmac_f32_e32 v109, v108, v108
	v_mul_f32_e32 v108, v111, v111
	v_add_f32_e32 v96, v100, v96
	v_cndmask_b32_e32 v97, v162, v97, vcc
	v_fmac_f32_e32 v108, v110, v110
	v_add_f32_e32 v96, v114, v96
	v_lshlrev_b32_e32 v97, 2, v97
	v_fmac_f32_e32 v107, v98, v98
	v_add_f32_e32 v108, v109, v108
	ds_bpermute_b32 v100, v97, v96
	v_add_f32_e32 v98, v106, v107
	v_add_f32_e32 v104, v108, v104
	v_add_f32_e32 v98, v105, v98
	v_add_f32_e32 v98, v104, v98
	ds_bpermute_b32 v101, v97, v98
	s_waitcnt lgkmcnt(1)
	v_add_f32_e32 v96, v96, v100
	v_xor_b32_e32 v100, 32, v162
	v_cmp_lt_i32_e32 vcc, v100, v99
	s_waitcnt lgkmcnt(0)
	v_add_f32_e32 v98, v98, v101
	v_cndmask_b32_e32 v97, v162, v100, vcc
	v_lshlrev_b32_e32 v99, 2, v97
	ds_bpermute_b32 v97, v99, v96
	ds_bpermute_b32 v99, v99, v98
	s_and_saveexec_b64 s[14:15], s[8:9]
	s_cbranch_execz .LBB0_369
	s_waitcnt lgkmcnt(0)
	v_add_f32_e32 v98, v98, v99
	v_add_f32_e32 v99, v96, v97
	v_lshlrev_b64 v[96:97], 7, v[112:113]
	v_lshl_add_u64 v[96:97], s[78:79], 0, v[96:97]
	v_lshl_add_u64 v[96:97], s[12:13], 2, v[96:97]
	s_lshl_b32 s46, s36, 2
	s_mov_b32 s47, s13
	v_lshl_add_u64 v[96:97], v[96:97], 0, s[46:47]
	global_store_dword v[96:97], v99, off offset:-64
	global_store_dword v[96:97], v98, off

; __device__ __forceinline__ u32x4 pack8(f32x4 v0, f32x4 v1) { u32x4 w; w.x = cvt_pk_bf16(v0[0], v0[1]); w.y = cvt_pk_bf16(v0[2], v0[3]); w.z = cvt_pk_bf16(v1[0], v1[1]); w.w = cvt_pk_bf16(v1[2], v1[3]); return w; }
; __device__ __forceinline__ f32x4 gelu4(f32x4 v) { f32x2 a = gelu_pk((f32x2){v[0], v[1]}), b = gelu_pk((f32x2){v[2], v[3]}); return (f32x4){a.x, a.y, b.x, b.y}; }
; __device__ __forceinline__ f32x2 gelu_pk(f32x2 v) {
;     const f32x2 av = __builtin_elementwise_abs(v), d = av * 0.2316418882f + 1.0f;
;     f32x2 t; t.x = __builtin_amdgcn_rcpf(d.x); t.y = __builtin_amdgcn_rcpf(d.y);
;     f32x2 q = t * 0.5307027145f + (-0.7265760135f); q = q * t + 0.7107068705f; q = q * t + (-0.142248368f); q = q * t + 0.127414796f; q = q * t;
;     const f32x2 s = (v * v) * (-0.72134752044f);
;     f32x2 e; e.x = __builtin_amdgcn_exp2f(s.x); e.y = __builtin_amdgcn_exp2f(s.y);
;     const f32x2 m = v * (q * e), r = v - m;
;     f32x2 o; o.x = v.x < 0.f ? m.x : r.x; o.y = v.y < 0.f ? m.y : r.y; return o;
; }
;     __device__ __forceinline__ void operator()(f32x4 (&acc)[2][2][4][2], const Unit& u, int wr, int wc, int fr_, int fq_) const {
;     ...
;             for (int m = 0; m < 4; ++m) { const int row = row0 + ai * HALF + m * 16; const float rs = rstd[row]; bf16_t* rowp = base + (size_t)row * ld + col0;
;                 float s1 = 0.f, s2 = 0.f;
; #pragma unroll
;                 for (int bj = 0; bj < 2; ++bj) { f32x4 v0 = acc[ai][bj][m][0] * rs, v1 = acc[ai][bj][m][1] * rs;
;                     if (act) { v0 = gelu4(v0); v1 = gelu4(v1); }
;                     s1 += ((v0[0] + v0[1]) + (v0[2] + v0[3])) + ((v1[0] + v1[1]) + (v1[2] + v1[3]));
;                     s2 += ((v0[0] * v0[0] + v0[1] * v0[1]) + (v0[2] * v0[2] + v0[3] * v0[3])) + ((v1[0] * v1[0] + v1[1] * v1[1]) + (v1[2] * v1[2] + v1[3] * v1[3]));
;                     *(u32x4*)(rowp + bj * HALF) = pack8(v0, v1); }
;                 if (pn >= 4 && pn < 8) { s1 += __shfl_xor(s1, 16); s1 += __shfl_xor(s1, 32); s2 += __shfl_xor(s2, 16); s2 += __shfl_xor(s2, 32);
;                     if (fq == 0) { lns[(size_t)row * 32 + (pn - 4) * 4 + wc] = s1; lns[(size_t)row * 32 + 16 + (pn - 4) * 4 + wc] = s2; } } }
.LBB0_372:
	v_add_u32_e32 v96, 32, v146
	v_ashrrev_i32_e32 v97, 31, v96
	v_mul_lo_u32 v102, s86, v97
	v_mul_lo_u32 v103, s87, v96
	v_mad_u64_u32 v[100:101], s[14:15], s86, v96, 0
	v_add3_u32 v101, v101, v102, v103
	v_lshl_add_u64 v[100:101], v[100:101], 1, v[120:121]
	v_cvt_pk_bf16_f32 v102, v92, v93
	v_cvt_pk_bf16_f32 v103, v94, v95
	v_cvt_pk_bf16_f32 v104, v88, v89
	v_cvt_pk_bf16_f32 v105, v90, v91
	v_mov_b32_e32 v99, v98
	global_store_dwordx4 v[100:101], v[102:105], off nt
	v_pk_mul_f32 v[84:85], v[84:85], v[98:99]
	s_and_b64 vcc, exec, s[6:7]
	v_mov_b32_e32 v102, v98
	v_mov_b32_e32 v103, v98
	v_pk_mul_f32 v[86:87], v[86:87], v[102:103]
	v_pk_mul_f32 v[82:83], v[82:83], v[102:103]
	v_pk_mul_f32 v[80:81], v[80:81], v[98:99]
	s_cbranch_vccnz .LBB0_374
	v_fma_f32 v98, |v84|, s90, 1.0
	v_fma_f32 v99, |v85|, s90, 1.0
	v_mov_b64_e32 v[102:103], s[94:95]
	v_rcp_f32_e32 v98, v98
	v_rcp_f32_e32 v99, v99
	v_pk_mul_f32 v[106:107], v[84:85], v[84:85]
	v_pk_mul_f32 v[106:107], v[106:107], s[18:19] op_sel_hi:[1,0]
	v_pk_fma_f32 v[104:105], v[98:99], s[92:93], v[102:103] op_sel_hi:[1,0,0]
	v_exp_f32_e32 v106, v106
	v_pk_fma_f32 v[104:105], v[98:99], v[104:105], s[96:97] op_sel_hi:[1,1,0]
	v_exp_f32_e32 v107, v107
	v_pk_fma_f32 v[104:105], v[98:99], v[104:105], s[16:17] op_sel_hi:[1,1,0]
	v_pk_fma_f32 v[104:105], v[98:99], v[104:105], s[84:85] op_sel_hi:[1,1,0]
	v_pk_mul_f32 v[98:99], v[98:99], v[104:105]
	v_pk_mul_f32 v[104:105], v[86:87], v[86:87]
	v_pk_mul_f32 v[98:99], v[106:107], v[98:99]
	v_pk_mul_f32 v[104:105], v[104:105], s[18:19] op_sel_hi:[1,0]
	v_max_f32_e32 v106, 0, v84
	v_max_f32_e32 v107, 0, v85
	v_exp_f32_e32 v104, v104
	v_fma_f32 v84, -|v84|, v98, v106
	v_fma_f32 v85, -|v85|, v99, v107
	v_exp_f32_e32 v105, v105
	v_fma_f32 v98, |v86|, s90, 1.0
	v_fma_f32 v99, |v87|, s90, 1.0
	v_rcp_f32_e32 v98, v98
	v_rcp_f32_e32 v99, v99
	s_nop 0
	v_pk_fma_f32 v[106:107], v[98:99], s[92:93], v[102:103] op_sel_hi:[1,0,0]
	v_pk_fma_f32 v[106:107], v[98:99], v[106:107], s[96:97] op_sel_hi:[1,1,0]
	v_pk_fma_f32 v[106:107], v[98:99], v[106:107], s[16:17] op_sel_hi:[1,1,0]
	v_pk_fma_f32 v[106:107], v[98:99], v[106:107], s[84:85] op_sel_hi:[1,1,0]
	v_pk_mul_f32 v[98:99], v[98:99], v[106:107]
	v_pk_mul_f32 v[106:107], v[80:81], v[80:81]
	v_pk_mul_f32 v[98:99], v[104:105], v[98:99]
	v_pk_mul_f32 v[106:107], v[106:107], s[18:19] op_sel_hi:[1,0]
	v_max_f32_e32 v104, 0, v86
	v_max_f32_e32 v105, 0, v87
	v_exp_f32_e32 v106, v106
	v_fma_f32 v86, -|v86|, v98, v104
	v_fma_f32 v87, -|v87|, v99, v105
	v_exp_f32_e32 v107, v107
	v_fma_f32 v98, |v80|, s90, 1.0
	v_fma_f32 v99, |v81|, s90, 1.0
	v_rcp_f32_e32 v98, v98
	v_rcp_f32_e32 v99, v99
	s_nop 0
	v_pk_fma_f32 v[104:105], v[98:99], s[92:93], v[102:103] op_sel_hi:[1,0,0]
	v_pk_fma_f32 v[104:105], v[98:99], v[104:105], s[96:97] op_sel_hi:[1,1,0]
	v_pk_fma_f32 v[104:105], v[98:99], v[104:105], s[16:17] op_sel_hi:[1,1,0]
	v_pk_fma_f32 v[104:105], v[98:99], v[104:105], s[84:85] op_sel_hi:[1,1,0]
	v_pk_mul_f32 v[98:99], v[98:99], v[104:105]
	v_pk_mul_f32 v[104:105], v[82:83], v[82:83]
	v_pk_mul_f32 v[98:99], v[106:107], v[98:99]
	v_max_f32_e32 v106, 0, v80
	v_max_f32_e32 v107, 0, v81
	v_fma_f32 v80, -|v80|, v98, v106
	v_fma_f32 v81, -|v81|, v99, v107
	s_nop 0
	v_fma_f32 v98, |v82|, s90, 1.0
	v_fma_f32 v99, |v83|, s90, 1.0
	v_rcp_f32_e32 v98, v98
	v_rcp_f32_e32 v99, v99
	s_nop 0
	v_pk_fma_f32 v[102:103], v[98:99], s[92:93], v[102:103] op_sel_hi:[1,0,0]
	v_pk_fma_f32 v[102:103], v[98:99], v[102:103], s[96:97] op_sel_hi:[1,1,0]
	v_pk_fma_f32 v[102:103], v[98:99], v[102:103], s[16:17] op_sel_hi:[1,1,0]
	v_pk_fma_f32 v[102:103], v[98:99], v[102:103], s[84:85] op_sel_hi:[1,1,0]
	v_pk_mul_f32 v[98:99], v[98:99], v[102:103]
	v_pk_mul_f32 v[102:103], v[104:105], s[18:19] op_sel_hi:[1,0]
	v_exp_f32_e32 v102, v102
	v_exp_f32_e32 v103, v103
	s_nop 0
	v_pk_mul_f32 v[98:99], v[102:103], v[98:99]
	v_max_f32_e32 v102, 0, v82
	v_max_f32_e32 v103, 0, v83
	v_fma_f32 v82, -|v82|, v98, v102
	v_fma_f32 v83, -|v83|, v99, v103
	s_nop 1
.LBB0_374:
	v_cvt_pk_bf16_f32 v102, v84, v85
	v_cvt_pk_bf16_f32 v103, v86, v87
	v_cvt_pk_bf16_f32 v104, v80, v81
	v_cvt_pk_bf16_f32 v105, v82, v83
	s_and_b64 vcc, exec, s[10:11]
	global_store_dwordx4 v[100:101], v[102:105], off offset:256 nt
	s_cbranch_vccnz .LBB0_378
	v_add_f32_e32 v98, v92, v93
	v_add_f32_e32 v99, v94, v95
	v_add_f32_e32 v98, v98, v99
	v_add_f32_e32 v99, v88, v89
	v_mul_f32_e32 v89, v89, v89
	v_fmac_f32_e32 v89, v88, v88
	v_mul_f32_e32 v88, v91, v91
	v_fmac_f32_e32 v88, v90, v90
	v_add_f32_e32 v100, v90, v91
	v_add_f32_e32 v88, v89, v88
	v_mul_f32_e32 v89, v85, v85
	v_mul_f32_e32 v90, v87, v87
	v_fmac_f32_e32 v89, v84, v84
	v_fmac_f32_e32 v90, v86, v86
	v_add_f32_e32 v89, v89, v90
	v_mul_f32_e32 v90, v81, v81
	v_fmac_f32_e32 v90, v80, v80
	v_mul_f32_e32 v91, v83, v83
	v_add_f32_e32 v80, v80, v81
	v_add_f32_e32 v81, v82, v83
	v_and_b32_e32 v83, 64, v162
	v_add_f32_e32 v99, v99, v100
	v_add_f32_e32 v84, v84, v85
	v_add_f32_e32 v85, v86, v87
	v_add_f32_e32 v80, v80, v81
	v_xor_b32_e32 v81, 16, v162
	v_add_u32_e32 v83, 64, v83
	v_add_f32_e32 v98, v98, v99
	v_mul_f32_e32 v93, v93, v93
	v_add_f32_e32 v84, v84, v85
	v_cmp_lt_i32_e32 vcc, v81, v83
	v_add_f32_e32 v98, 0, v98
	v_fmac_f32_e32 v93, v92, v92
	v_mul_f32_e32 v92, v95, v95
	v_add_f32_e32 v80, v84, v80
	v_cndmask_b32_e32 v81, v162, v81, vcc
	v_fmac_f32_e32 v92, v94, v94
	v_add_f32_e32 v80, v98, v80
	v_lshlrev_b32_e32 v81, 2, v81
	v_fmac_f32_e32 v91, v82, v82
	v_add_f32_e32 v92, v93, v92
	ds_bpermute_b32 v84, v81, v80
	v_add_f32_e32 v82, v90, v91
	v_add_f32_e32 v88, v92, v88
	v_add_f32_e32 v82, v89, v82
	v_add_f32_e32 v82, v88, v82
	ds_bpermute_b32 v85, v81, v82
	s_waitcnt lgkmcnt(1)
	v_add_f32_e32 v80, v80, v84
	v_xor_b32_e32 v84, 32, v162
	v_cmp_lt_i32_e32 vcc, v84, v83
	s_waitcnt lgkmcnt(0)
	v_add_f32_e32 v82, v82, v85
	v_cndmask_b32_e32 v81, v162, v84, vcc
	v_lshlrev_b32_e32 v83, 2, v81
	ds_bpermute_b32 v81, v83, v80
	ds_bpermute_b32 v83, v83, v82
	s_and_saveexec_b64 s[14:15], s[8:9]
	s_cbranch_execz .LBB0_377
	s_waitcnt lgkmcnt(0)
	v_add_f32_e32 v82, v82, v83
	v_add_f32_e32 v83, v80, v81
	v_lshlrev_b64 v[80:81], 7, v[96:97]
	v_lshl_add_u64 v[80:81], s[78:79], 0, v[80:81]
	v_lshl_add_u64 v[80:81], s[12:13], 2, v[80:81]
	s_lshl_b32 s46, s36, 2
	s_mov_b32 s47, s13
	v_lshl_add_u64 v[80:81], v[80:81], 0, s[46:47]
	global_store_dword v[80:81], v83, off offset:-64
	global_store_dword v[80:81], v82, off

; __device__ __forceinline__ u32x4 pack8(f32x4 v0, f32x4 v1) { u32x4 w; w.x = cvt_pk_bf16(v0[0], v0[1]); w.y = cvt_pk_bf16(v0[2], v0[3]); w.z = cvt_pk_bf16(v1[0], v1[1]); w.w = cvt_pk_bf16(v1[2], v1[3]); return w; }
; __device__ __forceinline__ f32x4 gelu4(f32x4 v) { f32x2 a = gelu_pk((f32x2){v[0], v[1]}), b = gelu_pk((f32x2){v[2], v[3]}); return (f32x4){a.x, a.y, b.x, b.y}; }
; __device__ __forceinline__ f32x2 gelu_pk(f32x2 v) {
;     const f32x2 av = __builtin_elementwise_abs(v), d = av * 0.2316418882f + 1.0f;
;     f32x2 t; t.x = __builtin_amdgcn_rcpf(d.x); t.y = __builtin_amdgcn_rcpf(d.y);
;     f32x2 q = t * 0.5307027145f + (-0.7265760135f); q = q * t + 0.7107068705f; q = q * t + (-0.142248368f); q = q * t + 0.127414796f; q = q * t;
;     const f32x2 s = (v * v) * (-0.72134752044f);
;     f32x2 e; e.x = __builtin_amdgcn_exp2f(s.x); e.y = __builtin_amdgcn_exp2f(s.y);
;     const f32x2 m = v * (q * e), r = v - m;
;     f32x2 o; o.x = v.x < 0.f ? m.x : r.x; o.y = v.y < 0.f ? m.y : r.y; return o;
; }
;     __device__ __forceinline__ void operator()(f32x4 (&acc)[2][2][4][2], const Unit& u, int wr, int wc, int fr_, int fq_) const {
;     ...
;             for (int m = 0; m < 4; ++m) { const int row = row0 + ai * HALF + m * 16; const float rs = rstd[row]; bf16_t* rowp = base + (size_t)row * ld + col0;
;                 float s1 = 0.f, s2 = 0.f;
; #pragma unroll
;                 for (int bj = 0; bj < 2; ++bj) { f32x4 v0 = acc[ai][bj][m][0] * rs, v1 = acc[ai][bj][m][1] * rs;
;                     if (act) { v0 = gelu4(v0); v1 = gelu4(v1); }
;                     s1 += ((v0[0] + v0[1]) + (v0[2] + v0[3])) + ((v1[0] + v1[1]) + (v1[2] + v1[3]));
;                     s2 += ((v0[0] * v0[0] + v0[1] * v0[1]) + (v0[2] * v0[2] + v0[3] * v0[3])) + ((v1[0] * v1[0] + v1[1] * v1[1]) + (v1[2] * v1[2] + v1[3] * v1[3]));
;                     *(u32x4*)(rowp + bj * HALF) = pack8(v0, v1); }
;                 if (pn >= 4 && pn < 8) { s1 += __shfl_xor(s1, 16); s1 += __shfl_xor(s1, 32); s2 += __shfl_xor(s2, 16); s2 += __shfl_xor(s2, 32);
;                     if (fq == 0) { lns[(size_t)row * 32 + (pn - 4) * 4 + wc] = s1; lns[(size_t)row * 32 + 16 + (pn - 4) * 4 + wc] = s2; } } }
.LBB0_380:
	v_add_u32_e32 v80, 48, v146
	v_ashrrev_i32_e32 v81, 31, v80
	v_mul_lo_u32 v86, s86, v81
	v_mul_lo_u32 v87, s87, v80
	v_mad_u64_u32 v[84:85], s[14:15], s86, v80, 0
	v_add3_u32 v85, v85, v86, v87
	v_lshl_add_u64 v[84:85], v[84:85], 1, v[120:121]
	v_cvt_pk_bf16_f32 v86, v76, v77
	v_cvt_pk_bf16_f32 v87, v78, v79
	v_cvt_pk_bf16_f32 v88, v72, v73
	v_cvt_pk_bf16_f32 v89, v74, v75
	v_mov_b32_e32 v83, v82
	global_store_dwordx4 v[84:85], v[86:89], off nt
	v_pk_mul_f32 v[68:69], v[68:69], v[82:83]
	s_and_b64 vcc, exec, s[6:7]
	v_mov_b32_e32 v86, v82
	v_mov_b32_e32 v87, v82
	v_pk_mul_f32 v[70:71], v[70:71], v[86:87]
	v_pk_mul_f32 v[66:67], v[66:67], v[86:87]
	v_pk_mul_f32 v[64:65], v[64:65], v[82:83]
	s_cbranch_vccnz .LBB0_382
	v_fma_f32 v82, |v68|, s90, 1.0
	v_fma_f32 v83, |v69|, s90, 1.0
	v_mov_b64_e32 v[86:87], s[94:95]
	v_rcp_f32_e32 v82, v82
	v_rcp_f32_e32 v83, v83
	v_pk_mul_f32 v[90:91], v[68:69], v[68:69]
	v_pk_mul_f32 v[90:91], v[90:91], s[18:19] op_sel_hi:[1,0]
	v_pk_fma_f32 v[88:89], v[82:83], s[92:93], v[86:87] op_sel_hi:[1,0,0]
	v_exp_f32_e32 v90, v90
	v_pk_fma_f32 v[88:89], v[82:83], v[88:89], s[96:97] op_sel_hi:[1,1,0]
	v_exp_f32_e32 v91, v91
	v_pk_fma_f32 v[88:89], v[82:83], v[88:89], s[16:17] op_sel_hi:[1,1,0]
	v_pk_fma_f32 v[88:89], v[82:83], v[88:89], s[84:85] op_sel_hi:[1,1,0]
	v_pk_mul_f32 v[82:83], v[82:83], v[88:89]
	v_pk_mul_f32 v[88:89], v[70:71], v[70:71]
	v_pk_mul_f32 v[82:83], v[90:91], v[82:83]
	v_pk_mul_f32 v[88:89], v[88:89], s[18:19] op_sel_hi:[1,0]
	v_max_f32_e32 v90, 0, v68
	v_max_f32_e32 v91, 0, v69
	v_exp_f32_e32 v88, v88
	v_fma_f32 v68, -|v68|, v82, v90
	v_fma_f32 v69, -|v69|, v83, v91
	v_exp_f32_e32 v89, v89
	v_fma_f32 v82, |v70|, s90, 1.0
	v_fma_f32 v83, |v71|, s90, 1.0
	v_rcp_f32_e32 v82, v82
	v_rcp_f32_e32 v83, v83
	s_nop 0
	v_pk_fma_f32 v[90:91], v[82:83], s[92:93], v[86:87] op_sel_hi:[1,0,0]
	v_pk_fma_f32 v[90:91], v[82:83], v[90:91], s[96:97] op_sel_hi:[1,1,0]
	v_pk_fma_f32 v[90:91], v[82:83], v[90:91], s[16:17] op_sel_hi:[1,1,0]
	v_pk_fma_f32 v[90:91], v[82:83], v[90:91], s[84:85] op_sel_hi:[1,1,0]
	v_pk_mul_f32 v[82:83], v[82:83], v[90:91]
	v_pk_mul_f32 v[90:91], v[64:65], v[64:65]
	v_pk_mul_f32 v[82:83], v[88:89], v[82:83]
	v_pk_mul_f32 v[90:91], v[90:91], s[18:19] op_sel_hi:[1,0]
	v_max_f32_e32 v88, 0, v70
	v_max_f32_e32 v89, 0, v71
	v_exp_f32_e32 v90, v90
	v_fma_f32 v70, -|v70|, v82, v88
	v_fma_f32 v71, -|v71|, v83, v89
	v_exp_f32_e32 v91, v91
	v_fma_f32 v82, |v64|, s90, 1.0
	v_fma_f32 v83, |v65|, s90, 1.0
	v_rcp_f32_e32 v82, v82
	v_rcp_f32_e32 v83, v83
	s_nop 0
	v_pk_fma_f32 v[88:89], v[82:83], s[92:93], v[86:87] op_sel_hi:[1,0,0]
	v_pk_fma_f32 v[88:89], v[82:83], v[88:89], s[96:97] op_sel_hi:[1,1,0]
	v_pk_fma_f32 v[88:89], v[82:83], v[88:89], s[16:17] op_sel_hi:[1,1,0]
	v_pk_fma_f32 v[88:89], v[82:83], v[88:89], s[84:85] op_sel_hi:[1,1,0]
	v_pk_mul_f32 v[82:83], v[82:83], v[88:89]
	v_pk_mul_f32 v[88:89], v[66:67], v[66:67]
	v_pk_mul_f32 v[82:83], v[90:91], v[82:83]
	v_max_f32_e32 v90, 0, v64
	v_max_f32_e32 v91, 0, v65
	v_fma_f32 v64, -|v64|, v82, v90
	v_fma_f32 v65, -|v65|, v83, v91
	s_nop 0
	v_fma_f32 v82, |v66|, s90, 1.0
	v_fma_f32 v83, |v67|, s90, 1.0
	v_rcp_f32_e32 v82, v82
	v_rcp_f32_e32 v83, v83
	s_nop 0
	v_pk_fma_f32 v[86:87], v[82:83], s[92:93], v[86:87] op_sel_hi:[1,0,0]
	v_pk_fma_f32 v[86:87], v[82:83], v[86:87], s[96:97] op_sel_hi:[1,1,0]
	v_pk_fma_f32 v[86:87], v[82:83], v[86:87], s[16:17] op_sel_hi:[1,1,0]
	v_pk_fma_f32 v[86:87], v[82:83], v[86:87], s[84:85] op_sel_hi:[1,1,0]
	v_pk_mul_f32 v[82:83], v[82:83], v[86:87]
	v_pk_mul_f32 v[86:87], v[88:89], s[18:19] op_sel_hi:[1,0]
	v_exp_f32_e32 v86, v86
	v_exp_f32_e32 v87, v87
	s_nop 0
	v_pk_mul_f32 v[82:83], v[86:87], v[82:83]
	v_max_f32_e32 v86, 0, v66
	v_max_f32_e32 v87, 0, v67
	v_fma_f32 v66, -|v66|, v82, v86
	v_fma_f32 v67, -|v67|, v83, v87
	s_nop 1
.LBB0_382:
	v_cvt_pk_bf16_f32 v86, v68, v69
	v_cvt_pk_bf16_f32 v87, v70, v71
	v_cvt_pk_bf16_f32 v88, v64, v65
	v_cvt_pk_bf16_f32 v89, v66, v67
	s_and_b64 vcc, exec, s[10:11]
	global_store_dwordx4 v[84:85], v[86:89], off offset:256 nt
	s_cbranch_vccnz .LBB0_386
	v_add_f32_e32 v82, v76, v77
	v_add_f32_e32 v83, v78, v79
	v_add_f32_e32 v82, v82, v83
	v_add_f32_e32 v83, v72, v73
	v_mul_f32_e32 v73, v73, v73
	v_fmac_f32_e32 v73, v72, v72
	v_mul_f32_e32 v72, v75, v75
	v_fmac_f32_e32 v72, v74, v74
	v_add_f32_e32 v84, v74, v75
	v_add_f32_e32 v72, v73, v72
	v_mul_f32_e32 v73, v69, v69
	v_mul_f32_e32 v74, v71, v71
	v_fmac_f32_e32 v73, v68, v68
	v_fmac_f32_e32 v74, v70, v70
	v_add_f32_e32 v73, v73, v74
	v_mul_f32_e32 v74, v65, v65
	v_fmac_f32_e32 v74, v64, v64
	v_mul_f32_e32 v75, v67, v67
	v_add_f32_e32 v64, v64, v65
	v_add_f32_e32 v65, v66, v67
	v_and_b32_e32 v67, 64, v162
	v_add_f32_e32 v83, v83, v84
	v_add_f32_e32 v68, v68, v69
	v_add_f32_e32 v69, v70, v71
	v_add_f32_e32 v64, v64, v65
	v_xor_b32_e32 v65, 16, v162
	v_add_u32_e32 v67, 64, v67
	v_add_f32_e32 v82, v82, v83
	v_mul_f32_e32 v77, v77, v77
	v_add_f32_e32 v68, v68, v69
	v_cmp_lt_i32_e32 vcc, v65, v67
	v_add_f32_e32 v82, 0, v82
	v_fmac_f32_e32 v77, v76, v76
	v_mul_f32_e32 v76, v79, v79
	v_add_f32_e32 v64, v68, v64
	v_cndmask_b32_e32 v65, v162, v65, vcc
	v_fmac_f32_e32 v76, v78, v78
	v_add_f32_e32 v64, v82, v64
	v_lshlrev_b32_e32 v65, 2, v65
	v_fmac_f32_e32 v75, v66, v66
	v_add_f32_e32 v76, v77, v76
	ds_bpermute_b32 v68, v65, v64
	v_add_f32_e32 v66, v74, v75
	v_add_f32_e32 v72, v76, v72
	v_add_f32_e32 v66, v73, v66
	v_add_f32_e32 v66, v72, v66
	ds_bpermute_b32 v69, v65, v66
	s_waitcnt lgkmcnt(1)
	v_add_f32_e32 v64, v64, v68
	v_xor_b32_e32 v68, 32, v162
	v_cmp_lt_i32_e32 vcc, v68, v67
	s_waitcnt lgkmcnt(0)
	v_add_f32_e32 v66, v66, v69
	v_cndmask_b32_e32 v65, v162, v68, vcc
	v_lshlrev_b32_e32 v67, 2, v65
	ds_bpermute_b32 v65, v67, v64
	ds_bpermute_b32 v67, v67, v66
	s_and_saveexec_b64 s[14:15], s[8:9]
	s_cbranch_execz .LBB0_385
	s_waitcnt lgkmcnt(0)
	v_add_f32_e32 v66, v66, v67
	v_add_f32_e32 v67, v64, v65
	v_lshlrev_b64 v[64:65], 7, v[80:81]
	v_lshl_add_u64 v[64:65], s[78:79], 0, v[64:65]
	v_lshl_add_u64 v[64:65], s[12:13], 2, v[64:65]
	s_lshl_b32 s46, s36, 2
	s_mov_b32 s47, s13
	v_lshl_add_u64 v[64:65], v[64:65], 0, s[46:47]
	global_store_dword v[64:65], v67, off offset:-64
	global_store_dword v[64:65], v66, off

; __device__ __forceinline__ u32x4 pack8(f32x4 v0, f32x4 v1) { u32x4 w; w.x = cvt_pk_bf16(v0[0], v0[1]); w.y = cvt_pk_bf16(v0[2], v0[3]); w.z = cvt_pk_bf16(v1[0], v1[1]); w.w = cvt_pk_bf16(v1[2], v1[3]); return w; }
; __device__ __forceinline__ f32x4 gelu4(f32x4 v) { f32x2 a = gelu_pk((f32x2){v[0], v[1]}), b = gelu_pk((f32x2){v[2], v[3]}); return (f32x4){a.x, a.y, b.x, b.y}; }
; __device__ __forceinline__ f32x2 gelu_pk(f32x2 v) {
;     const f32x2 av = __builtin_elementwise_abs(v), d = av * 0.2316418882f + 1.0f;
;     f32x2 t; t.x = __builtin_amdgcn_rcpf(d.x); t.y = __builtin_amdgcn_rcpf(d.y);
;     f32x2 q = t * 0.5307027145f + (-0.7265760135f); q = q * t + 0.7107068705f; q = q * t + (-0.142248368f); q = q * t + 0.127414796f; q = q * t;
;     const f32x2 s = (v * v) * (-0.72134752044f);
;     f32x2 e; e.x = __builtin_amdgcn_exp2f(s.x); e.y = __builtin_amdgcn_exp2f(s.y);
;     const f32x2 m = v * (q * e), r = v - m;
;     f32x2 o; o.x = v.x < 0.f ? m.x : r.x; o.y = v.y < 0.f ? m.y : r.y; return o;
; }
;     __device__ __forceinline__ void operator()(f32x4 (&acc)[2][2][4][2], const Unit& u, int wr, int wc, int fr_, int fq_) const {
;     ...
;             for (int m = 0; m < 4; ++m) { const int row = row0 + ai * HALF + m * 16; const float rs = rstd[row]; bf16_t* rowp = base + (size_t)row * ld + col0;
;                 float s1 = 0.f, s2 = 0.f;
; #pragma unroll
;                 for (int bj = 0; bj < 2; ++bj) { f32x4 v0 = acc[ai][bj][m][0] * rs, v1 = acc[ai][bj][m][1] * rs;
;                     if (act) { v0 = gelu4(v0); v1 = gelu4(v1); }
;                     s1 += ((v0[0] + v0[1]) + (v0[2] + v0[3])) + ((v1[0] + v1[1]) + (v1[2] + v1[3]));
;                     s2 += ((v0[0] * v0[0] + v0[1] * v0[1]) + (v0[2] * v0[2] + v0[3] * v0[3])) + ((v1[0] * v1[0] + v1[1] * v1[1]) + (v1[2] * v1[2] + v1[3] * v1[3]));
;                     *(u32x4*)(rowp + bj * HALF) = pack8(v0, v1); }
;                 if (pn >= 4 && pn < 8) { s1 += __shfl_xor(s1, 16); s1 += __shfl_xor(s1, 32); s2 += __shfl_xor(s2, 16); s2 += __shfl_xor(s2, 32);
;                     if (fq == 0) { lns[(size_t)row * 32 + (pn - 4) * 4 + wc] = s1; lns[(size_t)row * 32 + 16 + (pn - 4) * 4 + wc] = s2; } } }
.LBB0_388:
	v_add_u32_e32 v64, 0x80, v146
	v_ashrrev_i32_e32 v65, 31, v64
	v_mul_lo_u32 v70, s86, v65
	v_mul_lo_u32 v71, s87, v64
	v_mad_u64_u32 v[68:69], s[14:15], s86, v64, 0
	v_add3_u32 v69, v69, v70, v71
	v_lshl_add_u64 v[68:69], v[68:69], 1, v[120:121]
	v_cvt_pk_bf16_f32 v70, v60, v61
	v_cvt_pk_bf16_f32 v71, v62, v63
	v_cvt_pk_bf16_f32 v72, v56, v57
	v_cvt_pk_bf16_f32 v73, v58, v59
	v_mov_b32_e32 v67, v66
	global_store_dwordx4 v[68:69], v[70:73], off nt
	v_pk_mul_f32 v[52:53], v[52:53], v[66:67]
	s_and_b64 vcc, exec, s[6:7]
	v_mov_b32_e32 v70, v66
	v_mov_b32_e32 v71, v66
	v_pk_mul_f32 v[54:55], v[54:55], v[70:71]
	v_pk_mul_f32 v[50:51], v[50:51], v[70:71]
	v_pk_mul_f32 v[48:49], v[48:49], v[66:67]
	s_cbranch_vccnz .LBB0_390
	v_fma_f32 v66, |v52|, s90, 1.0
	v_fma_f32 v67, |v53|, s90, 1.0
	v_mov_b64_e32 v[70:71], s[94:95]
	v_rcp_f32_e32 v66, v66
	v_rcp_f32_e32 v67, v67
	v_pk_mul_f32 v[74:75], v[52:53], v[52:53]
	v_pk_mul_f32 v[74:75], v[74:75], s[18:19] op_sel_hi:[1,0]
	v_pk_fma_f32 v[72:73], v[66:67], s[92:93], v[70:71] op_sel_hi:[1,0,0]
	v_exp_f32_e32 v74, v74
	v_pk_fma_f32 v[72:73], v[66:67], v[72:73], s[96:97] op_sel_hi:[1,1,0]
	v_exp_f32_e32 v75, v75
	v_pk_fma_f32 v[72:73], v[66:67], v[72:73], s[16:17] op_sel_hi:[1,1,0]
	v_pk_fma_f32 v[72:73], v[66:67], v[72:73], s[84:85] op_sel_hi:[1,1,0]
	v_pk_mul_f32 v[66:67], v[66:67], v[72:73]
	v_pk_mul_f32 v[72:73], v[54:55], v[54:55]
	v_pk_mul_f32 v[66:67], v[74:75], v[66:67]
	v_pk_mul_f32 v[72:73], v[72:73], s[18:19] op_sel_hi:[1,0]
	v_max_f32_e32 v74, 0, v52
	v_max_f32_e32 v75, 0, v53
	v_exp_f32_e32 v72, v72
	v_fma_f32 v52, -|v52|, v66, v74
	v_fma_f32 v53, -|v53|, v67, v75
	v_exp_f32_e32 v73, v73
	v_fma_f32 v66, |v54|, s90, 1.0
	v_fma_f32 v67, |v55|, s90, 1.0
	v_rcp_f32_e32 v66, v66
	v_rcp_f32_e32 v67, v67
	s_nop 0
	v_pk_fma_f32 v[74:75], v[66:67], s[92:93], v[70:71] op_sel_hi:[1,0,0]
	v_pk_fma_f32 v[74:75], v[66:67], v[74:75], s[96:97] op_sel_hi:[1,1,0]
	v_pk_fma_f32 v[74:75], v[66:67], v[74:75], s[16:17] op_sel_hi:[1,1,0]
	v_pk_fma_f32 v[74:75], v[66:67], v[74:75], s[84:85] op_sel_hi:[1,1,0]
	v_pk_mul_f32 v[66:67], v[66:67], v[74:75]
	v_pk_mul_f32 v[74:75], v[48:49], v[48:49]
	v_pk_mul_f32 v[66:67], v[72:73], v[66:67]
	v_pk_mul_f32 v[74:75], v[74:75], s[18:19] op_sel_hi:[1,0]
	v_max_f32_e32 v72, 0, v54
	v_max_f32_e32 v73, 0, v55
	v_exp_f32_e32 v74, v74
	v_fma_f32 v54, -|v54|, v66, v72
	v_fma_f32 v55, -|v55|, v67, v73
	v_exp_f32_e32 v75, v75
	v_fma_f32 v66, |v48|, s90, 1.0
	v_fma_f32 v67, |v49|, s90, 1.0
	v_rcp_f32_e32 v66, v66
	v_rcp_f32_e32 v67, v67
	s_nop 0
	v_pk_fma_f32 v[72:73], v[66:67], s[92:93], v[70:71] op_sel_hi:[1,0,0]
	v_pk_fma_f32 v[72:73], v[66:67], v[72:73], s[96:97] op_sel_hi:[1,1,0]
	v_pk_fma_f32 v[72:73], v[66:67], v[72:73], s[16:17] op_sel_hi:[1,1,0]
	v_pk_fma_f32 v[72:73], v[66:67], v[72:73], s[84:85] op_sel_hi:[1,1,0]
	v_pk_mul_f32 v[66:67], v[66:67], v[72:73]
	v_pk_mul_f32 v[72:73], v[50:51], v[50:51]
	v_pk_mul_f32 v[66:67], v[74:75], v[66:67]
	v_max_f32_e32 v74, 0, v48
	v_max_f32_e32 v75, 0, v49
	v_fma_f32 v48, -|v48|, v66, v74
	v_fma_f32 v49, -|v49|, v67, v75
	s_nop 0
	v_fma_f32 v66, |v50|, s90, 1.0
	v_fma_f32 v67, |v51|, s90, 1.0
	v_rcp_f32_e32 v66, v66
	v_rcp_f32_e32 v67, v67
	s_nop 0
	v_pk_fma_f32 v[70:71], v[66:67], s[92:93], v[70:71] op_sel_hi:[1,0,0]
	v_pk_fma_f32 v[70:71], v[66:67], v[70:71], s[96:97] op_sel_hi:[1,1,0]
	v_pk_fma_f32 v[70:71], v[66:67], v[70:71], s[16:17] op_sel_hi:[1,1,0]
	v_pk_fma_f32 v[70:71], v[66:67], v[70:71], s[84:85] op_sel_hi:[1,1,0]
	v_pk_mul_f32 v[66:67], v[66:67], v[70:71]
	v_pk_mul_f32 v[70:71], v[72:73], s[18:19] op_sel_hi:[1,0]
	v_exp_f32_e32 v70, v70
	v_exp_f32_e32 v71, v71
	s_nop 0
	v_pk_mul_f32 v[66:67], v[70:71], v[66:67]
	v_max_f32_e32 v70, 0, v50
	v_max_f32_e32 v71, 0, v51
	v_fma_f32 v50, -|v50|, v66, v70
	v_fma_f32 v51, -|v51|, v67, v71
	s_nop 1
.LBB0_390:
	v_cvt_pk_bf16_f32 v70, v52, v53
	v_cvt_pk_bf16_f32 v71, v54, v55
	v_cvt_pk_bf16_f32 v72, v48, v49
	v_cvt_pk_bf16_f32 v73, v50, v51
	s_and_b64 vcc, exec, s[10:11]
	global_store_dwordx4 v[68:69], v[70:73], off offset:256 nt
	s_cbranch_vccnz .LBB0_394
	v_add_f32_e32 v66, v60, v61
	v_add_f32_e32 v67, v62, v63
	v_add_f32_e32 v66, v66, v67
	v_add_f32_e32 v67, v56, v57
	v_mul_f32_e32 v57, v57, v57
	v_fmac_f32_e32 v57, v56, v56
	v_mul_f32_e32 v56, v59, v59
	v_fmac_f32_e32 v56, v58, v58
	v_add_f32_e32 v68, v58, v59
	v_add_f32_e32 v56, v57, v56
	v_mul_f32_e32 v57, v53, v53
	v_mul_f32_e32 v58, v55, v55
	v_fmac_f32_e32 v57, v52, v52
	v_fmac_f32_e32 v58, v54, v54
	v_add_f32_e32 v57, v57, v58
	v_mul_f32_e32 v58, v49, v49
	v_fmac_f32_e32 v58, v48, v48
	v_mul_f32_e32 v59, v51, v51
	v_add_f32_e32 v48, v48, v49
	v_add_f32_e32 v49, v50, v51
	v_and_b32_e32 v51, 64, v162
	v_add_f32_e32 v67, v67, v68
	v_add_f32_e32 v52, v52, v53
	v_add_f32_e32 v53, v54, v55
	v_add_f32_e32 v48, v48, v49
	v_xor_b32_e32 v49, 16, v162
	v_add_u32_e32 v51, 64, v51
	v_add_f32_e32 v66, v66, v67
	v_mul_f32_e32 v61, v61, v61
	v_add_f32_e32 v52, v52, v53
	v_cmp_lt_i32_e32 vcc, v49, v51
	v_add_f32_e32 v66, 0, v66
	v_fmac_f32_e32 v61, v60, v60
	v_mul_f32_e32 v60, v63, v63
	v_add_f32_e32 v48, v52, v48
	v_cndmask_b32_e32 v49, v162, v49, vcc
	v_fmac_f32_e32 v60, v62, v62
	v_add_f32_e32 v48, v66, v48
	v_lshlrev_b32_e32 v49, 2, v49
	v_fmac_f32_e32 v59, v50, v50
	v_add_f32_e32 v60, v61, v60
	ds_bpermute_b32 v52, v49, v48
	v_add_f32_e32 v50, v58, v59
	v_add_f32_e32 v56, v60, v56
	v_add_f32_e32 v50, v57, v50
	v_add_f32_e32 v50, v56, v50
	ds_bpermute_b32 v53, v49, v50
	s_waitcnt lgkmcnt(1)
	v_add_f32_e32 v48, v48, v52
	v_xor_b32_e32 v52, 32, v162
	v_cmp_lt_i32_e32 vcc, v52, v51
	s_waitcnt lgkmcnt(0)
	v_add_f32_e32 v50, v50, v53
	v_cndmask_b32_e32 v49, v162, v52, vcc
	v_lshlrev_b32_e32 v51, 2, v49
	ds_bpermute_b32 v49, v51, v48
	ds_bpermute_b32 v51, v51, v50
	s_and_saveexec_b64 s[14:15], s[8:9]
	s_cbranch_execz .LBB0_393
	s_waitcnt lgkmcnt(0)
	v_add_f32_e32 v50, v50, v51
	v_add_f32_e32 v51, v48, v49
	v_lshlrev_b64 v[48:49], 7, v[64:65]
	v_lshl_add_u64 v[48:49], s[78:79], 0, v[48:49]
	v_lshl_add_u64 v[48:49], s[12:13], 2, v[48:49]
	s_lshl_b32 s46, s36, 2
	s_mov_b32 s47, s13
	v_lshl_add_u64 v[48:49], v[48:49], 0, s[46:47]
	global_store_dword v[48:49], v51, off offset:-64
	global_store_dword v[48:49], v50, off

; __device__ __forceinline__ u32x4 pack8(f32x4 v0, f32x4 v1) { u32x4 w; w.x = cvt_pk_bf16(v0[0], v0[1]); w.y = cvt_pk_bf16(v0[2], v0[3]); w.z = cvt_pk_bf16(v1[0], v1[1]); w.w = cvt_pk_bf16(v1[2], v1[3]); return w; }
; __device__ __forceinline__ f32x4 gelu4(f32x4 v) { f32x2 a = gelu_pk((f32x2){v[0], v[1]}), b = gelu_pk((f32x2){v[2], v[3]}); return (f32x4){a.x, a.y, b.x, b.y}; }
; __device__ __forceinline__ f32x2 gelu_pk(f32x2 v) {
;     const f32x2 av = __builtin_elementwise_abs(v), d = av * 0.2316418882f + 1.0f;
;     f32x2 t; t.x = __builtin_amdgcn_rcpf(d.x); t.y = __builtin_amdgcn_rcpf(d.y);
;     f32x2 q = t * 0.5307027145f + (-0.7265760135f); q = q * t + 0.7107068705f; q = q * t + (-0.142248368f); q = q * t + 0.127414796f; q = q * t;
;     const f32x2 s = (v * v) * (-0.72134752044f);
;     f32x2 e; e.x = __builtin_amdgcn_exp2f(s.x); e.y = __builtin_amdgcn_exp2f(s.y);
;     const f32x2 m = v * (q * e), r = v - m;
;     f32x2 o; o.x = v.x < 0.f ? m.x : r.x; o.y = v.y < 0.f ? m.y : r.y; return o;
; }
;     __device__ __forceinline__ void operator()(f32x4 (&acc)[2][2][4][2], const Unit& u, int wr, int wc, int fr_, int fq_) const {
;     ...
;             for (int m = 0; m < 4; ++m) { const int row = row0 + ai * HALF + m * 16; const float rs = rstd[row]; bf16_t* rowp = base + (size_t)row * ld + col0;
;                 float s1 = 0.f, s2 = 0.f;
; #pragma unroll
;                 for (int bj = 0; bj < 2; ++bj) { f32x4 v0 = acc[ai][bj][m][0] * rs, v1 = acc[ai][bj][m][1] * rs;
;                     if (act) { v0 = gelu4(v0); v1 = gelu4(v1); }
;                     s1 += ((v0[0] + v0[1]) + (v0[2] + v0[3])) + ((v1[0] + v1[1]) + (v1[2] + v1[3]));
;                     s2 += ((v0[0] * v0[0] + v0[1] * v0[1]) + (v0[2] * v0[2] + v0[3] * v0[3])) + ((v1[0] * v1[0] + v1[1] * v1[1]) + (v1[2] * v1[2] + v1[3] * v1[3]));
;                     *(u32x4*)(rowp + bj * HALF) = pack8(v0, v1); }
;                 if (pn >= 4 && pn < 8) { s1 += __shfl_xor(s1, 16); s1 += __shfl_xor(s1, 32); s2 += __shfl_xor(s2, 16); s2 += __shfl_xor(s2, 32);
;                     if (fq == 0) { lns[(size_t)row * 32 + (pn - 4) * 4 + wc] = s1; lns[(size_t)row * 32 + 16 + (pn - 4) * 4 + wc] = s2; } } }
.LBB0_396:
	v_add_u32_e32 v48, 0x90, v146
	v_ashrrev_i32_e32 v49, 31, v48
	v_mul_lo_u32 v54, s86, v49
	v_mul_lo_u32 v55, s87, v48
	v_mad_u64_u32 v[52:53], s[14:15], s86, v48, 0
	v_add3_u32 v53, v53, v54, v55
	v_lshl_add_u64 v[52:53], v[52:53], 1, v[120:121]
	v_cvt_pk_bf16_f32 v54, v44, v45
	v_cvt_pk_bf16_f32 v55, v46, v47
	v_cvt_pk_bf16_f32 v56, v40, v41
	v_cvt_pk_bf16_f32 v57, v42, v43
	v_mov_b32_e32 v51, v50
	global_store_dwordx4 v[52:53], v[54:57], off nt
	v_pk_mul_f32 v[36:37], v[36:37], v[50:51]
	s_and_b64 vcc, exec, s[6:7]
	v_mov_b32_e32 v54, v50
	v_mov_b32_e32 v55, v50
	v_pk_mul_f32 v[38:39], v[38:39], v[54:55]
	v_pk_mul_f32 v[34:35], v[34:35], v[54:55]
	v_pk_mul_f32 v[32:33], v[32:33], v[50:51]
	s_cbranch_vccnz .LBB0_398
	v_fma_f32 v50, |v36|, s90, 1.0
	v_fma_f32 v51, |v37|, s90, 1.0
	v_mov_b64_e32 v[54:55], s[94:95]
	v_rcp_f32_e32 v50, v50
	v_rcp_f32_e32 v51, v51
	v_pk_mul_f32 v[58:59], v[36:37], v[36:37]
	v_pk_mul_f32 v[58:59], v[58:59], s[18:19] op_sel_hi:[1,0]
	v_pk_fma_f32 v[56:57], v[50:51], s[92:93], v[54:55] op_sel_hi:[1,0,0]
	v_exp_f32_e32 v58, v58
	v_pk_fma_f32 v[56:57], v[50:51], v[56:57], s[96:97] op_sel_hi:[1,1,0]
	v_exp_f32_e32 v59, v59
	v_pk_fma_f32 v[56:57], v[50:51], v[56:57], s[16:17] op_sel_hi:[1,1,0]
	v_pk_fma_f32 v[56:57], v[50:51], v[56:57], s[84:85] op_sel_hi:[1,1,0]
	v_pk_mul_f32 v[50:51], v[50:51], v[56:57]
	v_pk_mul_f32 v[56:57], v[38:39], v[38:39]
	v_pk_mul_f32 v[50:51], v[58:59], v[50:51]
	v_pk_mul_f32 v[56:57], v[56:57], s[18:19] op_sel_hi:[1,0]
	v_max_f32_e32 v58, 0, v36
	v_max_f32_e32 v59, 0, v37
	v_exp_f32_e32 v56, v56
	v_fma_f32 v36, -|v36|, v50, v58
	v_fma_f32 v37, -|v37|, v51, v59
	v_exp_f32_e32 v57, v57
	v_fma_f32 v50, |v38|, s90, 1.0
	v_fma_f32 v51, |v39|, s90, 1.0
	v_rcp_f32_e32 v50, v50
	v_rcp_f32_e32 v51, v51
	s_nop 0
	v_pk_fma_f32 v[58:59], v[50:51], s[92:93], v[54:55] op_sel_hi:[1,0,0]
	v_pk_fma_f32 v[58:59], v[50:51], v[58:59], s[96:97] op_sel_hi:[1,1,0]
	v_pk_fma_f32 v[58:59], v[50:51], v[58:59], s[16:17] op_sel_hi:[1,1,0]
	v_pk_fma_f32 v[58:59], v[50:51], v[58:59], s[84:85] op_sel_hi:[1,1,0]
	v_pk_mul_f32 v[50:51], v[50:51], v[58:59]
	v_pk_mul_f32 v[58:59], v[32:33], v[32:33]
	v_pk_mul_f32 v[50:51], v[56:57], v[50:51]
	v_pk_mul_f32 v[58:59], v[58:59], s[18:19] op_sel_hi:[1,0]
	v_max_f32_e32 v56, 0, v38
	v_max_f32_e32 v57, 0, v39
	v_exp_f32_e32 v58, v58
	v_fma_f32 v38, -|v38|, v50, v56
	v_fma_f32 v39, -|v39|, v51, v57
	v_exp_f32_e32 v59, v59
	v_fma_f32 v50, |v32|, s90, 1.0
	v_fma_f32 v51, |v33|, s90, 1.0
	v_rcp_f32_e32 v50, v50
	v_rcp_f32_e32 v51, v51
	s_nop 0
	v_pk_fma_f32 v[56:57], v[50:51], s[92:93], v[54:55] op_sel_hi:[1,0,0]
	v_pk_fma_f32 v[56:57], v[50:51], v[56:57], s[96:97] op_sel_hi:[1,1,0]
	v_pk_fma_f32 v[56:57], v[50:51], v[56:57], s[16:17] op_sel_hi:[1,1,0]
	v_pk_fma_f32 v[56:57], v[50:51], v[56:57], s[84:85] op_sel_hi:[1,1,0]
	v_pk_mul_f32 v[50:51], v[50:51], v[56:57]
	v_pk_mul_f32 v[56:57], v[34:35], v[34:35]
	v_pk_mul_f32 v[50:51], v[58:59], v[50:51]
	v_max_f32_e32 v58, 0, v32
	v_max_f32_e32 v59, 0, v33
	v_fma_f32 v32, -|v32|, v50, v58
	v_fma_f32 v33, -|v33|, v51, v59
	s_nop 0
	v_fma_f32 v50, |v34|, s90, 1.0
	v_fma_f32 v51, |v35|, s90, 1.0
	v_rcp_f32_e32 v50, v50
	v_rcp_f32_e32 v51, v51
	s_nop 0
	v_pk_fma_f32 v[54:55], v[50:51], s[92:93], v[54:55] op_sel_hi:[1,0,0]
	v_pk_fma_f32 v[54:55], v[50:51], v[54:55], s[96:97] op_sel_hi:[1,1,0]
	v_pk_fma_f32 v[54:55], v[50:51], v[54:55], s[16:17] op_sel_hi:[1,1,0]
	v_pk_fma_f32 v[54:55], v[50:51], v[54:55], s[84:85] op_sel_hi:[1,1,0]
	v_pk_mul_f32 v[50:51], v[50:51], v[54:55]
	v_pk_mul_f32 v[54:55], v[56:57], s[18:19] op_sel_hi:[1,0]
	v_exp_f32_e32 v54, v54
	v_exp_f32_e32 v55, v55
	s_nop 0
	v_pk_mul_f32 v[50:51], v[54:55], v[50:51]
	v_max_f32_e32 v54, 0, v34
	v_max_f32_e32 v55, 0, v35
	v_fma_f32 v34, -|v34|, v50, v54
	v_fma_f32 v35, -|v35|, v51, v55
	s_nop 1
.LBB0_398:
	v_cvt_pk_bf16_f32 v54, v36, v37
	v_cvt_pk_bf16_f32 v55, v38, v39
	v_cvt_pk_bf16_f32 v56, v32, v33
	v_cvt_pk_bf16_f32 v57, v34, v35
	s_and_b64 vcc, exec, s[10:11]
	global_store_dwordx4 v[52:53], v[54:57], off offset:256 nt
	s_cbranch_vccnz .LBB0_402
	v_add_f32_e32 v50, v44, v45
	v_add_f32_e32 v51, v46, v47
	v_add_f32_e32 v50, v50, v51
	v_add_f32_e32 v51, v40, v41
	v_mul_f32_e32 v41, v41, v41
	v_fmac_f32_e32 v41, v40, v40
	v_mul_f32_e32 v40, v43, v43
	v_fmac_f32_e32 v40, v42, v42
	v_add_f32_e32 v52, v42, v43
	v_add_f32_e32 v40, v41, v40
	v_mul_f32_e32 v41, v37, v37
	v_mul_f32_e32 v42, v39, v39
	v_fmac_f32_e32 v41, v36, v36
	v_fmac_f32_e32 v42, v38, v38
	v_add_f32_e32 v41, v41, v42
	v_mul_f32_e32 v42, v33, v33
	v_fmac_f32_e32 v42, v32, v32
	v_mul_f32_e32 v43, v35, v35
	v_add_f32_e32 v32, v32, v33
	v_add_f32_e32 v33, v34, v35
	v_and_b32_e32 v35, 64, v162
	v_add_f32_e32 v51, v51, v52
	v_add_f32_e32 v36, v36, v37
	v_add_f32_e32 v37, v38, v39
	v_add_f32_e32 v32, v32, v33
	v_xor_b32_e32 v33, 16, v162
	v_add_u32_e32 v35, 64, v35
	v_add_f32_e32 v50, v50, v51
	v_mul_f32_e32 v45, v45, v45
	v_add_f32_e32 v36, v36, v37
	v_cmp_lt_i32_e32 vcc, v33, v35
	v_add_f32_e32 v50, 0, v50
	v_fmac_f32_e32 v45, v44, v44
	v_mul_f32_e32 v44, v47, v47
	v_add_f32_e32 v32, v36, v32
	v_cndmask_b32_e32 v33, v162, v33, vcc
	v_fmac_f32_e32 v44, v46, v46
	v_add_f32_e32 v32, v50, v32
	v_lshlrev_b32_e32 v33, 2, v33
	v_fmac_f32_e32 v43, v34, v34
	v_add_f32_e32 v44, v45, v44
	ds_bpermute_b32 v36, v33, v32
	v_add_f32_e32 v34, v42, v43
	v_add_f32_e32 v40, v44, v40
	v_add_f32_e32 v34, v41, v34
	v_add_f32_e32 v34, v40, v34
	ds_bpermute_b32 v37, v33, v34
	s_waitcnt lgkmcnt(1)
	v_add_f32_e32 v32, v32, v36
	v_xor_b32_e32 v36, 32, v162
	v_cmp_lt_i32_e32 vcc, v36, v35
	s_waitcnt lgkmcnt(0)
	v_add_f32_e32 v34, v34, v37
	v_cndmask_b32_e32 v33, v162, v36, vcc
	v_lshlrev_b32_e32 v35, 2, v33
	ds_bpermute_b32 v33, v35, v32
	ds_bpermute_b32 v35, v35, v34
	s_and_saveexec_b64 s[14:15], s[8:9]
	s_cbranch_execz .LBB0_401
	s_waitcnt lgkmcnt(0)
	v_add_f32_e32 v34, v34, v35
	v_add_f32_e32 v35, v32, v33
	v_lshlrev_b64 v[32:33], 7, v[48:49]
	v_lshl_add_u64 v[32:33], s[78:79], 0, v[32:33]
	v_lshl_add_u64 v[32:33], s[12:13], 2, v[32:33]
	s_lshl_b32 s46, s36, 2
	s_mov_b32 s47, s13
	v_lshl_add_u64 v[32:33], v[32:33], 0, s[46:47]
	global_store_dword v[32:33], v35, off offset:-64
	global_store_dword v[32:33], v34, off

; __device__ __forceinline__ u32x4 pack8(f32x4 v0, f32x4 v1) { u32x4 w; w.x = cvt_pk_bf16(v0[0], v0[1]); w.y = cvt_pk_bf16(v0[2], v0[3]); w.z = cvt_pk_bf16(v1[0], v1[1]); w.w = cvt_pk_bf16(v1[2], v1[3]); return w; }
; __device__ __forceinline__ f32x4 gelu4(f32x4 v) { f32x2 a = gelu_pk((f32x2){v[0], v[1]}), b = gelu_pk((f32x2){v[2], v[3]}); return (f32x4){a.x, a.y, b.x, b.y}; }
; __device__ __forceinline__ f32x2 gelu_pk(f32x2 v) {
;     const f32x2 av = __builtin_elementwise_abs(v), d = av * 0.2316418882f + 1.0f;
;     f32x2 t; t.x = __builtin_amdgcn_rcpf(d.x); t.y = __builtin_amdgcn_rcpf(d.y);
;     f32x2 q = t * 0.5307027145f + (-0.7265760135f); q = q * t + 0.7107068705f; q = q * t + (-0.142248368f); q = q * t + 0.127414796f; q = q * t;
;     const f32x2 s = (v * v) * (-0.72134752044f);
;     f32x2 e; e.x = __builtin_amdgcn_exp2f(s.x); e.y = __builtin_amdgcn_exp2f(s.y);
;     const f32x2 m = v * (q * e), r = v - m;
;     f32x2 o; o.x = v.x < 0.f ? m.x : r.x; o.y = v.y < 0.f ? m.y : r.y; return o;
; }
;     __device__ __forceinline__ void operator()(f32x4 (&acc)[2][2][4][2], const Unit& u, int wr, int wc, int fr_, int fq_) const {
;     ...
;             for (int m = 0; m < 4; ++m) { const int row = row0 + ai * HALF + m * 16; const float rs = rstd[row]; bf16_t* rowp = base + (size_t)row * ld + col0;
;                 float s1 = 0.f, s2 = 0.f;
; #pragma unroll
;                 for (int bj = 0; bj < 2; ++bj) { f32x4 v0 = acc[ai][bj][m][0] * rs, v1 = acc[ai][bj][m][1] * rs;
;                     if (act) { v0 = gelu4(v0); v1 = gelu4(v1); }
;                     s1 += ((v0[0] + v0[1]) + (v0[2] + v0[3])) + ((v1[0] + v1[1]) + (v1[2] + v1[3]));
;                     s2 += ((v0[0] * v0[0] + v0[1] * v0[1]) + (v0[2] * v0[2] + v0[3] * v0[3])) + ((v1[0] * v1[0] + v1[1] * v1[1]) + (v1[2] * v1[2] + v1[3] * v1[3]));
;                     *(u32x4*)(rowp + bj * HALF) = pack8(v0, v1); }
;                 if (pn >= 4 && pn < 8) { s1 += __shfl_xor(s1, 16); s1 += __shfl_xor(s1, 32); s2 += __shfl_xor(s2, 16); s2 += __shfl_xor(s2, 32);
;                     if (fq == 0) { lns[(size_t)row * 32 + (pn - 4) * 4 + wc] = s1; lns[(size_t)row * 32 + 16 + (pn - 4) * 4 + wc] = s2; } } }
.LBB0_404:
	v_add_u32_e32 v32, 0xa0, v146
	v_ashrrev_i32_e32 v33, 31, v32
	v_mul_lo_u32 v38, s86, v33
	v_mul_lo_u32 v39, s87, v32
	v_mad_u64_u32 v[36:37], s[14:15], s86, v32, 0
	v_add3_u32 v37, v37, v38, v39
	v_lshl_add_u64 v[36:37], v[36:37], 1, v[120:121]
	v_cvt_pk_bf16_f32 v38, v28, v29
	v_cvt_pk_bf16_f32 v39, v30, v31
	v_cvt_pk_bf16_f32 v40, v24, v25
	v_cvt_pk_bf16_f32 v41, v26, v27
	v_mov_b32_e32 v35, v34
	global_store_dwordx4 v[36:37], v[38:41], off nt
	v_pk_mul_f32 v[20:21], v[20:21], v[34:35]
	s_and_b64 vcc, exec, s[6:7]
	v_mov_b32_e32 v38, v34
	v_mov_b32_e32 v39, v34
	v_pk_mul_f32 v[22:23], v[22:23], v[38:39]
	v_pk_mul_f32 v[18:19], v[18:19], v[38:39]
	v_pk_mul_f32 v[16:17], v[16:17], v[34:35]
	s_cbranch_vccnz .LBB0_406
	v_fma_f32 v34, |v20|, s90, 1.0
	v_fma_f32 v35, |v21|, s90, 1.0
	v_mov_b64_e32 v[38:39], s[94:95]
	v_rcp_f32_e32 v34, v34
	v_rcp_f32_e32 v35, v35
	v_pk_mul_f32 v[42:43], v[20:21], v[20:21]
	v_pk_mul_f32 v[42:43], v[42:43], s[18:19] op_sel_hi:[1,0]
	v_pk_fma_f32 v[40:41], v[34:35], s[92:93], v[38:39] op_sel_hi:[1,0,0]
	v_exp_f32_e32 v42, v42
	v_pk_fma_f32 v[40:41], v[34:35], v[40:41], s[96:97] op_sel_hi:[1,1,0]
	v_exp_f32_e32 v43, v43
	v_pk_fma_f32 v[40:41], v[34:35], v[40:41], s[16:17] op_sel_hi:[1,1,0]
	v_pk_fma_f32 v[40:41], v[34:35], v[40:41], s[84:85] op_sel_hi:[1,1,0]
	v_pk_mul_f32 v[34:35], v[34:35], v[40:41]
	v_pk_mul_f32 v[40:41], v[22:23], v[22:23]
	v_pk_mul_f32 v[34:35], v[42:43], v[34:35]
	v_pk_mul_f32 v[40:41], v[40:41], s[18:19] op_sel_hi:[1,0]
	v_max_f32_e32 v42, 0, v20
	v_max_f32_e32 v43, 0, v21
	v_exp_f32_e32 v40, v40
	v_fma_f32 v20, -|v20|, v34, v42
	v_fma_f32 v21, -|v21|, v35, v43
	v_exp_f32_e32 v41, v41
	v_fma_f32 v34, |v22|, s90, 1.0
	v_fma_f32 v35, |v23|, s90, 1.0
	v_rcp_f32_e32 v34, v34
	v_rcp_f32_e32 v35, v35
	s_nop 0
	v_pk_fma_f32 v[42:43], v[34:35], s[92:93], v[38:39] op_sel_hi:[1,0,0]
	v_pk_fma_f32 v[42:43], v[34:35], v[42:43], s[96:97] op_sel_hi:[1,1,0]
	v_pk_fma_f32 v[42:43], v[34:35], v[42:43], s[16:17] op_sel_hi:[1,1,0]
	v_pk_fma_f32 v[42:43], v[34:35], v[42:43], s[84:85] op_sel_hi:[1,1,0]
	v_pk_mul_f32 v[34:35], v[34:35], v[42:43]
	v_pk_mul_f32 v[42:43], v[16:17], v[16:17]
	v_pk_mul_f32 v[34:35], v[40:41], v[34:35]
	v_pk_mul_f32 v[42:43], v[42:43], s[18:19] op_sel_hi:[1,0]
	v_max_f32_e32 v40, 0, v22
	v_max_f32_e32 v41, 0, v23
	v_exp_f32_e32 v42, v42
	v_fma_f32 v22, -|v22|, v34, v40
	v_fma_f32 v23, -|v23|, v35, v41
	v_exp_f32_e32 v43, v43
	v_fma_f32 v34, |v16|, s90, 1.0
	v_fma_f32 v35, |v17|, s90, 1.0
	v_rcp_f32_e32 v34, v34
	v_rcp_f32_e32 v35, v35
	s_nop 0
	v_pk_fma_f32 v[40:41], v[34:35], s[92:93], v[38:39] op_sel_hi:[1,0,0]
	v_pk_fma_f32 v[40:41], v[34:35], v[40:41], s[96:97] op_sel_hi:[1,1,0]
	v_pk_fma_f32 v[40:41], v[34:35], v[40:41], s[16:17] op_sel_hi:[1,1,0]
	v_pk_fma_f32 v[40:41], v[34:35], v[40:41], s[84:85] op_sel_hi:[1,1,0]
	v_pk_mul_f32 v[34:35], v[34:35], v[40:41]
	v_pk_mul_f32 v[40:41], v[18:19], v[18:19]
	v_pk_mul_f32 v[34:35], v[42:43], v[34:35]
	v_max_f32_e32 v42, 0, v16
	v_max_f32_e32 v43, 0, v17
	v_fma_f32 v16, -|v16|, v34, v42
	v_fma_f32 v17, -|v17|, v35, v43
	s_nop 0
	v_fma_f32 v34, |v18|, s90, 1.0
	v_fma_f32 v35, |v19|, s90, 1.0
	v_rcp_f32_e32 v34, v34
	v_rcp_f32_e32 v35, v35
	s_nop 0
	v_pk_fma_f32 v[38:39], v[34:35], s[92:93], v[38:39] op_sel_hi:[1,0,0]
	v_pk_fma_f32 v[38:39], v[34:35], v[38:39], s[96:97] op_sel_hi:[1,1,0]
	v_pk_fma_f32 v[38:39], v[34:35], v[38:39], s[16:17] op_sel_hi:[1,1,0]
	v_pk_fma_f32 v[38:39], v[34:35], v[38:39], s[84:85] op_sel_hi:[1,1,0]
	v_pk_mul_f32 v[34:35], v[34:35], v[38:39]
	v_pk_mul_f32 v[38:39], v[40:41], s[18:19] op_sel_hi:[1,0]
	v_exp_f32_e32 v38, v38
	v_exp_f32_e32 v39, v39
	s_nop 0
	v_pk_mul_f32 v[34:35], v[38:39], v[34:35]
	v_max_f32_e32 v38, 0, v18
	v_max_f32_e32 v39, 0, v19
	v_fma_f32 v18, -|v18|, v34, v38
	v_fma_f32 v19, -|v19|, v35, v39
	s_nop 1
.LBB0_406:
	v_cvt_pk_bf16_f32 v38, v20, v21
	v_cvt_pk_bf16_f32 v39, v22, v23
	v_cvt_pk_bf16_f32 v40, v16, v17
	v_cvt_pk_bf16_f32 v41, v18, v19
	s_and_b64 vcc, exec, s[10:11]
	global_store_dwordx4 v[36:37], v[38:41], off offset:256 nt
	s_cbranch_vccnz .LBB0_410
	v_add_f32_e32 v34, v28, v29
	v_add_f32_e32 v35, v30, v31
	v_add_f32_e32 v34, v34, v35
	v_add_f32_e32 v35, v24, v25
	v_mul_f32_e32 v25, v25, v25
	v_fmac_f32_e32 v25, v24, v24
	v_mul_f32_e32 v24, v27, v27
	v_fmac_f32_e32 v24, v26, v26
	v_add_f32_e32 v36, v26, v27
	v_add_f32_e32 v24, v25, v24
	v_mul_f32_e32 v25, v21, v21
	v_mul_f32_e32 v26, v23, v23
	v_fmac_f32_e32 v25, v20, v20
	v_fmac_f32_e32 v26, v22, v22
	v_add_f32_e32 v25, v25, v26
	v_mul_f32_e32 v26, v17, v17
	v_fmac_f32_e32 v26, v16, v16
	v_mul_f32_e32 v27, v19, v19
	v_add_f32_e32 v16, v16, v17
	v_add_f32_e32 v17, v18, v19
	v_and_b32_e32 v19, 64, v162
	v_add_f32_e32 v35, v35, v36
	v_add_f32_e32 v20, v20, v21
	v_add_f32_e32 v21, v22, v23
	v_add_f32_e32 v16, v16, v17
	v_xor_b32_e32 v17, 16, v162
	v_add_u32_e32 v19, 64, v19
	v_add_f32_e32 v34, v34, v35
	v_mul_f32_e32 v29, v29, v29
	v_add_f32_e32 v20, v20, v21
	v_cmp_lt_i32_e32 vcc, v17, v19
	v_add_f32_e32 v34, 0, v34
	v_fmac_f32_e32 v29, v28, v28
	v_mul_f32_e32 v28, v31, v31
	v_add_f32_e32 v16, v20, v16
	v_cndmask_b32_e32 v17, v162, v17, vcc
	v_fmac_f32_e32 v28, v30, v30
	v_add_f32_e32 v16, v34, v16
	v_lshlrev_b32_e32 v17, 2, v17
	v_fmac_f32_e32 v27, v18, v18
	v_add_f32_e32 v28, v29, v28
	ds_bpermute_b32 v20, v17, v16
	v_add_f32_e32 v18, v26, v27
	v_add_f32_e32 v24, v28, v24
	v_add_f32_e32 v18, v25, v18
	v_add_f32_e32 v18, v24, v18
	ds_bpermute_b32 v21, v17, v18
	s_waitcnt lgkmcnt(1)
	v_add_f32_e32 v16, v16, v20
	v_xor_b32_e32 v20, 32, v162
	v_cmp_lt_i32_e32 vcc, v20, v19
	s_waitcnt lgkmcnt(0)
	v_add_f32_e32 v18, v18, v21
	v_cndmask_b32_e32 v17, v162, v20, vcc
	v_lshlrev_b32_e32 v19, 2, v17
	ds_bpermute_b32 v17, v19, v16
	ds_bpermute_b32 v19, v19, v18
	s_and_saveexec_b64 s[14:15], s[8:9]
	s_cbranch_execz .LBB0_409
	s_waitcnt lgkmcnt(0)
	v_add_f32_e32 v18, v18, v19
	v_add_f32_e32 v19, v16, v17
	v_lshlrev_b64 v[16:17], 7, v[32:33]
	v_lshl_add_u64 v[16:17], s[78:79], 0, v[16:17]
	v_lshl_add_u64 v[16:17], s[12:13], 2, v[16:17]
	s_lshl_b32 s46, s36, 2
	s_mov_b32 s47, s13
	v_lshl_add_u64 v[16:17], v[16:17], 0, s[46:47]
	global_store_dword v[16:17], v19, off offset:-64
	global_store_dword v[16:17], v18, off

; __device__ __forceinline__ u32x4 pack8(f32x4 v0, f32x4 v1) { u32x4 w; w.x = cvt_pk_bf16(v0[0], v0[1]); w.y = cvt_pk_bf16(v0[2], v0[3]); w.z = cvt_pk_bf16(v1[0], v1[1]); w.w = cvt_pk_bf16(v1[2], v1[3]); return w; }
; __device__ __forceinline__ f32x4 gelu4(f32x4 v) { f32x2 a = gelu_pk((f32x2){v[0], v[1]}), b = gelu_pk((f32x2){v[2], v[3]}); return (f32x4){a.x, a.y, b.x, b.y}; }
; __device__ __forceinline__ f32x2 gelu_pk(f32x2 v) {
;     const f32x2 av = __builtin_elementwise_abs(v), d = av * 0.2316418882f + 1.0f;
;     f32x2 t; t.x = __builtin_amdgcn_rcpf(d.x); t.y = __builtin_amdgcn_rcpf(d.y);
;     f32x2 q = t * 0.5307027145f + (-0.7265760135f); q = q * t + 0.7107068705f; q = q * t + (-0.142248368f); q = q * t + 0.127414796f; q = q * t;
;     const f32x2 s = (v * v) * (-0.72134752044f);
;     f32x2 e; e.x = __builtin_amdgcn_exp2f(s.x); e.y = __builtin_amdgcn_exp2f(s.y);
;     const f32x2 m = v * (q * e), r = v - m;
;     f32x2 o; o.x = v.x < 0.f ? m.x : r.x; o.y = v.y < 0.f ? m.y : r.y; return o;
; }
;     __device__ __forceinline__ void operator()(f32x4 (&acc)[2][2][4][2], const Unit& u, int wr, int wc, int fr_, int fq_) const {
;     ...
;             for (int m = 0; m < 4; ++m) { const int row = row0 + ai * HALF + m * 16; const float rs = rstd[row]; bf16_t* rowp = base + (size_t)row * ld + col0;
;                 float s1 = 0.f, s2 = 0.f;
; #pragma unroll
;                 for (int bj = 0; bj < 2; ++bj) { f32x4 v0 = acc[ai][bj][m][0] * rs, v1 = acc[ai][bj][m][1] * rs;
;                     if (act) { v0 = gelu4(v0); v1 = gelu4(v1); }
;                     s1 += ((v0[0] + v0[1]) + (v0[2] + v0[3])) + ((v1[0] + v1[1]) + (v1[2] + v1[3]));
;                     s2 += ((v0[0] * v0[0] + v0[1] * v0[1]) + (v0[2] * v0[2] + v0[3] * v0[3])) + ((v1[0] * v1[0] + v1[1] * v1[1]) + (v1[2] * v1[2] + v1[3] * v1[3]));
;                     *(u32x4*)(rowp + bj * HALF) = pack8(v0, v1); }
;                 if (pn >= 4 && pn < 8) { s1 += __shfl_xor(s1, 16); s1 += __shfl_xor(s1, 32); s2 += __shfl_xor(s2, 16); s2 += __shfl_xor(s2, 32);
;                     if (fq == 0) { lns[(size_t)row * 32 + (pn - 4) * 4 + wc] = s1; lns[(size_t)row * 32 + 16 + (pn - 4) * 4 + wc] = s2; } } }
.LBB0_412:
	v_add_u32_e32 v16, 0xb0, v146
	v_ashrrev_i32_e32 v17, 31, v16
	v_mul_lo_u32 v22, s86, v17
	v_mul_lo_u32 v23, s87, v16
	v_mad_u64_u32 v[20:21], s[14:15], s86, v16, 0
	v_add3_u32 v21, v21, v22, v23
	v_lshl_add_u64 v[20:21], v[20:21], 1, v[120:121]
	v_cvt_pk_bf16_f32 v22, v12, v13
	v_cvt_pk_bf16_f32 v23, v14, v15
	v_cvt_pk_bf16_f32 v24, v8, v9
	v_cvt_pk_bf16_f32 v25, v10, v11
	v_mov_b32_e32 v19, v18
	global_store_dwordx4 v[20:21], v[22:25], off nt
	v_pk_mul_f32 v[4:5], v[4:5], v[18:19]
	s_and_b64 vcc, exec, s[6:7]
	v_mov_b32_e32 v22, v18
	v_mov_b32_e32 v23, v18
	v_pk_mul_f32 v[6:7], v[6:7], v[22:23]
	v_pk_mul_f32 v[2:3], v[2:3], v[22:23]
	v_pk_mul_f32 v[0:1], v[0:1], v[18:19]
	s_cbranch_vccnz .LBB0_414
	v_fma_f32 v18, |v4|, s90, 1.0
	v_fma_f32 v19, |v5|, s90, 1.0
	v_mov_b64_e32 v[22:23], s[94:95]
	v_rcp_f32_e32 v18, v18
	v_rcp_f32_e32 v19, v19
	v_pk_mul_f32 v[26:27], v[4:5], v[4:5]
	v_pk_mul_f32 v[26:27], v[26:27], s[18:19] op_sel_hi:[1,0]
	v_pk_fma_f32 v[24:25], v[18:19], s[92:93], v[22:23] op_sel_hi:[1,0,0]
	v_exp_f32_e32 v26, v26
	v_pk_fma_f32 v[24:25], v[18:19], v[24:25], s[96:97] op_sel_hi:[1,1,0]
	v_exp_f32_e32 v27, v27
	v_pk_fma_f32 v[24:25], v[18:19], v[24:25], s[16:17] op_sel_hi:[1,1,0]
	v_pk_fma_f32 v[24:25], v[18:19], v[24:25], s[84:85] op_sel_hi:[1,1,0]
	v_pk_mul_f32 v[18:19], v[18:19], v[24:25]
	v_pk_mul_f32 v[24:25], v[6:7], v[6:7]
	v_pk_mul_f32 v[18:19], v[26:27], v[18:19]
	v_pk_mul_f32 v[24:25], v[24:25], s[18:19] op_sel_hi:[1,0]
	v_max_f32_e32 v26, 0, v4
	v_max_f32_e32 v27, 0, v5
	v_exp_f32_e32 v24, v24
	v_fma_f32 v4, -|v4|, v18, v26
	v_fma_f32 v5, -|v5|, v19, v27
	v_exp_f32_e32 v25, v25
	v_fma_f32 v18, |v6|, s90, 1.0
	v_fma_f32 v19, |v7|, s90, 1.0
	v_rcp_f32_e32 v18, v18
	v_rcp_f32_e32 v19, v19
	s_nop 0
	v_pk_fma_f32 v[26:27], v[18:19], s[92:93], v[22:23] op_sel_hi:[1,0,0]
	v_pk_fma_f32 v[26:27], v[18:19], v[26:27], s[96:97] op_sel_hi:[1,1,0]
	v_pk_fma_f32 v[26:27], v[18:19], v[26:27], s[16:17] op_sel_hi:[1,1,0]
	v_pk_fma_f32 v[26:27], v[18:19], v[26:27], s[84:85] op_sel_hi:[1,1,0]
	v_pk_mul_f32 v[18:19], v[18:19], v[26:27]
	v_pk_mul_f32 v[26:27], v[0:1], v[0:1]
	v_pk_mul_f32 v[18:19], v[24:25], v[18:19]
	v_pk_mul_f32 v[26:27], v[26:27], s[18:19] op_sel_hi:[1,0]
	v_max_f32_e32 v24, 0, v6
	v_max_f32_e32 v25, 0, v7
	v_exp_f32_e32 v26, v26
	v_fma_f32 v6, -|v6|, v18, v24
	v_fma_f32 v7, -|v7|, v19, v25
	v_exp_f32_e32 v27, v27
	v_fma_f32 v18, |v0|, s90, 1.0
	v_fma_f32 v19, |v1|, s90, 1.0
	v_rcp_f32_e32 v18, v18
	v_rcp_f32_e32 v19, v19
	s_nop 0
	v_pk_fma_f32 v[24:25], v[18:19], s[92:93], v[22:23] op_sel_hi:[1,0,0]
	v_pk_fma_f32 v[24:25], v[18:19], v[24:25], s[96:97] op_sel_hi:[1,1,0]
	v_pk_fma_f32 v[24:25], v[18:19], v[24:25], s[16:17] op_sel_hi:[1,1,0]
	v_pk_fma_f32 v[24:25], v[18:19], v[24:25], s[84:85] op_sel_hi:[1,1,0]
	v_pk_mul_f32 v[18:19], v[18:19], v[24:25]
	v_pk_mul_f32 v[24:25], v[2:3], v[2:3]
	v_pk_mul_f32 v[18:19], v[26:27], v[18:19]
	v_max_f32_e32 v26, 0, v0
	v_max_f32_e32 v27, 0, v1
	v_fma_f32 v0, -|v0|, v18, v26
	v_fma_f32 v1, -|v1|, v19, v27
	s_nop 0
	v_fma_f32 v18, |v2|, s90, 1.0
	v_fma_f32 v19, |v3|, s90, 1.0
	v_rcp_f32_e32 v18, v18
	v_rcp_f32_e32 v19, v19
	s_nop 0
	v_pk_fma_f32 v[22:23], v[18:19], s[92:93], v[22:23] op_sel_hi:[1,0,0]
	v_pk_fma_f32 v[22:23], v[18:19], v[22:23], s[96:97] op_sel_hi:[1,1,0]
	v_pk_fma_f32 v[22:23], v[18:19], v[22:23], s[16:17] op_sel_hi:[1,1,0]
	v_pk_fma_f32 v[22:23], v[18:19], v[22:23], s[84:85] op_sel_hi:[1,1,0]
	v_pk_mul_f32 v[18:19], v[18:19], v[22:23]
	v_pk_mul_f32 v[22:23], v[24:25], s[18:19] op_sel_hi:[1,0]
	v_exp_f32_e32 v22, v22
	v_exp_f32_e32 v23, v23
	s_nop 0
	v_pk_mul_f32 v[18:19], v[22:23], v[18:19]
	v_max_f32_e32 v22, 0, v2
	v_max_f32_e32 v23, 0, v3
	v_fma_f32 v2, -|v2|, v18, v22
	v_fma_f32 v3, -|v3|, v19, v23
	s_nop 1
.LBB0_414:
	v_cvt_pk_bf16_f32 v22, v4, v5
	v_cvt_pk_bf16_f32 v23, v6, v7
	v_cvt_pk_bf16_f32 v24, v0, v1
	v_cvt_pk_bf16_f32 v25, v2, v3
	s_and_b64 vcc, exec, s[10:11]
	global_store_dwordx4 v[20:21], v[22:25], off offset:256 nt
	s_cbranch_vccnz .LBB0_418
	v_add_f32_e32 v18, v12, v13
	v_add_f32_e32 v19, v14, v15
	v_add_f32_e32 v18, v18, v19
	v_add_f32_e32 v19, v8, v9
	v_mul_f32_e32 v9, v9, v9
	v_fmac_f32_e32 v9, v8, v8
	v_mul_f32_e32 v8, v11, v11
	v_fmac_f32_e32 v8, v10, v10
	v_add_f32_e32 v20, v10, v11
	v_add_f32_e32 v8, v9, v8
	v_mul_f32_e32 v9, v5, v5
	v_mul_f32_e32 v10, v7, v7
	v_fmac_f32_e32 v9, v4, v4
	v_fmac_f32_e32 v10, v6, v6
	v_add_f32_e32 v9, v9, v10
	v_mul_f32_e32 v10, v1, v1
	v_fmac_f32_e32 v10, v0, v0
	v_mul_f32_e32 v11, v3, v3
	v_add_f32_e32 v0, v0, v1
	v_add_f32_e32 v1, v2, v3
	v_and_b32_e32 v3, 64, v162
	v_add_f32_e32 v19, v19, v20
	v_add_f32_e32 v4, v4, v5
	v_add_f32_e32 v5, v6, v7
	v_add_f32_e32 v0, v0, v1
	v_xor_b32_e32 v1, 16, v162
	v_add_u32_e32 v3, 64, v3
	v_add_f32_e32 v18, v18, v19
	v_mul_f32_e32 v13, v13, v13
	v_add_f32_e32 v4, v4, v5
	v_cmp_lt_i32_e32 vcc, v1, v3
	v_add_f32_e32 v18, 0, v18
	v_fmac_f32_e32 v13, v12, v12
	v_mul_f32_e32 v12, v15, v15
	v_add_f32_e32 v0, v4, v0
	v_cndmask_b32_e32 v1, v162, v1, vcc
	v_fmac_f32_e32 v12, v14, v14
	v_add_f32_e32 v0, v18, v0
	v_lshlrev_b32_e32 v1, 2, v1
	v_fmac_f32_e32 v11, v2, v2
	v_add_f32_e32 v12, v13, v12
	ds_bpermute_b32 v4, v1, v0
	v_add_f32_e32 v2, v10, v11
	v_add_f32_e32 v8, v12, v8
	v_add_f32_e32 v2, v9, v2
	v_add_f32_e32 v2, v8, v2
	ds_bpermute_b32 v5, v1, v2
	s_waitcnt lgkmcnt(1)
	v_add_f32_e32 v0, v0, v4
	v_xor_b32_e32 v4, 32, v162
	v_cmp_lt_i32_e32 vcc, v4, v3
	s_waitcnt lgkmcnt(0)
	v_add_f32_e32 v2, v2, v5
	v_cndmask_b32_e32 v1, v162, v4, vcc
	v_lshlrev_b32_e32 v3, 2, v1
	ds_bpermute_b32 v1, v3, v0
	ds_bpermute_b32 v3, v3, v2
	s_and_saveexec_b64 s[6:7], s[8:9]
	s_cbranch_execz .LBB0_417
	s_waitcnt lgkmcnt(0)
	v_add_f32_e32 v2, v2, v3
	v_add_f32_e32 v3, v0, v1
	v_lshlrev_b64 v[0:1], 7, v[16:17]
	v_lshl_add_u64 v[0:1], s[78:79], 0, v[0:1]
	v_lshl_add_u64 v[0:1], s[12:13], 2, v[0:1]
	s_lshl_b32 s12, s36, 2
	v_lshl_add_u64 v[0:1], v[0:1], 0, s[12:13]
	global_store_dword v[0:1], v3, off offset:-64
	global_store_dword v[0:1], v2, off

; __device__ __forceinline__ float sigm(float x) { return __builtin_amdgcn_rcpf(1.0f + __expf(-x)); }
; __device__ __forceinline__ u32x4 pack8(f32x4 v0, f32x4 v1) { u32x4 w; w.x = cvt_pk_bf16(v0[0], v0[1]); w.y = cvt_pk_bf16(v0[2], v0[3]); w.z = cvt_pk_bf16(v1[0], v1[1]); w.w = cvt_pk_bf16(v1[2], v1[3]); return w; }
;     __device__ __forceinline__ void operator()(f32x4 (&acc)[2][2][4][2], const Unit& u, int wr, int wc, int fr_, int fq_) const {
;     ...
;             const float* bias = kind == 0 ? w0 : a0;
; #pragma unroll
;             for (int bj = 0; bj < 2; ++bj) {
;                 const f32x4 b0 = *(const f32x4*)(bias + col0 + bj * HALF), b1 = *(const f32x4*)(bias + col0 + bj * HALF + 4);
; #pragma unroll
;                 for (int ai = 0; ai < 2; ++ai)
; #pragma unroll
;                     for (int m = 0; m < 4; ++m) { const size_t off = (size_t)(row0 + ai * HALF + m * 16) * 1024 + col0 + bj * HALF;
;                         f32x4 v0 = acc[ai][bj][m][0] + b0, v1 = acc[ai][bj][m][1] + b1;
;                         if (kind == 0) {
; #pragma unroll
;                             for (int i = 0; i < 4; ++i) { float z = -v0[i]; float sp = fmaxf(z, 0.f) + __logf(1.0f + __expf(-fabsf(z))); v0[i] = __expf(-__expf(-sp - 0.5f));
;                                                           z = -v1[i]; sp = fmaxf(z, 0.f) + __logf(1.0f + __expf(-fabsf(z))); v1[i] = __expf(-__expf(-sp - 0.5f)); }
;                             *(f32x4*)(DEC + off) = v0; *(f32x4*)(DEC + off + 4) = v1;
;                         } else {
; #pragma unroll
;                             for (int i = 0; i < 4; ++i) { v0[i] = sigm(v0[i]); v1[i] = sigm(v1[i]); }
;                             *(u32x4*)(AS + off) = pack8(v0, v1);
;                         }
;                         asm volatile("" ::: "memory"); __builtin_amdgcn_sched_barrier(0); }
.LBB0_925:
	s_cmp_gt_u32 s42, 3
	s_cselect_b64 s[72:73], -1, 0
	s_cmp_lt_u32 s42, 4
	s_cselect_b64 s[0:1], -1, 0
	s_and_b64 vcc, s[0:1], exec
	s_cselect_b32 s0, s77, s81
	s_cselect_b32 s1, s76, s80
	v_mov_b32_e32 v128, s1
	v_mov_b32_e32 v129, s0
	v_lshl_add_u64 v[160:161], v[156:157], 2, v[128:129]
	global_load_dwordx4 v[132:135], v[160:161], off
	global_load_dwordx4 v[128:131], v[160:161], off offset:16
	v_lshlrev_b64 v[158:159], 10, v[154:155]
	s_mov_b64 s[0:1], -1
	v_lshl_add_u64 v[162:163], v[158:159], 0, v[156:157]
	s_waitcnt vmcnt(0)
	v_pk_add_f32 v[166:167], v[122:123], v[134:135]
	v_pk_add_f32 v[170:171], v[120:121], v[132:133]
	v_pk_add_f32 v[164:165], v[126:127], v[130:131]
	v_pk_add_f32 v[168:169], v[124:125], v[128:129]
	s_cbranch_vccnz .LBB0_927
	v_mul_f32_e32 v173, 0xbfb8aa3b, v168
	v_exp_f32_e32 v173, v173
	v_mul_f32_e32 v174, 0xbfb8aa3b, v171
	v_mul_f32_e32 v175, 0xbfb8aa3b, v169
	v_exp_f32_e32 v174, v174
	v_exp_f32_e32 v175, v175
	v_add_f32_e32 v173, 1.0, v173
	v_mul_f32_e32 v172, 0xbfb8aa3b, v170
	v_rcp_f32_e32 v176, v173
	v_add_f32_e32 v173, 1.0, v174
	v_add_f32_e32 v174, 1.0, v175
	v_mul_f32_e32 v175, 0xbfb8aa3b, v166
	v_mul_f32_e32 v177, 0xbfb8aa3b, v164
	v_mul_f32_e32 v178, 0xbfb8aa3b, v167
	v_mul_f32_e32 v179, 0xbfb8aa3b, v165
	v_exp_f32_e32 v172, v172
	v_exp_f32_e32 v175, v175
	v_exp_f32_e32 v177, v177
	v_exp_f32_e32 v178, v178
	v_exp_f32_e32 v179, v179
	v_add_f32_e32 v172, 1.0, v172
	v_add_f32_e32 v175, 1.0, v175
	v_add_f32_e32 v177, 1.0, v177
	v_add_f32_e32 v178, 1.0, v178
	v_add_f32_e32 v179, 1.0, v179
	v_rcp_f32_e32 v172, v172
	v_rcp_f32_e32 v173, v173
	v_rcp_f32_e32 v174, v174
	v_rcp_f32_e32 v175, v175
	v_rcp_f32_e32 v177, v177
	v_rcp_f32_e32 v178, v178
	v_rcp_f32_e32 v179, v179
	v_cvt_pk_bf16_f32 v172, v172, v173
	v_cvt_pk_bf16_f32 v174, v176, v174
	v_cvt_pk_bf16_f32 v173, v175, v178
	v_cvt_pk_bf16_f32 v175, v177, v179
	v_lshl_add_u64 v[176:177], v[162:163], 1, s[38:39]
	s_mov_b64 s[0:1], 0
	global_store_dwordx4 v[176:177], v[172:175], off nt
.LBB0_927:
	s_andn2_b64 vcc, exec, s[0:1]
	s_cbranch_vccnz .LBB0_929
	v_lshl_add_u64 v[162:163], v[162:163], 2, s[36:37]
	v_mul_f32_e32 v170, 0xbfb8aa3b, v170
	v_mul_f32_e32 v171, 0xbfb8aa3b, v171
	v_mul_f32_e32 v172, 0xbfb8aa3b, v166
	v_mul_f32_e32 v173, 0xbfb8aa3b, v167
	v_mul_f32_e32 v174, 0xbfb8aa3b, v168
	v_mul_f32_e32 v175, 0xbfb8aa3b, v169
	v_mul_f32_e32 v176, 0xbfb8aa3b, v164
	v_mul_f32_e32 v177, 0xbfb8aa3b, v165
	v_exp_f32_e32 v170, v170
	v_exp_f32_e32 v171, v171
	v_exp_f32_e32 v172, v172
	v_exp_f32_e32 v173, v173
	v_exp_f32_e32 v174, v174
	v_exp_f32_e32 v175, v175
	v_exp_f32_e32 v176, v176
	v_exp_f32_e32 v177, v177
	v_add_f32_e32 v170, 1.0, v170
	v_add_f32_e32 v171, 1.0, v171
	v_add_f32_e32 v172, 1.0, v172
	v_add_f32_e32 v173, 1.0, v173
	v_add_f32_e32 v174, 1.0, v174
	v_add_f32_e32 v175, 1.0, v175
	v_add_f32_e32 v176, 1.0, v176
	v_add_f32_e32 v177, 1.0, v177
	v_rcp_f32_e32 v170, v170
	v_rcp_f32_e32 v171, v171
	v_rcp_f32_e32 v172, v172
	v_rcp_f32_e32 v173, v173
	v_rcp_f32_e32 v174, v174
	v_rcp_f32_e32 v175, v175
	v_rcp_f32_e32 v176, v176
	v_rcp_f32_e32 v177, v177
	v_mul_f32_e32 v170, 0xbf60028b, v170
	v_mul_f32_e32 v171, 0xbf60028b, v171
	v_mul_f32_e32 v172, 0xbf60028b, v172
	v_mul_f32_e32 v173, 0xbf60028b, v173
	v_mul_f32_e32 v174, 0xbf60028b, v174
	v_mul_f32_e32 v175, 0xbf60028b, v175
	v_mul_f32_e32 v176, 0xbf60028b, v176
	v_mul_f32_e32 v177, 0xbf60028b, v177
	v_exp_f32_e32 v170, v170
	v_exp_f32_e32 v171, v171
	v_exp_f32_e32 v172, v172
	v_exp_f32_e32 v173, v173
	v_exp_f32_e32 v174, v174
	v_exp_f32_e32 v175, v175
	v_exp_f32_e32 v176, v176
	v_exp_f32_e32 v177, v177
	s_nop 0
	global_store_dwordx4 v[162:163], v[170:173], off nt
	global_store_dwordx4 v[162:163], v[174:177], off offset:16 nt
.LBB0_929:
	v_lshlrev_b64 v[162:163], 10, v[154:155]
	s_mov_b64 s[0:1], 0x4000
	v_lshl_add_u64 v[162:163], v[162:163], 0, s[0:1]
	v_cndmask_b32_e64 v174, 0, 1, s[72:73]
	v_lshl_add_u64 v[164:165], v[162:163], 0, v[156:157]
	v_pk_add_f32 v[168:169], v[110:111], v[134:135]
	v_pk_add_f32 v[172:173], v[108:109], v[132:133]
	v_pk_add_f32 v[166:167], v[106:107], v[130:131]
	v_pk_add_f32 v[170:171], v[104:105], v[128:129]
	v_cmp_ne_u32_e64 s[6:7], 1, v174
	s_andn2_b64 vcc, exec, s[72:73]
	s_mov_b64 s[0:1], -1
	s_cbranch_vccnz .LBB0_931
	v_mul_f32_e32 v175, 0xbfb8aa3b, v170
	v_exp_f32_e32 v175, v175
	v_mul_f32_e32 v176, 0xbfb8aa3b, v173
	v_mul_f32_e32 v177, 0xbfb8aa3b, v171
	v_exp_f32_e32 v176, v176
	v_exp_f32_e32 v177, v177
	v_add_f32_e32 v175, 1.0, v175
	v_mul_f32_e32 v174, 0xbfb8aa3b, v172
	v_rcp_f32_e32 v178, v175
	v_add_f32_e32 v175, 1.0, v176
	v_add_f32_e32 v176, 1.0, v177
	v_mul_f32_e32 v177, 0xbfb8aa3b, v168
	v_mul_f32_e32 v179, 0xbfb8aa3b, v166
	v_mul_f32_e32 v180, 0xbfb8aa3b, v169
	v_mul_f32_e32 v181, 0xbfb8aa3b, v167
	v_exp_f32_e32 v174, v174
	v_exp_f32_e32 v177, v177
	v_exp_f32_e32 v179, v179
	v_exp_f32_e32 v180, v180
	v_exp_f32_e32 v181, v181
	v_add_f32_e32 v174, 1.0, v174
	v_add_f32_e32 v177, 1.0, v177
	v_add_f32_e32 v179, 1.0, v179
	v_add_f32_e32 v180, 1.0, v180
	v_add_f32_e32 v181, 1.0, v181
	v_rcp_f32_e32 v174, v174
	v_rcp_f32_e32 v175, v175
	v_rcp_f32_e32 v176, v176
	v_rcp_f32_e32 v177, v177
	v_rcp_f32_e32 v179, v179
	v_rcp_f32_e32 v180, v180
	v_rcp_f32_e32 v181, v181
	v_cvt_pk_bf16_f32 v174, v174, v175
	v_cvt_pk_bf16_f32 v176, v178, v176
	v_cvt_pk_bf16_f32 v175, v177, v180
	v_cvt_pk_bf16_f32 v177, v179, v181
	v_lshl_add_u64 v[178:179], v[164:165], 1, s[38:39]
	s_mov_b64 s[0:1], 0
	global_store_dwordx4 v[178:179], v[174:177], off nt
; __device__ __forceinline__ float sigm(float x) { return __builtin_amdgcn_rcpf(1.0f + __expf(-x)); }
; __device__ __forceinline__ u32x4 pack8(f32x4 v0, f32x4 v1) { u32x4 w; w.x = cvt_pk_bf16(v0[0], v0[1]); w.y = cvt_pk_bf16(v0[2], v0[3]); w.z = cvt_pk_bf16(v1[0], v1[1]); w.w = cvt_pk_bf16(v1[2], v1[3]); return w; }
;     __device__ __forceinline__ void operator()(f32x4 (&acc)[2][2][4][2], const Unit& u, int wr, int wc, int fr_, int fq_) const {
;     ...
;                     for (int m = 0; m < 4; ++m) { const size_t off = (size_t)(row0 + ai * HALF + m * 16) * 1024 + col0 + bj * HALF;
;                         f32x4 v0 = acc[ai][bj][m][0] + b0, v1 = acc[ai][bj][m][1] + b1;
;                         if (kind == 0) {
; #pragma unroll
;                             for (int i = 0; i < 4; ++i) { float z = -v0[i]; float sp = fmaxf(z, 0.f) + __logf(1.0f + __expf(-fabsf(z))); v0[i] = __expf(-__expf(-sp - 0.5f));
;                                                           z = -v1[i]; sp = fmaxf(z, 0.f) + __logf(1.0f + __expf(-fabsf(z))); v1[i] = __expf(-__expf(-sp - 0.5f)); }
;                             *(f32x4*)(DEC + off) = v0; *(f32x4*)(DEC + off + 4) = v1;
;                         } else {
; #pragma unroll
;                             for (int i = 0; i < 4; ++i) { v0[i] = sigm(v0[i]); v1[i] = sigm(v1[i]); }
;                             *(u32x4*)(AS + off) = pack8(v0, v1);
;                         }
;                         asm volatile("" ::: "memory"); __builtin_amdgcn_sched_barrier(0); }
.LBB0_931:
	s_andn2_b64 vcc, exec, s[0:1]
	s_cbranch_vccnz .LBB0_933
	v_lshl_add_u64 v[164:165], v[164:165], 2, s[36:37]
	v_mul_f32_e32 v172, 0xbfb8aa3b, v172
	v_mul_f32_e32 v173, 0xbfb8aa3b, v173
	v_mul_f32_e32 v174, 0xbfb8aa3b, v168
	v_mul_f32_e32 v175, 0xbfb8aa3b, v169
	v_mul_f32_e32 v176, 0xbfb8aa3b, v170
	v_mul_f32_e32 v177, 0xbfb8aa3b, v171
	v_mul_f32_e32 v178, 0xbfb8aa3b, v166
	v_mul_f32_e32 v179, 0xbfb8aa3b, v167
	v_exp_f32_e32 v172, v172
	v_exp_f32_e32 v173, v173
	v_exp_f32_e32 v174, v174
	v_exp_f32_e32 v175, v175
	v_exp_f32_e32 v176, v176
	v_exp_f32_e32 v177, v177
	v_exp_f32_e32 v178, v178
	v_exp_f32_e32 v179, v179
	v_add_f32_e32 v172, 1.0, v172
	v_add_f32_e32 v173, 1.0, v173
	v_add_f32_e32 v174, 1.0, v174
	v_add_f32_e32 v175, 1.0, v175
	v_add_f32_e32 v176, 1.0, v176
	v_add_f32_e32 v177, 1.0, v177
	v_add_f32_e32 v178, 1.0, v178
	v_add_f32_e32 v179, 1.0, v179
	v_rcp_f32_e32 v172, v172
	v_rcp_f32_e32 v173, v173
	v_rcp_f32_e32 v174, v174
	v_rcp_f32_e32 v175, v175
	v_rcp_f32_e32 v176, v176
	v_rcp_f32_e32 v177, v177
	v_rcp_f32_e32 v178, v178
	v_rcp_f32_e32 v179, v179
	v_mul_f32_e32 v172, 0xbf60028b, v172
	v_mul_f32_e32 v173, 0xbf60028b, v173
	v_mul_f32_e32 v174, 0xbf60028b, v174
	v_mul_f32_e32 v175, 0xbf60028b, v175
	v_mul_f32_e32 v176, 0xbf60028b, v176
	v_mul_f32_e32 v177, 0xbf60028b, v177
	v_mul_f32_e32 v178, 0xbf60028b, v178
	v_mul_f32_e32 v179, 0xbf60028b, v179
	v_exp_f32_e32 v172, v172
	v_exp_f32_e32 v173, v173
	v_exp_f32_e32 v174, v174
	v_exp_f32_e32 v175, v175
	v_exp_f32_e32 v176, v176
	v_exp_f32_e32 v177, v177
	v_exp_f32_e32 v178, v178
	v_exp_f32_e32 v179, v179
	s_nop 0
	global_store_dwordx4 v[164:165], v[172:175], off nt
	global_store_dwordx4 v[164:165], v[176:179], off offset:16 nt
.LBB0_933:
	v_lshlrev_b64 v[164:165], 10, v[154:155]
	v_lshl_add_u64 v[164:165], v[164:165], 0, s[56:57]
	v_lshl_add_u64 v[166:167], v[164:165], 0, v[156:157]
	v_pk_add_f32 v[170:171], v[94:95], v[134:135]
	v_pk_add_f32 v[174:175], v[92:93], v[132:133]
	v_pk_add_f32 v[168:169], v[90:91], v[130:131]
	v_pk_add_f32 v[172:173], v[88:89], v[128:129]
	s_and_b64 vcc, exec, s[6:7]
	s_mov_b64 s[0:1], -1
	s_cbranch_vccnz .LBB0_935
	v_mul_f32_e32 v177, 0xbfb8aa3b, v172
	v_exp_f32_e32 v177, v177
	v_mul_f32_e32 v178, 0xbfb8aa3b, v175
	v_mul_f32_e32 v179, 0xbfb8aa3b, v173
	v_exp_f32_e32 v178, v178
	v_exp_f32_e32 v179, v179
	v_add_f32_e32 v177, 1.0, v177
	v_mul_f32_e32 v176, 0xbfb8aa3b, v174
	v_rcp_f32_e32 v180, v177
	v_add_f32_e32 v177, 1.0, v178
	v_add_f32_e32 v178, 1.0, v179
	v_mul_f32_e32 v179, 0xbfb8aa3b, v170
	v_mul_f32_e32 v181, 0xbfb8aa3b, v168
	v_mul_f32_e32 v182, 0xbfb8aa3b, v171
	v_mul_f32_e32 v183, 0xbfb8aa3b, v169
	v_exp_f32_e32 v176, v176
	v_exp_f32_e32 v179, v179
	v_exp_f32_e32 v181, v181
	v_exp_f32_e32 v182, v182
	v_exp_f32_e32 v183, v183
	v_add_f32_e32 v176, 1.0, v176
	v_add_f32_e32 v179, 1.0, v179
	v_add_f32_e32 v181, 1.0, v181
	v_add_f32_e32 v182, 1.0, v182
	v_add_f32_e32 v183, 1.0, v183
	v_rcp_f32_e32 v176, v176
	v_rcp_f32_e32 v177, v177
	v_rcp_f32_e32 v178, v178
	v_rcp_f32_e32 v179, v179
	v_rcp_f32_e32 v181, v181
	v_rcp_f32_e32 v182, v182
	v_rcp_f32_e32 v183, v183
	v_cvt_pk_bf16_f32 v176, v176, v177
	v_cvt_pk_bf16_f32 v178, v180, v178
	v_cvt_pk_bf16_f32 v177, v179, v182
	v_cvt_pk_bf16_f32 v179, v181, v183
	v_lshl_add_u64 v[180:181], v[166:167], 1, s[38:39]
	s_mov_b64 s[0:1], 0
	global_store_dwordx4 v[180:181], v[176:179], off nt
.LBB0_935:
	s_andn2_b64 vcc, exec, s[0:1]
	s_cbranch_vccnz .LBB0_937
	v_lshl_add_u64 v[166:167], v[166:167], 2, s[36:37]
	v_mul_f32_e32 v174, 0xbfb8aa3b, v174
	v_mul_f32_e32 v175, 0xbfb8aa3b, v175
	v_mul_f32_e32 v176, 0xbfb8aa3b, v170
	v_mul_f32_e32 v177, 0xbfb8aa3b, v171
	v_mul_f32_e32 v178, 0xbfb8aa3b, v172
	v_mul_f32_e32 v179, 0xbfb8aa3b, v173
	v_mul_f32_e32 v180, 0xbfb8aa3b, v168
	v_mul_f32_e32 v181, 0xbfb8aa3b, v169
	v_exp_f32_e32 v174, v174
	v_exp_f32_e32 v175, v175
	v_exp_f32_e32 v176, v176
	v_exp_f32_e32 v177, v177
	v_exp_f32_e32 v178, v178
	v_exp_f32_e32 v179, v179
	v_exp_f32_e32 v180, v180
	v_exp_f32_e32 v181, v181
	v_add_f32_e32 v174, 1.0, v174
	v_add_f32_e32 v175, 1.0, v175
	v_add_f32_e32 v176, 1.0, v176
	v_add_f32_e32 v177, 1.0, v177
	v_add_f32_e32 v178, 1.0, v178
	v_add_f32_e32 v179, 1.0, v179
	v_add_f32_e32 v180, 1.0, v180
	v_add_f32_e32 v181, 1.0, v181
	v_rcp_f32_e32 v174, v174
	v_rcp_f32_e32 v175, v175
	v_rcp_f32_e32 v176, v176
	v_rcp_f32_e32 v177, v177
	v_rcp_f32_e32 v178, v178
	v_rcp_f32_e32 v179, v179
	v_rcp_f32_e32 v180, v180
	v_rcp_f32_e32 v181, v181
	v_mul_f32_e32 v174, 0xbf60028b, v174
	v_mul_f32_e32 v175, 0xbf60028b, v175
	v_mul_f32_e32 v176, 0xbf60028b, v176
	v_mul_f32_e32 v177, 0xbf60028b, v177
	v_mul_f32_e32 v178, 0xbf60028b, v178
	v_mul_f32_e32 v179, 0xbf60028b, v179
	v_mul_f32_e32 v180, 0xbf60028b, v180
	v_mul_f32_e32 v181, 0xbf60028b, v181
	v_exp_f32_e32 v174, v174
	v_exp_f32_e32 v175, v175
	v_exp_f32_e32 v176, v176
	v_exp_f32_e32 v177, v177
	v_exp_f32_e32 v178, v178
	v_exp_f32_e32 v179, v179
	v_exp_f32_e32 v180, v180
	v_exp_f32_e32 v181, v181
	s_nop 0
	global_store_dwordx4 v[166:167], v[174:177], off nt
	global_store_dwordx4 v[166:167], v[178:181], off offset:16 nt
; __device__ __forceinline__ float sigm(float x) { return __builtin_amdgcn_rcpf(1.0f + __expf(-x)); }
; __device__ __forceinline__ u32x4 pack8(f32x4 v0, f32x4 v1) { u32x4 w; w.x = cvt_pk_bf16(v0[0], v0[1]); w.y = cvt_pk_bf16(v0[2], v0[3]); w.z = cvt_pk_bf16(v1[0], v1[1]); w.w = cvt_pk_bf16(v1[2], v1[3]); return w; }
;     __device__ __forceinline__ void operator()(f32x4 (&acc)[2][2][4][2], const Unit& u, int wr, int wc, int fr_, int fq_) const {
;     ...
;                     for (int m = 0; m < 4; ++m) { const size_t off = (size_t)(row0 + ai * HALF + m * 16) * 1024 + col0 + bj * HALF;
;                         f32x4 v0 = acc[ai][bj][m][0] + b0, v1 = acc[ai][bj][m][1] + b1;
;                         if (kind == 0) {
; #pragma unroll
;                             for (int i = 0; i < 4; ++i) { float z = -v0[i]; float sp = fmaxf(z, 0.f) + __logf(1.0f + __expf(-fabsf(z))); v0[i] = __expf(-__expf(-sp - 0.5f));
;                                                           z = -v1[i]; sp = fmaxf(z, 0.f) + __logf(1.0f + __expf(-fabsf(z))); v1[i] = __expf(-__expf(-sp - 0.5f)); }
;                             *(f32x4*)(DEC + off) = v0; *(f32x4*)(DEC + off + 4) = v1;
;                         } else {
; #pragma unroll
;                             for (int i = 0; i < 4; ++i) { v0[i] = sigm(v0[i]); v1[i] = sigm(v1[i]); }
;                             *(u32x4*)(AS + off) = pack8(v0, v1);
;                         }
;                         asm volatile("" ::: "memory"); __builtin_amdgcn_sched_barrier(0); }
.LBB0_937:
	v_lshlrev_b64 v[166:167], 10, v[154:155]
	s_mov_b64 s[0:1], 0xc000
	v_lshl_add_u64 v[166:167], v[166:167], 0, s[0:1]
	v_lshl_add_u64 v[168:169], v[166:167], 0, v[156:157]
	v_pk_add_f32 v[172:173], v[78:79], v[134:135]
	v_pk_add_f32 v[176:177], v[76:77], v[132:133]
	v_pk_add_f32 v[170:171], v[74:75], v[130:131]
	v_pk_add_f32 v[174:175], v[72:73], v[128:129]
	s_and_b64 vcc, exec, s[6:7]
	s_mov_b64 s[0:1], -1
	s_cbranch_vccnz .LBB0_939
	v_mul_f32_e32 v179, 0xbfb8aa3b, v174
	v_exp_f32_e32 v179, v179
	v_mul_f32_e32 v180, 0xbfb8aa3b, v177
	v_mul_f32_e32 v181, 0xbfb8aa3b, v175
	v_exp_f32_e32 v180, v180
	v_exp_f32_e32 v181, v181
	v_add_f32_e32 v179, 1.0, v179
	v_mul_f32_e32 v178, 0xbfb8aa3b, v176
	v_rcp_f32_e32 v182, v179
	v_add_f32_e32 v179, 1.0, v180
	v_add_f32_e32 v180, 1.0, v181
	v_mul_f32_e32 v181, 0xbfb8aa3b, v172
	v_mul_f32_e32 v183, 0xbfb8aa3b, v170
	v_mul_f32_e32 v191, 0xbfb8aa3b, v173
	v_mul_f32_e32 v192, 0xbfb8aa3b, v171
	v_exp_f32_e32 v178, v178
	v_exp_f32_e32 v181, v181
	v_exp_f32_e32 v183, v183
	v_exp_f32_e32 v191, v191
	v_exp_f32_e32 v192, v192
	v_add_f32_e32 v178, 1.0, v178
	v_add_f32_e32 v181, 1.0, v181
	v_add_f32_e32 v183, 1.0, v183
	v_add_f32_e32 v191, 1.0, v191
	v_add_f32_e32 v192, 1.0, v192
	v_rcp_f32_e32 v178, v178
	v_rcp_f32_e32 v179, v179
	v_rcp_f32_e32 v180, v180
	v_rcp_f32_e32 v181, v181
	v_rcp_f32_e32 v183, v183
	v_rcp_f32_e32 v191, v191
	v_rcp_f32_e32 v192, v192
	v_cvt_pk_bf16_f32 v178, v178, v179
	v_cvt_pk_bf16_f32 v180, v182, v180
	v_cvt_pk_bf16_f32 v179, v181, v191
	v_cvt_pk_bf16_f32 v181, v183, v192
	v_lshl_add_u64 v[182:183], v[168:169], 1, s[38:39]
	s_mov_b64 s[0:1], 0
	global_store_dwordx4 v[182:183], v[178:181], off nt
.LBB0_939:
	s_andn2_b64 vcc, exec, s[0:1]
	s_cbranch_vccnz .LBB0_941
	v_lshl_add_u64 v[168:169], v[168:169], 2, s[36:37]
	v_mul_f32_e32 v176, 0xbfb8aa3b, v176
	v_mul_f32_e32 v177, 0xbfb8aa3b, v177
	v_mul_f32_e32 v178, 0xbfb8aa3b, v172
	v_mul_f32_e32 v179, 0xbfb8aa3b, v173
	v_mul_f32_e32 v180, 0xbfb8aa3b, v174
	v_mul_f32_e32 v181, 0xbfb8aa3b, v175
	v_mul_f32_e32 v182, 0xbfb8aa3b, v170
	v_mul_f32_e32 v183, 0xbfb8aa3b, v171
	v_exp_f32_e32 v176, v176
	v_exp_f32_e32 v177, v177
	v_exp_f32_e32 v178, v178
	v_exp_f32_e32 v179, v179
	v_exp_f32_e32 v180, v180
	v_exp_f32_e32 v181, v181
	v_exp_f32_e32 v182, v182
	v_exp_f32_e32 v183, v183
	v_add_f32_e32 v176, 1.0, v176
	v_add_f32_e32 v177, 1.0, v177
	v_add_f32_e32 v178, 1.0, v178
	v_add_f32_e32 v179, 1.0, v179
	v_add_f32_e32 v180, 1.0, v180
	v_add_f32_e32 v181, 1.0, v181
	v_add_f32_e32 v182, 1.0, v182
	v_add_f32_e32 v183, 1.0, v183
	v_rcp_f32_e32 v176, v176
	v_rcp_f32_e32 v177, v177
	v_rcp_f32_e32 v178, v178
	v_rcp_f32_e32 v179, v179
	v_rcp_f32_e32 v180, v180
	v_rcp_f32_e32 v181, v181
	v_rcp_f32_e32 v182, v182
	v_rcp_f32_e32 v183, v183
	v_mul_f32_e32 v176, 0xbf60028b, v176
	v_mul_f32_e32 v177, 0xbf60028b, v177
	v_mul_f32_e32 v178, 0xbf60028b, v178
	v_mul_f32_e32 v179, 0xbf60028b, v179
	v_mul_f32_e32 v180, 0xbf60028b, v180
	v_mul_f32_e32 v181, 0xbf60028b, v181
	v_mul_f32_e32 v182, 0xbf60028b, v182
	v_mul_f32_e32 v183, 0xbf60028b, v183
	v_exp_f32_e32 v176, v176
	v_exp_f32_e32 v177, v177
	v_exp_f32_e32 v178, v178
	v_exp_f32_e32 v179, v179
	v_exp_f32_e32 v180, v180
	v_exp_f32_e32 v181, v181
	v_exp_f32_e32 v182, v182
	v_exp_f32_e32 v183, v183
	s_nop 0
	global_store_dwordx4 v[168:169], v[176:179], off nt
	global_store_dwordx4 v[168:169], v[180:183], off offset:16 nt
.LBB0_941:
	v_lshlrev_b64 v[168:169], 10, v[154:155]
	s_mov_b64 s[0:1], 0x20000
	v_lshl_add_u64 v[168:169], v[168:169], 0, s[0:1]
	v_lshl_add_u64 v[170:171], v[168:169], 0, v[156:157]
	v_pk_add_f32 v[174:175], v[62:63], v[134:135]
	v_pk_add_f32 v[178:179], v[60:61], v[132:133]
	v_pk_add_f32 v[172:173], v[58:59], v[130:131]
	v_pk_add_f32 v[176:177], v[56:57], v[128:129]
	s_and_b64 vcc, exec, s[6:7]
	s_mov_b64 s[0:1], -1
	s_cbranch_vccnz .LBB0_943
	v_mul_f32_e32 v181, 0xbfb8aa3b, v176
	v_exp_f32_e32 v181, v181
	v_mul_f32_e32 v182, 0xbfb8aa3b, v179
	v_mul_f32_e32 v183, 0xbfb8aa3b, v177
	v_exp_f32_e32 v182, v182
	v_exp_f32_e32 v183, v183
	v_add_f32_e32 v181, 1.0, v181
	v_mul_f32_e32 v180, 0xbfb8aa3b, v178
	v_rcp_f32_e32 v191, v181
	v_add_f32_e32 v181, 1.0, v182
	v_add_f32_e32 v182, 1.0, v183
	v_mul_f32_e32 v183, 0xbfb8aa3b, v174
	v_mul_f32_e32 v192, 0xbfb8aa3b, v172
	v_mul_f32_e32 v193, 0xbfb8aa3b, v175
	v_mul_f32_e32 v194, 0xbfb8aa3b, v173
	v_exp_f32_e32 v180, v180
	v_exp_f32_e32 v183, v183
	v_exp_f32_e32 v192, v192
	v_exp_f32_e32 v193, v193
	v_exp_f32_e32 v194, v194
	v_add_f32_e32 v180, 1.0, v180
	v_add_f32_e32 v183, 1.0, v183
	v_add_f32_e32 v192, 1.0, v192
	v_add_f32_e32 v193, 1.0, v193
	v_add_f32_e32 v194, 1.0, v194
	v_rcp_f32_e32 v180, v180
	v_rcp_f32_e32 v181, v181
	v_rcp_f32_e32 v182, v182
	v_rcp_f32_e32 v183, v183
	v_rcp_f32_e32 v192, v192
	v_rcp_f32_e32 v193, v193
	v_rcp_f32_e32 v194, v194
	v_cvt_pk_bf16_f32 v180, v180, v181
	v_cvt_pk_bf16_f32 v182, v191, v182
	v_cvt_pk_bf16_f32 v181, v183, v193
	v_cvt_pk_bf16_f32 v183, v192, v194
	v_lshl_add_u64 v[192:193], v[170:171], 1, s[38:39]
	s_mov_b64 s[0:1], 0
	global_store_dwordx4 v[192:193], v[180:183], off nt
; __device__ __forceinline__ float sigm(float x) { return __builtin_amdgcn_rcpf(1.0f + __expf(-x)); }
; __device__ __forceinline__ u32x4 pack8(f32x4 v0, f32x4 v1) { u32x4 w; w.x = cvt_pk_bf16(v0[0], v0[1]); w.y = cvt_pk_bf16(v0[2], v0[3]); w.z = cvt_pk_bf16(v1[0], v1[1]); w.w = cvt_pk_bf16(v1[2], v1[3]); return w; }
;     __device__ __forceinline__ void operator()(f32x4 (&acc)[2][2][4][2], const Unit& u, int wr, int wc, int fr_, int fq_) const {
;     ...
;                     for (int m = 0; m < 4; ++m) { const size_t off = (size_t)(row0 + ai * HALF + m * 16) * 1024 + col0 + bj * HALF;
;                         f32x4 v0 = acc[ai][bj][m][0] + b0, v1 = acc[ai][bj][m][1] + b1;
;                         if (kind == 0) {
; #pragma unroll
;                             for (int i = 0; i < 4; ++i) { float z = -v0[i]; float sp = fmaxf(z, 0.f) + __logf(1.0f + __expf(-fabsf(z))); v0[i] = __expf(-__expf(-sp - 0.5f));
;                                                           z = -v1[i]; sp = fmaxf(z, 0.f) + __logf(1.0f + __expf(-fabsf(z))); v1[i] = __expf(-__expf(-sp - 0.5f)); }
;                             *(f32x4*)(DEC + off) = v0; *(f32x4*)(DEC + off + 4) = v1;
;                         } else {
; #pragma unroll
;                             for (int i = 0; i < 4; ++i) { v0[i] = sigm(v0[i]); v1[i] = sigm(v1[i]); }
;                             *(u32x4*)(AS + off) = pack8(v0, v1);
;                         }
;                         asm volatile("" ::: "memory"); __builtin_amdgcn_sched_barrier(0); }
.LBB0_943:
	s_andn2_b64 vcc, exec, s[0:1]
	s_cbranch_vccnz .LBB0_945
	v_lshl_add_u64 v[170:171], v[170:171], 2, s[36:37]
	v_mul_f32_e32 v178, 0xbfb8aa3b, v178
	v_mul_f32_e32 v179, 0xbfb8aa3b, v179
	v_mul_f32_e32 v180, 0xbfb8aa3b, v174
	v_mul_f32_e32 v181, 0xbfb8aa3b, v175
	v_mul_f32_e32 v192, 0xbfb8aa3b, v176
	v_mul_f32_e32 v193, 0xbfb8aa3b, v177
	v_mul_f32_e32 v194, 0xbfb8aa3b, v172
	v_mul_f32_e32 v195, 0xbfb8aa3b, v173
	v_exp_f32_e32 v178, v178
	v_exp_f32_e32 v179, v179
	v_exp_f32_e32 v180, v180
	v_exp_f32_e32 v181, v181
	v_exp_f32_e32 v192, v192
	v_exp_f32_e32 v193, v193
	v_exp_f32_e32 v194, v194
	v_exp_f32_e32 v195, v195
	v_add_f32_e32 v178, 1.0, v178
	v_add_f32_e32 v179, 1.0, v179
	v_add_f32_e32 v180, 1.0, v180
	v_add_f32_e32 v181, 1.0, v181
	v_add_f32_e32 v192, 1.0, v192
	v_add_f32_e32 v193, 1.0, v193
	v_add_f32_e32 v194, 1.0, v194
	v_add_f32_e32 v195, 1.0, v195
	v_rcp_f32_e32 v178, v178
	v_rcp_f32_e32 v179, v179
	v_rcp_f32_e32 v180, v180
	v_rcp_f32_e32 v181, v181
	v_rcp_f32_e32 v192, v192
	v_rcp_f32_e32 v193, v193
	v_rcp_f32_e32 v194, v194
	v_rcp_f32_e32 v195, v195
	v_mul_f32_e32 v178, 0xbf60028b, v178
	v_mul_f32_e32 v179, 0xbf60028b, v179
	v_mul_f32_e32 v180, 0xbf60028b, v180
	v_mul_f32_e32 v181, 0xbf60028b, v181
	v_mul_f32_e32 v192, 0xbf60028b, v192
	v_mul_f32_e32 v193, 0xbf60028b, v193
	v_mul_f32_e32 v194, 0xbf60028b, v194
	v_mul_f32_e32 v195, 0xbf60028b, v195
	v_exp_f32_e32 v178, v178
	v_exp_f32_e32 v179, v179
	v_exp_f32_e32 v180, v180
	v_exp_f32_e32 v181, v181
	v_exp_f32_e32 v192, v192
	v_exp_f32_e32 v193, v193
	v_exp_f32_e32 v194, v194
	v_exp_f32_e32 v195, v195
	s_nop 0
	global_store_dwordx4 v[170:171], v[178:181], off nt
	global_store_dwordx4 v[170:171], v[192:195], off offset:16 nt
.LBB0_945:
	v_lshlrev_b64 v[170:171], 10, v[154:155]
	s_mov_b64 s[0:1], 0x24000
	v_lshl_add_u64 v[170:171], v[170:171], 0, s[0:1]
	v_lshl_add_u64 v[172:173], v[170:171], 0, v[156:157]
	v_pk_add_f32 v[176:177], v[46:47], v[134:135]
	v_pk_add_f32 v[180:181], v[44:45], v[132:133]
	v_pk_add_f32 v[174:175], v[42:43], v[130:131]
	v_pk_add_f32 v[178:179], v[40:41], v[128:129]
	s_and_b64 vcc, exec, s[6:7]
	s_mov_b64 s[0:1], -1
	s_cbranch_vccnz .LBB0_947
	v_mul_f32_e32 v192, 0xbfb8aa3b, v179
	v_exp_f32_e32 v192, v192
	v_mul_f32_e32 v193, 0xbfb8aa3b, v176
	v_exp_f32_e32 v193, v193
	v_mul_f32_e32 v194, 0xbfb8aa3b, v174
	v_exp_f32_e32 v194, v194
	v_add_f32_e32 v192, 1.0, v192
	v_rcp_f32_e32 v195, v192
	v_add_f32_e32 v192, 1.0, v193
	v_rcp_f32_e32 v193, v192
	v_add_f32_e32 v192, 1.0, v194
	v_mul_f32_e32 v194, 0xbfb8aa3b, v177
	v_mul_f32_e32 v182, 0xbfb8aa3b, v180
	v_mul_f32_e32 v183, 0xbfb8aa3b, v178
	v_mul_f32_e32 v191, 0xbfb8aa3b, v181
	v_exp_f32_e32 v194, v194
	v_mul_f32_e32 v196, 0xbfb8aa3b, v175
	v_exp_f32_e32 v182, v182
	v_exp_f32_e32 v183, v183
	v_exp_f32_e32 v191, v191
	v_exp_f32_e32 v196, v196
	v_rcp_f32_e32 v197, v192
	v_add_f32_e32 v192, 1.0, v194
	v_add_f32_e32 v182, 1.0, v182
	v_add_f32_e32 v183, 1.0, v183
	v_add_f32_e32 v191, 1.0, v191
	v_rcp_f32_e32 v194, v192
	v_add_f32_e32 v192, 1.0, v196
	v_rcp_f32_e32 v182, v182
	v_rcp_f32_e32 v183, v183
	v_rcp_f32_e32 v191, v191
	v_rcp_f32_e32 v196, v192
	v_cvt_pk_bf16_f32 v193, v193, v194
	v_cvt_pk_bf16_f32 v194, v183, v195
	v_cvt_pk_bf16_f32 v192, v182, v191
	v_cvt_pk_bf16_f32 v195, v197, v196
	v_lshl_add_u64 v[182:183], v[172:173], 1, s[38:39]
	s_mov_b64 s[0:1], 0
	global_store_dwordx4 v[182:183], v[192:195], off nt
.LBB0_947:
	s_andn2_b64 vcc, exec, s[0:1]
	s_cbranch_vccnz .LBB0_949
	v_lshl_add_u64 v[172:173], v[172:173], 2, s[36:37]
	v_mul_f32_e32 v180, 0xbfb8aa3b, v180
	v_mul_f32_e32 v181, 0xbfb8aa3b, v181
	v_mul_f32_e32 v182, 0xbfb8aa3b, v176
	v_mul_f32_e32 v183, 0xbfb8aa3b, v177
	v_mul_f32_e32 v192, 0xbfb8aa3b, v178
	v_mul_f32_e32 v193, 0xbfb8aa3b, v179
	v_mul_f32_e32 v194, 0xbfb8aa3b, v174
	v_mul_f32_e32 v195, 0xbfb8aa3b, v175
	v_exp_f32_e32 v180, v180
	v_exp_f32_e32 v181, v181
	v_exp_f32_e32 v182, v182
	v_exp_f32_e32 v183, v183
	v_exp_f32_e32 v192, v192
	v_exp_f32_e32 v193, v193
	v_exp_f32_e32 v194, v194
	v_exp_f32_e32 v195, v195
	v_add_f32_e32 v180, 1.0, v180
	v_add_f32_e32 v181, 1.0, v181
	v_add_f32_e32 v182, 1.0, v182
	v_add_f32_e32 v183, 1.0, v183
	v_add_f32_e32 v192, 1.0, v192
	v_add_f32_e32 v193, 1.0, v193
	v_add_f32_e32 v194, 1.0, v194
	v_add_f32_e32 v195, 1.0, v195
	v_rcp_f32_e32 v180, v180
	v_rcp_f32_e32 v181, v181
	v_rcp_f32_e32 v182, v182
	v_rcp_f32_e32 v183, v183
	v_rcp_f32_e32 v192, v192
	v_rcp_f32_e32 v193, v193
	v_rcp_f32_e32 v194, v194
	v_rcp_f32_e32 v195, v195
	v_mul_f32_e32 v180, 0xbf60028b, v180
	v_mul_f32_e32 v181, 0xbf60028b, v181
	v_mul_f32_e32 v182, 0xbf60028b, v182
	v_mul_f32_e32 v183, 0xbf60028b, v183
	v_mul_f32_e32 v192, 0xbf60028b, v192
	v_mul_f32_e32 v193, 0xbf60028b, v193
	v_mul_f32_e32 v194, 0xbf60028b, v194
	v_mul_f32_e32 v195, 0xbf60028b, v195
	v_exp_f32_e32 v180, v180
	v_exp_f32_e32 v181, v181
	v_exp_f32_e32 v182, v182
	v_exp_f32_e32 v183, v183
	v_exp_f32_e32 v192, v192
	v_exp_f32_e32 v193, v193
	v_exp_f32_e32 v194, v194
	v_exp_f32_e32 v195, v195
	s_nop 0
	global_store_dwordx4 v[172:173], v[180:183], off nt
	global_store_dwordx4 v[172:173], v[192:195], off offset:16 nt
; __device__ __forceinline__ float sigm(float x) { return __builtin_amdgcn_rcpf(1.0f + __expf(-x)); }
; __device__ __forceinline__ u32x4 pack8(f32x4 v0, f32x4 v1) { u32x4 w; w.x = cvt_pk_bf16(v0[0], v0[1]); w.y = cvt_pk_bf16(v0[2], v0[3]); w.z = cvt_pk_bf16(v1[0], v1[1]); w.w = cvt_pk_bf16(v1[2], v1[3]); return w; }
;     __device__ __forceinline__ void operator()(f32x4 (&acc)[2][2][4][2], const Unit& u, int wr, int wc, int fr_, int fq_) const {
;     ...
;                     for (int m = 0; m < 4; ++m) { const size_t off = (size_t)(row0 + ai * HALF + m * 16) * 1024 + col0 + bj * HALF;
;                         f32x4 v0 = acc[ai][bj][m][0] + b0, v1 = acc[ai][bj][m][1] + b1;
;                         if (kind == 0) {
; #pragma unroll
;                             for (int i = 0; i < 4; ++i) { float z = -v0[i]; float sp = fmaxf(z, 0.f) + __logf(1.0f + __expf(-fabsf(z))); v0[i] = __expf(-__expf(-sp - 0.5f));
;                                                           z = -v1[i]; sp = fmaxf(z, 0.f) + __logf(1.0f + __expf(-fabsf(z))); v1[i] = __expf(-__expf(-sp - 0.5f)); }
;                             *(f32x4*)(DEC + off) = v0; *(f32x4*)(DEC + off + 4) = v1;
;                         } else {
; #pragma unroll
;                             for (int i = 0; i < 4; ++i) { v0[i] = sigm(v0[i]); v1[i] = sigm(v1[i]); }
;                             *(u32x4*)(AS + off) = pack8(v0, v1);
;                         }
;                         asm volatile("" ::: "memory"); __builtin_amdgcn_sched_barrier(0); }
.LBB0_949:
	v_lshlrev_b64 v[172:173], 10, v[154:155]
	s_mov_b64 s[0:1], 0x28000
	v_lshl_add_u64 v[172:173], v[172:173], 0, s[0:1]
	v_lshl_add_u64 v[174:175], v[172:173], 0, v[156:157]
	v_pk_add_f32 v[178:179], v[30:31], v[134:135]
	v_pk_add_f32 v[182:183], v[28:29], v[132:133]
	v_pk_add_f32 v[176:177], v[26:27], v[130:131]
	v_pk_add_f32 v[180:181], v[24:25], v[128:129]
	s_and_b64 vcc, exec, s[6:7]
	s_mov_b64 s[0:1], -1
	s_cbranch_vccnz .LBB0_951
	v_mul_f32_e32 v192, 0xbfb8aa3b, v180
	v_exp_f32_e32 v192, v192
	v_mul_f32_e32 v193, 0xbfb8aa3b, v183
	v_mul_f32_e32 v194, 0xbfb8aa3b, v181
	v_exp_f32_e32 v193, v193
	v_exp_f32_e32 v194, v194
	v_add_f32_e32 v192, 1.0, v192
	v_rcp_f32_e32 v195, v192
	v_add_f32_e32 v192, 1.0, v193
	v_add_f32_e32 v193, 1.0, v194
	v_mul_f32_e32 v194, 0xbfb8aa3b, v178
	v_mul_f32_e32 v196, 0xbfb8aa3b, v176
	v_exp_f32_e32 v194, v194
	v_exp_f32_e32 v196, v196
	v_mul_f32_e32 v191, 0xbfb8aa3b, v182
	v_rcp_f32_e32 v197, v193
	v_add_f32_e32 v193, 1.0, v194
	v_add_f32_e32 v194, 1.0, v196
	v_mul_f32_e32 v196, 0xbfb8aa3b, v179
	v_mul_f32_e32 v198, 0xbfb8aa3b, v177
	v_exp_f32_e32 v191, v191
	v_exp_f32_e32 v196, v196
	v_exp_f32_e32 v198, v198
	v_rcp_f32_e32 v199, v194
	v_add_f32_e32 v191, 1.0, v191
	v_add_f32_e32 v194, 1.0, v196
	v_add_f32_e32 v196, 1.0, v198
	v_rcp_f32_e32 v191, v191
	v_rcp_f32_e32 v192, v192
	v_rcp_f32_e32 v193, v193
	v_rcp_f32_e32 v194, v194
	v_rcp_f32_e32 v196, v196
	v_cvt_pk_bf16_f32 v192, v191, v192
	s_mov_b64 s[0:1], 0
	v_cvt_pk_bf16_f32 v193, v193, v194
	v_cvt_pk_bf16_f32 v194, v195, v197
	v_cvt_pk_bf16_f32 v195, v199, v196
	v_lshl_add_u64 v[196:197], v[174:175], 1, s[38:39]
	global_store_dwordx4 v[196:197], v[192:195], off nt
.LBB0_951:
	s_andn2_b64 vcc, exec, s[0:1]
	s_cbranch_vccnz .LBB0_953
	v_lshl_add_u64 v[174:175], v[174:175], 2, s[36:37]
	v_mul_f32_e32 v192, 0xbfb8aa3b, v182
	v_mul_f32_e32 v193, 0xbfb8aa3b, v183
	v_mul_f32_e32 v194, 0xbfb8aa3b, v178
	v_mul_f32_e32 v195, 0xbfb8aa3b, v179
	v_mul_f32_e32 v180, 0xbfb8aa3b, v180
	v_mul_f32_e32 v181, 0xbfb8aa3b, v181
	v_mul_f32_e32 v182, 0xbfb8aa3b, v176
	v_mul_f32_e32 v183, 0xbfb8aa3b, v177
	v_exp_f32_e32 v192, v192
	v_exp_f32_e32 v193, v193
	v_exp_f32_e32 v194, v194
	v_exp_f32_e32 v195, v195
	v_exp_f32_e32 v180, v180
	v_exp_f32_e32 v181, v181
	v_exp_f32_e32 v182, v182
	v_exp_f32_e32 v183, v183
	v_add_f32_e32 v192, 1.0, v192
	v_add_f32_e32 v193, 1.0, v193
	v_add_f32_e32 v194, 1.0, v194
	v_add_f32_e32 v195, 1.0, v195
	v_add_f32_e32 v180, 1.0, v180
	v_add_f32_e32 v181, 1.0, v181
	v_add_f32_e32 v182, 1.0, v182
	v_add_f32_e32 v183, 1.0, v183
	v_rcp_f32_e32 v192, v192
	v_rcp_f32_e32 v193, v193
	v_rcp_f32_e32 v194, v194
	v_rcp_f32_e32 v195, v195
	v_rcp_f32_e32 v180, v180
	v_rcp_f32_e32 v181, v181
	v_rcp_f32_e32 v182, v182
	v_rcp_f32_e32 v183, v183
	v_mul_f32_e32 v192, 0xbf60028b, v192
	v_mul_f32_e32 v193, 0xbf60028b, v193
	v_mul_f32_e32 v194, 0xbf60028b, v194
	v_mul_f32_e32 v195, 0xbf60028b, v195
	v_mul_f32_e32 v180, 0xbf60028b, v180
	v_mul_f32_e32 v181, 0xbf60028b, v181
	v_mul_f32_e32 v182, 0xbf60028b, v182
	v_mul_f32_e32 v183, 0xbf60028b, v183
	v_exp_f32_e32 v192, v192
	v_exp_f32_e32 v193, v193
	v_exp_f32_e32 v194, v194
	v_exp_f32_e32 v195, v195
	v_exp_f32_e32 v180, v180
	v_exp_f32_e32 v181, v181
	v_exp_f32_e32 v182, v182
	v_exp_f32_e32 v183, v183
	s_nop 0
	global_store_dwordx4 v[174:175], v[192:195], off nt
	global_store_dwordx4 v[174:175], v[180:183], off offset:16 nt
.LBB0_953:
	v_lshlrev_b64 v[174:175], 10, v[154:155]
	s_mov_b64 s[0:1], 0x2c000
	v_lshl_add_u64 v[174:175], v[174:175], 0, s[0:1]
	v_lshl_add_u64 v[176:177], v[174:175], 0, v[156:157]
	v_pk_add_f32 v[134:135], v[14:15], v[134:135]
	v_pk_add_f32 v[132:133], v[12:13], v[132:133]
	v_pk_add_f32 v[130:131], v[10:11], v[130:131]
	v_pk_add_f32 v[128:129], v[8:9], v[128:129]
	s_and_b64 vcc, exec, s[6:7]
	s_mov_b64 s[0:1], -1
	s_cbranch_vccnz .LBB0_955
	v_mul_f32_e32 v179, 0xbfb8aa3b, v128
	v_exp_f32_e32 v179, v179
	v_mul_f32_e32 v180, 0xbfb8aa3b, v133
	v_mul_f32_e32 v181, 0xbfb8aa3b, v129
	v_exp_f32_e32 v180, v180
	v_exp_f32_e32 v181, v181
	v_add_f32_e32 v179, 1.0, v179
	v_mul_f32_e32 v178, 0xbfb8aa3b, v132
	v_rcp_f32_e32 v182, v179
	v_add_f32_e32 v179, 1.0, v180
	v_add_f32_e32 v180, 1.0, v181
	v_mul_f32_e32 v181, 0xbfb8aa3b, v134
	v_mul_f32_e32 v183, 0xbfb8aa3b, v130
	v_mul_f32_e32 v191, 0xbfb8aa3b, v135
	v_mul_f32_e32 v192, 0xbfb8aa3b, v131
	v_exp_f32_e32 v178, v178
	v_exp_f32_e32 v181, v181
	v_exp_f32_e32 v183, v183
	v_exp_f32_e32 v191, v191
	v_exp_f32_e32 v192, v192
	v_add_f32_e32 v178, 1.0, v178
	v_add_f32_e32 v181, 1.0, v181
	v_add_f32_e32 v183, 1.0, v183
	v_add_f32_e32 v191, 1.0, v191
	v_add_f32_e32 v192, 1.0, v192
	v_rcp_f32_e32 v178, v178
	v_rcp_f32_e32 v179, v179
	v_rcp_f32_e32 v180, v180
	v_rcp_f32_e32 v181, v181
	v_rcp_f32_e32 v183, v183
	v_rcp_f32_e32 v191, v191
	v_rcp_f32_e32 v192, v192
	v_cvt_pk_bf16_f32 v178, v178, v179
	v_cvt_pk_bf16_f32 v180, v182, v180
	v_cvt_pk_bf16_f32 v179, v181, v191
	v_cvt_pk_bf16_f32 v181, v183, v192
	v_lshl_add_u64 v[182:183], v[176:177], 1, s[38:39]
	s_mov_b64 s[0:1], 0
	global_store_dwordx4 v[182:183], v[178:181], off nt
; __device__ __forceinline__ float sigm(float x) { return __builtin_amdgcn_rcpf(1.0f + __expf(-x)); }
; __device__ __forceinline__ u32x4 pack8(f32x4 v0, f32x4 v1) { u32x4 w; w.x = cvt_pk_bf16(v0[0], v0[1]); w.y = cvt_pk_bf16(v0[2], v0[3]); w.z = cvt_pk_bf16(v1[0], v1[1]); w.w = cvt_pk_bf16(v1[2], v1[3]); return w; }
;     __device__ __forceinline__ void operator()(f32x4 (&acc)[2][2][4][2], const Unit& u, int wr, int wc, int fr_, int fq_) const {
;     ...
;                 const f32x4 b0 = *(const f32x4*)(bias + col0 + bj * HALF), b1 = *(const f32x4*)(bias + col0 + bj * HALF + 4);
; #pragma unroll
;                 for (int ai = 0; ai < 2; ++ai)
; #pragma unroll
;                     for (int m = 0; m < 4; ++m) { const size_t off = (size_t)(row0 + ai * HALF + m * 16) * 1024 + col0 + bj * HALF;
;                         f32x4 v0 = acc[ai][bj][m][0] + b0, v1 = acc[ai][bj][m][1] + b1;
;                         if (kind == 0) {
; #pragma unroll
;                             for (int i = 0; i < 4; ++i) { float z = -v0[i]; float sp = fmaxf(z, 0.f) + __logf(1.0f + __expf(-fabsf(z))); v0[i] = __expf(-__expf(-sp - 0.5f));
;                                                           z = -v1[i]; sp = fmaxf(z, 0.f) + __logf(1.0f + __expf(-fabsf(z))); v1[i] = __expf(-__expf(-sp - 0.5f)); }
;                             *(f32x4*)(DEC + off) = v0; *(f32x4*)(DEC + off + 4) = v1;
;                         } else {
; #pragma unroll
;                             for (int i = 0; i < 4; ++i) { v0[i] = sigm(v0[i]); v1[i] = sigm(v1[i]); }
;                             *(u32x4*)(AS + off) = pack8(v0, v1);
;                         }
;                         asm volatile("" ::: "memory"); __builtin_amdgcn_sched_barrier(0); }
.LBB0_955:
	s_andn2_b64 vcc, exec, s[0:1]
	s_cbranch_vccnz .LBB0_957
	v_lshl_add_u64 v[176:177], v[176:177], 2, s[36:37]
	v_mul_f32_e32 v132, 0xbfb8aa3b, v132
	v_mul_f32_e32 v133, 0xbfb8aa3b, v133
	v_mul_f32_e32 v134, 0xbfb8aa3b, v134
	v_mul_f32_e32 v135, 0xbfb8aa3b, v135
	v_mul_f32_e32 v128, 0xbfb8aa3b, v128
	v_mul_f32_e32 v129, 0xbfb8aa3b, v129
	v_mul_f32_e32 v130, 0xbfb8aa3b, v130
	v_mul_f32_e32 v131, 0xbfb8aa3b, v131
	v_exp_f32_e32 v132, v132
	v_exp_f32_e32 v133, v133
	v_exp_f32_e32 v134, v134
	v_exp_f32_e32 v135, v135
	v_exp_f32_e32 v128, v128
	v_exp_f32_e32 v129, v129
	v_exp_f32_e32 v130, v130
	v_exp_f32_e32 v131, v131
	v_add_f32_e32 v132, 1.0, v132
	v_add_f32_e32 v133, 1.0, v133
	v_add_f32_e32 v134, 1.0, v134
	v_add_f32_e32 v135, 1.0, v135
	v_add_f32_e32 v128, 1.0, v128
	v_add_f32_e32 v129, 1.0, v129
	v_add_f32_e32 v130, 1.0, v130
	v_add_f32_e32 v131, 1.0, v131
	v_rcp_f32_e32 v132, v132
	v_rcp_f32_e32 v133, v133
	v_rcp_f32_e32 v134, v134
	v_rcp_f32_e32 v135, v135
	v_rcp_f32_e32 v128, v128
	v_rcp_f32_e32 v129, v129
	v_rcp_f32_e32 v130, v130
	v_rcp_f32_e32 v131, v131
	v_mul_f32_e32 v132, 0xbf60028b, v132
	v_mul_f32_e32 v133, 0xbf60028b, v133
	v_mul_f32_e32 v134, 0xbf60028b, v134
	v_mul_f32_e32 v135, 0xbf60028b, v135
	v_mul_f32_e32 v128, 0xbf60028b, v128
	v_mul_f32_e32 v129, 0xbf60028b, v129
	v_mul_f32_e32 v130, 0xbf60028b, v130
	v_mul_f32_e32 v131, 0xbf60028b, v131
	v_exp_f32_e32 v132, v132
	v_exp_f32_e32 v133, v133
	v_exp_f32_e32 v134, v134
	v_exp_f32_e32 v135, v135
	v_exp_f32_e32 v128, v128
	v_exp_f32_e32 v129, v129
	v_exp_f32_e32 v130, v130
	v_exp_f32_e32 v131, v131
	s_nop 0
	global_store_dwordx4 v[176:177], v[132:135], off nt
	global_store_dwordx4 v[176:177], v[128:131], off offset:16 nt
.LBB0_957:
	global_load_dwordx4 v[132:135], v[160:161], off offset:512
	global_load_dwordx4 v[128:131], v[160:161], off offset:528
	v_lshl_add_u64 v[160:161], v[156:157], 0, s[64:65]
	s_and_b64 vcc, exec, s[6:7]
	v_lshl_add_u64 v[158:159], v[160:161], 0, v[158:159]
	s_mov_b64 s[0:1], -1
	s_waitcnt vmcnt(0)
	v_pk_add_f32 v[178:179], v[118:119], v[134:135]
	v_pk_add_f32 v[182:183], v[116:117], v[132:133]
	v_pk_add_f32 v[176:177], v[114:115], v[130:131]
	v_pk_add_f32 v[180:181], v[112:113], v[128:129]
	s_cbranch_vccnz .LBB0_959
	v_mul_f32_e32 v192, 0xbfb8aa3b, v180
	v_exp_f32_e32 v192, v192
	v_mul_f32_e32 v193, 0xbfb8aa3b, v183
	v_mul_f32_e32 v194, 0xbfb8aa3b, v181
	v_exp_f32_e32 v193, v193
	v_exp_f32_e32 v194, v194
	v_add_f32_e32 v192, 1.0, v192
	v_rcp_f32_e32 v195, v192
	v_add_f32_e32 v192, 1.0, v193
	v_add_f32_e32 v193, 1.0, v194
	v_mul_f32_e32 v194, 0xbfb8aa3b, v178
	v_mul_f32_e32 v196, 0xbfb8aa3b, v176
	v_exp_f32_e32 v194, v194
	v_exp_f32_e32 v196, v196
	v_mul_f32_e32 v191, 0xbfb8aa3b, v182
	v_rcp_f32_e32 v197, v193
	v_add_f32_e32 v193, 1.0, v194
	v_add_f32_e32 v194, 1.0, v196
	v_mul_f32_e32 v196, 0xbfb8aa3b, v179
	v_mul_f32_e32 v198, 0xbfb8aa3b, v177
	v_exp_f32_e32 v191, v191
	v_exp_f32_e32 v196, v196
	v_exp_f32_e32 v198, v198
	v_rcp_f32_e32 v199, v194
	v_add_f32_e32 v191, 1.0, v191
	v_add_f32_e32 v194, 1.0, v196
	v_add_f32_e32 v196, 1.0, v198
	v_rcp_f32_e32 v191, v191
	v_rcp_f32_e32 v192, v192
	v_rcp_f32_e32 v193, v193
	v_rcp_f32_e32 v194, v194
	v_rcp_f32_e32 v196, v196
	v_cvt_pk_bf16_f32 v192, v191, v192
	s_mov_b64 s[0:1], 0
	v_cvt_pk_bf16_f32 v193, v193, v194
	v_cvt_pk_bf16_f32 v194, v195, v197
	v_cvt_pk_bf16_f32 v195, v199, v196
	v_lshl_add_u64 v[196:197], v[158:159], 1, s[38:39]
	global_store_dwordx4 v[196:197], v[192:195], off nt
.LBB0_959:
	s_andn2_b64 vcc, exec, s[0:1]
	s_cbranch_vccnz .LBB0_961
	v_lshl_add_u64 v[158:159], v[158:159], 2, s[36:37]
	v_mul_f32_e32 v192, 0xbfb8aa3b, v182
	v_mul_f32_e32 v193, 0xbfb8aa3b, v183
	v_mul_f32_e32 v194, 0xbfb8aa3b, v178
	v_mul_f32_e32 v195, 0xbfb8aa3b, v179
	v_mul_f32_e32 v180, 0xbfb8aa3b, v180
	v_mul_f32_e32 v181, 0xbfb8aa3b, v181
	v_mul_f32_e32 v182, 0xbfb8aa3b, v176
	v_mul_f32_e32 v183, 0xbfb8aa3b, v177
	v_exp_f32_e32 v192, v192
	v_exp_f32_e32 v193, v193
	v_exp_f32_e32 v194, v194
	v_exp_f32_e32 v195, v195
	v_exp_f32_e32 v180, v180
	v_exp_f32_e32 v181, v181
	v_exp_f32_e32 v182, v182
	v_exp_f32_e32 v183, v183
	v_add_f32_e32 v192, 1.0, v192
	v_add_f32_e32 v193, 1.0, v193
	v_add_f32_e32 v194, 1.0, v194
	v_add_f32_e32 v195, 1.0, v195
	v_add_f32_e32 v180, 1.0, v180
	v_add_f32_e32 v181, 1.0, v181
	v_add_f32_e32 v182, 1.0, v182
	v_add_f32_e32 v183, 1.0, v183
	v_rcp_f32_e32 v192, v192
	v_rcp_f32_e32 v193, v193
	v_rcp_f32_e32 v194, v194
	v_rcp_f32_e32 v195, v195
	v_rcp_f32_e32 v180, v180
	v_rcp_f32_e32 v181, v181
	v_rcp_f32_e32 v182, v182
	v_rcp_f32_e32 v183, v183
	v_mul_f32_e32 v192, 0xbf60028b, v192
	v_mul_f32_e32 v193, 0xbf60028b, v193
	v_mul_f32_e32 v194, 0xbf60028b, v194
	v_mul_f32_e32 v195, 0xbf60028b, v195
	v_mul_f32_e32 v180, 0xbf60028b, v180
	v_mul_f32_e32 v181, 0xbf60028b, v181
	v_mul_f32_e32 v182, 0xbf60028b, v182
	v_mul_f32_e32 v183, 0xbf60028b, v183
	v_exp_f32_e32 v192, v192
	v_exp_f32_e32 v193, v193
	v_exp_f32_e32 v194, v194
	v_exp_f32_e32 v195, v195
	v_exp_f32_e32 v180, v180
	v_exp_f32_e32 v181, v181
	v_exp_f32_e32 v182, v182
	v_exp_f32_e32 v183, v183
	s_nop 0
	global_store_dwordx4 v[158:159], v[192:195], off nt
	global_store_dwordx4 v[158:159], v[180:183], off offset:16 nt
; __device__ __forceinline__ float sigm(float x) { return __builtin_amdgcn_rcpf(1.0f + __expf(-x)); }
; __device__ __forceinline__ u32x4 pack8(f32x4 v0, f32x4 v1) { u32x4 w; w.x = cvt_pk_bf16(v0[0], v0[1]); w.y = cvt_pk_bf16(v0[2], v0[3]); w.z = cvt_pk_bf16(v1[0], v1[1]); w.w = cvt_pk_bf16(v1[2], v1[3]); return w; }
;     __device__ __forceinline__ void operator()(f32x4 (&acc)[2][2][4][2], const Unit& u, int wr, int wc, int fr_, int fq_) const {
;     ...
;                     for (int m = 0; m < 4; ++m) { const size_t off = (size_t)(row0 + ai * HALF + m * 16) * 1024 + col0 + bj * HALF;
;                         f32x4 v0 = acc[ai][bj][m][0] + b0, v1 = acc[ai][bj][m][1] + b1;
;                         if (kind == 0) {
; #pragma unroll
;                             for (int i = 0; i < 4; ++i) { float z = -v0[i]; float sp = fmaxf(z, 0.f) + __logf(1.0f + __expf(-fabsf(z))); v0[i] = __expf(-__expf(-sp - 0.5f));
;                                                           z = -v1[i]; sp = fmaxf(z, 0.f) + __logf(1.0f + __expf(-fabsf(z))); v1[i] = __expf(-__expf(-sp - 0.5f)); }
;                             *(f32x4*)(DEC + off) = v0; *(f32x4*)(DEC + off + 4) = v1;
;                         } else {
; #pragma unroll
;                             for (int i = 0; i < 4; ++i) { v0[i] = sigm(v0[i]); v1[i] = sigm(v1[i]); }
;                             *(u32x4*)(AS + off) = pack8(v0, v1);
;                         }
;                         asm volatile("" ::: "memory"); __builtin_amdgcn_sched_barrier(0); }
.LBB0_961:
	v_lshl_add_u64 v[158:159], v[160:161], 0, v[162:163]
	v_pk_add_f32 v[176:177], v[102:103], v[134:135]
	v_pk_add_f32 v[180:181], v[100:101], v[132:133]
	v_pk_add_f32 v[162:163], v[98:99], v[130:131]
	v_pk_add_f32 v[178:179], v[96:97], v[128:129]
	s_and_b64 vcc, exec, s[6:7]
	s_mov_b64 s[0:1], -1
	s_cbranch_vccnz .LBB0_963
	v_mul_f32_e32 v192, 0xbfb8aa3b, v179
	v_exp_f32_e32 v192, v192
	v_mul_f32_e32 v193, 0xbfb8aa3b, v176
	v_exp_f32_e32 v193, v193
	v_mul_f32_e32 v194, 0xbfb8aa3b, v162
	v_exp_f32_e32 v194, v194
	v_add_f32_e32 v192, 1.0, v192
	v_rcp_f32_e32 v195, v192
	v_add_f32_e32 v192, 1.0, v193
	v_rcp_f32_e32 v193, v192
	v_add_f32_e32 v192, 1.0, v194
	v_mul_f32_e32 v194, 0xbfb8aa3b, v177
	v_mul_f32_e32 v182, 0xbfb8aa3b, v180
	v_mul_f32_e32 v183, 0xbfb8aa3b, v178
	v_mul_f32_e32 v191, 0xbfb8aa3b, v181
	v_exp_f32_e32 v194, v194
	v_mul_f32_e32 v196, 0xbfb8aa3b, v163
	v_exp_f32_e32 v182, v182
	v_exp_f32_e32 v183, v183
	v_exp_f32_e32 v191, v191
	v_exp_f32_e32 v196, v196
	v_rcp_f32_e32 v197, v192
	v_add_f32_e32 v192, 1.0, v194
	v_add_f32_e32 v182, 1.0, v182
	v_add_f32_e32 v183, 1.0, v183
	v_add_f32_e32 v191, 1.0, v191
	v_rcp_f32_e32 v194, v192
	v_add_f32_e32 v192, 1.0, v196
	v_rcp_f32_e32 v182, v182
	v_rcp_f32_e32 v183, v183
	v_rcp_f32_e32 v191, v191
	v_rcp_f32_e32 v196, v192
	v_cvt_pk_bf16_f32 v193, v193, v194
	v_cvt_pk_bf16_f32 v194, v183, v195
	v_cvt_pk_bf16_f32 v192, v182, v191
	v_cvt_pk_bf16_f32 v195, v197, v196
	v_lshl_add_u64 v[182:183], v[158:159], 1, s[38:39]
	s_mov_b64 s[0:1], 0
	global_store_dwordx4 v[182:183], v[192:195], off nt
.LBB0_963:
	s_andn2_b64 vcc, exec, s[0:1]
	s_cbranch_vccnz .LBB0_965
	v_lshl_add_u64 v[158:159], v[158:159], 2, s[36:37]
	v_mul_f32_e32 v180, 0xbfb8aa3b, v180
	v_mul_f32_e32 v181, 0xbfb8aa3b, v181
	v_mul_f32_e32 v182, 0xbfb8aa3b, v176
	v_mul_f32_e32 v183, 0xbfb8aa3b, v177
	v_mul_f32_e32 v192, 0xbfb8aa3b, v178
	v_mul_f32_e32 v193, 0xbfb8aa3b, v179
	v_mul_f32_e32 v194, 0xbfb8aa3b, v162
	v_mul_f32_e32 v195, 0xbfb8aa3b, v163
	v_exp_f32_e32 v180, v180
	v_exp_f32_e32 v181, v181
	v_exp_f32_e32 v182, v182
	v_exp_f32_e32 v183, v183
	v_exp_f32_e32 v192, v192
	v_exp_f32_e32 v193, v193
	v_exp_f32_e32 v194, v194
	v_exp_f32_e32 v195, v195
	v_add_f32_e32 v180, 1.0, v180
	v_add_f32_e32 v181, 1.0, v181
	v_add_f32_e32 v182, 1.0, v182
	v_add_f32_e32 v183, 1.0, v183
	v_add_f32_e32 v192, 1.0, v192
	v_add_f32_e32 v193, 1.0, v193
	v_add_f32_e32 v194, 1.0, v194
	v_add_f32_e32 v195, 1.0, v195
	v_rcp_f32_e32 v180, v180
	v_rcp_f32_e32 v181, v181
	v_rcp_f32_e32 v182, v182
	v_rcp_f32_e32 v183, v183
	v_rcp_f32_e32 v192, v192
	v_rcp_f32_e32 v193, v193
	v_rcp_f32_e32 v194, v194
	v_rcp_f32_e32 v195, v195
	v_mul_f32_e32 v180, 0xbf60028b, v180
	v_mul_f32_e32 v181, 0xbf60028b, v181
	v_mul_f32_e32 v182, 0xbf60028b, v182
	v_mul_f32_e32 v183, 0xbf60028b, v183
	v_mul_f32_e32 v192, 0xbf60028b, v192
	v_mul_f32_e32 v193, 0xbf60028b, v193
	v_mul_f32_e32 v194, 0xbf60028b, v194
	v_mul_f32_e32 v195, 0xbf60028b, v195
	v_exp_f32_e32 v180, v180
	v_exp_f32_e32 v181, v181
	v_exp_f32_e32 v182, v182
	v_exp_f32_e32 v183, v183
	v_exp_f32_e32 v192, v192
	v_exp_f32_e32 v193, v193
	v_exp_f32_e32 v194, v194
	v_exp_f32_e32 v195, v195
	s_nop 0
	global_store_dwordx4 v[158:159], v[180:183], off nt
	global_store_dwordx4 v[158:159], v[192:195], off offset:16 nt
.LBB0_965:
	v_lshl_add_u64 v[158:159], v[160:161], 0, v[164:165]
	v_pk_add_f32 v[164:165], v[86:87], v[134:135]
	v_pk_add_f32 v[178:179], v[84:85], v[132:133]
	v_pk_add_f32 v[162:163], v[82:83], v[130:131]
	v_pk_add_f32 v[176:177], v[80:81], v[128:129]
	s_and_b64 vcc, exec, s[6:7]
	s_mov_b64 s[0:1], -1
	s_cbranch_vccnz .LBB0_967
	v_mul_f32_e32 v181, 0xbfb8aa3b, v176
	v_exp_f32_e32 v181, v181
	v_mul_f32_e32 v182, 0xbfb8aa3b, v179
	v_mul_f32_e32 v183, 0xbfb8aa3b, v177
	v_exp_f32_e32 v182, v182
	v_exp_f32_e32 v183, v183
	v_add_f32_e32 v181, 1.0, v181
	v_mul_f32_e32 v180, 0xbfb8aa3b, v178
	v_rcp_f32_e32 v191, v181
	v_add_f32_e32 v181, 1.0, v182
	v_add_f32_e32 v182, 1.0, v183
	v_mul_f32_e32 v183, 0xbfb8aa3b, v164
	v_mul_f32_e32 v192, 0xbfb8aa3b, v162
	v_mul_f32_e32 v193, 0xbfb8aa3b, v165
	v_mul_f32_e32 v194, 0xbfb8aa3b, v163
	v_exp_f32_e32 v180, v180
	v_exp_f32_e32 v183, v183
	v_exp_f32_e32 v192, v192
	v_exp_f32_e32 v193, v193
	v_exp_f32_e32 v194, v194
	v_add_f32_e32 v180, 1.0, v180
	v_add_f32_e32 v183, 1.0, v183
	v_add_f32_e32 v192, 1.0, v192
	v_add_f32_e32 v193, 1.0, v193
	v_add_f32_e32 v194, 1.0, v194
	v_rcp_f32_e32 v180, v180
	v_rcp_f32_e32 v181, v181
	v_rcp_f32_e32 v182, v182
	v_rcp_f32_e32 v183, v183
	v_rcp_f32_e32 v192, v192
	v_rcp_f32_e32 v193, v193
	v_rcp_f32_e32 v194, v194
	v_cvt_pk_bf16_f32 v180, v180, v181
	v_cvt_pk_bf16_f32 v182, v191, v182
	v_cvt_pk_bf16_f32 v181, v183, v193
	v_cvt_pk_bf16_f32 v183, v192, v194
	v_lshl_add_u64 v[192:193], v[158:159], 1, s[38:39]
	s_mov_b64 s[0:1], 0
	global_store_dwordx4 v[192:193], v[180:183], off nt
; __device__ __forceinline__ float sigm(float x) { return __builtin_amdgcn_rcpf(1.0f + __expf(-x)); }
; __device__ __forceinline__ u32x4 pack8(f32x4 v0, f32x4 v1) { u32x4 w; w.x = cvt_pk_bf16(v0[0], v0[1]); w.y = cvt_pk_bf16(v0[2], v0[3]); w.z = cvt_pk_bf16(v1[0], v1[1]); w.w = cvt_pk_bf16(v1[2], v1[3]); return w; }
;     __device__ __forceinline__ void operator()(f32x4 (&acc)[2][2][4][2], const Unit& u, int wr, int wc, int fr_, int fq_) const {
;     ...
;                     for (int m = 0; m < 4; ++m) { const size_t off = (size_t)(row0 + ai * HALF + m * 16) * 1024 + col0 + bj * HALF;
;                         f32x4 v0 = acc[ai][bj][m][0] + b0, v1 = acc[ai][bj][m][1] + b1;
;                         if (kind == 0) {
; #pragma unroll
;                             for (int i = 0; i < 4; ++i) { float z = -v0[i]; float sp = fmaxf(z, 0.f) + __logf(1.0f + __expf(-fabsf(z))); v0[i] = __expf(-__expf(-sp - 0.5f));
;                                                           z = -v1[i]; sp = fmaxf(z, 0.f) + __logf(1.0f + __expf(-fabsf(z))); v1[i] = __expf(-__expf(-sp - 0.5f)); }
;                             *(f32x4*)(DEC + off) = v0; *(f32x4*)(DEC + off + 4) = v1;
;                         } else {
; #pragma unroll
;                             for (int i = 0; i < 4; ++i) { v0[i] = sigm(v0[i]); v1[i] = sigm(v1[i]); }
;                             *(u32x4*)(AS + off) = pack8(v0, v1);
;                         }
;                         asm volatile("" ::: "memory"); __builtin_amdgcn_sched_barrier(0); }
.LBB0_967:
	s_andn2_b64 vcc, exec, s[0:1]
	s_cbranch_vccnz .LBB0_969
	v_lshl_add_u64 v[158:159], v[158:159], 2, s[36:37]
	v_mul_f32_e32 v178, 0xbfb8aa3b, v178
	v_mul_f32_e32 v179, 0xbfb8aa3b, v179
	v_mul_f32_e32 v180, 0xbfb8aa3b, v164
	v_mul_f32_e32 v181, 0xbfb8aa3b, v165
	v_mul_f32_e32 v192, 0xbfb8aa3b, v176
	v_mul_f32_e32 v193, 0xbfb8aa3b, v177
	v_mul_f32_e32 v194, 0xbfb8aa3b, v162
	v_mul_f32_e32 v195, 0xbfb8aa3b, v163
	v_exp_f32_e32 v178, v178
	v_exp_f32_e32 v179, v179
	v_exp_f32_e32 v180, v180
	v_exp_f32_e32 v181, v181
	v_exp_f32_e32 v192, v192
	v_exp_f32_e32 v193, v193
	v_exp_f32_e32 v194, v194
	v_exp_f32_e32 v195, v195
	v_add_f32_e32 v178, 1.0, v178
	v_add_f32_e32 v179, 1.0, v179
	v_add_f32_e32 v180, 1.0, v180
	v_add_f32_e32 v181, 1.0, v181
	v_add_f32_e32 v192, 1.0, v192
	v_add_f32_e32 v193, 1.0, v193
	v_add_f32_e32 v194, 1.0, v194
	v_add_f32_e32 v195, 1.0, v195
	v_rcp_f32_e32 v178, v178
	v_rcp_f32_e32 v179, v179
	v_rcp_f32_e32 v180, v180
	v_rcp_f32_e32 v181, v181
	v_rcp_f32_e32 v192, v192
	v_rcp_f32_e32 v193, v193
	v_rcp_f32_e32 v194, v194
	v_rcp_f32_e32 v195, v195
	v_mul_f32_e32 v178, 0xbf60028b, v178
	v_mul_f32_e32 v179, 0xbf60028b, v179
	v_mul_f32_e32 v180, 0xbf60028b, v180
	v_mul_f32_e32 v181, 0xbf60028b, v181
	v_mul_f32_e32 v192, 0xbf60028b, v192
	v_mul_f32_e32 v193, 0xbf60028b, v193
	v_mul_f32_e32 v194, 0xbf60028b, v194
	v_mul_f32_e32 v195, 0xbf60028b, v195
	v_exp_f32_e32 v178, v178
	v_exp_f32_e32 v179, v179
	v_exp_f32_e32 v180, v180
	v_exp_f32_e32 v181, v181
	v_exp_f32_e32 v192, v192
	v_exp_f32_e32 v193, v193
	v_exp_f32_e32 v194, v194
	v_exp_f32_e32 v195, v195
	s_nop 0
	global_store_dwordx4 v[158:159], v[178:181], off nt
	global_store_dwordx4 v[158:159], v[192:195], off offset:16 nt
.LBB0_969:
	v_lshl_add_u64 v[158:159], v[160:161], 0, v[166:167]
	v_pk_add_f32 v[164:165], v[70:71], v[134:135]
	v_pk_add_f32 v[176:177], v[68:69], v[132:133]
	v_pk_add_f32 v[162:163], v[66:67], v[130:131]
	v_pk_add_f32 v[166:167], v[64:65], v[128:129]
	s_and_b64 vcc, exec, s[6:7]
	s_mov_b64 s[0:1], -1
	s_cbranch_vccnz .LBB0_971
	v_mul_f32_e32 v179, 0xbfb8aa3b, v166
	v_exp_f32_e32 v179, v179
	v_mul_f32_e32 v180, 0xbfb8aa3b, v177
	v_mul_f32_e32 v181, 0xbfb8aa3b, v167
	v_exp_f32_e32 v180, v180
	v_exp_f32_e32 v181, v181
	v_add_f32_e32 v179, 1.0, v179
	v_mul_f32_e32 v178, 0xbfb8aa3b, v176
	v_rcp_f32_e32 v182, v179
	v_add_f32_e32 v179, 1.0, v180
	v_add_f32_e32 v180, 1.0, v181
	v_mul_f32_e32 v181, 0xbfb8aa3b, v164
	v_mul_f32_e32 v183, 0xbfb8aa3b, v162
	v_mul_f32_e32 v191, 0xbfb8aa3b, v165
	v_mul_f32_e32 v192, 0xbfb8aa3b, v163
	v_exp_f32_e32 v178, v178
	v_exp_f32_e32 v181, v181
	v_exp_f32_e32 v183, v183
	v_exp_f32_e32 v191, v191
	v_exp_f32_e32 v192, v192
	v_add_f32_e32 v178, 1.0, v178
	v_add_f32_e32 v181, 1.0, v181
	v_add_f32_e32 v183, 1.0, v183
	v_add_f32_e32 v191, 1.0, v191
	v_add_f32_e32 v192, 1.0, v192
	v_rcp_f32_e32 v178, v178
	v_rcp_f32_e32 v179, v179
	v_rcp_f32_e32 v180, v180
	v_rcp_f32_e32 v181, v181
	v_rcp_f32_e32 v183, v183
	v_rcp_f32_e32 v191, v191
	v_rcp_f32_e32 v192, v192
	v_cvt_pk_bf16_f32 v178, v178, v179
	v_cvt_pk_bf16_f32 v180, v182, v180
	v_cvt_pk_bf16_f32 v179, v181, v191
	v_cvt_pk_bf16_f32 v181, v183, v192
	v_lshl_add_u64 v[182:183], v[158:159], 1, s[38:39]
	s_mov_b64 s[0:1], 0
	global_store_dwordx4 v[182:183], v[178:181], off nt
.LBB0_971:
	s_andn2_b64 vcc, exec, s[0:1]
	s_cbranch_vccnz .LBB0_973
	v_lshl_add_u64 v[158:159], v[158:159], 2, s[36:37]
	v_mul_f32_e32 v176, 0xbfb8aa3b, v176
	v_mul_f32_e32 v177, 0xbfb8aa3b, v177
	v_mul_f32_e32 v178, 0xbfb8aa3b, v164
	v_mul_f32_e32 v179, 0xbfb8aa3b, v165
	v_mul_f32_e32 v180, 0xbfb8aa3b, v166
	v_mul_f32_e32 v181, 0xbfb8aa3b, v167
	v_mul_f32_e32 v182, 0xbfb8aa3b, v162
	v_mul_f32_e32 v183, 0xbfb8aa3b, v163
	v_exp_f32_e32 v176, v176
	v_exp_f32_e32 v177, v177
	v_exp_f32_e32 v178, v178
	v_exp_f32_e32 v179, v179
	v_exp_f32_e32 v180, v180
	v_exp_f32_e32 v181, v181
	v_exp_f32_e32 v182, v182
	v_exp_f32_e32 v183, v183
	v_add_f32_e32 v176, 1.0, v176
	v_add_f32_e32 v177, 1.0, v177
	v_add_f32_e32 v178, 1.0, v178
	v_add_f32_e32 v179, 1.0, v179
	v_add_f32_e32 v180, 1.0, v180
	v_add_f32_e32 v181, 1.0, v181
	v_add_f32_e32 v182, 1.0, v182
	v_add_f32_e32 v183, 1.0, v183
	v_rcp_f32_e32 v176, v176
	v_rcp_f32_e32 v177, v177
	v_rcp_f32_e32 v178, v178
	v_rcp_f32_e32 v179, v179
	v_rcp_f32_e32 v180, v180
	v_rcp_f32_e32 v181, v181
	v_rcp_f32_e32 v182, v182
	v_rcp_f32_e32 v183, v183
	v_mul_f32_e32 v176, 0xbf60028b, v176
	v_mul_f32_e32 v177, 0xbf60028b, v177
	v_mul_f32_e32 v178, 0xbf60028b, v178
	v_mul_f32_e32 v179, 0xbf60028b, v179
	v_mul_f32_e32 v180, 0xbf60028b, v180
	v_mul_f32_e32 v181, 0xbf60028b, v181
	v_mul_f32_e32 v182, 0xbf60028b, v182
	v_mul_f32_e32 v183, 0xbf60028b, v183
	v_exp_f32_e32 v176, v176
	v_exp_f32_e32 v177, v177
	v_exp_f32_e32 v178, v178
	v_exp_f32_e32 v179, v179
	v_exp_f32_e32 v180, v180
	v_exp_f32_e32 v181, v181
	v_exp_f32_e32 v182, v182
	v_exp_f32_e32 v183, v183
	s_nop 0
	global_store_dwordx4 v[158:159], v[176:179], off nt
	global_store_dwordx4 v[158:159], v[180:183], off offset:16 nt
; __device__ __forceinline__ float sigm(float x) { return __builtin_amdgcn_rcpf(1.0f + __expf(-x)); }
; __device__ __forceinline__ u32x4 pack8(f32x4 v0, f32x4 v1) { u32x4 w; w.x = cvt_pk_bf16(v0[0], v0[1]); w.y = cvt_pk_bf16(v0[2], v0[3]); w.z = cvt_pk_bf16(v1[0], v1[1]); w.w = cvt_pk_bf16(v1[2], v1[3]); return w; }
;     __device__ __forceinline__ void operator()(f32x4 (&acc)[2][2][4][2], const Unit& u, int wr, int wc, int fr_, int fq_) const {
;     ...
;                     for (int m = 0; m < 4; ++m) { const size_t off = (size_t)(row0 + ai * HALF + m * 16) * 1024 + col0 + bj * HALF;
;                         f32x4 v0 = acc[ai][bj][m][0] + b0, v1 = acc[ai][bj][m][1] + b1;
;                         if (kind == 0) {
; #pragma unroll
;                             for (int i = 0; i < 4; ++i) { float z = -v0[i]; float sp = fmaxf(z, 0.f) + __logf(1.0f + __expf(-fabsf(z))); v0[i] = __expf(-__expf(-sp - 0.5f));
;                                                           z = -v1[i]; sp = fmaxf(z, 0.f) + __logf(1.0f + __expf(-fabsf(z))); v1[i] = __expf(-__expf(-sp - 0.5f)); }
;                             *(f32x4*)(DEC + off) = v0; *(f32x4*)(DEC + off + 4) = v1;
;                         } else {
; #pragma unroll
;                             for (int i = 0; i < 4; ++i) { v0[i] = sigm(v0[i]); v1[i] = sigm(v1[i]); }
;                             *(u32x4*)(AS + off) = pack8(v0, v1);
;                         }
;                         asm volatile("" ::: "memory"); __builtin_amdgcn_sched_barrier(0); }
.LBB0_973:
	v_lshl_add_u64 v[158:159], v[160:161], 0, v[168:169]
	v_pk_add_f32 v[164:165], v[54:55], v[134:135]
	v_pk_add_f32 v[168:169], v[52:53], v[132:133]
	v_pk_add_f32 v[162:163], v[50:51], v[130:131]
	v_pk_add_f32 v[166:167], v[48:49], v[128:129]
	s_and_b64 vcc, exec, s[6:7]
	s_mov_b64 s[0:1], -1
	s_cbranch_vccnz .LBB0_975
	v_mul_f32_e32 v177, 0xbfb8aa3b, v166
	v_exp_f32_e32 v177, v177
	v_mul_f32_e32 v178, 0xbfb8aa3b, v169
	v_mul_f32_e32 v179, 0xbfb8aa3b, v167
	v_exp_f32_e32 v178, v178
	v_exp_f32_e32 v179, v179
	v_add_f32_e32 v177, 1.0, v177
	v_mul_f32_e32 v176, 0xbfb8aa3b, v168
	v_rcp_f32_e32 v180, v177
	v_add_f32_e32 v177, 1.0, v178
	v_add_f32_e32 v178, 1.0, v179
	v_mul_f32_e32 v179, 0xbfb8aa3b, v164
	v_mul_f32_e32 v181, 0xbfb8aa3b, v162
	v_mul_f32_e32 v182, 0xbfb8aa3b, v165
	v_mul_f32_e32 v183, 0xbfb8aa3b, v163
	v_exp_f32_e32 v176, v176
	v_exp_f32_e32 v179, v179
	v_exp_f32_e32 v181, v181
	v_exp_f32_e32 v182, v182
	v_exp_f32_e32 v183, v183
	v_add_f32_e32 v176, 1.0, v176
	v_add_f32_e32 v179, 1.0, v179
	v_add_f32_e32 v181, 1.0, v181
	v_add_f32_e32 v182, 1.0, v182
	v_add_f32_e32 v183, 1.0, v183
	v_rcp_f32_e32 v176, v176
	v_rcp_f32_e32 v177, v177
	v_rcp_f32_e32 v178, v178
	v_rcp_f32_e32 v179, v179
	v_rcp_f32_e32 v181, v181
	v_rcp_f32_e32 v182, v182
	v_rcp_f32_e32 v183, v183
	v_cvt_pk_bf16_f32 v176, v176, v177
	v_cvt_pk_bf16_f32 v178, v180, v178
	v_cvt_pk_bf16_f32 v177, v179, v182
	v_cvt_pk_bf16_f32 v179, v181, v183
	v_lshl_add_u64 v[180:181], v[158:159], 1, s[38:39]
	s_mov_b64 s[0:1], 0
	global_store_dwordx4 v[180:181], v[176:179], off nt
.LBB0_975:
	s_andn2_b64 vcc, exec, s[0:1]
	s_cbranch_vccnz .LBB0_977
	v_lshl_add_u64 v[158:159], v[158:159], 2, s[36:37]
	v_mul_f32_e32 v176, 0xbfb8aa3b, v168
	v_mul_f32_e32 v177, 0xbfb8aa3b, v169
	v_mul_f32_e32 v178, 0xbfb8aa3b, v164
	v_mul_f32_e32 v179, 0xbfb8aa3b, v165
	v_mul_f32_e32 v166, 0xbfb8aa3b, v166
	v_mul_f32_e32 v167, 0xbfb8aa3b, v167
	v_mul_f32_e32 v168, 0xbfb8aa3b, v162
	v_mul_f32_e32 v169, 0xbfb8aa3b, v163
	v_exp_f32_e32 v176, v176
	v_exp_f32_e32 v177, v177
	v_exp_f32_e32 v178, v178
	v_exp_f32_e32 v179, v179
	v_exp_f32_e32 v166, v166
	v_exp_f32_e32 v167, v167
	v_exp_f32_e32 v168, v168
	v_exp_f32_e32 v169, v169
	v_add_f32_e32 v176, 1.0, v176
	v_add_f32_e32 v177, 1.0, v177
	v_add_f32_e32 v178, 1.0, v178
	v_add_f32_e32 v179, 1.0, v179
	v_add_f32_e32 v166, 1.0, v166
	v_add_f32_e32 v167, 1.0, v167
	v_add_f32_e32 v168, 1.0, v168
	v_add_f32_e32 v169, 1.0, v169
	v_rcp_f32_e32 v176, v176
	v_rcp_f32_e32 v177, v177
	v_rcp_f32_e32 v178, v178
	v_rcp_f32_e32 v179, v179
	v_rcp_f32_e32 v166, v166
	v_rcp_f32_e32 v167, v167
	v_rcp_f32_e32 v168, v168
	v_rcp_f32_e32 v169, v169
	v_mul_f32_e32 v176, 0xbf60028b, v176
	v_mul_f32_e32 v177, 0xbf60028b, v177
	v_mul_f32_e32 v178, 0xbf60028b, v178
	v_mul_f32_e32 v179, 0xbf60028b, v179
	v_mul_f32_e32 v166, 0xbf60028b, v166
	v_mul_f32_e32 v167, 0xbf60028b, v167
	v_mul_f32_e32 v168, 0xbf60028b, v168
	v_mul_f32_e32 v169, 0xbf60028b, v169
	v_exp_f32_e32 v176, v176
	v_exp_f32_e32 v177, v177
	v_exp_f32_e32 v178, v178
	v_exp_f32_e32 v179, v179
	v_exp_f32_e32 v166, v166
	v_exp_f32_e32 v167, v167
	v_exp_f32_e32 v168, v168
	v_exp_f32_e32 v169, v169
	s_nop 0
	global_store_dwordx4 v[158:159], v[176:179], off nt
	global_store_dwordx4 v[158:159], v[166:169], off offset:16 nt
; __device__ __forceinline__ float sigm(float x) { return __builtin_amdgcn_rcpf(1.0f + __expf(-x)); }
; __device__ __forceinline__ u32x4 pack8(f32x4 v0, f32x4 v1) { u32x4 w; w.x = cvt_pk_bf16(v0[0], v0[1]); w.y = cvt_pk_bf16(v0[2], v0[3]); w.z = cvt_pk_bf16(v1[0], v1[1]); w.w = cvt_pk_bf16(v1[2], v1[3]); return w; }
;     __device__ __forceinline__ void operator()(f32x4 (&acc)[2][2][4][2], const Unit& u, int wr, int wc, int fr_, int fq_) const {
;     ...
;                     for (int m = 0; m < 4; ++m) { const size_t off = (size_t)(row0 + ai * HALF + m * 16) * 1024 + col0 + bj * HALF;
;                         f32x4 v0 = acc[ai][bj][m][0] + b0, v1 = acc[ai][bj][m][1] + b1;
;                         if (kind == 0) {
; #pragma unroll
;                             for (int i = 0; i < 4; ++i) { float z = -v0[i]; float sp = fmaxf(z, 0.f) + __logf(1.0f + __expf(-fabsf(z))); v0[i] = __expf(-__expf(-sp - 0.5f));
;                                                           z = -v1[i]; sp = fmaxf(z, 0.f) + __logf(1.0f + __expf(-fabsf(z))); v1[i] = __expf(-__expf(-sp - 0.5f)); }
;                             *(f32x4*)(DEC + off) = v0; *(f32x4*)(DEC + off + 4) = v1;
;                         } else {
; #pragma unroll
;                             for (int i = 0; i < 4; ++i) { v0[i] = sigm(v0[i]); v1[i] = sigm(v1[i]); }
;                             *(u32x4*)(AS + off) = pack8(v0, v1);
;                         }
;                         asm volatile("" ::: "memory"); __builtin_amdgcn_sched_barrier(0); }
.LBB0_977:
	v_lshl_add_u64 v[158:159], v[160:161], 0, v[170:171]
	v_pk_add_f32 v[164:165], v[38:39], v[134:135]
	v_pk_add_f32 v[168:169], v[36:37], v[132:133]
	v_pk_add_f32 v[162:163], v[34:35], v[130:131]
	v_pk_add_f32 v[166:167], v[32:33], v[128:129]
	s_and_b64 vcc, exec, s[6:7]
	s_mov_b64 s[0:1], -1
	s_cbranch_vccnz .LBB0_979
	v_mul_f32_e32 v177, 0xbfb8aa3b, v167
	v_exp_f32_e32 v177, v177
	v_mul_f32_e32 v178, 0xbfb8aa3b, v164
	v_mul_f32_e32 v179, 0xbfb8aa3b, v162
	v_exp_f32_e32 v178, v178
	v_exp_f32_e32 v179, v179
	v_add_f32_e32 v177, 1.0, v177
	v_mul_f32_e32 v170, 0xbfb8aa3b, v168
	v_mul_f32_e32 v171, 0xbfb8aa3b, v166
	v_mul_f32_e32 v176, 0xbfb8aa3b, v169
	v_rcp_f32_e32 v180, v177
	v_add_f32_e32 v177, 1.0, v178
	v_add_f32_e32 v178, 1.0, v179
	v_mul_f32_e32 v179, 0xbfb8aa3b, v165
	v_mul_f32_e32 v181, 0xbfb8aa3b, v163
	v_exp_f32_e32 v170, v170
	v_exp_f32_e32 v171, v171
	v_exp_f32_e32 v176, v176
	v_exp_f32_e32 v179, v179
	v_exp_f32_e32 v181, v181
	v_add_f32_e32 v170, 1.0, v170
	v_add_f32_e32 v171, 1.0, v171
	v_add_f32_e32 v176, 1.0, v176
	v_rcp_f32_e32 v182, v178
	v_add_f32_e32 v178, 1.0, v179
	v_add_f32_e32 v179, 1.0, v181
	v_rcp_f32_e32 v170, v170
	v_rcp_f32_e32 v171, v171
	v_rcp_f32_e32 v176, v176
	v_rcp_f32_e32 v177, v177
	v_rcp_f32_e32 v178, v178
	v_rcp_f32_e32 v179, v179
	v_cvt_pk_bf16_f32 v176, v170, v176
	s_mov_b64 s[0:1], 0
	v_cvt_pk_bf16_f32 v177, v177, v178
	v_cvt_pk_bf16_f32 v178, v171, v180
	v_cvt_pk_bf16_f32 v179, v182, v179
	v_lshl_add_u64 v[170:171], v[158:159], 1, s[38:39]
	global_store_dwordx4 v[170:171], v[176:179], off nt
.LBB0_979:
	s_andn2_b64 vcc, exec, s[0:1]
	s_cbranch_vccnz .LBB0_981
	v_lshl_add_u64 v[158:159], v[158:159], 2, s[36:37]
	v_mul_f32_e32 v168, 0xbfb8aa3b, v168
	v_mul_f32_e32 v169, 0xbfb8aa3b, v169
	v_mul_f32_e32 v170, 0xbfb8aa3b, v164
	v_mul_f32_e32 v171, 0xbfb8aa3b, v165
	v_mul_f32_e32 v176, 0xbfb8aa3b, v166
	v_mul_f32_e32 v177, 0xbfb8aa3b, v167
	v_mul_f32_e32 v178, 0xbfb8aa3b, v162
	v_mul_f32_e32 v179, 0xbfb8aa3b, v163
	v_exp_f32_e32 v168, v168
	v_exp_f32_e32 v169, v169
	v_exp_f32_e32 v170, v170
	v_exp_f32_e32 v171, v171
	v_exp_f32_e32 v176, v176
	v_exp_f32_e32 v177, v177
	v_exp_f32_e32 v178, v178
	v_exp_f32_e32 v179, v179
	v_add_f32_e32 v168, 1.0, v168
	v_add_f32_e32 v169, 1.0, v169
	v_add_f32_e32 v170, 1.0, v170
	v_add_f32_e32 v171, 1.0, v171
	v_add_f32_e32 v176, 1.0, v176
	v_add_f32_e32 v177, 1.0, v177
	v_add_f32_e32 v178, 1.0, v178
	v_add_f32_e32 v179, 1.0, v179
	v_rcp_f32_e32 v168, v168
	v_rcp_f32_e32 v169, v169
	v_rcp_f32_e32 v170, v170
	v_rcp_f32_e32 v171, v171
	v_rcp_f32_e32 v176, v176
	v_rcp_f32_e32 v177, v177
	v_rcp_f32_e32 v178, v178
	v_rcp_f32_e32 v179, v179
	v_mul_f32_e32 v168, 0xbf60028b, v168
	v_mul_f32_e32 v169, 0xbf60028b, v169
	v_mul_f32_e32 v170, 0xbf60028b, v170
	v_mul_f32_e32 v171, 0xbf60028b, v171
	v_mul_f32_e32 v176, 0xbf60028b, v176
	v_mul_f32_e32 v177, 0xbf60028b, v177
	v_mul_f32_e32 v178, 0xbf60028b, v178
	v_mul_f32_e32 v179, 0xbf60028b, v179
	v_exp_f32_e32 v168, v168
	v_exp_f32_e32 v169, v169
	v_exp_f32_e32 v170, v170
	v_exp_f32_e32 v171, v171
	v_exp_f32_e32 v176, v176
	v_exp_f32_e32 v177, v177
	v_exp_f32_e32 v178, v178
	v_exp_f32_e32 v179, v179
	s_nop 0
	global_store_dwordx4 v[158:159], v[168:171], off nt
	global_store_dwordx4 v[158:159], v[176:179], off offset:16 nt
.LBB0_981:
	v_lshl_add_u64 v[158:159], v[160:161], 0, v[172:173]
	v_pk_add_f32 v[164:165], v[22:23], v[134:135]
	v_pk_add_f32 v[168:169], v[20:21], v[132:133]
	v_pk_add_f32 v[162:163], v[18:19], v[130:131]
	v_pk_add_f32 v[166:167], v[16:17], v[128:129]
	s_and_b64 vcc, exec, s[6:7]
	s_mov_b64 s[0:1], -1
	s_cbranch_vccnz .LBB0_983
	v_mul_f32_e32 v171, 0xbfb8aa3b, v166
	v_exp_f32_e32 v171, v171
	v_mul_f32_e32 v172, 0xbfb8aa3b, v169
	v_mul_f32_e32 v173, 0xbfb8aa3b, v167
	v_exp_f32_e32 v172, v172
	v_exp_f32_e32 v173, v173
	v_add_f32_e32 v171, 1.0, v171
	v_mul_f32_e32 v170, 0xbfb8aa3b, v168
	v_rcp_f32_e32 v176, v171
	v_add_f32_e32 v171, 1.0, v172
	v_add_f32_e32 v172, 1.0, v173
	v_mul_f32_e32 v173, 0xbfb8aa3b, v164
	v_mul_f32_e32 v177, 0xbfb8aa3b, v162
	v_mul_f32_e32 v178, 0xbfb8aa3b, v165
	v_mul_f32_e32 v179, 0xbfb8aa3b, v163
	v_exp_f32_e32 v170, v170
	v_exp_f32_e32 v173, v173
	v_exp_f32_e32 v177, v177
	v_exp_f32_e32 v178, v178
	v_exp_f32_e32 v179, v179
	v_add_f32_e32 v170, 1.0, v170
	v_add_f32_e32 v173, 1.0, v173
	v_add_f32_e32 v177, 1.0, v177
	v_add_f32_e32 v178, 1.0, v178
	v_add_f32_e32 v179, 1.0, v179
	v_rcp_f32_e32 v170, v170
	v_rcp_f32_e32 v171, v171
	v_rcp_f32_e32 v172, v172
	v_rcp_f32_e32 v173, v173
	v_rcp_f32_e32 v177, v177
	v_rcp_f32_e32 v178, v178
	v_rcp_f32_e32 v179, v179
	v_cvt_pk_bf16_f32 v170, v170, v171
	v_cvt_pk_bf16_f32 v172, v176, v172
	v_cvt_pk_bf16_f32 v171, v173, v178
	v_cvt_pk_bf16_f32 v173, v177, v179
	v_lshl_add_u64 v[176:177], v[158:159], 1, s[38:39]
	s_mov_b64 s[0:1], 0
	global_store_dwordx4 v[176:177], v[170:173], off nt

; __device__ __forceinline__ float sigm(float x) { return __builtin_amdgcn_rcpf(1.0f + __expf(-x)); }
; __device__ __forceinline__ u32x4 pack8(f32x4 v0, f32x4 v1) { u32x4 w; w.x = cvt_pk_bf16(v0[0], v0[1]); w.y = cvt_pk_bf16(v0[2], v0[3]); w.z = cvt_pk_bf16(v1[0], v1[1]); w.w = cvt_pk_bf16(v1[2], v1[3]); return w; }
;     __device__ __forceinline__ void operator()(f32x4 (&acc)[2][2][4][2], const Unit& u, int wr, int wc, int fr_, int fq_) const {
;     ...
;                     for (int m = 0; m < 4; ++m) { const size_t off = (size_t)(row0 + ai * HALF + m * 16) * 1024 + col0 + bj * HALF;
;                         f32x4 v0 = acc[ai][bj][m][0] + b0, v1 = acc[ai][bj][m][1] + b1;
;                         if (kind == 0) {
; #pragma unroll
;                             for (int i = 0; i < 4; ++i) { float z = -v0[i]; float sp = fmaxf(z, 0.f) + __logf(1.0f + __expf(-fabsf(z))); v0[i] = __expf(-__expf(-sp - 0.5f));
;                                                           z = -v1[i]; sp = fmaxf(z, 0.f) + __logf(1.0f + __expf(-fabsf(z))); v1[i] = __expf(-__expf(-sp - 0.5f)); }
;                             *(f32x4*)(DEC + off) = v0; *(f32x4*)(DEC + off + 4) = v1;
;                         } else {
; #pragma unroll
;                             for (int i = 0; i < 4; ++i) { v0[i] = sigm(v0[i]); v1[i] = sigm(v1[i]); }
;                             *(u32x4*)(AS + off) = pack8(v0, v1);
;                         }
;                         asm volatile("" ::: "memory"); __builtin_amdgcn_sched_barrier(0); }
.LBB0_985:
	v_lshl_add_u64 v[158:159], v[160:161], 0, v[174:175]
	v_pk_add_f32 v[134:135], v[6:7], v[134:135]
	v_pk_add_f32 v[132:133], v[4:5], v[132:133]
	v_pk_add_f32 v[130:131], v[2:3], v[130:131]
	v_pk_add_f32 v[128:129], v[0:1], v[128:129]
	s_and_b64 vcc, exec, s[6:7]
	s_mov_b64 s[0:1], -1
	s_cbranch_vccnz .LBB0_987
	v_mul_f32_e32 v161, 0xbfb8aa3b, v128
	v_exp_f32_e32 v161, v161
	v_mul_f32_e32 v162, 0xbfb8aa3b, v133
	v_mul_f32_e32 v163, 0xbfb8aa3b, v129
	v_exp_f32_e32 v162, v162
	v_exp_f32_e32 v163, v163
	v_add_f32_e32 v161, 1.0, v161
	v_mul_f32_e32 v160, 0xbfb8aa3b, v132
	v_rcp_f32_e32 v164, v161
	v_add_f32_e32 v161, 1.0, v162
	v_add_f32_e32 v162, 1.0, v163
	v_mul_f32_e32 v163, 0xbfb8aa3b, v134
	v_mul_f32_e32 v165, 0xbfb8aa3b, v130
	v_mul_f32_e32 v166, 0xbfb8aa3b, v135
	v_mul_f32_e32 v167, 0xbfb8aa3b, v131
	v_exp_f32_e32 v160, v160
	v_exp_f32_e32 v163, v163
	v_exp_f32_e32 v165, v165
	v_exp_f32_e32 v166, v166
	v_exp_f32_e32 v167, v167
	v_add_f32_e32 v160, 1.0, v160
	v_add_f32_e32 v163, 1.0, v163
	v_add_f32_e32 v165, 1.0, v165
	v_add_f32_e32 v166, 1.0, v166
	v_add_f32_e32 v167, 1.0, v167
	v_rcp_f32_e32 v160, v160
	v_rcp_f32_e32 v161, v161
	v_rcp_f32_e32 v162, v162
	v_rcp_f32_e32 v163, v163
	v_rcp_f32_e32 v165, v165
	v_rcp_f32_e32 v166, v166
	v_rcp_f32_e32 v167, v167
	v_cvt_pk_bf16_f32 v160, v160, v161
	v_cvt_pk_bf16_f32 v162, v164, v162
	v_cvt_pk_bf16_f32 v161, v163, v166
	v_cvt_pk_bf16_f32 v163, v165, v167
	v_lshl_add_u64 v[164:165], v[158:159], 1, s[38:39]
	s_mov_b64 s[0:1], 0
	global_store_dwordx4 v[164:165], v[160:163], off nt
.LBB0_987:
	s_andn2_b64 vcc, exec, s[0:1]
	s_cbranch_vccnz .LBB0_989
	v_lshl_add_u64 v[158:159], v[158:159], 2, s[36:37]
	v_mul_f32_e32 v132, 0xbfb8aa3b, v132
	v_mul_f32_e32 v133, 0xbfb8aa3b, v133
	v_mul_f32_e32 v134, 0xbfb8aa3b, v134
	v_mul_f32_e32 v135, 0xbfb8aa3b, v135
	v_mul_f32_e32 v128, 0xbfb8aa3b, v128
	v_mul_f32_e32 v129, 0xbfb8aa3b, v129
	v_mul_f32_e32 v130, 0xbfb8aa3b, v130
	v_mul_f32_e32 v131, 0xbfb8aa3b, v131
	v_exp_f32_e32 v132, v132
	v_exp_f32_e32 v133, v133
	v_exp_f32_e32 v134, v134
	v_exp_f32_e32 v135, v135
	v_exp_f32_e32 v128, v128
	v_exp_f32_e32 v129, v129
	v_exp_f32_e32 v130, v130
	v_exp_f32_e32 v131, v131
	v_add_f32_e32 v132, 1.0, v132
	v_add_f32_e32 v133, 1.0, v133
	v_add_f32_e32 v134, 1.0, v134
	v_add_f32_e32 v135, 1.0, v135
	v_add_f32_e32 v128, 1.0, v128
	v_add_f32_e32 v129, 1.0, v129
	v_add_f32_e32 v130, 1.0, v130
	v_add_f32_e32 v131, 1.0, v131
	v_rcp_f32_e32 v132, v132
	v_rcp_f32_e32 v133, v133
	v_rcp_f32_e32 v134, v134
	v_rcp_f32_e32 v135, v135
	v_rcp_f32_e32 v128, v128
	v_rcp_f32_e32 v129, v129
	v_rcp_f32_e32 v130, v130
	v_rcp_f32_e32 v131, v131
	v_mul_f32_e32 v132, 0xbf60028b, v132
	v_mul_f32_e32 v133, 0xbf60028b, v133
	v_mul_f32_e32 v134, 0xbf60028b, v134
	v_mul_f32_e32 v135, 0xbf60028b, v135
	v_mul_f32_e32 v128, 0xbf60028b, v128
	v_mul_f32_e32 v129, 0xbf60028b, v129
	v_mul_f32_e32 v130, 0xbf60028b, v130
	v_mul_f32_e32 v131, 0xbf60028b, v131
	v_exp_f32_e32 v132, v132
	v_exp_f32_e32 v133, v133
	v_exp_f32_e32 v134, v134
	v_exp_f32_e32 v135, v135
	v_exp_f32_e32 v128, v128
	v_exp_f32_e32 v129, v129
	v_exp_f32_e32 v130, v130
	v_exp_f32_e32 v131, v131
	s_nop 0
	global_store_dwordx4 v[158:159], v[132:135], off nt
	global_store_dwordx4 v[158:159], v[128:131], off offset:16 nt

; __device__ __forceinline__ u32x4 pack8(f32x4 v0, f32x4 v1) { u32x4 w; w.x = cvt_pk_bf16(v0[0], v0[1]); w.y = cvt_pk_bf16(v0[2], v0[3]); w.z = cvt_pk_bf16(v1[0], v1[1]); w.w = cvt_pk_bf16(v1[2], v1[3]); return w; }
;     __device__ __forceinline__ void operator()(f32x4 (&acc)[2][2][4][2], const Unit& u, int wr, int wc, int fr_, int fq_) const {
;     ...
;         if (kind == 2) {
; #pragma unroll
;             for (int ai = 0; ai < 2; ++ai)
; #pragma unroll
;                 for (int m = 0; m < 4; ++m) { bf16_t* rowp = G + (size_t)(row0 + ai * HALF + m * 16) * 1024 + col0;
; #pragma unroll
;                     for (int bj = 0; bj < 2; ++bj) *(u32x4*)(rowp + bj * HALF) = pack8(acc[ai][bj][m][0], acc[ai][bj][m][1]); }
.LBB0_990:
	v_lshlrev_b64 v[128:129], 11, v[154:155]
	v_lshl_add_u64 v[128:129], s[52:53], 0, v[128:129]
	v_lshl_add_u64 v[128:129], v[156:157], 1, v[128:129]
	s_mov_b32 s0, 0x8000
	v_cvt_pk_bf16_f32 v108, v108, v109
	v_cvt_pk_bf16_f32 v109, v110, v111
	v_cvt_pk_bf16_f32 v110, v104, v105
	v_add_co_u32_e32 v104, vcc, s0, v128
	s_mov_b64 s[0:1], 0x10000
	s_nop 0
	v_addc_co_u32_e32 v105, vcc, 0, v129, vcc
	v_cvt_pk_bf16_f32 v100, v100, v101
	v_cvt_pk_bf16_f32 v101, v102, v103
	v_cvt_pk_bf16_f32 v102, v96, v97
	v_lshl_add_u64 v[96:97], v[128:129], 0, s[0:1]
	s_mov_b32 s0, 0x10000
	v_cvt_pk_bf16_f32 v92, v92, v93
	v_cvt_pk_bf16_f32 v93, v94, v95
	v_cvt_pk_bf16_f32 v94, v88, v89
	v_add_co_u32_e32 v88, vcc, s0, v128
	s_mov_b64 s[0:1], 0x18000
	s_nop 0
	v_addc_co_u32_e32 v89, vcc, 0, v129, vcc
	v_cvt_pk_bf16_f32 v84, v84, v85
	v_cvt_pk_bf16_f32 v85, v86, v87
	v_cvt_pk_bf16_f32 v86, v80, v81
	v_lshl_add_u64 v[80:81], v[128:129], 0, s[0:1]
	s_mov_b32 s0, 0x18000
	v_cvt_pk_bf16_f32 v76, v76, v77
	v_cvt_pk_bf16_f32 v77, v78, v79
	v_cvt_pk_bf16_f32 v78, v72, v73
	v_add_co_u32_e32 v72, vcc, s0, v128
	s_mov_b64 s[0:1], 0x40000
	s_nop 0
	v_addc_co_u32_e32 v73, vcc, 0, v129, vcc
	v_cvt_pk_bf16_f32 v68, v68, v69
	v_cvt_pk_bf16_f32 v69, v70, v71
	v_cvt_pk_bf16_f32 v70, v64, v65
	v_lshl_add_u64 v[64:65], v[128:129], 0, s[0:1]
	s_mov_b32 s0, 0x40000
	v_cvt_pk_bf16_f32 v60, v60, v61
	v_cvt_pk_bf16_f32 v61, v62, v63
	v_cvt_pk_bf16_f32 v62, v56, v57
	v_add_co_u32_e32 v56, vcc, s0, v128
	s_mov_b64 s[0:1], 0x48000
	s_nop 0
	v_addc_co_u32_e32 v57, vcc, 0, v129, vcc
	v_cvt_pk_bf16_f32 v52, v52, v53
	v_cvt_pk_bf16_f32 v53, v54, v55
	v_cvt_pk_bf16_f32 v54, v48, v49
	v_lshl_add_u64 v[48:49], v[128:129], 0, s[0:1]
	s_mov_b32 s0, 0x48000
	v_cvt_pk_bf16_f32 v44, v44, v45
	v_cvt_pk_bf16_f32 v45, v46, v47
	v_cvt_pk_bf16_f32 v46, v40, v41
	v_add_co_u32_e32 v40, vcc, s0, v128
	s_mov_b64 s[0:1], 0x50000
	s_nop 0
	v_addc_co_u32_e32 v41, vcc, 0, v129, vcc
	v_cvt_pk_bf16_f32 v36, v36, v37
	v_cvt_pk_bf16_f32 v37, v38, v39
	v_cvt_pk_bf16_f32 v38, v32, v33
	v_lshl_add_u64 v[32:33], v[128:129], 0, s[0:1]
	s_mov_b32 s0, 0x50000
	v_cvt_pk_bf16_f32 v28, v28, v29
	v_cvt_pk_bf16_f32 v29, v30, v31
	v_cvt_pk_bf16_f32 v30, v24, v25
	v_add_co_u32_e32 v24, vcc, s0, v128
	s_mov_b64 s[0:1], 0x58000
	s_nop 0
	v_addc_co_u32_e32 v25, vcc, 0, v129, vcc
	v_cvt_pk_bf16_f32 v20, v20, v21
	v_cvt_pk_bf16_f32 v21, v22, v23
	v_cvt_pk_bf16_f32 v22, v16, v17
	v_lshl_add_u64 v[16:17], v[128:129], 0, s[0:1]
	s_mov_b32 s0, 0x58000
	v_cvt_pk_bf16_f32 v12, v12, v13
	v_cvt_pk_bf16_f32 v13, v14, v15
	v_cvt_pk_bf16_f32 v14, v8, v9
	v_add_co_u32_e32 v8, vcc, s0, v128
	v_cvt_pk_bf16_f32 v120, v120, v121
	v_cvt_pk_bf16_f32 v121, v122, v123
	v_cvt_pk_bf16_f32 v122, v124, v125
	v_cvt_pk_bf16_f32 v123, v126, v127
	v_cvt_pk_bf16_f32 v116, v116, v117
	v_cvt_pk_bf16_f32 v117, v118, v119
	v_cvt_pk_bf16_f32 v118, v112, v113
	v_cvt_pk_bf16_f32 v119, v114, v115
	v_lshl_add_u64 v[112:113], v[128:129], 0, s[56:57]
	v_cvt_pk_bf16_f32 v111, v106, v107
	v_cvt_pk_bf16_f32 v103, v98, v99
	v_cvt_pk_bf16_f32 v95, v90, v91
	v_cvt_pk_bf16_f32 v87, v82, v83
	v_cvt_pk_bf16_f32 v79, v74, v75
	v_cvt_pk_bf16_f32 v71, v66, v67
	v_cvt_pk_bf16_f32 v63, v58, v59
	v_cvt_pk_bf16_f32 v55, v50, v51
	v_cvt_pk_bf16_f32 v47, v42, v43
	v_cvt_pk_bf16_f32 v39, v34, v35
	v_cvt_pk_bf16_f32 v31, v26, v27
	v_cvt_pk_bf16_f32 v23, v18, v19
	v_cvt_pk_bf16_f32 v15, v10, v11
	v_addc_co_u32_e32 v9, vcc, 0, v129, vcc
	v_cvt_pk_bf16_f32 v4, v4, v5
	v_cvt_pk_bf16_f32 v5, v6, v7
	v_cvt_pk_bf16_f32 v6, v0, v1
	v_cvt_pk_bf16_f32 v7, v2, v3
	global_store_dwordx4 v[128:129], v[120:123], off nt
	global_store_dwordx4 v[128:129], v[116:119], off offset:256 nt
	global_store_dwordx4 v[104:105], v[108:111], off nt
	global_store_dwordx4 v[112:113], v[100:103], off offset:256 nt
	global_store_dwordx4 v[88:89], v[92:95], off nt
	global_store_dwordx4 v[96:97], v[84:87], off offset:256 nt
	global_store_dwordx4 v[72:73], v[76:79], off nt
	global_store_dwordx4 v[80:81], v[68:71], off offset:256 nt
	global_store_dwordx4 v[56:57], v[60:63], off nt
	global_store_dwordx4 v[64:65], v[52:55], off offset:256 nt
	global_store_dwordx4 v[40:41], v[44:47], off nt
	global_store_dwordx4 v[48:49], v[36:39], off offset:256 nt
	global_store_dwordx4 v[24:25], v[28:31], off nt
	global_store_dwordx4 v[32:33], v[20:23], off offset:256 nt
	global_store_dwordx4 v[8:9], v[12:15], off nt
	global_store_dwordx4 v[16:17], v[4:7], off offset:256 nt
	s_and_b64 vcc, exec, s[4:5]
	s_mov_b64 s[0:1], -1
	s_cbranch_vccnz .LBB0_910

; __device__ __forceinline__ u32x4 pack8(f32x4 v0, f32x4 v1) { u32x4 w; w.x = cvt_pk_bf16(v0[0], v0[1]); w.y = cvt_pk_bf16(v0[2], v0[3]); w.z = cvt_pk_bf16(v1[0], v1[1]); w.w = cvt_pk_bf16(v1[2], v1[3]); return w; }
; __device__ __forceinline__ float sigm(float x) { return __builtin_amdgcn_rcpf(1.0f + __expf(-x)); }
;     __device__ __forceinline__ void operator()(f32x4 (&acc)[2][2][4][2], const Unit& u, int wr, int wc, int fr_, int fq_) const {
;     ...
;             for (int m = 0; m < 4; ++m) { const int row = row0 + ai * HALF + m * 16; const float rs = rstd[row]; bf16_t* rowp = GAB + (size_t)row * 4096 + col0;
; #pragma unroll
;                 for (int bj = 0; bj < 2; ++bj) { f32x4 v0 = acc[ai][bj][m][0] * rs, v1 = acc[ai][bj][m][1] * rs;
; #pragma unroll
;                     for (int i = 0; i < 4; ++i) { v0[i] = sigm(v0[i]); v1[i] = sigm(v1[i]); }
;                     *(u32x4*)(rowp + bj * HALF) = pack8(v0, v1); } }
.LBB0_1443:
	v_mov_b32_e32 v146, v150
	v_mov_b32_e32 v167, v151
	s_lshl_b32 s0, s0, 8
	s_add_i32 s0, s0, s69
	v_add_u32_e32 v146, s0, v146
	v_readlane_b32 s34, v244, 38
	v_ashrrev_i32_e32 v147, 31, v146
	v_readlane_b32 s35, v244, 39
	s_lshl_b32 s0, s1, 8
	s_or_b32 s0, s0, s70
	v_lshl_add_u64 v[148:149], v[146:147], 2, s[34:35]
	global_load_dword v168, v[148:149], off
	global_load_dword v245, v[148:149], off offset:64
	global_load_dword v246, v[148:149], off offset:128
	global_load_dword v247, v[148:149], off offset:192
	global_load_dword v248, v[148:149], off offset:512
	global_load_dword v249, v[148:149], off offset:576
	global_load_dword v250, v[148:149], off offset:640
	global_load_dword v251, v[148:149], off offset:704
	v_lshl_add_u32 v170, v167, 3, s0
	v_lshlrev_b64 v[146:147], 13, v[146:147]
	v_ashrrev_i32_e32 v171, 31, v170
	v_lshl_add_u64 v[146:147], s[26:27], 0, v[146:147]
	v_lshl_add_u64 v[146:147], v[170:171], 1, v[146:147]
	s_waitcnt vmcnt(0)
	v_pk_mul_f32 v[126:127], v[126:127], v[168:169] op_sel_hi:[1,0]
	v_pk_mul_f32 v[124:125], v[124:125], v[168:169] op_sel_hi:[1,0]
	v_pk_mul_f32 v[122:123], v[122:123], v[168:169] op_sel_hi:[1,0]
	v_pk_mul_f32 v[120:121], v[120:121], v[168:169] op_sel_hi:[1,0]
	v_pk_mul_f32 v[118:119], v[118:119], v[168:169] op_sel_hi:[1,0]
	v_pk_mul_f32 v[116:117], v[116:117], v[168:169] op_sel_hi:[1,0]
	v_pk_mul_f32 v[114:115], v[114:115], v[168:169] op_sel_hi:[1,0]
	v_pk_mul_f32 v[112:113], v[112:113], v[168:169] op_sel_hi:[1,0]
	v_mul_f32_e32 v124, 0xbfb8aa3b, v124
	v_mul_f32_e32 v120, 0xbfb8aa3b, v120
	v_mul_f32_e32 v125, 0xbfb8aa3b, v125
	v_mul_f32_e32 v121, 0xbfb8aa3b, v121
	v_mul_f32_e32 v126, 0xbfb8aa3b, v126
	v_mul_f32_e32 v122, 0xbfb8aa3b, v122
	v_mul_f32_e32 v127, 0xbfb8aa3b, v127
	v_mul_f32_e32 v123, 0xbfb8aa3b, v123
	v_mul_f32_e32 v116, 0xbfb8aa3b, v116
	v_mul_f32_e32 v112, 0xbfb8aa3b, v112
	v_mul_f32_e32 v117, 0xbfb8aa3b, v117
	v_mul_f32_e32 v113, 0xbfb8aa3b, v113
	v_mul_f32_e32 v118, 0xbfb8aa3b, v118
	v_mul_f32_e32 v114, 0xbfb8aa3b, v114
	v_mul_f32_e32 v119, 0xbfb8aa3b, v119
	v_mul_f32_e32 v115, 0xbfb8aa3b, v115
	v_exp_f32_e32 v124, v124
	v_exp_f32_e32 v120, v120
	v_exp_f32_e32 v125, v125
	v_exp_f32_e32 v121, v121
	v_exp_f32_e32 v126, v126
	v_exp_f32_e32 v122, v122
	v_exp_f32_e32 v127, v127
	v_exp_f32_e32 v123, v123
	v_exp_f32_e32 v116, v116
	v_exp_f32_e32 v112, v112
	v_exp_f32_e32 v117, v117
	v_exp_f32_e32 v113, v113
	v_exp_f32_e32 v118, v118
	v_exp_f32_e32 v114, v114
	v_exp_f32_e32 v119, v119
	v_exp_f32_e32 v115, v115
	v_add_f32_e32 v124, 1.0, v124
	v_add_f32_e32 v120, 1.0, v120
	v_add_f32_e32 v125, 1.0, v125
	v_add_f32_e32 v121, 1.0, v121
	v_add_f32_e32 v126, 1.0, v126
	v_add_f32_e32 v122, 1.0, v122
	v_add_f32_e32 v127, 1.0, v127
	v_add_f32_e32 v123, 1.0, v123
	v_add_f32_e32 v116, 1.0, v116
	v_add_f32_e32 v112, 1.0, v112
	v_add_f32_e32 v117, 1.0, v117
	v_add_f32_e32 v113, 1.0, v113
	v_add_f32_e32 v118, 1.0, v118
	v_add_f32_e32 v114, 1.0, v114
	v_add_f32_e32 v119, 1.0, v119
	v_add_f32_e32 v115, 1.0, v115
	v_rcp_f32_e32 v124, v124
	v_rcp_f32_e32 v120, v120
	v_rcp_f32_e32 v125, v125
	v_rcp_f32_e32 v121, v121
	v_rcp_f32_e32 v126, v126
	v_rcp_f32_e32 v122, v122
	v_rcp_f32_e32 v127, v127
	v_rcp_f32_e32 v123, v123
	v_rcp_f32_e32 v116, v116
	v_rcp_f32_e32 v167, v112
	v_rcp_f32_e32 v117, v117
	v_rcp_f32_e32 v168, v113
	v_rcp_f32_e32 v118, v118
	v_rcp_f32_e32 v169, v114
	v_rcp_f32_e32 v119, v119
	v_rcp_f32_e32 v170, v115
	v_cvt_pk_bf16_f32 v112, v124, v125
	v_cvt_pk_bf16_f32 v113, v126, v127
	v_cvt_pk_bf16_f32 v114, v120, v121
	v_cvt_pk_bf16_f32 v115, v122, v123
	v_cvt_pk_bf16_f32 v116, v116, v117
	v_cvt_pk_bf16_f32 v117, v118, v119
	v_cvt_pk_bf16_f32 v118, v167, v168
	v_cvt_pk_bf16_f32 v119, v169, v170
	global_store_dwordx4 v[146:147], v[112:115], off nt
	global_store_dwordx4 v[146:147], v[116:119], off offset:256 nt
	s_nop 0
	v_lshl_add_u64 v[114:115], v[146:147], 0, s[16:17]
	v_add_co_u32_e32 v116, vcc, s76, v146
	v_mov_b32_e32 v112, v245
	v_pk_mul_f32 v[110:111], v[110:111], v[112:113] op_sel_hi:[1,0]
	v_pk_mul_f32 v[108:109], v[108:109], v[112:113] op_sel_hi:[1,0]
	v_pk_mul_f32 v[106:107], v[106:107], v[112:113] op_sel_hi:[1,0]
	v_pk_mul_f32 v[104:105], v[104:105], v[112:113] op_sel_hi:[1,0]
	v_pk_mul_f32 v[102:103], v[102:103], v[112:113] op_sel_hi:[1,0]
	v_pk_mul_f32 v[100:101], v[100:101], v[112:113] op_sel_hi:[1,0]
	v_pk_mul_f32 v[98:99], v[98:99], v[112:113] op_sel_hi:[1,0]
	v_pk_mul_f32 v[96:97], v[96:97], v[112:113] op_sel_hi:[1,0]
	v_mul_f32_e32 v108, 0xbfb8aa3b, v108
	v_mul_f32_e32 v104, 0xbfb8aa3b, v104
	v_mul_f32_e32 v109, 0xbfb8aa3b, v109
	v_mul_f32_e32 v105, 0xbfb8aa3b, v105
	v_mul_f32_e32 v110, 0xbfb8aa3b, v110
	v_mul_f32_e32 v106, 0xbfb8aa3b, v106
	v_mul_f32_e32 v111, 0xbfb8aa3b, v111
	v_mul_f32_e32 v107, 0xbfb8aa3b, v107
	v_mul_f32_e32 v100, 0xbfb8aa3b, v100
	v_mul_f32_e32 v96, 0xbfb8aa3b, v96
	v_mul_f32_e32 v101, 0xbfb8aa3b, v101
	v_mul_f32_e32 v97, 0xbfb8aa3b, v97
	v_mul_f32_e32 v102, 0xbfb8aa3b, v102
	v_mul_f32_e32 v98, 0xbfb8aa3b, v98
	v_mul_f32_e32 v103, 0xbfb8aa3b, v103
	v_mul_f32_e32 v99, 0xbfb8aa3b, v99
	v_exp_f32_e32 v108, v108
	v_exp_f32_e32 v104, v104
	v_exp_f32_e32 v109, v109
	v_exp_f32_e32 v105, v105
	v_exp_f32_e32 v110, v110
	v_exp_f32_e32 v106, v106
	v_exp_f32_e32 v111, v111
	v_exp_f32_e32 v107, v107
	v_exp_f32_e32 v100, v100
	v_exp_f32_e32 v96, v96
	v_exp_f32_e32 v101, v101
	v_exp_f32_e32 v97, v97
	v_exp_f32_e32 v102, v102
	v_exp_f32_e32 v98, v98
	v_exp_f32_e32 v103, v103
	v_exp_f32_e32 v99, v99
	v_add_f32_e32 v108, 1.0, v108
	v_add_f32_e32 v104, 1.0, v104
	v_add_f32_e32 v109, 1.0, v109
	v_add_f32_e32 v105, 1.0, v105
	v_add_f32_e32 v110, 1.0, v110
; __device__ __forceinline__ u32x4 pack8(f32x4 v0, f32x4 v1) { u32x4 w; w.x = cvt_pk_bf16(v0[0], v0[1]); w.y = cvt_pk_bf16(v0[2], v0[3]); w.z = cvt_pk_bf16(v1[0], v1[1]); w.w = cvt_pk_bf16(v1[2], v1[3]); return w; }
; __device__ __forceinline__ float sigm(float x) { return __builtin_amdgcn_rcpf(1.0f + __expf(-x)); }
;     __device__ __forceinline__ void operator()(f32x4 (&acc)[2][2][4][2], const Unit& u, int wr, int wc, int fr_, int fq_) const {
;     ...
;             for (int m = 0; m < 4; ++m) { const int row = row0 + ai * HALF + m * 16; const float rs = rstd[row]; bf16_t* rowp = GAB + (size_t)row * 4096 + col0;
; #pragma unroll
;                 for (int bj = 0; bj < 2; ++bj) { f32x4 v0 = acc[ai][bj][m][0] * rs, v1 = acc[ai][bj][m][1] * rs;
; #pragma unroll
;                     for (int i = 0; i < 4; ++i) { v0[i] = sigm(v0[i]); v1[i] = sigm(v1[i]); }
;                     *(u32x4*)(rowp + bj * HALF) = pack8(v0, v1); } }
	v_add_f32_e32 v106, 1.0, v106
	v_add_f32_e32 v111, 1.0, v111
	v_add_f32_e32 v107, 1.0, v107
	v_add_f32_e32 v100, 1.0, v100
	v_add_f32_e32 v96, 1.0, v96
	v_add_f32_e32 v101, 1.0, v101
	v_add_f32_e32 v97, 1.0, v97
	v_add_f32_e32 v102, 1.0, v102
	v_add_f32_e32 v98, 1.0, v98
	v_add_f32_e32 v103, 1.0, v103
	v_add_f32_e32 v99, 1.0, v99
	v_rcp_f32_e32 v108, v108
	v_rcp_f32_e32 v104, v104
	v_rcp_f32_e32 v109, v109
	v_rcp_f32_e32 v105, v105
	v_rcp_f32_e32 v110, v110
	v_rcp_f32_e32 v106, v106
	v_rcp_f32_e32 v111, v111
	v_rcp_f32_e32 v107, v107
	v_rcp_f32_e32 v100, v100
	v_rcp_f32_e32 v112, v96
	v_rcp_f32_e32 v101, v101
	v_rcp_f32_e32 v113, v97
	v_rcp_f32_e32 v102, v102
	v_rcp_f32_e32 v118, v98
	v_rcp_f32_e32 v103, v103
	v_rcp_f32_e32 v119, v99
	v_addc_co_u32_e32 v117, vcc, 0, v147, vcc
	v_cvt_pk_bf16_f32 v96, v108, v109
	v_cvt_pk_bf16_f32 v97, v110, v111
	v_cvt_pk_bf16_f32 v98, v104, v105
	v_cvt_pk_bf16_f32 v99, v106, v107
	v_cvt_pk_bf16_f32 v100, v100, v101
	v_cvt_pk_bf16_f32 v101, v102, v103
	v_cvt_pk_bf16_f32 v102, v112, v113
	v_cvt_pk_bf16_f32 v103, v118, v119
	global_store_dwordx4 v[116:117], v[96:99], off nt
	global_store_dwordx4 v[114:115], v[100:103], off offset:256 nt
	s_nop 0
	v_lshl_add_u64 v[98:99], v[146:147], 0, s[18:19]
	v_add_co_u32_e32 v100, vcc, s77, v146
	v_mov_b32_e32 v96, v246
	v_pk_mul_f32 v[94:95], v[94:95], v[96:97] op_sel_hi:[1,0]
	v_pk_mul_f32 v[92:93], v[92:93], v[96:97] op_sel_hi:[1,0]
	v_pk_mul_f32 v[90:91], v[90:91], v[96:97] op_sel_hi:[1,0]
	v_pk_mul_f32 v[88:89], v[88:89], v[96:97] op_sel_hi:[1,0]
	v_pk_mul_f32 v[86:87], v[86:87], v[96:97] op_sel_hi:[1,0]
	v_pk_mul_f32 v[84:85], v[84:85], v[96:97] op_sel_hi:[1,0]
	v_pk_mul_f32 v[82:83], v[82:83], v[96:97] op_sel_hi:[1,0]
	v_pk_mul_f32 v[80:81], v[80:81], v[96:97] op_sel_hi:[1,0]
	v_mul_f32_e32 v92, 0xbfb8aa3b, v92
	v_mul_f32_e32 v88, 0xbfb8aa3b, v88
	v_mul_f32_e32 v93, 0xbfb8aa3b, v93
	v_mul_f32_e32 v89, 0xbfb8aa3b, v89
	v_mul_f32_e32 v94, 0xbfb8aa3b, v94
	v_mul_f32_e32 v90, 0xbfb8aa3b, v90
	v_mul_f32_e32 v95, 0xbfb8aa3b, v95
	v_mul_f32_e32 v91, 0xbfb8aa3b, v91
	v_mul_f32_e32 v84, 0xbfb8aa3b, v84
	v_mul_f32_e32 v80, 0xbfb8aa3b, v80
	v_mul_f32_e32 v85, 0xbfb8aa3b, v85
	v_mul_f32_e32 v81, 0xbfb8aa3b, v81
	v_mul_f32_e32 v86, 0xbfb8aa3b, v86
	v_mul_f32_e32 v82, 0xbfb8aa3b, v82
	v_mul_f32_e32 v87, 0xbfb8aa3b, v87
	v_mul_f32_e32 v83, 0xbfb8aa3b, v83
	v_exp_f32_e32 v92, v92
	v_exp_f32_e32 v88, v88
	v_exp_f32_e32 v93, v93
	v_exp_f32_e32 v89, v89
	v_exp_f32_e32 v94, v94
	v_exp_f32_e32 v90, v90
	v_exp_f32_e32 v95, v95
	v_exp_f32_e32 v91, v91
	v_exp_f32_e32 v84, v84
	v_exp_f32_e32 v80, v80
	v_exp_f32_e32 v85, v85
	v_exp_f32_e32 v81, v81
	v_exp_f32_e32 v86, v86
	v_exp_f32_e32 v82, v82
	v_exp_f32_e32 v87, v87
	v_exp_f32_e32 v83, v83
	v_add_f32_e32 v92, 1.0, v92
	v_add_f32_e32 v88, 1.0, v88
	v_add_f32_e32 v93, 1.0, v93
	v_add_f32_e32 v89, 1.0, v89
	v_add_f32_e32 v94, 1.0, v94
	v_add_f32_e32 v90, 1.0, v90
	v_add_f32_e32 v95, 1.0, v95
	v_add_f32_e32 v91, 1.0, v91
	v_add_f32_e32 v84, 1.0, v84
	v_add_f32_e32 v80, 1.0, v80
	v_add_f32_e32 v85, 1.0, v85
	v_add_f32_e32 v81, 1.0, v81
	v_add_f32_e32 v86, 1.0, v86
	v_add_f32_e32 v82, 1.0, v82
	v_add_f32_e32 v87, 1.0, v87
	v_add_f32_e32 v83, 1.0, v83
	v_rcp_f32_e32 v92, v92
	v_rcp_f32_e32 v88, v88
	v_rcp_f32_e32 v93, v93
	v_rcp_f32_e32 v89, v89
	v_rcp_f32_e32 v94, v94
	v_rcp_f32_e32 v90, v90
	v_rcp_f32_e32 v95, v95
	v_rcp_f32_e32 v91, v91
	v_rcp_f32_e32 v84, v84
	v_rcp_f32_e32 v96, v80
	v_rcp_f32_e32 v85, v85
	v_rcp_f32_e32 v97, v81
	v_rcp_f32_e32 v86, v86
	v_rcp_f32_e32 v102, v82
	v_rcp_f32_e32 v87, v87
	v_rcp_f32_e32 v103, v83
	v_addc_co_u32_e32 v101, vcc, 0, v147, vcc
	v_cvt_pk_bf16_f32 v80, v92, v93
	v_cvt_pk_bf16_f32 v81, v94, v95
	v_cvt_pk_bf16_f32 v82, v88, v89
	v_cvt_pk_bf16_f32 v83, v90, v91
	v_cvt_pk_bf16_f32 v84, v84, v85
	v_cvt_pk_bf16_f32 v85, v86, v87
	v_cvt_pk_bf16_f32 v86, v96, v97
	v_cvt_pk_bf16_f32 v87, v102, v103
	global_store_dwordx4 v[100:101], v[80:83], off nt
	global_store_dwordx4 v[98:99], v[84:87], off offset:256 nt
	s_nop 0
	v_lshl_add_u64 v[82:83], v[146:147], 0, s[22:23]
	v_add_co_u32_e32 v84, vcc, s78, v146
	v_mov_b32_e32 v80, v247
	v_pk_mul_f32 v[78:79], v[78:79], v[80:81] op_sel_hi:[1,0]
	v_pk_mul_f32 v[76:77], v[76:77], v[80:81] op_sel_hi:[1,0]
	v_pk_mul_f32 v[74:75], v[74:75], v[80:81] op_sel_hi:[1,0]
	v_pk_mul_f32 v[72:73], v[72:73], v[80:81] op_sel_hi:[1,0]
	v_pk_mul_f32 v[70:71], v[70:71], v[80:81] op_sel_hi:[1,0]
	v_pk_mul_f32 v[68:69], v[68:69], v[80:81] op_sel_hi:[1,0]
	v_pk_mul_f32 v[66:67], v[66:67], v[80:81] op_sel_hi:[1,0]
	v_pk_mul_f32 v[64:65], v[64:65], v[80:81] op_sel_hi:[1,0]
	v_mul_f32_e32 v76, 0xbfb8aa3b, v76
	v_mul_f32_e32 v72, 0xbfb8aa3b, v72
	v_mul_f32_e32 v77, 0xbfb8aa3b, v77
	v_mul_f32_e32 v73, 0xbfb8aa3b, v73
	v_mul_f32_e32 v78, 0xbfb8aa3b, v78
	v_mul_f32_e32 v74, 0xbfb8aa3b, v74
	v_mul_f32_e32 v79, 0xbfb8aa3b, v79
	v_mul_f32_e32 v75, 0xbfb8aa3b, v75
	v_mul_f32_e32 v68, 0xbfb8aa3b, v68
	v_mul_f32_e32 v64, 0xbfb8aa3b, v64
	v_mul_f32_e32 v69, 0xbfb8aa3b, v69
	v_mul_f32_e32 v65, 0xbfb8aa3b, v65
	v_mul_f32_e32 v70, 0xbfb8aa3b, v70
	v_mul_f32_e32 v66, 0xbfb8aa3b, v66
	v_mul_f32_e32 v71, 0xbfb8aa3b, v71
	v_mul_f32_e32 v67, 0xbfb8aa3b, v67
	v_exp_f32_e32 v76, v76
	v_exp_f32_e32 v72, v72
	v_exp_f32_e32 v77, v77
	v_exp_f32_e32 v73, v73
	v_exp_f32_e32 v78, v78
	v_exp_f32_e32 v74, v74
	v_exp_f32_e32 v79, v79
	v_exp_f32_e32 v75, v75
	v_exp_f32_e32 v68, v68
	v_exp_f32_e32 v64, v64
	v_exp_f32_e32 v69, v69
	v_exp_f32_e32 v65, v65
	v_exp_f32_e32 v70, v70
	v_exp_f32_e32 v66, v66
	v_exp_f32_e32 v71, v71
	v_exp_f32_e32 v67, v67
	v_add_f32_e32 v76, 1.0, v76
	v_add_f32_e32 v72, 1.0, v72
	v_add_f32_e32 v77, 1.0, v77
; __device__ __forceinline__ u32x4 pack8(f32x4 v0, f32x4 v1) { u32x4 w; w.x = cvt_pk_bf16(v0[0], v0[1]); w.y = cvt_pk_bf16(v0[2], v0[3]); w.z = cvt_pk_bf16(v1[0], v1[1]); w.w = cvt_pk_bf16(v1[2], v1[3]); return w; }
; __device__ __forceinline__ float sigm(float x) { return __builtin_amdgcn_rcpf(1.0f + __expf(-x)); }
;     __device__ __forceinline__ void operator()(f32x4 (&acc)[2][2][4][2], const Unit& u, int wr, int wc, int fr_, int fq_) const {
;     ...
;             for (int m = 0; m < 4; ++m) { const int row = row0 + ai * HALF + m * 16; const float rs = rstd[row]; bf16_t* rowp = GAB + (size_t)row * 4096 + col0;
; #pragma unroll
;                 for (int bj = 0; bj < 2; ++bj) { f32x4 v0 = acc[ai][bj][m][0] * rs, v1 = acc[ai][bj][m][1] * rs;
; #pragma unroll
;                     for (int i = 0; i < 4; ++i) { v0[i] = sigm(v0[i]); v1[i] = sigm(v1[i]); }
;                     *(u32x4*)(rowp + bj * HALF) = pack8(v0, v1); } }
	v_add_f32_e32 v73, 1.0, v73
	v_add_f32_e32 v78, 1.0, v78
	v_add_f32_e32 v74, 1.0, v74
	v_add_f32_e32 v79, 1.0, v79
	v_add_f32_e32 v75, 1.0, v75
	v_add_f32_e32 v68, 1.0, v68
	v_add_f32_e32 v64, 1.0, v64
	v_add_f32_e32 v69, 1.0, v69
	v_add_f32_e32 v65, 1.0, v65
	v_add_f32_e32 v70, 1.0, v70
	v_add_f32_e32 v66, 1.0, v66
	v_add_f32_e32 v71, 1.0, v71
	v_add_f32_e32 v67, 1.0, v67
	v_rcp_f32_e32 v76, v76
	v_rcp_f32_e32 v72, v72
	v_rcp_f32_e32 v77, v77
	v_rcp_f32_e32 v73, v73
	v_rcp_f32_e32 v78, v78
	v_rcp_f32_e32 v74, v74
	v_rcp_f32_e32 v79, v79
	v_rcp_f32_e32 v75, v75
	v_rcp_f32_e32 v68, v68
	v_rcp_f32_e32 v80, v64
	v_rcp_f32_e32 v69, v69
	v_rcp_f32_e32 v81, v65
	v_rcp_f32_e32 v70, v70
	v_rcp_f32_e32 v86, v66
	v_rcp_f32_e32 v71, v71
	v_rcp_f32_e32 v87, v67
	v_addc_co_u32_e32 v85, vcc, 0, v147, vcc
	v_cvt_pk_bf16_f32 v64, v76, v77
	v_cvt_pk_bf16_f32 v65, v78, v79
	v_cvt_pk_bf16_f32 v66, v72, v73
	v_cvt_pk_bf16_f32 v67, v74, v75
	v_cvt_pk_bf16_f32 v68, v68, v69
	v_cvt_pk_bf16_f32 v69, v70, v71
	v_cvt_pk_bf16_f32 v70, v80, v81
	v_cvt_pk_bf16_f32 v71, v86, v87
	global_store_dwordx4 v[84:85], v[64:67], off nt
	global_store_dwordx4 v[82:83], v[68:71], off offset:256 nt
	s_nop 0
	v_lshl_add_u64 v[66:67], v[146:147], 0, s[36:37]
	v_add_co_u32_e32 v68, vcc, s79, v146
	v_mov_b32_e32 v64, v248
	v_pk_mul_f32 v[62:63], v[62:63], v[64:65] op_sel_hi:[1,0]
	v_pk_mul_f32 v[60:61], v[60:61], v[64:65] op_sel_hi:[1,0]
	v_pk_mul_f32 v[58:59], v[58:59], v[64:65] op_sel_hi:[1,0]
	v_pk_mul_f32 v[56:57], v[56:57], v[64:65] op_sel_hi:[1,0]
	v_pk_mul_f32 v[54:55], v[54:55], v[64:65] op_sel_hi:[1,0]
	v_pk_mul_f32 v[52:53], v[52:53], v[64:65] op_sel_hi:[1,0]
	v_pk_mul_f32 v[50:51], v[50:51], v[64:65] op_sel_hi:[1,0]
	v_pk_mul_f32 v[48:49], v[48:49], v[64:65] op_sel_hi:[1,0]
	v_mul_f32_e32 v60, 0xbfb8aa3b, v60
	v_mul_f32_e32 v56, 0xbfb8aa3b, v56
	v_mul_f32_e32 v61, 0xbfb8aa3b, v61
	v_mul_f32_e32 v57, 0xbfb8aa3b, v57
	v_mul_f32_e32 v62, 0xbfb8aa3b, v62
	v_mul_f32_e32 v58, 0xbfb8aa3b, v58
	v_mul_f32_e32 v63, 0xbfb8aa3b, v63
	v_mul_f32_e32 v59, 0xbfb8aa3b, v59
	v_mul_f32_e32 v52, 0xbfb8aa3b, v52
	v_mul_f32_e32 v48, 0xbfb8aa3b, v48
	v_mul_f32_e32 v53, 0xbfb8aa3b, v53
	v_mul_f32_e32 v49, 0xbfb8aa3b, v49
	v_mul_f32_e32 v54, 0xbfb8aa3b, v54
	v_mul_f32_e32 v50, 0xbfb8aa3b, v50
	v_mul_f32_e32 v55, 0xbfb8aa3b, v55
	v_mul_f32_e32 v51, 0xbfb8aa3b, v51
	v_exp_f32_e32 v60, v60
	v_exp_f32_e32 v56, v56
	v_exp_f32_e32 v61, v61
	v_exp_f32_e32 v57, v57
	v_exp_f32_e32 v62, v62
	v_exp_f32_e32 v58, v58
	v_exp_f32_e32 v63, v63
	v_exp_f32_e32 v59, v59
	v_exp_f32_e32 v52, v52
	v_exp_f32_e32 v48, v48
	v_exp_f32_e32 v53, v53
	v_exp_f32_e32 v49, v49
	v_exp_f32_e32 v54, v54
	v_exp_f32_e32 v50, v50
	v_exp_f32_e32 v55, v55
	v_exp_f32_e32 v51, v51
	v_add_f32_e32 v60, 1.0, v60
	v_add_f32_e32 v56, 1.0, v56
	v_add_f32_e32 v61, 1.0, v61
	v_add_f32_e32 v57, 1.0, v57
	v_add_f32_e32 v62, 1.0, v62
	v_add_f32_e32 v58, 1.0, v58
	v_add_f32_e32 v63, 1.0, v63
	v_add_f32_e32 v59, 1.0, v59
	v_add_f32_e32 v52, 1.0, v52
	v_add_f32_e32 v48, 1.0, v48
	v_add_f32_e32 v53, 1.0, v53
	v_add_f32_e32 v49, 1.0, v49
	v_add_f32_e32 v54, 1.0, v54
	v_add_f32_e32 v50, 1.0, v50
	v_add_f32_e32 v55, 1.0, v55
	v_add_f32_e32 v51, 1.0, v51
	v_rcp_f32_e32 v60, v60
	v_rcp_f32_e32 v56, v56
	v_rcp_f32_e32 v61, v61
	v_rcp_f32_e32 v57, v57
	v_rcp_f32_e32 v62, v62
	v_rcp_f32_e32 v58, v58
	v_rcp_f32_e32 v63, v63
	v_rcp_f32_e32 v59, v59
	v_rcp_f32_e32 v52, v52
	v_rcp_f32_e32 v64, v48
	v_rcp_f32_e32 v53, v53
	v_rcp_f32_e32 v65, v49
	v_rcp_f32_e32 v54, v54
	v_rcp_f32_e32 v70, v50
	v_rcp_f32_e32 v55, v55
	v_rcp_f32_e32 v71, v51
	v_addc_co_u32_e32 v69, vcc, 0, v147, vcc
	v_cvt_pk_bf16_f32 v48, v60, v61
	v_cvt_pk_bf16_f32 v49, v62, v63
	v_cvt_pk_bf16_f32 v50, v56, v57
	v_cvt_pk_bf16_f32 v51, v58, v59
	v_cvt_pk_bf16_f32 v52, v52, v53
	v_cvt_pk_bf16_f32 v53, v54, v55
	v_cvt_pk_bf16_f32 v54, v64, v65
	v_cvt_pk_bf16_f32 v55, v70, v71
	global_store_dwordx4 v[68:69], v[48:51], off nt
	global_store_dwordx4 v[66:67], v[52:55], off offset:256 nt
	s_nop 0
	v_lshl_add_u64 v[50:51], v[146:147], 0, s[38:39]
	v_add_co_u32_e32 v52, vcc, s80, v146
	v_mov_b32_e32 v48, v249
	v_pk_mul_f32 v[46:47], v[46:47], v[48:49] op_sel_hi:[1,0]
	v_pk_mul_f32 v[44:45], v[44:45], v[48:49] op_sel_hi:[1,0]
	v_pk_mul_f32 v[42:43], v[42:43], v[48:49] op_sel_hi:[1,0]
	v_pk_mul_f32 v[40:41], v[40:41], v[48:49] op_sel_hi:[1,0]
	v_pk_mul_f32 v[38:39], v[38:39], v[48:49] op_sel_hi:[1,0]
	v_pk_mul_f32 v[36:37], v[36:37], v[48:49] op_sel_hi:[1,0]
	v_pk_mul_f32 v[34:35], v[34:35], v[48:49] op_sel_hi:[1,0]
	v_pk_mul_f32 v[32:33], v[32:33], v[48:49] op_sel_hi:[1,0]
	v_mul_f32_e32 v44, 0xbfb8aa3b, v44
	v_mul_f32_e32 v40, 0xbfb8aa3b, v40
	v_mul_f32_e32 v45, 0xbfb8aa3b, v45
	v_mul_f32_e32 v41, 0xbfb8aa3b, v41
	v_mul_f32_e32 v46, 0xbfb8aa3b, v46
	v_mul_f32_e32 v42, 0xbfb8aa3b, v42
	v_mul_f32_e32 v47, 0xbfb8aa3b, v47
	v_mul_f32_e32 v43, 0xbfb8aa3b, v43
	v_mul_f32_e32 v36, 0xbfb8aa3b, v36
	v_mul_f32_e32 v32, 0xbfb8aa3b, v32
	v_mul_f32_e32 v37, 0xbfb8aa3b, v37
	v_mul_f32_e32 v33, 0xbfb8aa3b, v33
	v_mul_f32_e32 v38, 0xbfb8aa3b, v38
	v_mul_f32_e32 v34, 0xbfb8aa3b, v34
	v_mul_f32_e32 v39, 0xbfb8aa3b, v39
	v_mul_f32_e32 v35, 0xbfb8aa3b, v35
	v_exp_f32_e32 v44, v44
	v_exp_f32_e32 v40, v40
	v_exp_f32_e32 v45, v45
	v_exp_f32_e32 v41, v41
	v_exp_f32_e32 v46, v46
	v_exp_f32_e32 v42, v42
	v_exp_f32_e32 v47, v47
	v_exp_f32_e32 v43, v43
	v_exp_f32_e32 v36, v36
	v_exp_f32_e32 v32, v32
	v_exp_f32_e32 v37, v37
	v_exp_f32_e32 v33, v33
	v_exp_f32_e32 v38, v38
	v_exp_f32_e32 v34, v34
	v_exp_f32_e32 v39, v39
	v_exp_f32_e32 v35, v35
	v_add_f32_e32 v44, 1.0, v44
	v_add_f32_e32 v40, 1.0, v40
	v_add_f32_e32 v45, 1.0, v45
; __device__ __forceinline__ u32x4 pack8(f32x4 v0, f32x4 v1) { u32x4 w; w.x = cvt_pk_bf16(v0[0], v0[1]); w.y = cvt_pk_bf16(v0[2], v0[3]); w.z = cvt_pk_bf16(v1[0], v1[1]); w.w = cvt_pk_bf16(v1[2], v1[3]); return w; }
; __device__ __forceinline__ float sigm(float x) { return __builtin_amdgcn_rcpf(1.0f + __expf(-x)); }
;     __device__ __forceinline__ void operator()(f32x4 (&acc)[2][2][4][2], const Unit& u, int wr, int wc, int fr_, int fq_) const {
;     ...
;             for (int m = 0; m < 4; ++m) { const int row = row0 + ai * HALF + m * 16; const float rs = rstd[row]; bf16_t* rowp = GAB + (size_t)row * 4096 + col0;
; #pragma unroll
;                 for (int bj = 0; bj < 2; ++bj) { f32x4 v0 = acc[ai][bj][m][0] * rs, v1 = acc[ai][bj][m][1] * rs;
; #pragma unroll
;                     for (int i = 0; i < 4; ++i) { v0[i] = sigm(v0[i]); v1[i] = sigm(v1[i]); }
;                     *(u32x4*)(rowp + bj * HALF) = pack8(v0, v1); } }
	v_add_f32_e32 v41, 1.0, v41
	v_add_f32_e32 v46, 1.0, v46
	v_add_f32_e32 v42, 1.0, v42
	v_add_f32_e32 v47, 1.0, v47
	v_add_f32_e32 v43, 1.0, v43
	v_add_f32_e32 v36, 1.0, v36
	v_add_f32_e32 v32, 1.0, v32
	v_add_f32_e32 v37, 1.0, v37
	v_add_f32_e32 v33, 1.0, v33
	v_add_f32_e32 v38, 1.0, v38
	v_add_f32_e32 v34, 1.0, v34
	v_add_f32_e32 v39, 1.0, v39
	v_add_f32_e32 v35, 1.0, v35
	v_rcp_f32_e32 v44, v44
	v_rcp_f32_e32 v40, v40
	v_rcp_f32_e32 v45, v45
	v_rcp_f32_e32 v41, v41
	v_rcp_f32_e32 v46, v46
	v_rcp_f32_e32 v42, v42
	v_rcp_f32_e32 v47, v47
	v_rcp_f32_e32 v43, v43
	v_rcp_f32_e32 v36, v36
	v_rcp_f32_e32 v48, v32
	v_rcp_f32_e32 v37, v37
	v_rcp_f32_e32 v49, v33
	v_rcp_f32_e32 v38, v38
	v_rcp_f32_e32 v54, v34
	v_rcp_f32_e32 v39, v39
	v_rcp_f32_e32 v55, v35
	v_addc_co_u32_e32 v53, vcc, 0, v147, vcc
	v_cvt_pk_bf16_f32 v32, v44, v45
	v_cvt_pk_bf16_f32 v33, v46, v47
	v_cvt_pk_bf16_f32 v34, v40, v41
	v_cvt_pk_bf16_f32 v35, v42, v43
	v_cvt_pk_bf16_f32 v36, v36, v37
	v_cvt_pk_bf16_f32 v37, v38, v39
	v_cvt_pk_bf16_f32 v38, v48, v49
	v_cvt_pk_bf16_f32 v39, v54, v55
	global_store_dwordx4 v[52:53], v[32:35], off nt
	global_store_dwordx4 v[50:51], v[36:39], off offset:256 nt
	s_nop 0
	v_lshl_add_u64 v[34:35], v[146:147], 0, s[40:41]
	v_add_co_u32_e32 v36, vcc, s81, v146
	v_mov_b32_e32 v32, v250
	v_pk_mul_f32 v[30:31], v[30:31], v[32:33] op_sel_hi:[1,0]
	v_pk_mul_f32 v[28:29], v[28:29], v[32:33] op_sel_hi:[1,0]
	v_pk_mul_f32 v[26:27], v[26:27], v[32:33] op_sel_hi:[1,0]
	v_pk_mul_f32 v[24:25], v[24:25], v[32:33] op_sel_hi:[1,0]
	v_pk_mul_f32 v[22:23], v[22:23], v[32:33] op_sel_hi:[1,0]
	v_pk_mul_f32 v[20:21], v[20:21], v[32:33] op_sel_hi:[1,0]
	v_pk_mul_f32 v[18:19], v[18:19], v[32:33] op_sel_hi:[1,0]
	v_pk_mul_f32 v[16:17], v[16:17], v[32:33] op_sel_hi:[1,0]
	v_mul_f32_e32 v28, 0xbfb8aa3b, v28
	v_mul_f32_e32 v24, 0xbfb8aa3b, v24
	v_mul_f32_e32 v29, 0xbfb8aa3b, v29
	v_mul_f32_e32 v25, 0xbfb8aa3b, v25
	v_mul_f32_e32 v30, 0xbfb8aa3b, v30
	v_mul_f32_e32 v26, 0xbfb8aa3b, v26
	v_mul_f32_e32 v31, 0xbfb8aa3b, v31
	v_mul_f32_e32 v27, 0xbfb8aa3b, v27
	v_mul_f32_e32 v20, 0xbfb8aa3b, v20
	v_mul_f32_e32 v16, 0xbfb8aa3b, v16
	v_mul_f32_e32 v21, 0xbfb8aa3b, v21
	v_mul_f32_e32 v17, 0xbfb8aa3b, v17
	v_mul_f32_e32 v22, 0xbfb8aa3b, v22
	v_mul_f32_e32 v18, 0xbfb8aa3b, v18
	v_mul_f32_e32 v23, 0xbfb8aa3b, v23
	v_mul_f32_e32 v19, 0xbfb8aa3b, v19
	v_exp_f32_e32 v28, v28
	v_exp_f32_e32 v24, v24
	v_exp_f32_e32 v29, v29
	v_exp_f32_e32 v25, v25
	v_exp_f32_e32 v30, v30
	v_exp_f32_e32 v26, v26
	v_exp_f32_e32 v31, v31
	v_exp_f32_e32 v27, v27
	v_exp_f32_e32 v20, v20
	v_exp_f32_e32 v16, v16
	v_exp_f32_e32 v21, v21
	v_exp_f32_e32 v17, v17
	v_exp_f32_e32 v22, v22
	v_exp_f32_e32 v18, v18
	v_exp_f32_e32 v23, v23
	v_exp_f32_e32 v19, v19
	v_add_f32_e32 v28, 1.0, v28
	v_add_f32_e32 v24, 1.0, v24
	v_add_f32_e32 v29, 1.0, v29
	v_add_f32_e32 v25, 1.0, v25
	v_add_f32_e32 v30, 1.0, v30
	v_add_f32_e32 v26, 1.0, v26
	v_add_f32_e32 v31, 1.0, v31
	v_add_f32_e32 v27, 1.0, v27
	v_add_f32_e32 v20, 1.0, v20
	v_add_f32_e32 v16, 1.0, v16
	v_add_f32_e32 v21, 1.0, v21
	v_add_f32_e32 v17, 1.0, v17
	v_add_f32_e32 v22, 1.0, v22
	v_add_f32_e32 v18, 1.0, v18
	v_add_f32_e32 v23, 1.0, v23
	v_add_f32_e32 v19, 1.0, v19
	v_rcp_f32_e32 v28, v28
	v_rcp_f32_e32 v24, v24
	v_rcp_f32_e32 v29, v29
	v_rcp_f32_e32 v25, v25
	v_rcp_f32_e32 v30, v30
	v_rcp_f32_e32 v26, v26
	v_rcp_f32_e32 v31, v31
	v_rcp_f32_e32 v27, v27
	v_rcp_f32_e32 v20, v20
	v_rcp_f32_e32 v32, v16
	v_rcp_f32_e32 v21, v21
	v_rcp_f32_e32 v33, v17
	v_rcp_f32_e32 v22, v22
	v_rcp_f32_e32 v38, v18
	v_rcp_f32_e32 v23, v23
	v_rcp_f32_e32 v39, v19
	v_addc_co_u32_e32 v37, vcc, 0, v147, vcc
	v_cvt_pk_bf16_f32 v16, v28, v29
	v_cvt_pk_bf16_f32 v17, v30, v31
	v_cvt_pk_bf16_f32 v18, v24, v25
	v_cvt_pk_bf16_f32 v19, v26, v27
	v_cvt_pk_bf16_f32 v20, v20, v21
	v_cvt_pk_bf16_f32 v21, v22, v23
	v_cvt_pk_bf16_f32 v22, v32, v33
	v_cvt_pk_bf16_f32 v23, v38, v39
	global_store_dwordx4 v[36:37], v[16:19], off nt
	global_store_dwordx4 v[34:35], v[20:23], off offset:256 nt
	s_nop 0
	s_andn2_b64 vcc, exec, s[4:5]
	v_add_co_u32_e64 v20, s[0:1], s82, v146
	v_lshl_add_u64 v[18:19], v[146:147], 0, s[42:43]
	s_nop 0
	v_addc_co_u32_e64 v21, s[0:1], 0, v147, s[0:1]
	s_mov_b64 s[0:1], -1
	v_mov_b32_e32 v16, v251
	v_pk_mul_f32 v[14:15], v[14:15], v[16:17] op_sel_hi:[1,0]
	v_pk_mul_f32 v[12:13], v[12:13], v[16:17] op_sel_hi:[1,0]
	v_pk_mul_f32 v[10:11], v[10:11], v[16:17] op_sel_hi:[1,0]
	v_pk_mul_f32 v[8:9], v[8:9], v[16:17] op_sel_hi:[1,0]
	v_pk_mul_f32 v[6:7], v[6:7], v[16:17] op_sel_hi:[1,0]
	v_pk_mul_f32 v[4:5], v[4:5], v[16:17] op_sel_hi:[1,0]
	v_pk_mul_f32 v[2:3], v[2:3], v[16:17] op_sel_hi:[1,0]
	v_pk_mul_f32 v[0:1], v[0:1], v[16:17] op_sel_hi:[1,0]
	v_mul_f32_e32 v12, 0xbfb8aa3b, v12
	v_mul_f32_e32 v8, 0xbfb8aa3b, v8
	v_mul_f32_e32 v13, 0xbfb8aa3b, v13
	v_mul_f32_e32 v9, 0xbfb8aa3b, v9
	v_mul_f32_e32 v14, 0xbfb8aa3b, v14
	v_mul_f32_e32 v10, 0xbfb8aa3b, v10
	v_mul_f32_e32 v15, 0xbfb8aa3b, v15
	v_mul_f32_e32 v11, 0xbfb8aa3b, v11
	v_mul_f32_e32 v4, 0xbfb8aa3b, v4
	v_mul_f32_e32 v0, 0xbfb8aa3b, v0
	v_mul_f32_e32 v5, 0xbfb8aa3b, v5
	v_mul_f32_e32 v1, 0xbfb8aa3b, v1
	v_mul_f32_e32 v6, 0xbfb8aa3b, v6
	v_mul_f32_e32 v2, 0xbfb8aa3b, v2
	v_mul_f32_e32 v7, 0xbfb8aa3b, v7
	v_mul_f32_e32 v3, 0xbfb8aa3b, v3
	v_exp_f32_e32 v12, v12
	v_exp_f32_e32 v8, v8
	v_exp_f32_e32 v13, v13
	v_exp_f32_e32 v9, v9
	v_exp_f32_e32 v14, v14
	v_exp_f32_e32 v10, v10
	v_exp_f32_e32 v15, v15
	v_exp_f32_e32 v11, v11
	v_exp_f32_e32 v4, v4
	v_exp_f32_e32 v0, v0
	v_exp_f32_e32 v5, v5
	v_exp_f32_e32 v1, v1
	v_exp_f32_e32 v6, v6
	v_exp_f32_e32 v2, v2
	v_exp_f32_e32 v7, v7
	v_exp_f32_e32 v3, v3
	v_add_f32_e32 v12, 1.0, v12
	v_add_f32_e32 v8, 1.0, v8
	v_add_f32_e32 v13, 1.0, v13
	v_add_f32_e32 v9, 1.0, v9
	v_add_f32_e32 v14, 1.0, v14
	v_add_f32_e32 v10, 1.0, v10
	v_add_f32_e32 v15, 1.0, v15
	v_add_f32_e32 v11, 1.0, v11
	v_add_f32_e32 v4, 1.0, v4
	v_add_f32_e32 v0, 1.0, v0
	v_add_f32_e32 v5, 1.0, v5
	v_add_f32_e32 v1, 1.0, v1
	v_add_f32_e32 v6, 1.0, v6
	v_add_f32_e32 v2, 1.0, v2
	v_add_f32_e32 v7, 1.0, v7
	v_add_f32_e32 v3, 1.0, v3
	v_rcp_f32_e32 v12, v12
	v_rcp_f32_e32 v8, v8
	v_rcp_f32_e32 v13, v13
	v_rcp_f32_e32 v9, v9
	v_rcp_f32_e32 v14, v14
	v_rcp_f32_e32 v10, v10
	v_rcp_f32_e32 v15, v15
	v_rcp_f32_e32 v11, v11
	v_rcp_f32_e32 v4, v4
	v_rcp_f32_e32 v16, v0
	v_rcp_f32_e32 v5, v5
	v_rcp_f32_e32 v17, v1
	v_rcp_f32_e32 v6, v6
	v_rcp_f32_e32 v22, v2
	v_rcp_f32_e32 v7, v7
	v_rcp_f32_e32 v23, v3
	v_cvt_pk_bf16_f32 v0, v12, v13
	v_cvt_pk_bf16_f32 v1, v14, v15
	v_cvt_pk_bf16_f32 v2, v8, v9
	v_cvt_pk_bf16_f32 v3, v10, v11
	v_cvt_pk_bf16_f32 v4, v4, v5
	v_cvt_pk_bf16_f32 v5, v6, v7
	v_cvt_pk_bf16_f32 v6, v16, v17
	v_cvt_pk_bf16_f32 v7, v22, v23
	global_store_dwordx4 v[20:21], v[0:3], off nt
	global_store_dwordx4 v[18:19], v[4:7], off offset:256 nt
	s_cbranch_vccnz .LBB0_1432
	s_andn2_b64 vcc, exec, s[10:11]
	s_cbranch_vccnz .LBB0_1431
	s_barrier
	s_branch .LBB0_1431

; __device__ __forceinline__ u32x4 pack8(f32x4 v0, f32x4 v1) { u32x4 w; w.x = cvt_pk_bf16(v0[0], v0[1]); w.y = cvt_pk_bf16(v0[2], v0[3]); w.z = cvt_pk_bf16(v1[0], v1[1]); w.w = cvt_pk_bf16(v1[2], v1[3]); return w; }
;     __device__ __forceinline__ void operator()(f32x4 (&acc)[2][2][4][2], const Unit& u, int wr, int wc, int fr_, int fq_) const {
;     ...
;         for (int ai = 0; ai < 2; ++ai)
; #pragma unroll
;             for (int m = 0; m < 4; ++m) { bf16_t* rowp = O + (size_t)(row0 + ai * HALF + m * 16) * 2048 + col0;
; #pragma unroll
;                 for (int bj = 0; bj < 2; ++bj) *(u32x4*)(rowp + bj * HALF) = pack8(acc[ai][bj][m][0], acc[ai][bj][m][1]); }
.LBB0_1463:
	v_mov_b32_e32 v152, v150
	v_mov_b32_e32 v153, v151
	s_lshl_b32 s42, s42, 8
	s_add_i32 s42, s42, s68
	v_add_u32_e32 v152, s42, v152
	s_lshl_b32 s42, s80, 8
	s_or_b32 s42, s42, s69
	v_lshl_add_u32 v154, v153, 3, s42
	v_ashrrev_i32_e32 v153, 31, v152
	v_lshlrev_b64 v[152:153], 12, v[152:153]
	v_ashrrev_i32_e32 v155, 31, v154
	v_lshl_add_u64 v[152:153], s[8:9], 0, v[152:153]
	v_lshl_add_u64 v[152:153], v[154:155], 1, v[152:153]
	v_cvt_pk_bf16_f32 v108, v108, v109
	v_cvt_pk_bf16_f32 v109, v110, v111
	v_cvt_pk_bf16_f32 v110, v104, v105
	v_cvt_pk_bf16_f32 v111, v106, v107
	global_store_dwordx4 v[152:153], v[108:111], off offset:256 nt
	v_cvt_pk_bf16_f32 v92, v92, v93
	v_cvt_pk_bf16_f32 v93, v94, v95
	v_add_co_u32_e32 v110, vcc, s67, v152
	v_lshl_add_u64 v[108:109], v[152:153], 0, s[14:15]
	s_nop 0
	v_addc_co_u32_e32 v111, vcc, 0, v153, vcc
	v_cvt_pk_bf16_f32 v94, v88, v89
	v_cvt_pk_bf16_f32 v95, v90, v91
	global_store_dwordx4 v[108:109], v[92:95], off offset:256 nt
	v_cvt_pk_bf16_f32 v76, v76, v77
	v_cvt_pk_bf16_f32 v77, v78, v79
	v_add_co_u32_e32 v94, vcc, s74, v152
	v_lshl_add_u64 v[92:93], v[152:153], 0, s[16:17]
	s_nop 0
	v_addc_co_u32_e32 v95, vcc, 0, v153, vcc
	v_cvt_pk_bf16_f32 v78, v72, v73
	v_cvt_pk_bf16_f32 v79, v74, v75
	global_store_dwordx4 v[92:93], v[76:79], off offset:256 nt
	v_cvt_pk_bf16_f32 v60, v60, v61
	v_cvt_pk_bf16_f32 v61, v62, v63
	v_add_co_u32_e32 v78, vcc, s75, v152
	v_cvt_pk_bf16_f32 v62, v56, v57
	s_nop 0
	v_addc_co_u32_e32 v79, vcc, 0, v153, vcc
	v_add_co_u32_e32 v56, vcc, s76, v152
	v_cvt_pk_bf16_f32 v68, v68, v69
	v_cvt_pk_bf16_f32 v69, v70, v71
	v_cvt_pk_bf16_f32 v70, v64, v65
	v_lshl_add_u64 v[64:65], v[152:153], 0, s[22:23]
	v_addc_co_u32_e32 v57, vcc, 0, v153, vcc
	v_cvt_pk_bf16_f32 v44, v44, v45
	v_cvt_pk_bf16_f32 v45, v46, v47
	v_cvt_pk_bf16_f32 v46, v40, v41
	v_cvt_pk_bf16_f32 v47, v42, v43
	global_store_dwordx4 v[64:65], v[44:47], off offset:256 nt
	v_cvt_pk_bf16_f32 v28, v28, v29
	v_cvt_pk_bf16_f32 v29, v30, v31
	v_add_co_u32_e32 v46, vcc, s77, v152
	v_lshl_add_u64 v[44:45], v[152:153], 0, s[36:37]
	s_nop 0
	v_addc_co_u32_e32 v47, vcc, 0, v153, vcc
	v_cvt_pk_bf16_f32 v30, v24, v25
	v_cvt_pk_bf16_f32 v31, v26, v27
	global_store_dwordx4 v[44:45], v[28:31], off offset:256 nt
	v_cvt_pk_bf16_f32 v12, v12, v13
	v_cvt_pk_bf16_f32 v13, v14, v15
	v_add_co_u32_e32 v30, vcc, s78, v152
	v_lshl_add_u64 v[28:29], v[152:153], 0, s[38:39]
	s_nop 0
	v_addc_co_u32_e32 v31, vcc, 0, v153, vcc
	v_cvt_pk_bf16_f32 v14, v8, v9
	v_cvt_pk_bf16_f32 v15, v10, v11
	global_store_dwordx4 v[28:29], v[12:15], off offset:256 nt
	v_cvt_pk_bf16_f32 v124, v124, v125
	v_cvt_pk_bf16_f32 v125, v126, v127
	v_add_co_u32_e32 v14, vcc, s79, v152
	v_cvt_pk_bf16_f32 v126, v120, v121
	s_nop 0
	v_addc_co_u32_e32 v15, vcc, 0, v153, vcc
	v_cvt_pk_bf16_f32 v127, v122, v123
	v_cvt_pk_bf16_f32 v104, v116, v117
	v_cvt_pk_bf16_f32 v105, v118, v119
	v_cvt_pk_bf16_f32 v106, v112, v113
	v_cvt_pk_bf16_f32 v107, v114, v115
	v_cvt_pk_bf16_f32 v88, v100, v101
	v_cvt_pk_bf16_f32 v89, v102, v103
	v_cvt_pk_bf16_f32 v90, v96, v97
	v_cvt_pk_bf16_f32 v91, v98, v99
	v_lshl_add_u64 v[76:77], v[152:153], 0, s[18:19]
	v_cvt_pk_bf16_f32 v72, v84, v85
	v_cvt_pk_bf16_f32 v73, v86, v87
	v_cvt_pk_bf16_f32 v74, v80, v81
	v_cvt_pk_bf16_f32 v75, v82, v83
	v_cvt_pk_bf16_f32 v71, v66, v67
	v_cvt_pk_bf16_f32 v63, v58, v59
	v_cvt_pk_bf16_f32 v40, v52, v53
	v_cvt_pk_bf16_f32 v41, v54, v55
	v_cvt_pk_bf16_f32 v42, v48, v49
	v_cvt_pk_bf16_f32 v43, v50, v51
	v_cvt_pk_bf16_f32 v24, v36, v37
	v_cvt_pk_bf16_f32 v25, v38, v39
	v_cvt_pk_bf16_f32 v26, v32, v33
	v_cvt_pk_bf16_f32 v27, v34, v35
	v_lshl_add_u64 v[12:13], v[152:153], 0, s[40:41]
	v_cvt_pk_bf16_f32 v8, v20, v21
	v_cvt_pk_bf16_f32 v9, v22, v23
	v_cvt_pk_bf16_f32 v10, v16, v17
	v_cvt_pk_bf16_f32 v11, v18, v19
	v_cvt_pk_bf16_f32 v4, v4, v5
	v_cvt_pk_bf16_f32 v5, v6, v7
	v_cvt_pk_bf16_f32 v6, v0, v1
	v_cvt_pk_bf16_f32 v7, v2, v3
	s_andn2_b64 vcc, exec, s[4:5]
	s_mov_b64 s[4:5], -1
	global_store_dwordx4 v[152:153], v[124:127], off nt
	global_store_dwordx4 v[110:111], v[104:107], off nt
	global_store_dwordx4 v[94:95], v[88:91], off nt
	global_store_dwordx4 v[78:79], v[72:75], off nt
	global_store_dwordx4 v[76:77], v[68:71], off offset:256 nt
	global_store_dwordx4 v[56:57], v[60:63], off nt
	global_store_dwordx4 v[46:47], v[40:43], off nt
	global_store_dwordx4 v[30:31], v[24:27], off nt
	global_store_dwordx4 v[14:15], v[8:11], off nt
	global_store_dwordx4 v[12:13], v[4:7], off offset:256 nt
	s_cbranch_vccnz .LBB0_1452
	s_andn2_b64 vcc, exec, s[0:1]
	s_cbranch_vccnz .LBB0_1451
	s_barrier
	s_branch .LBB0_1451

; __device__ __forceinline__ u32x4 pack8(f32x4 v0, f32x4 v1) { u32x4 w; w.x = cvt_pk_bf16(v0[0], v0[1]); w.y = cvt_pk_bf16(v0[2], v0[3]); w.z = cvt_pk_bf16(v1[0], v1[1]); w.w = cvt_pk_bf16(v1[2], v1[3]); return w; }
; __device__ __forceinline__ void unpack8(u32x4 w, f32x4& v0, f32x4& v1) {
;     v0[0] = __uint_as_float(w.x << 16); v0[1] = __uint_as_float(w.x & 0xffff0000u); v0[2] = __uint_as_float(w.y << 16); v0[3] = __uint_as_float(w.y & 0xffff0000u);
;     v1[0] = __uint_as_float(w.z << 16); v1[1] = __uint_as_float(w.z & 0xffff0000u); v1[2] = __uint_as_float(w.w << 16); v1[3] = __uint_as_float(w.w & 0xffff0000u); }
;     __device__ __forceinline__ void operator()(f32x4 (&acc)[2][2][4][2], const Unit& u, int wr, int wc, int fr_, int fq_) const {
;     ...
;             for (int m = 0; m < 4; ++m) { const int row = row0 + ai * HALF + m * 16;
; #pragma unroll
;                 for (int bj = 0; bj < 2; ++bj) { const int c = col0 + bj * HALF;
;                     f32x4 ga0, ga1, gb0, gb1, p0, p1;
;                     unpack8(*(const u32x4*)(GAB + (size_t)row * 4096 + c), ga0, ga1); unpack8(*(const u32x4*)(GAB + (size_t)row * 4096 + 2048 + c), gb0, gb1);
;                     unpack8(*(const u32x4*)(PA + (size_t)row * 2048 + c), p0, p1);
;                     const f32x4 o0 = ga0 * p0 + gb0 * acc[ai][bj][m][0], o1 = ga1 * p1 + gb1 * acc[ai][bj][m][1];
;                     *(u32x4*)(O + (size_t)row * 2048 + c) = pack8(o0, o1); } }
.LBB0_1538:
	s_lshl_b32 s19, s40, 8
	v_mov_b32_e32 v146, v150
	v_mov_b32_e32 v147, v151
	s_add_i32 s19, s19, s57
	s_nop 0
	v_add_u32_e32 v148, s19, v146
	s_lshl_b32 s19, s65, 8
	s_or_b32 s19, s19, s58
	v_lshl_add_u32 v146, v147, 3, s19
	v_ashrrev_i32_e32 v149, 31, v148
	v_lshlrev_b64 v[156:157], 13, v[148:149]
	v_ashrrev_i32_e32 v147, 31, v146
	v_lshl_add_u64 v[156:157], s[26:27], 0, v[156:157]
	v_lshlrev_b64 v[146:147], 1, v[146:147]
	v_lshlrev_b64 v[168:169], 12, v[148:149]
	v_lshl_add_u64 v[172:173], v[156:157], 0, v[146:147]
	v_lshl_add_u64 v[160:161], s[8:9], 0, v[168:169]
	v_lshl_add_u64 v[170:171], v[160:161], 0, v[146:147]
	v_add_co_u32_e32 v164, vcc, s64, v172
	global_load_dwordx4 v[156:159], v[172:173], off
	global_load_dwordx4 v[160:163], v[170:171], off
	v_addc_co_u32_e32 v165, vcc, 0, v173, vcc
	global_load_dwordx4 v[164:167], v[164:165], off
	v_lshl_add_u64 v[168:169], s[10:11], 0, v[168:169]
	v_lshl_add_u64 v[174:175], v[168:169], 0, v[146:147]
	global_load_dwordx4 v[168:171], v[170:171], off offset:256
	s_waitcnt vmcnt(0)
	v_lshlrev_b32_e32 v176, 16, v156
	v_and_b32_e32 v177, 0xffff0000, v156
	v_lshlrev_b32_e32 v156, 16, v157
	v_and_b32_e32 v157, 0xffff0000, v157
	v_lshlrev_b32_e32 v178, 16, v158
	v_and_b32_e32 v179, 0xffff0000, v158
	v_lshlrev_b32_e32 v158, 16, v159
	v_and_b32_e32 v159, 0xffff0000, v159
	v_lshlrev_b32_e32 v180, 16, v160
	v_and_b32_e32 v181, 0xffff0000, v160
	v_lshlrev_b32_e32 v160, 16, v161
	v_and_b32_e32 v161, 0xffff0000, v161
	v_lshlrev_b32_e32 v182, 16, v162
	v_and_b32_e32 v183, 0xffff0000, v162
	v_lshlrev_b32_e32 v162, 16, v163
	v_and_b32_e32 v163, 0xffff0000, v163
	v_lshlrev_b32_e32 v184, 16, v164
	v_and_b32_e32 v185, 0xffff0000, v164
	v_lshlrev_b32_e32 v164, 16, v165
	v_and_b32_e32 v165, 0xffff0000, v165
	v_lshlrev_b32_e32 v186, 16, v166
	v_and_b32_e32 v187, 0xffff0000, v166
	v_lshlrev_b32_e32 v166, 16, v167
	v_and_b32_e32 v167, 0xffff0000, v167
	v_pk_mul_f32 v[176:177], v[176:177], v[180:181]
	v_pk_mul_f32 v[156:157], v[156:157], v[160:161]
	v_pk_mul_f32 v[160:161], v[178:179], v[182:183]
	v_pk_mul_f32 v[158:159], v[158:159], v[162:163]
	v_pk_fma_f32 v[126:127], v[126:127], v[164:165], v[156:157]
	v_pk_fma_f32 v[124:125], v[124:125], v[184:185], v[176:177]
	v_pk_fma_f32 v[156:157], v[122:123], v[166:167], v[158:159]
	v_pk_fma_f32 v[122:123], v[120:121], v[186:187], v[160:161]
	v_cvt_pk_bf16_f32 v120, v124, v125
	v_cvt_pk_bf16_f32 v121, v126, v127
	v_cvt_pk_bf16_f32 v122, v122, v123
	v_cvt_pk_bf16_f32 v123, v156, v157
	global_store_dwordx4 v[174:175], v[120:123], off nt
	global_load_dwordx4 v[120:123], v[172:173], off offset:256
	v_lshl_add_u64 v[124:125], v[172:173], 0, s[16:17]
	global_load_dwordx4 v[124:127], v[124:125], off offset:256
	v_add_u32_e32 v156, 16, v148
	v_ashrrev_i32_e32 v157, 31, v156
	v_lshlrev_b32_e32 v166, 16, v168
	v_and_b32_e32 v167, 0xffff0000, v168
	v_lshlrev_b32_e32 v168, 16, v169
	v_and_b32_e32 v169, 0xffff0000, v169
	v_lshlrev_b32_e32 v172, 16, v170
	v_and_b32_e32 v173, 0xffff0000, v170
	v_lshlrev_b32_e32 v170, 16, v171
	v_and_b32_e32 v171, 0xffff0000, v171
	v_lshlrev_b64 v[158:159], 13, v[156:157]
	v_lshlrev_b64 v[160:161], 12, v[156:157]
	v_lshl_add_u64 v[156:157], s[26:27], 0, v[158:159]
	v_lshl_add_u64 v[158:159], s[8:9], 0, v[160:161]
	v_lshl_add_u64 v[162:163], v[156:157], 0, v[146:147]
	v_lshl_add_u64 v[164:165], v[158:159], 0, v[146:147]
	global_load_dwordx4 v[156:159], v[164:165], off
	s_waitcnt vmcnt(2)
	v_lshlrev_b32_e32 v176, 16, v120
	v_and_b32_e32 v177, 0xffff0000, v120
	v_lshlrev_b32_e32 v120, 16, v121
	v_and_b32_e32 v121, 0xffff0000, v121
	v_lshlrev_b32_e32 v178, 16, v122
	v_and_b32_e32 v179, 0xffff0000, v122
	v_lshlrev_b32_e32 v122, 16, v123
	v_and_b32_e32 v123, 0xffff0000, v123
	s_waitcnt vmcnt(1)
	v_lshlrev_b32_e32 v180, 16, v124
	v_and_b32_e32 v181, 0xffff0000, v124
	v_lshlrev_b32_e32 v124, 16, v125
	v_and_b32_e32 v125, 0xffff0000, v125
	v_lshlrev_b32_e32 v182, 16, v126
	v_and_b32_e32 v183, 0xffff0000, v126
	v_lshlrev_b32_e32 v126, 16, v127
	v_and_b32_e32 v127, 0xffff0000, v127
	v_pk_mul_f32 v[166:167], v[176:177], v[166:167]
	v_pk_mul_f32 v[120:121], v[120:121], v[168:169]
	v_pk_mul_f32 v[168:169], v[178:179], v[172:173]
	v_pk_mul_f32 v[122:123], v[122:123], v[170:171]
	v_pk_fma_f32 v[118:119], v[118:119], v[124:125], v[120:121]
	v_pk_fma_f32 v[116:117], v[116:117], v[180:181], v[166:167]
	v_pk_fma_f32 v[120:121], v[114:115], v[126:127], v[122:123]
	v_pk_fma_f32 v[114:115], v[112:113], v[182:183], v[168:169]
	v_cvt_pk_bf16_f32 v112, v116, v117
	v_cvt_pk_bf16_f32 v113, v118, v119
	v_cvt_pk_bf16_f32 v114, v114, v115
	v_cvt_pk_bf16_f32 v115, v120, v121
	global_store_dwordx4 v[174:175], v[112:115], off offset:256 nt
	v_add_co_u32_e32 v116, vcc, s64, v162
	global_load_dwordx4 v[112:115], v[162:163], off
	s_nop 0
	v_addc_co_u32_e32 v117, vcc, 0, v163, vcc
	global_load_dwordx4 v[116:119], v[116:117], off
	v_lshl_add_u64 v[120:121], s[10:11], 0, v[160:161]
	v_lshl_add_u64 v[124:125], v[120:121], 0, v[146:147]
	global_load_dwordx4 v[120:123], v[164:165], off offset:256
	s_waitcnt vmcnt(4)
	v_lshlrev_b32_e32 v126, 16, v156
	v_and_b32_e32 v127, 0xffff0000, v156
	v_lshlrev_b32_e32 v156, 16, v157
	v_and_b32_e32 v157, 0xffff0000, v157
	v_lshlrev_b32_e32 v160, 16, v158
	v_and_b32_e32 v161, 0xffff0000, v158
	v_lshlrev_b32_e32 v158, 16, v159
	v_and_b32_e32 v159, 0xffff0000, v159
	s_waitcnt vmcnt(2)
	v_lshlrev_b32_e32 v164, 16, v112
	v_and_b32_e32 v165, 0xffff0000, v112
	v_lshlrev_b32_e32 v112, 16, v113
	v_and_b32_e32 v113, 0xffff0000, v113
	v_lshlrev_b32_e32 v166, 16, v114
	v_and_b32_e32 v167, 0xffff0000, v114
	v_lshlrev_b32_e32 v114, 16, v115
	v_and_b32_e32 v115, 0xffff0000, v115
	s_waitcnt vmcnt(1)
; __device__ __forceinline__ u32x4 pack8(f32x4 v0, f32x4 v1) { u32x4 w; w.x = cvt_pk_bf16(v0[0], v0[1]); w.y = cvt_pk_bf16(v0[2], v0[3]); w.z = cvt_pk_bf16(v1[0], v1[1]); w.w = cvt_pk_bf16(v1[2], v1[3]); return w; }
; __device__ __forceinline__ void unpack8(u32x4 w, f32x4& v0, f32x4& v1) {
;     v0[0] = __uint_as_float(w.x << 16); v0[1] = __uint_as_float(w.x & 0xffff0000u); v0[2] = __uint_as_float(w.y << 16); v0[3] = __uint_as_float(w.y & 0xffff0000u);
;     v1[0] = __uint_as_float(w.z << 16); v1[1] = __uint_as_float(w.z & 0xffff0000u); v1[2] = __uint_as_float(w.w << 16); v1[3] = __uint_as_float(w.w & 0xffff0000u); }
;     __device__ __forceinline__ void operator()(f32x4 (&acc)[2][2][4][2], const Unit& u, int wr, int wc, int fr_, int fq_) const {
;     ...
;             for (int m = 0; m < 4; ++m) { const int row = row0 + ai * HALF + m * 16;
; #pragma unroll
;                 for (int bj = 0; bj < 2; ++bj) { const int c = col0 + bj * HALF;
;                     f32x4 ga0, ga1, gb0, gb1, p0, p1;
;                     unpack8(*(const u32x4*)(GAB + (size_t)row * 4096 + c), ga0, ga1); unpack8(*(const u32x4*)(GAB + (size_t)row * 4096 + 2048 + c), gb0, gb1);
;                     unpack8(*(const u32x4*)(PA + (size_t)row * 2048 + c), p0, p1);
;                     const f32x4 o0 = ga0 * p0 + gb0 * acc[ai][bj][m][0], o1 = ga1 * p1 + gb1 * acc[ai][bj][m][1];
;                     *(u32x4*)(O + (size_t)row * 2048 + c) = pack8(o0, o1); } }
	v_lshlrev_b32_e32 v168, 16, v116
	v_and_b32_e32 v169, 0xffff0000, v116
	v_lshlrev_b32_e32 v116, 16, v117
	v_and_b32_e32 v117, 0xffff0000, v117
	v_lshlrev_b32_e32 v170, 16, v118
	v_and_b32_e32 v171, 0xffff0000, v118
	v_lshlrev_b32_e32 v118, 16, v119
	v_and_b32_e32 v119, 0xffff0000, v119
	v_pk_mul_f32 v[126:127], v[164:165], v[126:127]
	v_pk_mul_f32 v[112:113], v[112:113], v[156:157]
	v_pk_mul_f32 v[156:157], v[166:167], v[160:161]
	v_pk_mul_f32 v[114:115], v[114:115], v[158:159]
	v_pk_fma_f32 v[110:111], v[110:111], v[116:117], v[112:113]
	v_pk_fma_f32 v[108:109], v[108:109], v[168:169], v[126:127]
	v_pk_fma_f32 v[112:113], v[106:107], v[118:119], v[114:115]
	v_pk_fma_f32 v[106:107], v[104:105], v[170:171], v[156:157]
	v_cvt_pk_bf16_f32 v104, v108, v109
	v_cvt_pk_bf16_f32 v105, v110, v111
	v_cvt_pk_bf16_f32 v106, v106, v107
	v_cvt_pk_bf16_f32 v107, v112, v113
	global_store_dwordx4 v[124:125], v[104:107], off nt
	global_load_dwordx4 v[104:107], v[162:163], off offset:256
	v_lshl_add_u64 v[108:109], v[162:163], 0, s[16:17]
	global_load_dwordx4 v[108:111], v[108:109], off offset:256
	v_add_u32_e32 v112, 32, v148
	v_ashrrev_i32_e32 v113, 31, v112
	s_waitcnt vmcnt(3)
	v_lshlrev_b32_e32 v156, 16, v120
	v_and_b32_e32 v157, 0xffff0000, v120
	v_lshlrev_b32_e32 v120, 16, v121
	v_and_b32_e32 v121, 0xffff0000, v121
	v_lshlrev_b32_e32 v158, 16, v122
	v_and_b32_e32 v159, 0xffff0000, v122
	v_lshlrev_b32_e32 v122, 16, v123
	v_and_b32_e32 v123, 0xffff0000, v123
	v_lshlrev_b64 v[114:115], 13, v[112:113]
	v_lshlrev_b64 v[116:117], 12, v[112:113]
	v_lshl_add_u64 v[112:113], s[26:27], 0, v[114:115]
	v_lshl_add_u64 v[114:115], s[8:9], 0, v[116:117]
	v_lshl_add_u64 v[118:119], v[112:113], 0, v[146:147]
	v_lshl_add_u64 v[126:127], v[114:115], 0, v[146:147]
	global_load_dwordx4 v[112:115], v[126:127], off
	s_waitcnt vmcnt(2)
	v_lshlrev_b32_e32 v160, 16, v104
	v_and_b32_e32 v161, 0xffff0000, v104
	v_lshlrev_b32_e32 v104, 16, v105
	v_and_b32_e32 v105, 0xffff0000, v105
	v_lshlrev_b32_e32 v162, 16, v106
	v_and_b32_e32 v163, 0xffff0000, v106
	v_lshlrev_b32_e32 v106, 16, v107
	v_and_b32_e32 v107, 0xffff0000, v107
	s_waitcnt vmcnt(1)
	v_lshlrev_b32_e32 v164, 16, v108
	v_and_b32_e32 v165, 0xffff0000, v108
	v_lshlrev_b32_e32 v108, 16, v109
	v_and_b32_e32 v109, 0xffff0000, v109
	v_lshlrev_b32_e32 v166, 16, v110
	v_and_b32_e32 v167, 0xffff0000, v110
	v_lshlrev_b32_e32 v110, 16, v111
	v_and_b32_e32 v111, 0xffff0000, v111
	v_pk_mul_f32 v[156:157], v[160:161], v[156:157]
	v_pk_mul_f32 v[104:105], v[104:105], v[120:121]
	v_pk_mul_f32 v[120:121], v[162:163], v[158:159]
	v_pk_mul_f32 v[106:107], v[106:107], v[122:123]
	v_pk_fma_f32 v[102:103], v[102:103], v[108:109], v[104:105]
	v_pk_fma_f32 v[100:101], v[100:101], v[164:165], v[156:157]
	v_pk_fma_f32 v[104:105], v[98:99], v[110:111], v[106:107]
	v_pk_fma_f32 v[98:99], v[96:97], v[166:167], v[120:121]
	v_cvt_pk_bf16_f32 v96, v100, v101
	v_cvt_pk_bf16_f32 v97, v102, v103
	v_cvt_pk_bf16_f32 v98, v98, v99
	v_cvt_pk_bf16_f32 v99, v104, v105
	global_store_dwordx4 v[124:125], v[96:99], off offset:256 nt
	v_add_co_u32_e32 v100, vcc, s64, v118
	global_load_dwordx4 v[96:99], v[118:119], off
	s_nop 0
	v_addc_co_u32_e32 v101, vcc, 0, v119, vcc
	global_load_dwordx4 v[100:103], v[100:101], off
	v_lshl_add_u64 v[104:105], s[10:11], 0, v[116:117]
	v_lshl_add_u64 v[108:109], v[104:105], 0, v[146:147]
	global_load_dwordx4 v[104:107], v[126:127], off offset:256
	s_waitcnt vmcnt(4)
	v_lshlrev_b32_e32 v110, 16, v112
	v_and_b32_e32 v111, 0xffff0000, v112
	v_lshlrev_b32_e32 v112, 16, v113
	v_and_b32_e32 v113, 0xffff0000, v113
	v_lshlrev_b32_e32 v116, 16, v114
	v_and_b32_e32 v117, 0xffff0000, v114
	v_lshlrev_b32_e32 v114, 16, v115
	v_and_b32_e32 v115, 0xffff0000, v115
	s_waitcnt vmcnt(2)
	v_lshlrev_b32_e32 v120, 16, v96
	v_and_b32_e32 v121, 0xffff0000, v96
	v_lshlrev_b32_e32 v96, 16, v97
	v_and_b32_e32 v97, 0xffff0000, v97
	v_lshlrev_b32_e32 v122, 16, v98
	v_and_b32_e32 v123, 0xffff0000, v98
	v_lshlrev_b32_e32 v98, 16, v99
	v_and_b32_e32 v99, 0xffff0000, v99
	s_waitcnt vmcnt(1)
	v_lshlrev_b32_e32 v124, 16, v100
	v_and_b32_e32 v125, 0xffff0000, v100
	v_lshlrev_b32_e32 v100, 16, v101
	v_and_b32_e32 v101, 0xffff0000, v101
	v_lshlrev_b32_e32 v126, 16, v102
	v_and_b32_e32 v127, 0xffff0000, v102
	v_lshlrev_b32_e32 v102, 16, v103
	v_and_b32_e32 v103, 0xffff0000, v103
	v_pk_mul_f32 v[110:111], v[120:121], v[110:111]
	v_pk_mul_f32 v[96:97], v[96:97], v[112:113]
	v_pk_mul_f32 v[112:113], v[122:123], v[116:117]
	v_pk_mul_f32 v[98:99], v[98:99], v[114:115]
	v_pk_fma_f32 v[94:95], v[94:95], v[100:101], v[96:97]
	v_pk_fma_f32 v[92:93], v[92:93], v[124:125], v[110:111]
	v_pk_fma_f32 v[96:97], v[90:91], v[102:103], v[98:99]
	v_pk_fma_f32 v[90:91], v[88:89], v[126:127], v[112:113]
	v_cvt_pk_bf16_f32 v88, v92, v93
	v_cvt_pk_bf16_f32 v89, v94, v95
	v_cvt_pk_bf16_f32 v90, v90, v91
	v_cvt_pk_bf16_f32 v91, v96, v97
	global_store_dwordx4 v[108:109], v[88:91], off nt
	global_load_dwordx4 v[88:91], v[118:119], off offset:256
	v_lshl_add_u64 v[92:93], v[118:119], 0, s[16:17]
	global_load_dwordx4 v[92:95], v[92:93], off offset:256
	v_add_u32_e32 v96, 48, v148
	v_ashrrev_i32_e32 v97, 31, v96
	s_waitcnt vmcnt(3)
	v_lshlrev_b32_e32 v112, 16, v104
	v_and_b32_e32 v113, 0xffff0000, v104
	v_lshlrev_b32_e32 v104, 16, v105
	v_and_b32_e32 v105, 0xffff0000, v105
	v_lshlrev_b32_e32 v114, 16, v106
	v_and_b32_e32 v115, 0xffff0000, v106
	v_lshlrev_b32_e32 v106, 16, v107
	v_and_b32_e32 v107, 0xffff0000, v107
	v_lshlrev_b64 v[98:99], 13, v[96:97]
	v_lshlrev_b64 v[100:101], 12, v[96:97]
	v_lshl_add_u64 v[96:97], s[26:27], 0, v[98:99]
	v_lshl_add_u64 v[98:99], s[8:9], 0, v[100:101]
	v_lshl_add_u64 v[102:103], v[96:97], 0, v[146:147]
	v_lshl_add_u64 v[110:111], v[98:99], 0, v[146:147]
	global_load_dwordx4 v[96:99], v[110:111], off
	s_waitcnt vmcnt(2)
; __device__ __forceinline__ u32x4 pack8(f32x4 v0, f32x4 v1) { u32x4 w; w.x = cvt_pk_bf16(v0[0], v0[1]); w.y = cvt_pk_bf16(v0[2], v0[3]); w.z = cvt_pk_bf16(v1[0], v1[1]); w.w = cvt_pk_bf16(v1[2], v1[3]); return w; }
; __device__ __forceinline__ void unpack8(u32x4 w, f32x4& v0, f32x4& v1) {
;     v0[0] = __uint_as_float(w.x << 16); v0[1] = __uint_as_float(w.x & 0xffff0000u); v0[2] = __uint_as_float(w.y << 16); v0[3] = __uint_as_float(w.y & 0xffff0000u);
;     v1[0] = __uint_as_float(w.z << 16); v1[1] = __uint_as_float(w.z & 0xffff0000u); v1[2] = __uint_as_float(w.w << 16); v1[3] = __uint_as_float(w.w & 0xffff0000u); }
;     __device__ __forceinline__ void operator()(f32x4 (&acc)[2][2][4][2], const Unit& u, int wr, int wc, int fr_, int fq_) const {
;     ...
;             for (int m = 0; m < 4; ++m) { const int row = row0 + ai * HALF + m * 16;
; #pragma unroll
;                 for (int bj = 0; bj < 2; ++bj) { const int c = col0 + bj * HALF;
;                     f32x4 ga0, ga1, gb0, gb1, p0, p1;
;                     unpack8(*(const u32x4*)(GAB + (size_t)row * 4096 + c), ga0, ga1); unpack8(*(const u32x4*)(GAB + (size_t)row * 4096 + 2048 + c), gb0, gb1);
;                     unpack8(*(const u32x4*)(PA + (size_t)row * 2048 + c), p0, p1);
;                     const f32x4 o0 = ga0 * p0 + gb0 * acc[ai][bj][m][0], o1 = ga1 * p1 + gb1 * acc[ai][bj][m][1];
;                     *(u32x4*)(O + (size_t)row * 2048 + c) = pack8(o0, o1); } }
	v_lshlrev_b32_e32 v116, 16, v88
	v_and_b32_e32 v117, 0xffff0000, v88
	v_lshlrev_b32_e32 v88, 16, v89
	v_and_b32_e32 v89, 0xffff0000, v89
	v_lshlrev_b32_e32 v118, 16, v90
	v_and_b32_e32 v119, 0xffff0000, v90
	v_lshlrev_b32_e32 v90, 16, v91
	v_and_b32_e32 v91, 0xffff0000, v91
	s_waitcnt vmcnt(1)
	v_lshlrev_b32_e32 v120, 16, v92
	v_and_b32_e32 v121, 0xffff0000, v92
	v_lshlrev_b32_e32 v92, 16, v93
	v_and_b32_e32 v93, 0xffff0000, v93
	v_lshlrev_b32_e32 v122, 16, v94
	v_and_b32_e32 v123, 0xffff0000, v94
	v_lshlrev_b32_e32 v94, 16, v95
	v_and_b32_e32 v95, 0xffff0000, v95
	v_pk_mul_f32 v[112:113], v[116:117], v[112:113]
	v_pk_mul_f32 v[88:89], v[88:89], v[104:105]
	v_pk_mul_f32 v[104:105], v[118:119], v[114:115]
	v_pk_mul_f32 v[90:91], v[90:91], v[106:107]
	v_pk_fma_f32 v[86:87], v[86:87], v[92:93], v[88:89]
	v_pk_fma_f32 v[84:85], v[84:85], v[120:121], v[112:113]
	v_pk_fma_f32 v[88:89], v[82:83], v[94:95], v[90:91]
	v_pk_fma_f32 v[82:83], v[80:81], v[122:123], v[104:105]
	v_cvt_pk_bf16_f32 v80, v84, v85
	v_cvt_pk_bf16_f32 v81, v86, v87
	v_cvt_pk_bf16_f32 v82, v82, v83
	v_cvt_pk_bf16_f32 v83, v88, v89
	global_store_dwordx4 v[108:109], v[80:83], off offset:256 nt
	v_add_co_u32_e32 v84, vcc, s64, v102
	global_load_dwordx4 v[80:83], v[102:103], off
	s_nop 0
	v_addc_co_u32_e32 v85, vcc, 0, v103, vcc
	global_load_dwordx4 v[84:87], v[84:85], off
	v_lshl_add_u64 v[88:89], s[10:11], 0, v[100:101]
	v_lshl_add_u64 v[92:93], v[88:89], 0, v[146:147]
	global_load_dwordx4 v[88:91], v[110:111], off offset:256
	s_waitcnt vmcnt(4)
	v_lshlrev_b32_e32 v94, 16, v96
	v_and_b32_e32 v95, 0xffff0000, v96
	v_lshlrev_b32_e32 v96, 16, v97
	v_and_b32_e32 v97, 0xffff0000, v97
	v_lshlrev_b32_e32 v100, 16, v98
	v_and_b32_e32 v101, 0xffff0000, v98
	v_lshlrev_b32_e32 v98, 16, v99
	v_and_b32_e32 v99, 0xffff0000, v99
	s_waitcnt vmcnt(2)
	v_lshlrev_b32_e32 v104, 16, v80
	v_and_b32_e32 v105, 0xffff0000, v80
	v_lshlrev_b32_e32 v80, 16, v81
	v_and_b32_e32 v81, 0xffff0000, v81
	v_lshlrev_b32_e32 v106, 16, v82
	v_and_b32_e32 v107, 0xffff0000, v82
	v_lshlrev_b32_e32 v82, 16, v83
	v_and_b32_e32 v83, 0xffff0000, v83
	s_waitcnt vmcnt(1)
	v_lshlrev_b32_e32 v108, 16, v84
	v_and_b32_e32 v109, 0xffff0000, v84
	v_lshlrev_b32_e32 v84, 16, v85
	v_and_b32_e32 v85, 0xffff0000, v85
	v_lshlrev_b32_e32 v110, 16, v86
	v_and_b32_e32 v111, 0xffff0000, v86
	v_lshlrev_b32_e32 v86, 16, v87
	v_and_b32_e32 v87, 0xffff0000, v87
	v_pk_mul_f32 v[94:95], v[104:105], v[94:95]
	v_pk_mul_f32 v[80:81], v[80:81], v[96:97]
	v_pk_mul_f32 v[96:97], v[106:107], v[100:101]
	v_pk_mul_f32 v[82:83], v[82:83], v[98:99]
	v_pk_fma_f32 v[78:79], v[78:79], v[84:85], v[80:81]
	v_pk_fma_f32 v[76:77], v[76:77], v[108:109], v[94:95]
	v_pk_fma_f32 v[80:81], v[74:75], v[86:87], v[82:83]
	v_pk_fma_f32 v[74:75], v[72:73], v[110:111], v[96:97]
	v_cvt_pk_bf16_f32 v72, v76, v77
	v_cvt_pk_bf16_f32 v73, v78, v79
	v_cvt_pk_bf16_f32 v74, v74, v75
	v_cvt_pk_bf16_f32 v75, v80, v81
	global_store_dwordx4 v[92:93], v[72:75], off nt
	global_load_dwordx4 v[72:75], v[102:103], off offset:256
	v_lshl_add_u64 v[76:77], v[102:103], 0, s[16:17]
	global_load_dwordx4 v[76:79], v[76:77], off offset:256
	v_add_u32_e32 v80, 0x80, v148
	v_ashrrev_i32_e32 v81, 31, v80
	s_waitcnt vmcnt(3)
	v_lshlrev_b32_e32 v96, 16, v88
	v_and_b32_e32 v97, 0xffff0000, v88
	v_lshlrev_b32_e32 v88, 16, v89
	v_and_b32_e32 v89, 0xffff0000, v89
	v_lshlrev_b32_e32 v98, 16, v90
	v_and_b32_e32 v99, 0xffff0000, v90
	v_lshlrev_b32_e32 v90, 16, v91
	v_and_b32_e32 v91, 0xffff0000, v91
	v_lshlrev_b64 v[82:83], 13, v[80:81]
	v_lshlrev_b64 v[84:85], 12, v[80:81]
	v_lshl_add_u64 v[80:81], s[26:27], 0, v[82:83]
	v_lshl_add_u64 v[82:83], s[8:9], 0, v[84:85]
	v_lshl_add_u64 v[86:87], v[80:81], 0, v[146:147]
	v_lshl_add_u64 v[94:95], v[82:83], 0, v[146:147]
	global_load_dwordx4 v[80:83], v[94:95], off
	s_waitcnt vmcnt(2)
	v_lshlrev_b32_e32 v100, 16, v72
	v_and_b32_e32 v101, 0xffff0000, v72
	v_lshlrev_b32_e32 v72, 16, v73
	v_and_b32_e32 v73, 0xffff0000, v73
	v_lshlrev_b32_e32 v102, 16, v74
	v_and_b32_e32 v103, 0xffff0000, v74
	v_lshlrev_b32_e32 v74, 16, v75
	v_and_b32_e32 v75, 0xffff0000, v75
	s_waitcnt vmcnt(1)
	v_lshlrev_b32_e32 v104, 16, v76
	v_and_b32_e32 v105, 0xffff0000, v76
	v_lshlrev_b32_e32 v76, 16, v77
	v_and_b32_e32 v77, 0xffff0000, v77
	v_lshlrev_b32_e32 v106, 16, v78
	v_and_b32_e32 v107, 0xffff0000, v78
	v_lshlrev_b32_e32 v78, 16, v79
	v_and_b32_e32 v79, 0xffff0000, v79
	v_pk_mul_f32 v[96:97], v[100:101], v[96:97]
	v_pk_mul_f32 v[72:73], v[72:73], v[88:89]
	v_pk_mul_f32 v[88:89], v[102:103], v[98:99]
	v_pk_mul_f32 v[74:75], v[74:75], v[90:91]
	v_pk_fma_f32 v[70:71], v[70:71], v[76:77], v[72:73]
	v_pk_fma_f32 v[68:69], v[68:69], v[104:105], v[96:97]
	v_pk_fma_f32 v[72:73], v[66:67], v[78:79], v[74:75]
	v_pk_fma_f32 v[66:67], v[64:65], v[106:107], v[88:89]
	v_cvt_pk_bf16_f32 v64, v68, v69
	v_cvt_pk_bf16_f32 v65, v70, v71
	v_cvt_pk_bf16_f32 v66, v66, v67
	v_cvt_pk_bf16_f32 v67, v72, v73
	global_store_dwordx4 v[92:93], v[64:67], off offset:256 nt
	v_add_co_u32_e32 v68, vcc, s64, v86
	global_load_dwordx4 v[64:67], v[86:87], off
	s_nop 0
	v_addc_co_u32_e32 v69, vcc, 0, v87, vcc
	global_load_dwordx4 v[68:71], v[68:69], off
	v_lshl_add_u64 v[72:73], s[10:11], 0, v[84:85]
	v_lshl_add_u64 v[76:77], v[72:73], 0, v[146:147]
	global_load_dwordx4 v[72:75], v[94:95], off offset:256
	s_waitcnt vmcnt(4)
	v_lshlrev_b32_e32 v78, 16, v80
	v_and_b32_e32 v79, 0xffff0000, v80
	v_lshlrev_b32_e32 v80, 16, v81
	v_and_b32_e32 v81, 0xffff0000, v81
	v_lshlrev_b32_e32 v84, 16, v82
	v_and_b32_e32 v85, 0xffff0000, v82
	v_lshlrev_b32_e32 v82, 16, v83
	v_and_b32_e32 v83, 0xffff0000, v83
	s_waitcnt vmcnt(2)
; __device__ __forceinline__ u32x4 pack8(f32x4 v0, f32x4 v1) { u32x4 w; w.x = cvt_pk_bf16(v0[0], v0[1]); w.y = cvt_pk_bf16(v0[2], v0[3]); w.z = cvt_pk_bf16(v1[0], v1[1]); w.w = cvt_pk_bf16(v1[2], v1[3]); return w; }
; __device__ __forceinline__ void unpack8(u32x4 w, f32x4& v0, f32x4& v1) {
;     v0[0] = __uint_as_float(w.x << 16); v0[1] = __uint_as_float(w.x & 0xffff0000u); v0[2] = __uint_as_float(w.y << 16); v0[3] = __uint_as_float(w.y & 0xffff0000u);
;     v1[0] = __uint_as_float(w.z << 16); v1[1] = __uint_as_float(w.z & 0xffff0000u); v1[2] = __uint_as_float(w.w << 16); v1[3] = __uint_as_float(w.w & 0xffff0000u); }
;     __device__ __forceinline__ void operator()(f32x4 (&acc)[2][2][4][2], const Unit& u, int wr, int wc, int fr_, int fq_) const {
;     ...
;             for (int m = 0; m < 4; ++m) { const int row = row0 + ai * HALF + m * 16;
; #pragma unroll
;                 for (int bj = 0; bj < 2; ++bj) { const int c = col0 + bj * HALF;
;                     f32x4 ga0, ga1, gb0, gb1, p0, p1;
;                     unpack8(*(const u32x4*)(GAB + (size_t)row * 4096 + c), ga0, ga1); unpack8(*(const u32x4*)(GAB + (size_t)row * 4096 + 2048 + c), gb0, gb1);
;                     unpack8(*(const u32x4*)(PA + (size_t)row * 2048 + c), p0, p1);
;                     const f32x4 o0 = ga0 * p0 + gb0 * acc[ai][bj][m][0], o1 = ga1 * p1 + gb1 * acc[ai][bj][m][1];
;                     *(u32x4*)(O + (size_t)row * 2048 + c) = pack8(o0, o1); } }
	v_lshlrev_b32_e32 v88, 16, v64
	v_and_b32_e32 v89, 0xffff0000, v64
	v_lshlrev_b32_e32 v64, 16, v65
	v_and_b32_e32 v65, 0xffff0000, v65
	v_lshlrev_b32_e32 v90, 16, v66
	v_and_b32_e32 v91, 0xffff0000, v66
	v_lshlrev_b32_e32 v66, 16, v67
	v_and_b32_e32 v67, 0xffff0000, v67
	s_waitcnt vmcnt(1)
	v_lshlrev_b32_e32 v92, 16, v68
	v_and_b32_e32 v93, 0xffff0000, v68
	v_lshlrev_b32_e32 v68, 16, v69
	v_and_b32_e32 v69, 0xffff0000, v69
	v_lshlrev_b32_e32 v94, 16, v70
	v_and_b32_e32 v95, 0xffff0000, v70
	v_lshlrev_b32_e32 v70, 16, v71
	v_and_b32_e32 v71, 0xffff0000, v71
	v_pk_mul_f32 v[78:79], v[88:89], v[78:79]
	v_pk_mul_f32 v[64:65], v[64:65], v[80:81]
	v_pk_mul_f32 v[80:81], v[90:91], v[84:85]
	v_pk_mul_f32 v[66:67], v[66:67], v[82:83]
	v_pk_fma_f32 v[62:63], v[62:63], v[68:69], v[64:65]
	v_pk_fma_f32 v[60:61], v[60:61], v[92:93], v[78:79]
	v_pk_fma_f32 v[64:65], v[58:59], v[70:71], v[66:67]
	v_pk_fma_f32 v[58:59], v[56:57], v[94:95], v[80:81]
	v_cvt_pk_bf16_f32 v56, v60, v61
	v_cvt_pk_bf16_f32 v57, v62, v63
	v_cvt_pk_bf16_f32 v58, v58, v59
	v_cvt_pk_bf16_f32 v59, v64, v65
	global_store_dwordx4 v[76:77], v[56:59], off nt
	global_load_dwordx4 v[56:59], v[86:87], off offset:256
	v_lshl_add_u64 v[60:61], v[86:87], 0, s[16:17]
	global_load_dwordx4 v[60:63], v[60:61], off offset:256
	v_add_u32_e32 v64, 0x90, v148
	v_ashrrev_i32_e32 v65, 31, v64
	s_waitcnt vmcnt(3)
	v_lshlrev_b32_e32 v80, 16, v72
	v_and_b32_e32 v81, 0xffff0000, v72
	v_lshlrev_b32_e32 v72, 16, v73
	v_and_b32_e32 v73, 0xffff0000, v73
	v_lshlrev_b32_e32 v82, 16, v74
	v_and_b32_e32 v83, 0xffff0000, v74
	v_lshlrev_b32_e32 v74, 16, v75
	v_and_b32_e32 v75, 0xffff0000, v75
	v_lshlrev_b64 v[66:67], 13, v[64:65]
	v_lshlrev_b64 v[68:69], 12, v[64:65]
	v_lshl_add_u64 v[64:65], s[26:27], 0, v[66:67]
	v_lshl_add_u64 v[66:67], s[8:9], 0, v[68:69]
	v_lshl_add_u64 v[70:71], v[64:65], 0, v[146:147]
	v_lshl_add_u64 v[78:79], v[66:67], 0, v[146:147]
	global_load_dwordx4 v[64:67], v[78:79], off
	s_waitcnt vmcnt(2)
	v_lshlrev_b32_e32 v84, 16, v56
	v_and_b32_e32 v85, 0xffff0000, v56
	v_lshlrev_b32_e32 v56, 16, v57
	v_and_b32_e32 v57, 0xffff0000, v57
	v_lshlrev_b32_e32 v86, 16, v58
	v_and_b32_e32 v87, 0xffff0000, v58
	v_lshlrev_b32_e32 v58, 16, v59
	v_and_b32_e32 v59, 0xffff0000, v59
	s_waitcnt vmcnt(1)
	v_lshlrev_b32_e32 v88, 16, v60
	v_and_b32_e32 v89, 0xffff0000, v60
	v_lshlrev_b32_e32 v60, 16, v61
	v_and_b32_e32 v61, 0xffff0000, v61
	v_lshlrev_b32_e32 v90, 16, v62
	v_and_b32_e32 v91, 0xffff0000, v62
	v_lshlrev_b32_e32 v62, 16, v63
	v_and_b32_e32 v63, 0xffff0000, v63
	v_pk_mul_f32 v[80:81], v[84:85], v[80:81]
	v_pk_mul_f32 v[56:57], v[56:57], v[72:73]
	v_pk_mul_f32 v[72:73], v[86:87], v[82:83]
	v_pk_mul_f32 v[58:59], v[58:59], v[74:75]
	v_pk_fma_f32 v[54:55], v[54:55], v[60:61], v[56:57]
	v_pk_fma_f32 v[52:53], v[52:53], v[88:89], v[80:81]
	v_pk_fma_f32 v[56:57], v[50:51], v[62:63], v[58:59]
	v_pk_fma_f32 v[50:51], v[48:49], v[90:91], v[72:73]
	v_cvt_pk_bf16_f32 v48, v52, v53
	v_cvt_pk_bf16_f32 v49, v54, v55
	v_cvt_pk_bf16_f32 v50, v50, v51
	v_cvt_pk_bf16_f32 v51, v56, v57
	global_store_dwordx4 v[76:77], v[48:51], off offset:256 nt
	v_add_co_u32_e32 v52, vcc, s64, v70
	global_load_dwordx4 v[48:51], v[70:71], off
	s_nop 0
	v_addc_co_u32_e32 v53, vcc, 0, v71, vcc
	global_load_dwordx4 v[52:55], v[52:53], off
	v_lshl_add_u64 v[56:57], s[10:11], 0, v[68:69]
	v_lshl_add_u64 v[60:61], v[56:57], 0, v[146:147]
	global_load_dwordx4 v[56:59], v[78:79], off offset:256
	s_waitcnt vmcnt(4)
	v_lshlrev_b32_e32 v62, 16, v64
	v_and_b32_e32 v63, 0xffff0000, v64
	v_lshlrev_b32_e32 v64, 16, v65
	v_and_b32_e32 v65, 0xffff0000, v65
	v_lshlrev_b32_e32 v68, 16, v66
	v_and_b32_e32 v69, 0xffff0000, v66
	v_lshlrev_b32_e32 v66, 16, v67
	v_and_b32_e32 v67, 0xffff0000, v67
	s_waitcnt vmcnt(2)
	v_lshlrev_b32_e32 v72, 16, v48
	v_and_b32_e32 v73, 0xffff0000, v48
	v_lshlrev_b32_e32 v48, 16, v49
	v_and_b32_e32 v49, 0xffff0000, v49
	v_lshlrev_b32_e32 v74, 16, v50
	v_and_b32_e32 v75, 0xffff0000, v50
	v_lshlrev_b32_e32 v50, 16, v51
	v_and_b32_e32 v51, 0xffff0000, v51
	s_waitcnt vmcnt(1)
	v_lshlrev_b32_e32 v76, 16, v52
	v_and_b32_e32 v77, 0xffff0000, v52
	v_lshlrev_b32_e32 v52, 16, v53
	v_and_b32_e32 v53, 0xffff0000, v53
	v_lshlrev_b32_e32 v78, 16, v54
	v_and_b32_e32 v79, 0xffff0000, v54
	v_lshlrev_b32_e32 v54, 16, v55
	v_and_b32_e32 v55, 0xffff0000, v55
	v_pk_mul_f32 v[62:63], v[72:73], v[62:63]
	v_pk_mul_f32 v[48:49], v[48:49], v[64:65]
	v_pk_mul_f32 v[64:65], v[74:75], v[68:69]
	v_pk_mul_f32 v[50:51], v[50:51], v[66:67]
	v_pk_fma_f32 v[46:47], v[46:47], v[52:53], v[48:49]
	v_pk_fma_f32 v[44:45], v[44:45], v[76:77], v[62:63]
	v_pk_fma_f32 v[48:49], v[42:43], v[54:55], v[50:51]
	v_pk_fma_f32 v[42:43], v[40:41], v[78:79], v[64:65]
	v_cvt_pk_bf16_f32 v40, v44, v45
	v_cvt_pk_bf16_f32 v41, v46, v47
	v_cvt_pk_bf16_f32 v42, v42, v43
	v_cvt_pk_bf16_f32 v43, v48, v49
	global_store_dwordx4 v[60:61], v[40:43], off nt
	global_load_dwordx4 v[40:43], v[70:71], off offset:256
	v_lshl_add_u64 v[44:45], v[70:71], 0, s[16:17]
	global_load_dwordx4 v[44:47], v[44:45], off offset:256
	v_add_u32_e32 v48, 0xa0, v148
	v_ashrrev_i32_e32 v49, 31, v48
	s_waitcnt vmcnt(3)
	v_lshlrev_b32_e32 v64, 16, v56
	v_and_b32_e32 v65, 0xffff0000, v56
	v_lshlrev_b32_e32 v56, 16, v57
	v_and_b32_e32 v57, 0xffff0000, v57
	v_lshlrev_b32_e32 v66, 16, v58
	v_and_b32_e32 v67, 0xffff0000, v58
	v_lshlrev_b32_e32 v58, 16, v59
	v_and_b32_e32 v59, 0xffff0000, v59
	v_lshlrev_b64 v[50:51], 13, v[48:49]
	v_lshlrev_b64 v[52:53], 12, v[48:49]
	v_lshl_add_u64 v[48:49], s[26:27], 0, v[50:51]
	v_lshl_add_u64 v[50:51], s[8:9], 0, v[52:53]
	v_lshl_add_u64 v[54:55], v[48:49], 0, v[146:147]
	v_lshl_add_u64 v[62:63], v[50:51], 0, v[146:147]
	global_load_dwordx4 v[48:51], v[62:63], off
	s_waitcnt vmcnt(2)
; __device__ __forceinline__ u32x4 pack8(f32x4 v0, f32x4 v1) { u32x4 w; w.x = cvt_pk_bf16(v0[0], v0[1]); w.y = cvt_pk_bf16(v0[2], v0[3]); w.z = cvt_pk_bf16(v1[0], v1[1]); w.w = cvt_pk_bf16(v1[2], v1[3]); return w; }
; __device__ __forceinline__ void unpack8(u32x4 w, f32x4& v0, f32x4& v1) {
;     v0[0] = __uint_as_float(w.x << 16); v0[1] = __uint_as_float(w.x & 0xffff0000u); v0[2] = __uint_as_float(w.y << 16); v0[3] = __uint_as_float(w.y & 0xffff0000u);
;     v1[0] = __uint_as_float(w.z << 16); v1[1] = __uint_as_float(w.z & 0xffff0000u); v1[2] = __uint_as_float(w.w << 16); v1[3] = __uint_as_float(w.w & 0xffff0000u); }
;     __device__ __forceinline__ void operator()(f32x4 (&acc)[2][2][4][2], const Unit& u, int wr, int wc, int fr_, int fq_) const {
;     ...
;             for (int m = 0; m < 4; ++m) { const int row = row0 + ai * HALF + m * 16;
; #pragma unroll
;                 for (int bj = 0; bj < 2; ++bj) { const int c = col0 + bj * HALF;
;                     f32x4 ga0, ga1, gb0, gb1, p0, p1;
;                     unpack8(*(const u32x4*)(GAB + (size_t)row * 4096 + c), ga0, ga1); unpack8(*(const u32x4*)(GAB + (size_t)row * 4096 + 2048 + c), gb0, gb1);
;                     unpack8(*(const u32x4*)(PA + (size_t)row * 2048 + c), p0, p1);
;                     const f32x4 o0 = ga0 * p0 + gb0 * acc[ai][bj][m][0], o1 = ga1 * p1 + gb1 * acc[ai][bj][m][1];
;                     *(u32x4*)(O + (size_t)row * 2048 + c) = pack8(o0, o1); } }
	v_lshlrev_b32_e32 v68, 16, v40
	v_and_b32_e32 v69, 0xffff0000, v40
	v_lshlrev_b32_e32 v40, 16, v41
	v_and_b32_e32 v41, 0xffff0000, v41
	v_lshlrev_b32_e32 v70, 16, v42
	v_and_b32_e32 v71, 0xffff0000, v42
	v_lshlrev_b32_e32 v42, 16, v43
	v_and_b32_e32 v43, 0xffff0000, v43
	s_waitcnt vmcnt(1)
	v_lshlrev_b32_e32 v72, 16, v44
	v_and_b32_e32 v73, 0xffff0000, v44
	v_lshlrev_b32_e32 v44, 16, v45
	v_and_b32_e32 v45, 0xffff0000, v45
	v_lshlrev_b32_e32 v74, 16, v46
	v_and_b32_e32 v75, 0xffff0000, v46
	v_lshlrev_b32_e32 v46, 16, v47
	v_and_b32_e32 v47, 0xffff0000, v47
	v_pk_mul_f32 v[64:65], v[68:69], v[64:65]
	v_pk_mul_f32 v[40:41], v[40:41], v[56:57]
	v_pk_mul_f32 v[56:57], v[70:71], v[66:67]
	v_pk_mul_f32 v[42:43], v[42:43], v[58:59]
	v_pk_fma_f32 v[38:39], v[38:39], v[44:45], v[40:41]
	v_pk_fma_f32 v[36:37], v[36:37], v[72:73], v[64:65]
	v_pk_fma_f32 v[40:41], v[34:35], v[46:47], v[42:43]
	v_pk_fma_f32 v[34:35], v[32:33], v[74:75], v[56:57]
	v_cvt_pk_bf16_f32 v32, v36, v37
	v_cvt_pk_bf16_f32 v33, v38, v39
	v_cvt_pk_bf16_f32 v34, v34, v35
	v_cvt_pk_bf16_f32 v35, v40, v41
	global_store_dwordx4 v[60:61], v[32:35], off offset:256 nt
	v_add_co_u32_e32 v36, vcc, s64, v54
	global_load_dwordx4 v[32:35], v[54:55], off
	s_nop 0
	v_addc_co_u32_e32 v37, vcc, 0, v55, vcc
	global_load_dwordx4 v[36:39], v[36:37], off
	v_lshl_add_u64 v[40:41], s[10:11], 0, v[52:53]
	v_lshl_add_u64 v[44:45], v[40:41], 0, v[146:147]
	global_load_dwordx4 v[40:43], v[62:63], off offset:256
	s_waitcnt vmcnt(4)
	v_lshlrev_b32_e32 v46, 16, v48
	v_and_b32_e32 v47, 0xffff0000, v48
	v_lshlrev_b32_e32 v48, 16, v49
	v_and_b32_e32 v49, 0xffff0000, v49
	v_lshlrev_b32_e32 v52, 16, v50
	v_and_b32_e32 v53, 0xffff0000, v50
	v_lshlrev_b32_e32 v50, 16, v51
	v_and_b32_e32 v51, 0xffff0000, v51
	s_waitcnt vmcnt(2)
	v_lshlrev_b32_e32 v56, 16, v32
	v_and_b32_e32 v57, 0xffff0000, v32
	v_lshlrev_b32_e32 v32, 16, v33
	v_and_b32_e32 v33, 0xffff0000, v33
	v_lshlrev_b32_e32 v58, 16, v34
	v_and_b32_e32 v59, 0xffff0000, v34
	v_lshlrev_b32_e32 v34, 16, v35
	v_and_b32_e32 v35, 0xffff0000, v35
	s_waitcnt vmcnt(1)
	v_lshlrev_b32_e32 v60, 16, v36
	v_and_b32_e32 v61, 0xffff0000, v36
	v_lshlrev_b32_e32 v36, 16, v37
	v_and_b32_e32 v37, 0xffff0000, v37
	v_lshlrev_b32_e32 v62, 16, v38
	v_and_b32_e32 v63, 0xffff0000, v38
	v_lshlrev_b32_e32 v38, 16, v39
	v_and_b32_e32 v39, 0xffff0000, v39
	v_pk_mul_f32 v[46:47], v[56:57], v[46:47]
	v_pk_mul_f32 v[32:33], v[32:33], v[48:49]
	v_pk_mul_f32 v[48:49], v[58:59], v[52:53]
	v_pk_mul_f32 v[34:35], v[34:35], v[50:51]
	v_pk_fma_f32 v[30:31], v[30:31], v[36:37], v[32:33]
	v_pk_fma_f32 v[28:29], v[28:29], v[60:61], v[46:47]
	v_pk_fma_f32 v[32:33], v[26:27], v[38:39], v[34:35]
	v_pk_fma_f32 v[26:27], v[24:25], v[62:63], v[48:49]
	v_cvt_pk_bf16_f32 v24, v28, v29
	v_cvt_pk_bf16_f32 v25, v30, v31
	v_cvt_pk_bf16_f32 v26, v26, v27
	v_cvt_pk_bf16_f32 v27, v32, v33
	global_store_dwordx4 v[44:45], v[24:27], off nt
	global_load_dwordx4 v[24:27], v[54:55], off offset:256
	v_lshl_add_u64 v[28:29], v[54:55], 0, s[16:17]
	global_load_dwordx4 v[28:31], v[28:29], off offset:256
	v_add_u32_e32 v32, 0xb0, v148
	v_ashrrev_i32_e32 v33, 31, v32
	s_waitcnt vmcnt(3)
	v_lshlrev_b32_e32 v48, 16, v40
	v_and_b32_e32 v49, 0xffff0000, v40
	v_lshlrev_b32_e32 v40, 16, v41
	v_and_b32_e32 v41, 0xffff0000, v41
	v_lshlrev_b32_e32 v50, 16, v42
	v_and_b32_e32 v51, 0xffff0000, v42
	v_lshlrev_b32_e32 v42, 16, v43
	v_and_b32_e32 v43, 0xffff0000, v43
	v_lshlrev_b64 v[34:35], 13, v[32:33]
	v_lshlrev_b64 v[36:37], 12, v[32:33]
	v_lshl_add_u64 v[32:33], s[26:27], 0, v[34:35]
	v_lshl_add_u64 v[34:35], s[8:9], 0, v[36:37]
	v_lshl_add_u64 v[38:39], v[32:33], 0, v[146:147]
	v_lshl_add_u64 v[46:47], v[34:35], 0, v[146:147]
	global_load_dwordx4 v[32:35], v[46:47], off
	s_waitcnt vmcnt(2)
	v_lshlrev_b32_e32 v52, 16, v24
	v_and_b32_e32 v53, 0xffff0000, v24
	v_lshlrev_b32_e32 v24, 16, v25
	v_and_b32_e32 v25, 0xffff0000, v25
	v_lshlrev_b32_e32 v54, 16, v26
	v_and_b32_e32 v55, 0xffff0000, v26
	v_lshlrev_b32_e32 v26, 16, v27
	v_and_b32_e32 v27, 0xffff0000, v27
	s_waitcnt vmcnt(1)
; __device__ __forceinline__ u32x4 pack8(f32x4 v0, f32x4 v1) { u32x4 w; w.x = cvt_pk_bf16(v0[0], v0[1]); w.y = cvt_pk_bf16(v0[2], v0[3]); w.z = cvt_pk_bf16(v1[0], v1[1]); w.w = cvt_pk_bf16(v1[2], v1[3]); return w; }
; __device__ __forceinline__ void unpack8(u32x4 w, f32x4& v0, f32x4& v1) {
;     v0[0] = __uint_as_float(w.x << 16); v0[1] = __uint_as_float(w.x & 0xffff0000u); v0[2] = __uint_as_float(w.y << 16); v0[3] = __uint_as_float(w.y & 0xffff0000u);
;     v1[0] = __uint_as_float(w.z << 16); v1[1] = __uint_as_float(w.z & 0xffff0000u); v1[2] = __uint_as_float(w.w << 16); v1[3] = __uint_as_float(w.w & 0xffff0000u); }
;     __device__ __forceinline__ void operator()(f32x4 (&acc)[2][2][4][2], const Unit& u, int wr, int wc, int fr_, int fq_) const {
;     ...
;             for (int m = 0; m < 4; ++m) { const int row = row0 + ai * HALF + m * 16;
; #pragma unroll
;                 for (int bj = 0; bj < 2; ++bj) { const int c = col0 + bj * HALF;
;                     f32x4 ga0, ga1, gb0, gb1, p0, p1;
;                     unpack8(*(const u32x4*)(GAB + (size_t)row * 4096 + c), ga0, ga1); unpack8(*(const u32x4*)(GAB + (size_t)row * 4096 + 2048 + c), gb0, gb1);
;                     unpack8(*(const u32x4*)(PA + (size_t)row * 2048 + c), p0, p1);
;                     const f32x4 o0 = ga0 * p0 + gb0 * acc[ai][bj][m][0], o1 = ga1 * p1 + gb1 * acc[ai][bj][m][1];
;                     *(u32x4*)(O + (size_t)row * 2048 + c) = pack8(o0, o1); } }
	v_lshlrev_b32_e32 v56, 16, v28
	v_and_b32_e32 v57, 0xffff0000, v28
	v_lshlrev_b32_e32 v28, 16, v29
	v_and_b32_e32 v29, 0xffff0000, v29
	v_lshlrev_b32_e32 v58, 16, v30
	v_and_b32_e32 v59, 0xffff0000, v30
	v_lshlrev_b32_e32 v30, 16, v31
	v_and_b32_e32 v31, 0xffff0000, v31
	v_pk_mul_f32 v[48:49], v[52:53], v[48:49]
	v_pk_mul_f32 v[24:25], v[24:25], v[40:41]
	v_pk_mul_f32 v[40:41], v[54:55], v[50:51]
	v_pk_mul_f32 v[26:27], v[26:27], v[42:43]
	v_pk_fma_f32 v[22:23], v[22:23], v[28:29], v[24:25]
	v_pk_fma_f32 v[20:21], v[20:21], v[56:57], v[48:49]
	v_pk_fma_f32 v[24:25], v[18:19], v[30:31], v[26:27]
	v_pk_fma_f32 v[18:19], v[16:17], v[58:59], v[40:41]
	v_cvt_pk_bf16_f32 v16, v20, v21
	v_cvt_pk_bf16_f32 v17, v22, v23
	v_cvt_pk_bf16_f32 v18, v18, v19
	v_cvt_pk_bf16_f32 v19, v24, v25
	global_store_dwordx4 v[44:45], v[16:19], off offset:256 nt
	v_add_co_u32_e32 v20, vcc, s64, v38
	global_load_dwordx4 v[16:19], v[38:39], off
	s_nop 0
	v_addc_co_u32_e32 v21, vcc, 0, v39, vcc
	global_load_dwordx4 v[20:23], v[20:21], off
	v_lshl_add_u64 v[24:25], s[10:11], 0, v[36:37]
	v_lshl_add_u64 v[28:29], v[24:25], 0, v[146:147]
	global_load_dwordx4 v[24:27], v[46:47], off offset:256
	s_waitcnt vmcnt(4)
	v_lshlrev_b32_e32 v30, 16, v32
	v_and_b32_e32 v31, 0xffff0000, v32
	v_lshlrev_b32_e32 v32, 16, v33
	v_and_b32_e32 v33, 0xffff0000, v33
	v_lshlrev_b32_e32 v36, 16, v34
	v_and_b32_e32 v37, 0xffff0000, v34
	v_lshlrev_b32_e32 v34, 16, v35
	v_and_b32_e32 v35, 0xffff0000, v35
	s_andn2_b64 vcc, exec, s[4:5]
	s_mov_b64 s[4:5], -1
	s_waitcnt vmcnt(2)
	v_lshlrev_b32_e32 v40, 16, v16
	v_and_b32_e32 v41, 0xffff0000, v16
	v_lshlrev_b32_e32 v16, 16, v17
	v_and_b32_e32 v17, 0xffff0000, v17
	v_lshlrev_b32_e32 v42, 16, v18
	v_and_b32_e32 v43, 0xffff0000, v18
	v_lshlrev_b32_e32 v18, 16, v19
	v_and_b32_e32 v19, 0xffff0000, v19
	s_waitcnt vmcnt(1)
	v_lshlrev_b32_e32 v44, 16, v20
	v_and_b32_e32 v45, 0xffff0000, v20
	v_lshlrev_b32_e32 v20, 16, v21
	v_and_b32_e32 v21, 0xffff0000, v21
	v_lshlrev_b32_e32 v46, 16, v22
	v_and_b32_e32 v47, 0xffff0000, v22
	v_lshlrev_b32_e32 v22, 16, v23
	v_and_b32_e32 v23, 0xffff0000, v23
	v_pk_mul_f32 v[30:31], v[40:41], v[30:31]
	v_pk_mul_f32 v[16:17], v[16:17], v[32:33]
	v_pk_mul_f32 v[32:33], v[42:43], v[36:37]
	v_pk_mul_f32 v[18:19], v[18:19], v[34:35]
	v_pk_fma_f32 v[14:15], v[14:15], v[20:21], v[16:17]
	v_pk_fma_f32 v[12:13], v[12:13], v[44:45], v[30:31]
	v_pk_fma_f32 v[16:17], v[10:11], v[22:23], v[18:19]
	v_pk_fma_f32 v[10:11], v[8:9], v[46:47], v[32:33]
	v_cvt_pk_bf16_f32 v8, v12, v13
	v_cvt_pk_bf16_f32 v9, v14, v15
	v_cvt_pk_bf16_f32 v10, v10, v11
	v_cvt_pk_bf16_f32 v11, v16, v17
	global_store_dwordx4 v[28:29], v[8:11], off nt
	global_load_dwordx4 v[8:11], v[38:39], off offset:256
	v_lshl_add_u64 v[12:13], v[38:39], 0, s[16:17]
	global_load_dwordx4 v[12:15], v[12:13], off offset:256
	s_waitcnt vmcnt(3)
	v_lshlrev_b32_e32 v16, 16, v24
	v_and_b32_e32 v17, 0xffff0000, v24
	v_lshlrev_b32_e32 v18, 16, v25
	v_and_b32_e32 v19, 0xffff0000, v25
	v_lshlrev_b32_e32 v20, 16, v26
	v_and_b32_e32 v21, 0xffff0000, v26
	v_lshlrev_b32_e32 v22, 16, v27
	v_and_b32_e32 v23, 0xffff0000, v27
	s_waitcnt vmcnt(1)
	v_lshlrev_b32_e32 v24, 16, v8
	v_and_b32_e32 v25, 0xffff0000, v8
	v_lshlrev_b32_e32 v8, 16, v9
	v_and_b32_e32 v9, 0xffff0000, v9
	v_lshlrev_b32_e32 v26, 16, v10
	v_and_b32_e32 v27, 0xffff0000, v10
	v_lshlrev_b32_e32 v10, 16, v11
	v_and_b32_e32 v11, 0xffff0000, v11
	s_waitcnt vmcnt(0)
	v_lshlrev_b32_e32 v30, 16, v12
	v_and_b32_e32 v31, 0xffff0000, v12
	v_lshlrev_b32_e32 v12, 16, v13
	v_and_b32_e32 v13, 0xffff0000, v13
	v_lshlrev_b32_e32 v32, 16, v14
	v_and_b32_e32 v33, 0xffff0000, v14
	v_lshlrev_b32_e32 v14, 16, v15
	v_and_b32_e32 v15, 0xffff0000, v15
	v_pk_mul_f32 v[16:17], v[24:25], v[16:17]
	v_pk_mul_f32 v[8:9], v[8:9], v[18:19]
	v_pk_mul_f32 v[18:19], v[26:27], v[20:21]
	v_pk_mul_f32 v[10:11], v[10:11], v[22:23]
	v_pk_fma_f32 v[6:7], v[6:7], v[12:13], v[8:9]
	v_pk_fma_f32 v[4:5], v[4:5], v[30:31], v[16:17]
	v_pk_fma_f32 v[8:9], v[2:3], v[14:15], v[10:11]
	v_pk_fma_f32 v[2:3], v[0:1], v[32:33], v[18:19]
	v_cvt_pk_bf16_f32 v0, v4, v5
	v_cvt_pk_bf16_f32 v1, v6, v7
	v_cvt_pk_bf16_f32 v2, v2, v3
	v_cvt_pk_bf16_f32 v3, v8, v9
	global_store_dwordx4 v[28:29], v[0:3], off offset:256 nt
	s_cbranch_vccnz .LBB0_1527
	s_andn2_b64 vcc, exec, s[6:7]
	s_cbranch_vccnz .LBB0_1526
	s_barrier
	s_branch .LBB0_1526

; __device__ __forceinline__ u32x4 pack8(f32x4 v0, f32x4 v1) { u32x4 w; w.x = cvt_pk_bf16(v0[0], v0[1]); w.y = cvt_pk_bf16(v0[2], v0[3]); w.z = cvt_pk_bf16(v1[0], v1[1]); w.w = cvt_pk_bf16(v1[2], v1[3]); return w; }
; __device__ __forceinline__ void unpack8(u32x4 w, f32x4& v0, f32x4& v1) {
;     v0[0] = __uint_as_float(w.x << 16); v0[1] = __uint_as_float(w.x & 0xffff0000u); v0[2] = __uint_as_float(w.y << 16); v0[3] = __uint_as_float(w.y & 0xffff0000u);
;     v1[0] = __uint_as_float(w.z << 16); v1[1] = __uint_as_float(w.z & 0xffff0000u); v1[2] = __uint_as_float(w.w << 16); v1[3] = __uint_as_float(w.w & 0xffff0000u); }
;     __device__ __forceinline__ void operator()(f32x4 (&acc)[2][2][4][2], const Unit& u, int wr, int wc, int fr_, int fq_) const {
;     ...
;             for (int m = 0; m < 4; ++m) { const int row = row0 + ai * HALF + m * 16; float s = 0.f;
; #pragma unroll
;                 for (int bj = 0; bj < 2; ++bj) { const size_t off = (size_t)row * 2048 + col0 + bj * HALF;
;                     f32x4 b0, b1; unpack8(*(const u32x4*)(base + off), b0, b1);
;                     const f32x4 x0 = b0 + acc[ai][bj][m][0], x1 = b1 + acc[ai][bj][m][1];
;                     if (OUTF) { *(f32x4*)(out + off) = x0; *(f32x4*)(out + off + 4) = x1; }
;                     else *(u32x4*)(ob + off) = pack8(x0, x1);
;                     s += (x0[0] * x0[0] + x0[1] * x0[1]) + (x0[2] * x0[2] + x0[3] * x0[3]) + (x1[0] * x1[0] + x1[1] * x1[1]) + (x1[2] * x1[2] + x1[3] * x1[3]); }
;                 s += __shfl_xor(s, 16); s += __shfl_xor(s, 32);
;                 if (fq == 0) ssq[(size_t)row * 32 + u.pn * 4 + wc] = s; }
.LBB0_1615:
	s_lshl_b32 s19, s40, 8
	v_mov_b32_e32 v157, v151
	v_mov_b32_e32 v146, v150
	s_add_i32 s19, s19, s58
	v_xor_b32_e32 v170, 32, v156
	v_add_u32_e32 v148, s19, v146
	s_lshl_b32 s19, s6, 8
	s_or_b32 s19, s19, s59
	v_ashrrev_i32_e32 v149, 31, v148
	v_lshl_add_u32 v146, v157, 3, s19
	v_lshlrev_b64 v[158:159], 12, v[148:149]
	v_ashrrev_i32_e32 v147, 31, v146
	v_lshl_add_u64 v[158:159], s[10:11], 0, v[158:159]
	v_lshl_add_u64 v[168:169], v[146:147], 1, v[158:159]
	global_load_dwordx4 v[160:163], v[168:169], off
	global_load_dwordx4 v[164:167], v[168:169], off offset:256
	v_and_b32_e32 v159, 64, v156
	v_xor_b32_e32 v158, 16, v156
	v_add_u32_e32 v159, 64, v159
	v_cmp_lt_i32_e32 vcc, v158, v159
	s_lshl_b32 s40, s6, 2
	s_ashr_i32 s41, s40, 31
	v_cndmask_b32_e32 v158, v156, v158, vcc
	v_cmp_lt_i32_e32 vcc, v170, v159
	v_lshlrev_b32_e32 v158, 2, v158
	s_waitcnt vmcnt(0)
	v_and_b32_e32 v171, 0xffff0000, v160
	v_cndmask_b32_e32 v159, v156, v170, vcc
	v_lshlrev_b32_e32 v170, 16, v160
	v_lshlrev_b32_e32 v160, 16, v161
	v_and_b32_e32 v161, 0xffff0000, v161
	v_lshlrev_b32_e32 v174, 16, v164
	v_and_b32_e32 v175, 0xffff0000, v164
	v_lshlrev_b32_e32 v164, 16, v165
	v_and_b32_e32 v165, 0xffff0000, v165
	v_lshlrev_b32_e32 v172, 16, v162
	v_and_b32_e32 v173, 0xffff0000, v162
	v_lshlrev_b32_e32 v162, 16, v163
	v_and_b32_e32 v163, 0xffff0000, v163
	v_lshlrev_b32_e32 v176, 16, v166
	v_and_b32_e32 v177, 0xffff0000, v166
	v_lshlrev_b32_e32 v166, 16, v167
	v_and_b32_e32 v167, 0xffff0000, v167
	v_pk_add_f32 v[126:127], v[126:127], v[160:161]
	v_pk_add_f32 v[124:125], v[124:125], v[170:171]
	v_pk_add_f32 v[118:119], v[118:119], v[164:165]
	v_pk_add_f32 v[116:117], v[116:117], v[174:175]
	v_cmp_eq_u32_e32 vcc, 0, v157
	v_lshlrev_b32_e32 v157, 2, v159
	v_pk_add_f32 v[122:123], v[122:123], v[162:163]
	v_pk_add_f32 v[120:121], v[120:121], v[172:173]
	v_pk_add_f32 v[160:161], v[114:115], v[166:167]
	v_pk_add_f32 v[162:163], v[112:113], v[176:177]
	v_mul_f32_e32 v114, v125, v125
	v_mul_f32_e32 v115, v127, v127
	v_mul_f32_e32 v159, v117, v117
	v_mul_f32_e32 v164, v119, v119
	v_cvt_pk_bf16_f32 v112, v124, v125
	v_mul_f32_e32 v125, v121, v121
	v_mul_f32_e32 v165, v163, v163
	v_fmac_f32_e32 v114, v124, v124
	v_fmac_f32_e32 v115, v126, v126
	v_fmac_f32_e32 v159, v116, v116
	v_fmac_f32_e32 v164, v118, v118
	v_cvt_pk_bf16_f32 v113, v126, v127
	v_mul_f32_e32 v127, v123, v123
	v_mul_f32_e32 v166, v161, v161
	v_fmac_f32_e32 v125, v120, v120
	v_fmac_f32_e32 v165, v162, v162
	v_add_f32_e32 v114, v114, v115
	v_add_f32_e32 v115, v159, v164
	v_fmac_f32_e32 v127, v122, v122
	v_fmac_f32_e32 v166, v160, v160
	v_add_f32_e32 v114, v125, v114
	v_add_f32_e32 v115, v165, v115
	v_add_f32_e32 v114, v127, v114
	v_add_f32_e32 v115, v166, v115
	v_add_f32_e32 v124, v114, v115
	ds_bpermute_b32 v125, v158, v124
	v_cvt_pk_bf16_f32 v114, v120, v121
	v_cvt_pk_bf16_f32 v115, v122, v123
	global_store_dwordx4 v[168:169], v[112:115], off nt
	s_waitcnt lgkmcnt(0)
	s_nop 0
	v_add_f32_e32 v112, v124, v125
	ds_bpermute_b32 v113, v157, v112
	v_cvt_pk_bf16_f32 v114, v116, v117
	v_cvt_pk_bf16_f32 v115, v118, v119
	v_cvt_pk_bf16_f32 v116, v162, v163
	v_cvt_pk_bf16_f32 v117, v160, v161
	global_store_dwordx4 v[168:169], v[114:117], off offset:256 nt
	s_and_saveexec_b64 s[42:43], vcc
	s_cbranch_execz .LBB0_1617
	v_lshlrev_b64 v[114:115], 7, v[148:149]
	v_lshl_add_u64 v[114:115], s[12:13], 0, v[114:115]
	v_lshl_add_u64 v[114:115], s[40:41], 2, v[114:115]
	s_lshl_b32 s6, s57, 2
	v_lshl_add_u64 v[114:115], v[114:115], 0, s[6:7]
	s_waitcnt lgkmcnt(0)
	v_add_f32_e32 v112, v112, v113
	global_store_dword v[114:115], v112, off
.LBB0_1617:
	s_or_b64 exec, exec, s[42:43]
	v_add_u32_e32 v112, 16, v148
	s_waitcnt lgkmcnt(0)
	v_ashrrev_i32_e32 v113, 31, v112
	v_lshlrev_b64 v[114:115], 12, v[112:113]
	v_lshl_add_u64 v[114:115], s[10:11], 0, v[114:115]
	v_lshl_add_u64 v[122:123], v[146:147], 1, v[114:115]
	global_load_dwordx4 v[114:117], v[122:123], off
	global_load_dwordx4 v[118:121], v[122:123], off offset:256
	s_waitcnt vmcnt(1)
	v_lshlrev_b32_e32 v124, 16, v114
	v_and_b32_e32 v125, 0xffff0000, v114
	v_lshlrev_b32_e32 v114, 16, v115
	v_and_b32_e32 v115, 0xffff0000, v115
	s_waitcnt vmcnt(0)
	v_lshlrev_b32_e32 v160, 16, v118
	v_and_b32_e32 v161, 0xffff0000, v118
	v_lshlrev_b32_e32 v118, 16, v119
	v_and_b32_e32 v119, 0xffff0000, v119
	v_lshlrev_b32_e32 v126, 16, v116
	v_and_b32_e32 v127, 0xffff0000, v116
	v_lshlrev_b32_e32 v116, 16, v117
	v_and_b32_e32 v117, 0xffff0000, v117
	v_lshlrev_b32_e32 v162, 16, v120
	v_and_b32_e32 v163, 0xffff0000, v120
	v_lshlrev_b32_e32 v120, 16, v121
	v_and_b32_e32 v121, 0xffff0000, v121
	v_pk_add_f32 v[110:111], v[110:111], v[114:115]
	v_pk_add_f32 v[108:109], v[108:109], v[124:125]
	v_pk_add_f32 v[102:103], v[102:103], v[118:119]
	v_pk_add_f32 v[100:101], v[100:101], v[160:161]
	v_pk_add_f32 v[106:107], v[106:107], v[116:117]
	v_pk_add_f32 v[104:105], v[104:105], v[126:127]
	v_pk_add_f32 v[114:115], v[98:99], v[120:121]
	v_pk_add_f32 v[116:117], v[96:97], v[162:163]
	v_mul_f32_e32 v98, v109, v109
	v_mul_f32_e32 v99, v111, v111
	v_mul_f32_e32 v118, v101, v101
	v_mul_f32_e32 v119, v103, v103
	v_cvt_pk_bf16_f32 v96, v108, v109
	v_mul_f32_e32 v109, v105, v105
	v_mul_f32_e32 v120, v117, v117
	v_fmac_f32_e32 v98, v108, v108
	v_fmac_f32_e32 v99, v110, v110
	v_fmac_f32_e32 v118, v100, v100
	v_fmac_f32_e32 v119, v102, v102
	v_cvt_pk_bf16_f32 v97, v110, v111
	v_mul_f32_e32 v111, v107, v107
	v_mul_f32_e32 v121, v115, v115
	v_fmac_f32_e32 v109, v104, v104
	v_fmac_f32_e32 v120, v116, v116
	v_add_f32_e32 v98, v98, v99
	v_add_f32_e32 v99, v118, v119
	v_fmac_f32_e32 v111, v106, v106
	v_fmac_f32_e32 v121, v114, v114
	v_add_f32_e32 v98, v109, v98
	v_add_f32_e32 v99, v120, v99
	v_add_f32_e32 v98, v111, v98
	v_add_f32_e32 v99, v121, v99
	v_add_f32_e32 v108, v98, v99
	ds_bpermute_b32 v109, v158, v108
	v_cvt_pk_bf16_f32 v98, v104, v105
	v_cvt_pk_bf16_f32 v99, v106, v107
	global_store_dwordx4 v[122:123], v[96:99], off nt
	s_waitcnt lgkmcnt(0)
	s_nop 0
	v_add_f32_e32 v96, v108, v109
	ds_bpermute_b32 v97, v157, v96
	v_cvt_pk_bf16_f32 v98, v100, v101
	v_cvt_pk_bf16_f32 v99, v102, v103
	v_cvt_pk_bf16_f32 v100, v116, v117
	v_cvt_pk_bf16_f32 v101, v114, v115
	global_store_dwordx4 v[122:123], v[98:101], off offset:256 nt
	s_and_saveexec_b64 s[42:43], vcc
	s_cbranch_execz .LBB0_1619
	v_lshlrev_b64 v[98:99], 7, v[112:113]
	v_lshl_add_u64 v[98:99], s[12:13], 0, v[98:99]
	v_lshl_add_u64 v[98:99], s[40:41], 2, v[98:99]
	s_lshl_b32 s6, s57, 2
	v_lshl_add_u64 v[98:99], v[98:99], 0, s[6:7]
	s_waitcnt lgkmcnt(0)
	v_add_f32_e32 v96, v96, v97
	global_store_dword v[98:99], v96, off
; __device__ __forceinline__ u32x4 pack8(f32x4 v0, f32x4 v1) { u32x4 w; w.x = cvt_pk_bf16(v0[0], v0[1]); w.y = cvt_pk_bf16(v0[2], v0[3]); w.z = cvt_pk_bf16(v1[0], v1[1]); w.w = cvt_pk_bf16(v1[2], v1[3]); return w; }
; __device__ __forceinline__ void unpack8(u32x4 w, f32x4& v0, f32x4& v1) {
;     v0[0] = __uint_as_float(w.x << 16); v0[1] = __uint_as_float(w.x & 0xffff0000u); v0[2] = __uint_as_float(w.y << 16); v0[3] = __uint_as_float(w.y & 0xffff0000u);
;     v1[0] = __uint_as_float(w.z << 16); v1[1] = __uint_as_float(w.z & 0xffff0000u); v1[2] = __uint_as_float(w.w << 16); v1[3] = __uint_as_float(w.w & 0xffff0000u); }
;     __device__ __forceinline__ void operator()(f32x4 (&acc)[2][2][4][2], const Unit& u, int wr, int wc, int fr_, int fq_) const {
;     ...
;             for (int m = 0; m < 4; ++m) { const int row = row0 + ai * HALF + m * 16; float s = 0.f;
; #pragma unroll
;                 for (int bj = 0; bj < 2; ++bj) { const size_t off = (size_t)row * 2048 + col0 + bj * HALF;
;                     f32x4 b0, b1; unpack8(*(const u32x4*)(base + off), b0, b1);
;                     const f32x4 x0 = b0 + acc[ai][bj][m][0], x1 = b1 + acc[ai][bj][m][1];
;                     if (OUTF) { *(f32x4*)(out + off) = x0; *(f32x4*)(out + off + 4) = x1; }
;                     else *(u32x4*)(ob + off) = pack8(x0, x1);
;                     s += (x0[0] * x0[0] + x0[1] * x0[1]) + (x0[2] * x0[2] + x0[3] * x0[3]) + (x1[0] * x1[0] + x1[1] * x1[1]) + (x1[2] * x1[2] + x1[3] * x1[3]); }
;                 s += __shfl_xor(s, 16); s += __shfl_xor(s, 32);
;                 if (fq == 0) ssq[(size_t)row * 32 + u.pn * 4 + wc] = s; }
.LBB0_1619:
	s_or_b64 exec, exec, s[42:43]
	v_add_u32_e32 v96, 32, v148
	s_waitcnt lgkmcnt(0)
	v_ashrrev_i32_e32 v97, 31, v96
	v_lshlrev_b64 v[98:99], 12, v[96:97]
	v_lshl_add_u64 v[98:99], s[10:11], 0, v[98:99]
	v_lshl_add_u64 v[106:107], v[146:147], 1, v[98:99]
	global_load_dwordx4 v[98:101], v[106:107], off
	global_load_dwordx4 v[102:105], v[106:107], off offset:256
	s_waitcnt vmcnt(1)
	v_lshlrev_b32_e32 v108, 16, v98
	v_and_b32_e32 v109, 0xffff0000, v98
	v_lshlrev_b32_e32 v98, 16, v99
	v_and_b32_e32 v99, 0xffff0000, v99
	s_waitcnt vmcnt(0)
	v_lshlrev_b32_e32 v112, 16, v102
	v_and_b32_e32 v113, 0xffff0000, v102
	v_lshlrev_b32_e32 v102, 16, v103
	v_and_b32_e32 v103, 0xffff0000, v103
	v_lshlrev_b32_e32 v110, 16, v100
	v_and_b32_e32 v111, 0xffff0000, v100
	v_lshlrev_b32_e32 v100, 16, v101
	v_and_b32_e32 v101, 0xffff0000, v101
	v_lshlrev_b32_e32 v114, 16, v104
	v_and_b32_e32 v115, 0xffff0000, v104
	v_lshlrev_b32_e32 v104, 16, v105
	v_and_b32_e32 v105, 0xffff0000, v105
	v_pk_add_f32 v[94:95], v[94:95], v[98:99]
	v_pk_add_f32 v[92:93], v[92:93], v[108:109]
	v_pk_add_f32 v[86:87], v[86:87], v[102:103]
	v_pk_add_f32 v[84:85], v[84:85], v[112:113]
	v_pk_add_f32 v[90:91], v[90:91], v[100:101]
	v_pk_add_f32 v[88:89], v[88:89], v[110:111]
	v_pk_add_f32 v[98:99], v[82:83], v[104:105]
	v_pk_add_f32 v[100:101], v[80:81], v[114:115]
	v_mul_f32_e32 v82, v93, v93
	v_mul_f32_e32 v83, v95, v95
	v_mul_f32_e32 v102, v85, v85
	v_mul_f32_e32 v103, v87, v87
	v_cvt_pk_bf16_f32 v80, v92, v93
	v_mul_f32_e32 v93, v89, v89
	v_mul_f32_e32 v104, v101, v101
	v_fmac_f32_e32 v82, v92, v92
	v_fmac_f32_e32 v83, v94, v94
	v_fmac_f32_e32 v102, v84, v84
	v_fmac_f32_e32 v103, v86, v86
	v_cvt_pk_bf16_f32 v81, v94, v95
	v_mul_f32_e32 v95, v91, v91
	v_mul_f32_e32 v105, v99, v99
	v_fmac_f32_e32 v93, v88, v88
	v_fmac_f32_e32 v104, v100, v100
	v_add_f32_e32 v82, v82, v83
	v_add_f32_e32 v83, v102, v103
	v_fmac_f32_e32 v95, v90, v90
	v_fmac_f32_e32 v105, v98, v98
	v_add_f32_e32 v82, v93, v82
	v_add_f32_e32 v83, v104, v83
	v_add_f32_e32 v82, v95, v82
	v_add_f32_e32 v83, v105, v83
	v_add_f32_e32 v92, v82, v83
	ds_bpermute_b32 v93, v158, v92
	v_cvt_pk_bf16_f32 v82, v88, v89
	v_cvt_pk_bf16_f32 v83, v90, v91
	global_store_dwordx4 v[106:107], v[80:83], off nt
	s_waitcnt lgkmcnt(0)
	s_nop 0
	v_add_f32_e32 v80, v92, v93
	ds_bpermute_b32 v81, v157, v80
	v_cvt_pk_bf16_f32 v82, v84, v85
	v_cvt_pk_bf16_f32 v83, v86, v87
	v_cvt_pk_bf16_f32 v84, v100, v101
	v_cvt_pk_bf16_f32 v85, v98, v99
	global_store_dwordx4 v[106:107], v[82:85], off offset:256 nt
	s_and_saveexec_b64 s[42:43], vcc
	s_cbranch_execz .LBB0_1621
	v_lshlrev_b64 v[82:83], 7, v[96:97]
	v_lshl_add_u64 v[82:83], s[12:13], 0, v[82:83]
	v_lshl_add_u64 v[82:83], s[40:41], 2, v[82:83]
	s_lshl_b32 s6, s57, 2
	v_lshl_add_u64 v[82:83], v[82:83], 0, s[6:7]
	s_waitcnt lgkmcnt(0)
	v_add_f32_e32 v80, v80, v81
	global_store_dword v[82:83], v80, off
.LBB0_1621:
	s_or_b64 exec, exec, s[42:43]
	v_add_u32_e32 v80, 48, v148
	s_waitcnt lgkmcnt(0)
	v_ashrrev_i32_e32 v81, 31, v80
	v_lshlrev_b64 v[82:83], 12, v[80:81]
	v_lshl_add_u64 v[82:83], s[10:11], 0, v[82:83]
	v_lshl_add_u64 v[90:91], v[146:147], 1, v[82:83]
	global_load_dwordx4 v[82:85], v[90:91], off
	global_load_dwordx4 v[86:89], v[90:91], off offset:256
	s_waitcnt vmcnt(1)
	v_lshlrev_b32_e32 v92, 16, v82
	v_and_b32_e32 v93, 0xffff0000, v82
	v_lshlrev_b32_e32 v82, 16, v83
	v_and_b32_e32 v83, 0xffff0000, v83
	s_waitcnt vmcnt(0)
	v_lshlrev_b32_e32 v96, 16, v86
	v_and_b32_e32 v97, 0xffff0000, v86
	v_lshlrev_b32_e32 v86, 16, v87
	v_and_b32_e32 v87, 0xffff0000, v87
	v_lshlrev_b32_e32 v94, 16, v84
	v_and_b32_e32 v95, 0xffff0000, v84
	v_lshlrev_b32_e32 v84, 16, v85
	v_and_b32_e32 v85, 0xffff0000, v85
	v_lshlrev_b32_e32 v98, 16, v88
	v_and_b32_e32 v99, 0xffff0000, v88
	v_lshlrev_b32_e32 v88, 16, v89
	v_and_b32_e32 v89, 0xffff0000, v89
	v_pk_add_f32 v[78:79], v[78:79], v[82:83]
	v_pk_add_f32 v[76:77], v[76:77], v[92:93]
	v_pk_add_f32 v[70:71], v[70:71], v[86:87]
	v_pk_add_f32 v[68:69], v[68:69], v[96:97]
	v_pk_add_f32 v[74:75], v[74:75], v[84:85]
	v_pk_add_f32 v[72:73], v[72:73], v[94:95]
	v_pk_add_f32 v[82:83], v[66:67], v[88:89]
	v_pk_add_f32 v[84:85], v[64:65], v[98:99]
	v_mul_f32_e32 v66, v77, v77
	v_mul_f32_e32 v67, v79, v79
	v_mul_f32_e32 v86, v69, v69
	v_mul_f32_e32 v87, v71, v71
	v_cvt_pk_bf16_f32 v64, v76, v77
	v_mul_f32_e32 v77, v73, v73
	v_mul_f32_e32 v88, v85, v85
	v_fmac_f32_e32 v66, v76, v76
	v_fmac_f32_e32 v67, v78, v78
	v_fmac_f32_e32 v86, v68, v68
	v_fmac_f32_e32 v87, v70, v70
	v_cvt_pk_bf16_f32 v65, v78, v79
	v_mul_f32_e32 v79, v75, v75
	v_mul_f32_e32 v89, v83, v83
	v_fmac_f32_e32 v77, v72, v72
	v_fmac_f32_e32 v88, v84, v84
	v_add_f32_e32 v66, v66, v67
	v_add_f32_e32 v67, v86, v87
	v_fmac_f32_e32 v79, v74, v74
	v_fmac_f32_e32 v89, v82, v82
	v_add_f32_e32 v66, v77, v66
	v_add_f32_e32 v67, v88, v67
	v_add_f32_e32 v66, v79, v66
	v_add_f32_e32 v67, v89, v67
	v_add_f32_e32 v76, v66, v67
	ds_bpermute_b32 v77, v158, v76
	v_cvt_pk_bf16_f32 v66, v72, v73
	v_cvt_pk_bf16_f32 v67, v74, v75
	global_store_dwordx4 v[90:91], v[64:67], off nt
	s_waitcnt lgkmcnt(0)
	s_nop 0
	v_add_f32_e32 v64, v76, v77
	ds_bpermute_b32 v65, v157, v64
	v_cvt_pk_bf16_f32 v66, v68, v69
	v_cvt_pk_bf16_f32 v67, v70, v71
	v_cvt_pk_bf16_f32 v68, v84, v85
	v_cvt_pk_bf16_f32 v69, v82, v83
	global_store_dwordx4 v[90:91], v[66:69], off offset:256 nt
	s_and_saveexec_b64 s[42:43], vcc
	s_cbranch_execz .LBB0_1623
	v_lshlrev_b64 v[66:67], 7, v[80:81]
	v_lshl_add_u64 v[66:67], s[12:13], 0, v[66:67]
	v_lshl_add_u64 v[66:67], s[40:41], 2, v[66:67]
	s_lshl_b32 s6, s57, 2
	v_lshl_add_u64 v[66:67], v[66:67], 0, s[6:7]
	s_waitcnt lgkmcnt(0)
	v_add_f32_e32 v64, v64, v65
	global_store_dword v[66:67], v64, off
; __device__ __forceinline__ u32x4 pack8(f32x4 v0, f32x4 v1) { u32x4 w; w.x = cvt_pk_bf16(v0[0], v0[1]); w.y = cvt_pk_bf16(v0[2], v0[3]); w.z = cvt_pk_bf16(v1[0], v1[1]); w.w = cvt_pk_bf16(v1[2], v1[3]); return w; }
; __device__ __forceinline__ void unpack8(u32x4 w, f32x4& v0, f32x4& v1) {
;     v0[0] = __uint_as_float(w.x << 16); v0[1] = __uint_as_float(w.x & 0xffff0000u); v0[2] = __uint_as_float(w.y << 16); v0[3] = __uint_as_float(w.y & 0xffff0000u);
;     v1[0] = __uint_as_float(w.z << 16); v1[1] = __uint_as_float(w.z & 0xffff0000u); v1[2] = __uint_as_float(w.w << 16); v1[3] = __uint_as_float(w.w & 0xffff0000u); }
;     __device__ __forceinline__ void operator()(f32x4 (&acc)[2][2][4][2], const Unit& u, int wr, int wc, int fr_, int fq_) const {
;     ...
;             for (int m = 0; m < 4; ++m) { const int row = row0 + ai * HALF + m * 16; float s = 0.f;
; #pragma unroll
;                 for (int bj = 0; bj < 2; ++bj) { const size_t off = (size_t)row * 2048 + col0 + bj * HALF;
;                     f32x4 b0, b1; unpack8(*(const u32x4*)(base + off), b0, b1);
;                     const f32x4 x0 = b0 + acc[ai][bj][m][0], x1 = b1 + acc[ai][bj][m][1];
;                     if (OUTF) { *(f32x4*)(out + off) = x0; *(f32x4*)(out + off + 4) = x1; }
;                     else *(u32x4*)(ob + off) = pack8(x0, x1);
;                     s += (x0[0] * x0[0] + x0[1] * x0[1]) + (x0[2] * x0[2] + x0[3] * x0[3]) + (x1[0] * x1[0] + x1[1] * x1[1]) + (x1[2] * x1[2] + x1[3] * x1[3]); }
;                 s += __shfl_xor(s, 16); s += __shfl_xor(s, 32);
;                 if (fq == 0) ssq[(size_t)row * 32 + u.pn * 4 + wc] = s; }
.LBB0_1623:
	s_or_b64 exec, exec, s[42:43]
	v_add_u32_e32 v64, 0x80, v148
	s_waitcnt lgkmcnt(0)
	v_ashrrev_i32_e32 v65, 31, v64
	v_lshlrev_b64 v[66:67], 12, v[64:65]
	v_lshl_add_u64 v[66:67], s[10:11], 0, v[66:67]
	v_lshl_add_u64 v[74:75], v[146:147], 1, v[66:67]
	global_load_dwordx4 v[66:69], v[74:75], off
	global_load_dwordx4 v[70:73], v[74:75], off offset:256
	s_waitcnt vmcnt(1)
	v_lshlrev_b32_e32 v76, 16, v66
	v_and_b32_e32 v77, 0xffff0000, v66
	v_lshlrev_b32_e32 v66, 16, v67
	v_and_b32_e32 v67, 0xffff0000, v67
	s_waitcnt vmcnt(0)
	v_lshlrev_b32_e32 v80, 16, v70
	v_and_b32_e32 v81, 0xffff0000, v70
	v_lshlrev_b32_e32 v70, 16, v71
	v_and_b32_e32 v71, 0xffff0000, v71
	v_lshlrev_b32_e32 v78, 16, v68
	v_and_b32_e32 v79, 0xffff0000, v68
	v_lshlrev_b32_e32 v68, 16, v69
	v_and_b32_e32 v69, 0xffff0000, v69
	v_lshlrev_b32_e32 v82, 16, v72
	v_and_b32_e32 v83, 0xffff0000, v72
	v_lshlrev_b32_e32 v72, 16, v73
	v_and_b32_e32 v73, 0xffff0000, v73
	v_pk_add_f32 v[62:63], v[62:63], v[66:67]
	v_pk_add_f32 v[60:61], v[60:61], v[76:77]
	v_pk_add_f32 v[54:55], v[54:55], v[70:71]
	v_pk_add_f32 v[52:53], v[52:53], v[80:81]
	v_pk_add_f32 v[58:59], v[58:59], v[68:69]
	v_pk_add_f32 v[56:57], v[56:57], v[78:79]
	v_pk_add_f32 v[66:67], v[50:51], v[72:73]
	v_pk_add_f32 v[68:69], v[48:49], v[82:83]
	v_mul_f32_e32 v50, v61, v61
	v_mul_f32_e32 v51, v63, v63
	v_mul_f32_e32 v70, v53, v53
	v_mul_f32_e32 v71, v55, v55
	v_cvt_pk_bf16_f32 v48, v60, v61
	v_mul_f32_e32 v61, v57, v57
	v_mul_f32_e32 v72, v69, v69
	v_fmac_f32_e32 v50, v60, v60
	v_fmac_f32_e32 v51, v62, v62
	v_fmac_f32_e32 v70, v52, v52
	v_fmac_f32_e32 v71, v54, v54
	v_cvt_pk_bf16_f32 v49, v62, v63
	v_mul_f32_e32 v63, v59, v59
	v_mul_f32_e32 v73, v67, v67
	v_fmac_f32_e32 v61, v56, v56
	v_fmac_f32_e32 v72, v68, v68
	v_add_f32_e32 v50, v50, v51
	v_add_f32_e32 v51, v70, v71
	v_fmac_f32_e32 v63, v58, v58
	v_fmac_f32_e32 v73, v66, v66
	v_add_f32_e32 v50, v61, v50
	v_add_f32_e32 v51, v72, v51
	v_add_f32_e32 v50, v63, v50
	v_add_f32_e32 v51, v73, v51
	v_add_f32_e32 v60, v50, v51
	ds_bpermute_b32 v61, v158, v60
	v_cvt_pk_bf16_f32 v50, v56, v57
	v_cvt_pk_bf16_f32 v51, v58, v59
	global_store_dwordx4 v[74:75], v[48:51], off nt
	s_waitcnt lgkmcnt(0)
	s_nop 0
	v_add_f32_e32 v48, v60, v61
	ds_bpermute_b32 v49, v157, v48
	v_cvt_pk_bf16_f32 v50, v52, v53
	v_cvt_pk_bf16_f32 v51, v54, v55
	v_cvt_pk_bf16_f32 v52, v68, v69
	v_cvt_pk_bf16_f32 v53, v66, v67
	global_store_dwordx4 v[74:75], v[50:53], off offset:256 nt
	s_and_saveexec_b64 s[42:43], vcc
	s_cbranch_execz .LBB0_1625
	v_lshlrev_b64 v[50:51], 7, v[64:65]
	v_lshl_add_u64 v[50:51], s[12:13], 0, v[50:51]
	v_lshl_add_u64 v[50:51], s[40:41], 2, v[50:51]
	s_lshl_b32 s6, s57, 2
	v_lshl_add_u64 v[50:51], v[50:51], 0, s[6:7]
	s_waitcnt lgkmcnt(0)
	v_add_f32_e32 v48, v48, v49
	global_store_dword v[50:51], v48, off
.LBB0_1625:
	s_or_b64 exec, exec, s[42:43]
	v_add_u32_e32 v48, 0x90, v148
	s_waitcnt lgkmcnt(0)
	v_ashrrev_i32_e32 v49, 31, v48
	v_lshlrev_b64 v[50:51], 12, v[48:49]
	v_lshl_add_u64 v[50:51], s[10:11], 0, v[50:51]
	v_lshl_add_u64 v[58:59], v[146:147], 1, v[50:51]
	global_load_dwordx4 v[50:53], v[58:59], off
	global_load_dwordx4 v[54:57], v[58:59], off offset:256
	s_waitcnt vmcnt(1)
	v_lshlrev_b32_e32 v60, 16, v50
	v_and_b32_e32 v61, 0xffff0000, v50
	v_lshlrev_b32_e32 v50, 16, v51
	v_and_b32_e32 v51, 0xffff0000, v51
	s_waitcnt vmcnt(0)
	v_lshlrev_b32_e32 v64, 16, v54
	v_and_b32_e32 v65, 0xffff0000, v54
	v_lshlrev_b32_e32 v54, 16, v55
	v_and_b32_e32 v55, 0xffff0000, v55
	v_lshlrev_b32_e32 v62, 16, v52
	v_and_b32_e32 v63, 0xffff0000, v52
	v_lshlrev_b32_e32 v52, 16, v53
	v_and_b32_e32 v53, 0xffff0000, v53
	v_lshlrev_b32_e32 v66, 16, v56
	v_and_b32_e32 v67, 0xffff0000, v56
	v_lshlrev_b32_e32 v56, 16, v57
	v_and_b32_e32 v57, 0xffff0000, v57
	v_pk_add_f32 v[46:47], v[46:47], v[50:51]
	v_pk_add_f32 v[44:45], v[44:45], v[60:61]
	v_pk_add_f32 v[38:39], v[38:39], v[54:55]
	v_pk_add_f32 v[36:37], v[36:37], v[64:65]
	v_pk_add_f32 v[42:43], v[42:43], v[52:53]
	v_pk_add_f32 v[40:41], v[40:41], v[62:63]
	v_pk_add_f32 v[50:51], v[34:35], v[56:57]
	v_pk_add_f32 v[52:53], v[32:33], v[66:67]
	v_mul_f32_e32 v34, v45, v45
	v_mul_f32_e32 v35, v47, v47
	v_mul_f32_e32 v54, v37, v37
	v_mul_f32_e32 v55, v39, v39
	v_cvt_pk_bf16_f32 v32, v44, v45
	v_mul_f32_e32 v45, v41, v41
	v_mul_f32_e32 v56, v53, v53
	v_fmac_f32_e32 v34, v44, v44
	v_fmac_f32_e32 v35, v46, v46
	v_fmac_f32_e32 v54, v36, v36
	v_fmac_f32_e32 v55, v38, v38
	v_cvt_pk_bf16_f32 v33, v46, v47
	v_mul_f32_e32 v47, v43, v43
	v_mul_f32_e32 v57, v51, v51
	v_fmac_f32_e32 v45, v40, v40
	v_fmac_f32_e32 v56, v52, v52
	v_add_f32_e32 v34, v34, v35
	v_add_f32_e32 v35, v54, v55
	v_fmac_f32_e32 v47, v42, v42
	v_fmac_f32_e32 v57, v50, v50
	v_add_f32_e32 v34, v45, v34
	v_add_f32_e32 v35, v56, v35
	v_add_f32_e32 v34, v47, v34
	v_add_f32_e32 v35, v57, v35
	v_add_f32_e32 v44, v34, v35
	ds_bpermute_b32 v45, v158, v44
	v_cvt_pk_bf16_f32 v34, v40, v41
	v_cvt_pk_bf16_f32 v35, v42, v43
	global_store_dwordx4 v[58:59], v[32:35], off nt
	s_waitcnt lgkmcnt(0)
	s_nop 0
	v_add_f32_e32 v32, v44, v45
	ds_bpermute_b32 v33, v157, v32
	v_cvt_pk_bf16_f32 v34, v36, v37
	v_cvt_pk_bf16_f32 v35, v38, v39
	v_cvt_pk_bf16_f32 v36, v52, v53
	v_cvt_pk_bf16_f32 v37, v50, v51
	global_store_dwordx4 v[58:59], v[34:37], off offset:256 nt
	s_and_saveexec_b64 s[42:43], vcc
	s_cbranch_execz .LBB0_1627
	v_lshlrev_b64 v[34:35], 7, v[48:49]
	v_lshl_add_u64 v[34:35], s[12:13], 0, v[34:35]
	v_lshl_add_u64 v[34:35], s[40:41], 2, v[34:35]
	s_lshl_b32 s6, s57, 2
	v_lshl_add_u64 v[34:35], v[34:35], 0, s[6:7]
	s_waitcnt lgkmcnt(0)
	v_add_f32_e32 v32, v32, v33
	global_store_dword v[34:35], v32, off
; __device__ __forceinline__ u32x4 pack8(f32x4 v0, f32x4 v1) { u32x4 w; w.x = cvt_pk_bf16(v0[0], v0[1]); w.y = cvt_pk_bf16(v0[2], v0[3]); w.z = cvt_pk_bf16(v1[0], v1[1]); w.w = cvt_pk_bf16(v1[2], v1[3]); return w; }
; __device__ __forceinline__ void unpack8(u32x4 w, f32x4& v0, f32x4& v1) {
;     v0[0] = __uint_as_float(w.x << 16); v0[1] = __uint_as_float(w.x & 0xffff0000u); v0[2] = __uint_as_float(w.y << 16); v0[3] = __uint_as_float(w.y & 0xffff0000u);
;     v1[0] = __uint_as_float(w.z << 16); v1[1] = __uint_as_float(w.z & 0xffff0000u); v1[2] = __uint_as_float(w.w << 16); v1[3] = __uint_as_float(w.w & 0xffff0000u); }
;     __device__ __forceinline__ void operator()(f32x4 (&acc)[2][2][4][2], const Unit& u, int wr, int wc, int fr_, int fq_) const {
;     ...
;             for (int m = 0; m < 4; ++m) { const int row = row0 + ai * HALF + m * 16; float s = 0.f;
; #pragma unroll
;                 for (int bj = 0; bj < 2; ++bj) { const size_t off = (size_t)row * 2048 + col0 + bj * HALF;
;                     f32x4 b0, b1; unpack8(*(const u32x4*)(base + off), b0, b1);
;                     const f32x4 x0 = b0 + acc[ai][bj][m][0], x1 = b1 + acc[ai][bj][m][1];
;                     if (OUTF) { *(f32x4*)(out + off) = x0; *(f32x4*)(out + off + 4) = x1; }
;                     else *(u32x4*)(ob + off) = pack8(x0, x1);
;                     s += (x0[0] * x0[0] + x0[1] * x0[1]) + (x0[2] * x0[2] + x0[3] * x0[3]) + (x1[0] * x1[0] + x1[1] * x1[1]) + (x1[2] * x1[2] + x1[3] * x1[3]); }
;                 s += __shfl_xor(s, 16); s += __shfl_xor(s, 32);
;                 if (fq == 0) ssq[(size_t)row * 32 + u.pn * 4 + wc] = s; }
.LBB0_1627:
	s_or_b64 exec, exec, s[42:43]
	v_add_u32_e32 v32, 0xa0, v148
	s_waitcnt lgkmcnt(0)
	v_ashrrev_i32_e32 v33, 31, v32
	v_lshlrev_b64 v[34:35], 12, v[32:33]
	v_lshl_add_u64 v[34:35], s[10:11], 0, v[34:35]
	v_lshl_add_u64 v[42:43], v[146:147], 1, v[34:35]
	global_load_dwordx4 v[34:37], v[42:43], off
	global_load_dwordx4 v[38:41], v[42:43], off offset:256
	s_waitcnt vmcnt(1)
	v_lshlrev_b32_e32 v44, 16, v34
	v_and_b32_e32 v45, 0xffff0000, v34
	v_lshlrev_b32_e32 v34, 16, v35
	v_and_b32_e32 v35, 0xffff0000, v35
	s_waitcnt vmcnt(0)
	v_lshlrev_b32_e32 v48, 16, v38
	v_and_b32_e32 v49, 0xffff0000, v38
	v_lshlrev_b32_e32 v38, 16, v39
	v_and_b32_e32 v39, 0xffff0000, v39
	v_lshlrev_b32_e32 v46, 16, v36
	v_and_b32_e32 v47, 0xffff0000, v36
	v_lshlrev_b32_e32 v36, 16, v37
	v_and_b32_e32 v37, 0xffff0000, v37
	v_lshlrev_b32_e32 v50, 16, v40
	v_and_b32_e32 v51, 0xffff0000, v40
	v_lshlrev_b32_e32 v40, 16, v41
	v_and_b32_e32 v41, 0xffff0000, v41
	v_pk_add_f32 v[30:31], v[30:31], v[34:35]
	v_pk_add_f32 v[28:29], v[28:29], v[44:45]
	v_pk_add_f32 v[22:23], v[22:23], v[38:39]
	v_pk_add_f32 v[20:21], v[20:21], v[48:49]
	v_pk_add_f32 v[26:27], v[26:27], v[36:37]
	v_pk_add_f32 v[24:25], v[24:25], v[46:47]
	v_pk_add_f32 v[34:35], v[18:19], v[40:41]
	v_pk_add_f32 v[36:37], v[16:17], v[50:51]
	v_mul_f32_e32 v18, v29, v29
	v_mul_f32_e32 v19, v31, v31
	v_mul_f32_e32 v38, v21, v21
	v_mul_f32_e32 v39, v23, v23
	v_cvt_pk_bf16_f32 v16, v28, v29
	v_mul_f32_e32 v29, v25, v25
	v_mul_f32_e32 v40, v37, v37
	v_fmac_f32_e32 v18, v28, v28
	v_fmac_f32_e32 v19, v30, v30
	v_fmac_f32_e32 v38, v20, v20
	v_fmac_f32_e32 v39, v22, v22
	v_cvt_pk_bf16_f32 v17, v30, v31
	v_mul_f32_e32 v31, v27, v27
	v_mul_f32_e32 v41, v35, v35
	v_fmac_f32_e32 v29, v24, v24
	v_fmac_f32_e32 v40, v36, v36
	v_add_f32_e32 v18, v18, v19
	v_add_f32_e32 v19, v38, v39
	v_fmac_f32_e32 v31, v26, v26
	v_fmac_f32_e32 v41, v34, v34
	v_add_f32_e32 v18, v29, v18
	v_add_f32_e32 v19, v40, v19
	v_add_f32_e32 v18, v31, v18
	v_add_f32_e32 v19, v41, v19
	v_add_f32_e32 v28, v18, v19
	ds_bpermute_b32 v29, v158, v28
	v_cvt_pk_bf16_f32 v18, v24, v25
	v_cvt_pk_bf16_f32 v19, v26, v27
	global_store_dwordx4 v[42:43], v[16:19], off nt
	s_waitcnt lgkmcnt(0)
	s_nop 0
	v_add_f32_e32 v16, v28, v29
	ds_bpermute_b32 v17, v157, v16
	v_cvt_pk_bf16_f32 v18, v20, v21
	v_cvt_pk_bf16_f32 v19, v22, v23
	v_cvt_pk_bf16_f32 v20, v36, v37
	v_cvt_pk_bf16_f32 v21, v34, v35
	global_store_dwordx4 v[42:43], v[18:21], off offset:256 nt
	s_and_saveexec_b64 s[42:43], vcc
	s_cbranch_execz .LBB0_1629
	v_lshlrev_b64 v[18:19], 7, v[32:33]
	v_lshl_add_u64 v[18:19], s[12:13], 0, v[18:19]
	v_lshl_add_u64 v[18:19], s[40:41], 2, v[18:19]
	s_lshl_b32 s6, s57, 2
	v_lshl_add_u64 v[18:19], v[18:19], 0, s[6:7]
	s_waitcnt lgkmcnt(0)
	v_add_f32_e32 v16, v16, v17
	global_store_dword v[18:19], v16, off
.LBB0_1629:
	s_or_b64 exec, exec, s[42:43]
	v_add_u32_e32 v16, 0xb0, v148
	s_waitcnt lgkmcnt(0)
	v_ashrrev_i32_e32 v17, 31, v16
	v_lshlrev_b64 v[18:19], 12, v[16:17]
	v_lshl_add_u64 v[18:19], s[10:11], 0, v[18:19]
	v_lshl_add_u64 v[26:27], v[146:147], 1, v[18:19]
	global_load_dwordx4 v[18:21], v[26:27], off
	global_load_dwordx4 v[22:25], v[26:27], off offset:256
	s_waitcnt vmcnt(1)
	v_lshlrev_b32_e32 v28, 16, v18
	v_and_b32_e32 v29, 0xffff0000, v18
	v_lshlrev_b32_e32 v18, 16, v19
	v_and_b32_e32 v19, 0xffff0000, v19
	s_waitcnt vmcnt(0)
	v_lshlrev_b32_e32 v32, 16, v22
	v_and_b32_e32 v33, 0xffff0000, v22
	v_lshlrev_b32_e32 v22, 16, v23
	v_and_b32_e32 v23, 0xffff0000, v23
	v_lshlrev_b32_e32 v30, 16, v20
	v_and_b32_e32 v31, 0xffff0000, v20
	v_lshlrev_b32_e32 v20, 16, v21
	v_and_b32_e32 v21, 0xffff0000, v21
	v_lshlrev_b32_e32 v34, 16, v24
	v_and_b32_e32 v35, 0xffff0000, v24
	v_lshlrev_b32_e32 v24, 16, v25
	v_and_b32_e32 v25, 0xffff0000, v25
	v_pk_add_f32 v[14:15], v[14:15], v[18:19]
	v_pk_add_f32 v[12:13], v[12:13], v[28:29]
	v_pk_add_f32 v[6:7], v[6:7], v[22:23]
	v_pk_add_f32 v[4:5], v[4:5], v[32:33]
	v_pk_add_f32 v[10:11], v[10:11], v[20:21]
	v_pk_add_f32 v[8:9], v[8:9], v[30:31]
	v_pk_add_f32 v[18:19], v[2:3], v[24:25]
	v_pk_add_f32 v[20:21], v[0:1], v[34:35]
	v_mul_f32_e32 v2, v13, v13
	v_mul_f32_e32 v3, v15, v15
	v_mul_f32_e32 v22, v5, v5
	v_mul_f32_e32 v23, v7, v7
	v_cvt_pk_bf16_f32 v0, v12, v13
	v_mul_f32_e32 v13, v9, v9
	v_mul_f32_e32 v24, v21, v21
	v_fmac_f32_e32 v2, v12, v12
	v_fmac_f32_e32 v3, v14, v14
	v_fmac_f32_e32 v22, v4, v4
	v_fmac_f32_e32 v23, v6, v6
	v_cvt_pk_bf16_f32 v1, v14, v15
	v_mul_f32_e32 v15, v11, v11
	v_mul_f32_e32 v25, v19, v19
	v_fmac_f32_e32 v13, v8, v8
	v_fmac_f32_e32 v24, v20, v20
	v_add_f32_e32 v2, v2, v3
	v_add_f32_e32 v3, v22, v23
	v_fmac_f32_e32 v15, v10, v10
	v_fmac_f32_e32 v25, v18, v18
	v_add_f32_e32 v2, v13, v2
	v_add_f32_e32 v3, v24, v3
	v_add_f32_e32 v2, v15, v2
	v_add_f32_e32 v3, v25, v3
	v_add_f32_e32 v12, v2, v3
	ds_bpermute_b32 v13, v158, v12
	v_cvt_pk_bf16_f32 v2, v8, v9
	v_cvt_pk_bf16_f32 v3, v10, v11
	global_store_dwordx4 v[26:27], v[0:3], off nt
	s_waitcnt lgkmcnt(0)
	s_nop 0
	v_add_f32_e32 v0, v12, v13
	ds_bpermute_b32 v1, v157, v0
	v_cvt_pk_bf16_f32 v2, v4, v5
	v_cvt_pk_bf16_f32 v3, v6, v7
	v_cvt_pk_bf16_f32 v4, v20, v21
	v_cvt_pk_bf16_f32 v5, v18, v19
	global_store_dwordx4 v[26:27], v[2:5], off offset:256 nt
	s_and_saveexec_b64 s[42:43], vcc
	s_cbranch_execz .LBB0_1631
	v_lshlrev_b64 v[2:3], 7, v[16:17]
	v_lshl_add_u64 v[2:3], s[12:13], 0, v[2:3]
	v_lshl_add_u64 v[2:3], s[40:41], 2, v[2:3]
	s_lshl_b32 s6, s57, 2
	v_lshl_add_u64 v[2:3], v[2:3], 0, s[6:7]
	s_waitcnt lgkmcnt(0)
	v_add_f32_e32 v0, v0, v1
	global_store_dword v[2:3], v0, off

;     __device__ __forceinline__ void operator()(f32x4 (&acc)[2][2][4][2], const Unit& u, int wr, int wc, int fr_, int fq_) const {
;     ...
;         asm volatile("s_waitcnt lgkmcnt(0)" ::: "memory"); __builtin_amdgcn_s_barrier(); asm volatile("" ::: "memory");
;         const int jcol = u.pn * HALF + wc * 32 + 8 * fq;
;         if (wr == 1 && fr >= 14) { const float rsb = rsL[240 + fr];
; #pragma unroll
;             for (int bj = 0; bj < 2; ++bj)
; #pragma unroll
;                 for (int n = 0; n < 2; ++n) *(f32x4*)(BOT + ((size_t)u.pm * 2 + (fr - 14)) * 11264 + u.pn * BM + bj * HALF + wc * 32 + 8 * fq + 4 * n) = acc[1][bj][3][n] * rsb; }
.LBB0_1708:
	s_or_b64 exec, exec, s[0:1]
	s_waitcnt lgkmcnt(0)
	s_barrier
	v_lshlrev_b32_e32 v176, 3, v128
	s_and_b64 s[0:1], s[18:19], vcc
	s_xor_b64 s[0:1], s[0:1], -1
	v_ashrrev_i32_e32 v177, 31, v176
	s_and_saveexec_b64 s[12:13], s[0:1]
	s_xor_b64 s[0:1], exec, s[12:13]
	s_ashr_i32 s91, s90, 31
	s_lshl_b32 s10, s38, 8
	s_lshl_b64 s[8:9], s[90:91], 1
	s_ashr_i32 s11, s10, 31
	s_or_saveexec_b64 s[0:1], s[0:1]
	v_mov_b64_e32 v[182:183], s[10:11]
	v_mov_b64_e32 v[184:185], s[8:9]
	v_lshl_add_u32 v225, v178, 2, s39
	s_xor_b64 exec, exec, s[0:1]
	s_cbranch_execz .LBB0_1712
	s_ashr_i32 s91, s90, 31
	v_readlane_b32 s6, v244, 51
	s_lshl_b64 s[8:9], s[90:91], 1
	v_add_u32_e32 v154, -14, v178
	v_readlane_b32 s7, v244, 52
	ds_read_b32 v132, v225 offset:960
	v_lshl_add_u64 v[134:135], s[8:9], 0, v[154:155]
	v_mov_b64_e32 v[136:137], s[6:7]
	s_mov_b32 s6, 0xb000
	s_lshl_b32 s10, s38, 8
	v_mad_u64_u32 v[136:137], s[12:13], v134, s6, v[136:137]
	s_ashr_i32 s11, s10, 31
	v_mad_i32_i24 v137, v135, s6, v137
	v_lshl_add_u64 v[134:135], s[10:11], 2, v[136:137]
	s_lshl_b32 s16, s33, 2
	v_lshl_add_u64 v[134:135], v[134:135], 0, s[16:17]
	s_waitcnt lgkmcnt(0)
	v_pk_mul_f32 v[130:131], v[50:51], v[132:133] op_sel_hi:[1,0]
	v_pk_mul_f32 v[128:129], v[48:49], v[132:133] op_sel_hi:[1,0]
	v_lshl_add_u64 v[134:135], v[176:177], 2, v[134:135]
	global_store_dwordx4 v[134:135], v[128:131], off nt
	v_mov_b64_e32 v[182:183], s[10:11]
	v_mov_b64_e32 v[184:185], s[8:9]
	v_pk_mul_f32 v[130:131], v[34:35], v[132:133] op_sel_hi:[1,0]
	v_pk_mul_f32 v[128:129], v[32:33], v[132:133] op_sel_hi:[1,0]
	global_store_dwordx4 v[134:135], v[128:131], off offset:16 nt
	s_nop 1
	v_pk_mul_f32 v[130:131], v[18:19], v[132:133] op_sel_hi:[1,0]
	v_pk_mul_f32 v[128:129], v[16:17], v[132:133] op_sel_hi:[1,0]
	global_store_dwordx4 v[134:135], v[128:131], off offset:512 nt
	s_nop 1
	v_pk_mul_f32 v[130:131], v[2:3], v[132:133] op_sel_hi:[1,0]
	v_pk_mul_f32 v[128:129], v[0:1], v[132:133] op_sel_hi:[1,0]
	global_store_dwordx4 v[134:135], v[128:131], off offset:528 nt

; #define PG8_LAS __attribute__((address_space(3)))
; __device__ __forceinline__ float dpp_ror1(float x) { float r; asm volatile("s_nop 1\n\tv_mov_b32_dpp %0, %1 row_ror:1 row_mask:0xf bank_mask:0xf" : "=&v"(r) : "v"(x)); return r; }
; __device__ __forceinline__ float dpp_ror2(float x) { float r; asm volatile("s_nop 1\n\tv_mov_b32_dpp %0, %1 row_ror:2 row_mask:0xf bank_mask:0xf" : "=&v"(r) : "v"(x)); return r; }
;     __device__ __forceinline__ void operator()(f32x4 (&acc)[2][2][4][2], const Unit& u, int wr, int wc, int fr_, int fq_) const {
;     ...
;             for (int bj = 0; bj < 2; ++bj)
; #pragma unroll
;                 for (int n = 0; n < 2; ++n) {
;                     const int ct = bj * HALF + wc * 32 + 8 * fq + 4 * n;
;                     const int cidx = bj * 5632 + jcol + 4 * n;
;                     const f32x4 w0 = *(const f32x4*)(cw + cidx), w1 = *(const f32x4*)(cw + 11264 + cidx), w2 = *(const f32x4*)(cw + 22528 + cidx), b4 = *(const f32x4*)(cb + cidx);
;                     f32x4 pR1 = (f32x4){0.f, 0.f, 0.f, 0.f}, pR2 = pR1;
;                     if (blk) { const f32x4 h14 = *(const PG8_LAS f32x4*)(hal + ((blk - 1) * 2 + 0) * 256 + ct) * rs14, h15 = *(const PG8_LAS f32x4*)(hal + ((blk - 1) * 2 + 1) * 256 + ct) * rs15;
;                         pR1 = h15; pR2 = (fr == 0) ? h14 : h15; }
; #pragma unroll
;                     for (int m = 0; m < 4; ++m) {
;                         const f32x4 U = acc[ai][bj][m][n] * rsr[m];
;                         f32x4 R1, R2;
; #pragma unroll
;                         for (int i = 0; i < 4; ++i) { R1[i] = dpp_ror1(U[i]); R2[i] = dpp_ror2(U[i]); }
;                         const f32x4 U1 = (fr >= 1) ? R1 : pR1, U2 = (fr >= 2) ? R2 : pR2;
;                         const f32x4 C = b4 + w0 * U2 + w1 * U1 + w2 * U;
;                         acc[ai][bj][m][n] = C; pR1 = R1; pR2 = R2;
;                         asm volatile("" : "+v"(acc[ai][bj][m][n]));
;                         __builtin_amdgcn_sched_barrier(0);
;                     }
;                     asm volatile("" ::: "memory");
;                 }
;             if (ai == 0 && wr == 0 && fr < 2) {
; #pragma unroll
;                 for (int bj = 0; bj < 2; ++bj)
; #pragma unroll
;                     for (int n = 0; n < 2; ++n) *(f32x4*)(TOP + ((size_t)u.pm * 2 + fr) * 11264 + u.pn * BM + bj * HALF + wc * 32 + 8 * fq + 4 * n) = acc[0][bj][0][n]; }
.LBB0_1725:
	v_mov_b32_e32 v202, v192
	v_mov_b32_e32 v203, v192
	v_pk_mul_f32 v[78:79], v[78:79], v[202:203]
	v_pk_mul_f32 v[76:77], v[76:77], v[192:193]
	s_nop 0
	s_nop 1
	v_mov_b32_dpp v201, v76 row_ror:1 row_mask:0xf bank_mask:0xf
	v_mov_b32_dpp v202, v76 row_ror:2 row_mask:0xf bank_mask:0xf
	v_mov_b32_dpp v203, v77 row_ror:1 row_mask:0xf bank_mask:0xf
	v_mov_b32_dpp v204, v77 row_ror:2 row_mask:0xf bank_mask:0xf
	v_mov_b32_dpp v205, v78 row_ror:1 row_mask:0xf bank_mask:0xf
	v_mov_b32_dpp v206, v78 row_ror:2 row_mask:0xf bank_mask:0xf
	v_mov_b32_dpp v207, v79 row_ror:1 row_mask:0xf bank_mask:0xf
	v_mov_b32_dpp v208, v79 row_ror:2 row_mask:0xf bank_mask:0xf
	v_cndmask_b32_e64 v192, v196, v205, s[6:7]
	v_cndmask_b32_e64 v193, v197, v207, s[6:7]
	v_cndmask_b32_e64 v196, v198, v201, s[6:7]
	v_cndmask_b32_e64 v197, v199, v203, s[6:7]
	v_cndmask_b32_e64 v198, v194, v206, s[8:9]
	v_cndmask_b32_e64 v199, v200, v208, s[8:9]
	v_cndmask_b32_e64 v194, v179, v202, s[8:9]
	v_cndmask_b32_e64 v195, v195, v204, s[8:9]
	s_waitcnt vmcnt(0)
	v_pk_fma_f32 v[198:199], v[134:135], v[198:199], v[142:143]
	v_pk_fma_f32 v[194:195], v[132:133], v[194:195], v[140:141]
	v_pk_fma_f32 v[192:193], v[130:131], v[192:193], v[198:199]
	v_pk_fma_f32 v[194:195], v[128:129], v[196:197], v[194:195]
	v_pk_fma_f32 v[78:79], v[78:79], v[138:139], v[192:193]
	v_pk_fma_f32 v[76:77], v[76:77], v[136:137], v[194:195]
	v_mov_b32_e32 v192, v190
	v_mov_b32_e32 v193, v190
	v_pk_mul_f32 v[74:75], v[74:75], v[192:193]
	v_pk_mul_f32 v[72:73], v[72:73], v[190:191]
	s_nop 1
	v_mov_b32_dpp v179, v72 row_ror:1 row_mask:0xf bank_mask:0xf
	v_mov_b32_dpp v198, v72 row_ror:2 row_mask:0xf bank_mask:0xf
	v_mov_b32_dpp v199, v73 row_ror:1 row_mask:0xf bank_mask:0xf
	v_mov_b32_dpp v200, v73 row_ror:2 row_mask:0xf bank_mask:0xf
	v_mov_b32_dpp v209, v74 row_ror:1 row_mask:0xf bank_mask:0xf
	v_mov_b32_dpp v210, v74 row_ror:2 row_mask:0xf bank_mask:0xf
	v_mov_b32_dpp v211, v75 row_ror:1 row_mask:0xf bank_mask:0xf
	v_mov_b32_dpp v212, v75 row_ror:2 row_mask:0xf bank_mask:0xf
	v_cndmask_b32_e64 v196, v202, v198, s[8:9]
	v_cndmask_b32_e64 v194, v206, v210, s[8:9]
	v_cndmask_b32_e64 v195, v208, v212, s[8:9]
	v_cndmask_b32_e64 v197, v204, v200, s[8:9]
	v_cndmask_b32_e64 v190, v205, v209, s[6:7]
	v_cndmask_b32_e64 v191, v207, v211, s[6:7]
	v_cndmask_b32_e64 v192, v201, v179, s[6:7]
	v_cndmask_b32_e64 v193, v203, v199, s[6:7]
	v_pk_fma_f32 v[194:195], v[134:135], v[194:195], v[142:143]
	v_pk_fma_f32 v[196:197], v[132:133], v[196:197], v[140:141]
	v_pk_fma_f32 v[190:191], v[130:131], v[190:191], v[194:195]
	v_pk_fma_f32 v[192:193], v[128:129], v[192:193], v[196:197]
	v_pk_fma_f32 v[74:75], v[74:75], v[138:139], v[190:191]
	v_pk_fma_f32 v[72:73], v[72:73], v[136:137], v[192:193]
	v_mov_b32_e32 v190, v188
	v_mov_b32_e32 v191, v188
	v_pk_mul_f32 v[70:71], v[70:71], v[190:191]
	v_pk_mul_f32 v[68:69], v[68:69], v[188:189]
	s_nop 1
	v_mov_b32_dpp v196, v68 row_ror:1 row_mask:0xf bank_mask:0xf
	v_mov_b32_dpp v197, v68 row_ror:2 row_mask:0xf bank_mask:0xf
	v_mov_b32_dpp v201, v69 row_ror:1 row_mask:0xf bank_mask:0xf
	v_mov_b32_dpp v202, v69 row_ror:2 row_mask:0xf bank_mask:0xf
	v_mov_b32_dpp v203, v70 row_ror:1 row_mask:0xf bank_mask:0xf
	v_mov_b32_dpp v204, v70 row_ror:2 row_mask:0xf bank_mask:0xf
	v_mov_b32_dpp v205, v71 row_ror:1 row_mask:0xf bank_mask:0xf
	v_mov_b32_dpp v206, v71 row_ror:2 row_mask:0xf bank_mask:0xf
	v_cndmask_b32_e64 v194, v198, v197, s[8:9]
	v_cndmask_b32_e64 v192, v210, v204, s[8:9]
	v_cndmask_b32_e64 v193, v212, v206, s[8:9]
	v_cndmask_b32_e64 v195, v200, v202, s[8:9]
	v_cndmask_b32_e64 v188, v209, v203, s[6:7]
	v_cndmask_b32_e64 v189, v211, v205, s[6:7]
	v_cndmask_b32_e64 v190, v179, v196, s[6:7]
	v_cndmask_b32_e64 v191, v199, v201, s[6:7]
	v_pk_fma_f32 v[192:193], v[134:135], v[192:193], v[142:143]
	v_pk_fma_f32 v[194:195], v[132:133], v[194:195], v[140:141]
	v_pk_fma_f32 v[188:189], v[130:131], v[188:189], v[192:193]
	v_pk_fma_f32 v[190:191], v[128:129], v[190:191], v[194:195]
	v_pk_fma_f32 v[70:71], v[70:71], v[138:139], v[188:189]
	v_pk_fma_f32 v[68:69], v[68:69], v[136:137], v[190:191]
	v_mov_b32_e32 v188, v186
	v_mov_b32_e32 v189, v186
	v_pk_mul_f32 v[66:67], v[66:67], v[188:189]
	v_pk_mul_f32 v[64:65], v[64:65], v[186:187]
	s_nop 1
	v_mov_b32_dpp v179, v64 row_ror:1 row_mask:0xf bank_mask:0xf
	v_mov_b32_dpp v192, v64 row_ror:2 row_mask:0xf bank_mask:0xf
	v_mov_b32_dpp v189, v65 row_ror:1 row_mask:0xf bank_mask:0xf
	v_mov_b32_dpp v193, v65 row_ror:2 row_mask:0xf bank_mask:0xf
	v_mov_b32_dpp v186, v66 row_ror:1 row_mask:0xf bank_mask:0xf
	v_mov_b32_dpp v190, v66 row_ror:2 row_mask:0xf bank_mask:0xf
	v_mov_b32_dpp v187, v67 row_ror:1 row_mask:0xf bank_mask:0xf
	v_mov_b32_dpp v191, v67 row_ror:2 row_mask:0xf bank_mask:0xf
	v_cndmask_b32_e64 v192, v197, v192, s[8:9]
	v_cndmask_b32_e64 v190, v204, v190, s[8:9]
	v_cndmask_b32_e64 v191, v206, v191, s[8:9]
	v_cndmask_b32_e64 v193, v202, v193, s[8:9]
	v_cndmask_b32_e64 v186, v203, v186, s[6:7]
	v_cndmask_b32_e64 v187, v205, v187, s[6:7]
	v_cndmask_b32_e64 v188, v196, v179, s[6:7]
	v_cndmask_b32_e64 v189, v201, v189, s[6:7]
	v_pk_fma_f32 v[134:135], v[134:135], v[190:191], v[142:143]
	v_pk_fma_f32 v[132:133], v[132:133], v[192:193], v[140:141]
	v_pk_fma_f32 v[130:131], v[130:131], v[186:187], v[134:135]
	v_pk_fma_f32 v[128:129], v[128:129], v[188:189], v[132:133]
	v_pk_fma_f32 v[66:67], v[66:67], v[138:139], v[130:131]
	v_pk_fma_f32 v[64:65], v[64:65], v[136:137], v[128:129]
	s_nop 0
	s_and_saveexec_b64 s[12:13], s[0:1]
	s_cbranch_execz .LBB0_1727
	v_readlane_b32 s0, v244, 49
	v_ashrrev_i32_e32 v179, 31, v178
	v_readlane_b32 s1, v244, 50
	v_lshl_add_u64 v[128:129], v[184:185], 0, v[178:179]
	s_mov_b32 s16, 0xb000
	v_mov_b64_e32 v[130:131], s[0:1]
	v_mad_u64_u32 v[130:131], s[0:1], v128, s16, v[130:131]
	v_mov_b32_e32 v128, v131
	v_mad_u64_u32 v[128:129], s[0:1], v129, s16, v[128:129]
	v_mov_b32_e32 v131, v128
	v_lshl_add_u64 v[128:129], v[182:183], 2, v[130:131]
	s_lshl_b32 s16, s33, 2
	v_lshl_add_u64 v[128:129], v[128:129], 0, s[16:17]
	v_lshl_add_u64 v[128:129], v[176:177], 2, v[128:129]
	global_store_dwordx4 v[128:129], v[124:127], off nt
	global_store_dwordx4 v[128:129], v[116:119], off offset:16 nt
	global_store_dwordx4 v[128:129], v[100:103], off offset:512 nt
	global_store_dwordx4 v[128:129], v[76:79], off offset:528 nt
; __device__ __forceinline__ u32x4 pack8(f32x4 v0, f32x4 v1) { u32x4 w; w.x = cvt_pk_bf16(v0[0], v0[1]); w.y = cvt_pk_bf16(v0[2], v0[3]); w.z = cvt_pk_bf16(v1[0], v1[1]); w.w = cvt_pk_bf16(v1[2], v1[3]); return w; }
; __device__ __forceinline__ f32x4 gelu4(f32x4 v) { f32x2 a = gelu_pk((f32x2){v[0], v[1]}), b = gelu_pk((f32x2){v[2], v[3]}); return (f32x4){a.x, a.y, b.x, b.y}; }
; __device__ __forceinline__ f32x2 gelu_pk(f32x2 v) {
;     const f32x2 av = __builtin_elementwise_abs(v), d = av * 0.2316418882f + 1.0f;
;     f32x2 t; t.x = __builtin_amdgcn_rcpf(d.x); t.y = __builtin_amdgcn_rcpf(d.y);
;     f32x2 q = t * 0.5307027145f + (-0.7265760135f); q = q * t + 0.7107068705f; q = q * t + (-0.142248368f); q = q * t + 0.127414796f; q = q * t;
;     const f32x2 s = (v * v) * (-0.72134752044f);
;     f32x2 e; e.x = __builtin_amdgcn_exp2f(s.x); e.y = __builtin_amdgcn_exp2f(s.y);
;     const f32x2 m = v * (q * e), r = v - m;
;     f32x2 o; o.x = v.x < 0.f ? m.x : r.x; o.y = v.y < 0.f ? m.y : r.y; return o;
; }
;     __device__ __forceinline__ void operator()(f32x4 (&acc)[2][2][4][2], const Unit& u, int wr, int wc, int fr_, int fq_) const {
;     ...
;             for (int m = 0; m < 4; ++m) { const int row = u.pm * BM + blk * 64 + m * 16 + fr;
;                 const f32x4 g0 = gelu4(acc[ai][0][m][0]), g1 = gelu4(acc[ai][0][m][1]);
;                 *(u32x4*)(ACT + (size_t)row * 5632 + jcol) = pack8(g0 * acc[ai][1][m][0], g1 * acc[ai][1][m][1]); asm volatile("" ::: "memory"); __builtin_amdgcn_sched_barrier(0); }
.LBB0_1727:
	s_or_b64 exec, exec, s[12:13]
	v_fma_f32 v128, |v124|, s58, 1.0
	v_fma_f32 v129, |v125|, s58, 1.0
	v_lshl_add_u32 v178, s90, 8, v178
	v_rcp_f32_e32 v182, v128
	v_rcp_f32_e32 v183, v129
	v_readlane_b32 s0, v244, 55
	v_pk_mul_f32 v[186:187], v[124:125], v[124:125]
	s_nop 0
	v_add_u32_e32 v179, s0, v178
	s_mov_b32 s0, 0xbf3a00e3
	v_mov_b64_e32 v[128:129], s[0:1]
	v_pk_fma_f32 v[184:185], v[182:183], s[60:61], v[128:129] op_sel_hi:[1,0,0]
	v_pk_mul_f32 v[186:187], v[186:187], s[50:51] op_sel_hi:[1,0]
	v_pk_fma_f32 v[184:185], v[182:183], v[184:185], s[62:63] op_sel_hi:[1,1,0]
	v_exp_f32_e32 v186, v186
	v_exp_f32_e32 v187, v187
	v_pk_fma_f32 v[184:185], v[182:183], v[184:185], s[64:65] op_sel_hi:[1,1,0]
	v_lshl_add_u64 v[138:139], v[164:165], 0, s[54:55]
	v_pk_fma_f32 v[184:185], v[182:183], v[184:185], s[66:67] op_sel_hi:[1,1,0]
	v_lshl_add_u64 v[140:141], v[168:169], 0, s[54:55]
	v_pk_mul_f32 v[182:183], v[182:183], v[184:185]
	v_pk_mul_f32 v[184:185], v[126:127], v[126:127]
	v_pk_mul_f32 v[182:183], v[186:187], v[182:183]
	v_pk_mul_f32 v[184:185], v[184:185], s[50:51] op_sel_hi:[1,0]
	v_max_f32_e32 v186, 0, v124
	v_max_f32_e32 v187, 0, v125
	v_exp_f32_e32 v184, v184
	v_fma_f32 v124, -|v124|, v182, v186
	v_fma_f32 v125, -|v125|, v183, v187
	v_exp_f32_e32 v185, v185
	v_fma_f32 v182, |v126|, s58, 1.0
	v_fma_f32 v183, |v127|, s58, 1.0
	v_rcp_f32_e32 v182, v182
	v_rcp_f32_e32 v183, v183
	v_pk_mul_f32 v[100:101], v[124:125], v[100:101]
	v_lshl_add_u64 v[142:143], v[170:171], 0, s[54:55]
	v_cvt_pk_bf16_f32 v100, v100, v101
	v_pk_fma_f32 v[186:187], v[182:183], s[60:61], v[128:129] op_sel_hi:[1,0,0]
	v_lshl_add_u64 v[176:177], v[166:167], 0, s[54:55]
	v_pk_fma_f32 v[186:187], v[182:183], v[186:187], s[62:63] op_sel_hi:[1,1,0]
	v_lshl_add_u64 v[130:131], v[164:165], 0, s[56:57]
	v_pk_fma_f32 v[186:187], v[182:183], v[186:187], s[64:65] op_sel_hi:[1,1,0]
	v_lshl_add_u64 v[132:133], v[168:169], 0, s[56:57]
	v_pk_fma_f32 v[186:187], v[182:183], v[186:187], s[66:67] op_sel_hi:[1,1,0]
	v_lshl_add_u64 v[134:135], v[170:171], 0, s[56:57]
	v_pk_mul_f32 v[182:183], v[182:183], v[186:187]
	v_pk_mul_f32 v[186:187], v[116:117], v[116:117]
	v_pk_mul_f32 v[182:183], v[184:185], v[182:183]
	v_pk_mul_f32 v[186:187], v[186:187], s[50:51] op_sel_hi:[1,0]
	v_max_f32_e32 v184, 0, v126
	v_max_f32_e32 v185, 0, v127
	v_exp_f32_e32 v186, v186
	v_fma_f32 v126, -|v126|, v182, v184
	v_fma_f32 v127, -|v127|, v183, v185
	v_exp_f32_e32 v187, v187
	v_fma_f32 v182, |v116|, s58, 1.0
	v_fma_f32 v183, |v117|, s58, 1.0
	v_rcp_f32_e32 v182, v182
	v_rcp_f32_e32 v183, v183
	v_pk_mul_f32 v[102:103], v[126:127], v[102:103]
	v_lshl_add_u64 v[136:137], v[166:167], 0, s[56:57]
	v_cvt_pk_bf16_f32 v101, v102, v103
	v_pk_fma_f32 v[184:185], v[182:183], s[60:61], v[128:129] op_sel_hi:[1,0,0]
	v_pk_fma_f32 v[184:185], v[182:183], v[184:185], s[62:63] op_sel_hi:[1,1,0]
	v_pk_fma_f32 v[184:185], v[182:183], v[184:185], s[64:65] op_sel_hi:[1,1,0]
	v_pk_fma_f32 v[184:185], v[182:183], v[184:185], s[66:67] op_sel_hi:[1,1,0]
	v_pk_mul_f32 v[182:183], v[182:183], v[184:185]
	v_pk_mul_f32 v[184:185], v[118:119], v[118:119]
	v_pk_mul_f32 v[182:183], v[186:187], v[182:183]
	v_pk_mul_f32 v[184:185], v[184:185], s[50:51] op_sel_hi:[1,0]
	v_max_f32_e32 v186, 0, v116
	v_max_f32_e32 v187, 0, v117
	v_exp_f32_e32 v184, v184
	v_fma_f32 v116, -|v116|, v182, v186
	v_fma_f32 v117, -|v117|, v183, v187
	v_exp_f32_e32 v185, v185
	v_fma_f32 v182, |v118|, s58, 1.0
	v_fma_f32 v183, |v119|, s58, 1.0
	v_rcp_f32_e32 v182, v182
	v_rcp_f32_e32 v183, v183
	v_pk_mul_f32 v[76:77], v[116:117], v[76:77]
	v_pk_fma_f32 v[186:187], v[182:183], s[60:61], v[128:129] op_sel_hi:[1,0,0]
	v_pk_fma_f32 v[186:187], v[182:183], v[186:187], s[62:63] op_sel_hi:[1,1,0]
	v_cvt_pk_bf16_f32 v102, v76, v77
	v_pk_fma_f32 v[186:187], v[182:183], v[186:187], s[64:65] op_sel_hi:[1,1,0]
	v_mov_b64_e32 v[76:77], s[22:23]
	v_pk_fma_f32 v[186:187], v[182:183], v[186:187], s[66:67] op_sel_hi:[1,1,0]
	v_mad_i64_i32 v[116:117], s[0:1], v179, s93, v[76:77]
	v_pk_mul_f32 v[182:183], v[182:183], v[186:187]
	s_nop 0
	v_pk_mul_f32 v[182:183], v[184:185], v[182:183]
	s_nop 0
	v_max_f32_e32 v184, 0, v118
	v_max_f32_e32 v185, 0, v119
	v_fma_f32 v118, -|v118|, v182, v184
	v_fma_f32 v119, -|v119|, v183, v185
	s_nop 1
	v_pk_mul_f32 v[78:79], v[118:119], v[78:79]
	s_nop 0
	v_cvt_pk_bf16_f32 v103, v78, v79
	v_lshlrev_b64 v[78:79], 1, v[180:181]
	v_lshl_add_u64 v[116:117], v[116:117], 0, v[78:79]
	global_store_dwordx4 v[116:117], v[100:103], off nt
	s_nop 1
	v_fma_f32 v100, |v120|, s58, 1.0
	v_fma_f32 v101, |v121|, s58, 1.0
	v_pk_mul_f32 v[116:117], v[120:121], v[120:121]
	v_rcp_f32_e32 v100, v100
	v_rcp_f32_e32 v101, v101
	v_pk_mul_f32 v[116:117], v[116:117], s[50:51] op_sel_hi:[1,0]
	v_exp_f32_e32 v116, v116
	v_pk_fma_f32 v[102:103], v[100:101], s[60:61], v[128:129] op_sel_hi:[1,0,0]
	v_exp_f32_e32 v117, v117
	v_pk_fma_f32 v[102:103], v[100:101], v[102:103], s[62:63] op_sel_hi:[1,1,0]
	v_add_u32_e32 v124, 16, v179
	v_pk_fma_f32 v[102:103], v[100:101], v[102:103], s[64:65] op_sel_hi:[1,1,0]
	v_pk_fma_f32 v[102:103], v[100:101], v[102:103], s[66:67] op_sel_hi:[1,1,0]
	v_pk_mul_f32 v[100:101], v[100:101], v[102:103]
	v_pk_mul_f32 v[102:103], v[122:123], v[122:123]
	v_pk_mul_f32 v[100:101], v[116:117], v[100:101]
	v_pk_mul_f32 v[102:103], v[102:103], s[50:51] op_sel_hi:[1,0]
	v_max_f32_e32 v116, 0, v120
	v_max_f32_e32 v117, 0, v121
	v_exp_f32_e32 v102, v102
	v_fma_f32 v100, -|v120|, v100, v116
	v_fma_f32 v101, -|v121|, v101, v117
	v_exp_f32_e32 v103, v103
	v_fma_f32 v116, |v122|, s58, 1.0
	v_fma_f32 v117, |v123|, s58, 1.0
	v_rcp_f32_e32 v116, v116
	v_rcp_f32_e32 v117, v117
; __device__ __forceinline__ u32x4 pack8(f32x4 v0, f32x4 v1) { u32x4 w; w.x = cvt_pk_bf16(v0[0], v0[1]); w.y = cvt_pk_bf16(v0[2], v0[3]); w.z = cvt_pk_bf16(v1[0], v1[1]); w.w = cvt_pk_bf16(v1[2], v1[3]); return w; }
; __device__ __forceinline__ f32x4 gelu4(f32x4 v) { f32x2 a = gelu_pk((f32x2){v[0], v[1]}), b = gelu_pk((f32x2){v[2], v[3]}); return (f32x4){a.x, a.y, b.x, b.y}; }
; __device__ __forceinline__ f32x2 gelu_pk(f32x2 v) {
;     const f32x2 av = __builtin_elementwise_abs(v), d = av * 0.2316418882f + 1.0f;
;     f32x2 t; t.x = __builtin_amdgcn_rcpf(d.x); t.y = __builtin_amdgcn_rcpf(d.y);
;     f32x2 q = t * 0.5307027145f + (-0.7265760135f); q = q * t + 0.7107068705f; q = q * t + (-0.142248368f); q = q * t + 0.127414796f; q = q * t;
;     const f32x2 s = (v * v) * (-0.72134752044f);
;     f32x2 e; e.x = __builtin_amdgcn_exp2f(s.x); e.y = __builtin_amdgcn_exp2f(s.y);
;     const f32x2 m = v * (q * e), r = v - m;
;     f32x2 o; o.x = v.x < 0.f ? m.x : r.x; o.y = v.y < 0.f ? m.y : r.y; return o;
; }
;     __device__ __forceinline__ void operator()(f32x4 (&acc)[2][2][4][2], const Unit& u, int wr, int wc, int fr_, int fq_) const {
;     ...
;             for (int m = 0; m < 4; ++m) { const int row = u.pm * BM + blk * 64 + m * 16 + fr;
;                 const f32x4 g0 = gelu4(acc[ai][0][m][0]), g1 = gelu4(acc[ai][0][m][1]);
;                 *(u32x4*)(ACT + (size_t)row * 5632 + jcol) = pack8(g0 * acc[ai][1][m][0], g1 * acc[ai][1][m][1]); asm volatile("" ::: "memory"); __builtin_amdgcn_sched_barrier(0); }
	v_pk_mul_f32 v[120:121], v[112:113], v[112:113]
	v_pk_mul_f32 v[96:97], v[100:101], v[96:97]
	v_pk_mul_f32 v[120:121], v[120:121], s[50:51] op_sel_hi:[1,0]
	v_pk_fma_f32 v[118:119], v[116:117], s[60:61], v[128:129] op_sel_hi:[1,0,0]
	v_exp_f32_e32 v120, v120
	v_pk_fma_f32 v[118:119], v[116:117], v[118:119], s[62:63] op_sel_hi:[1,1,0]
	v_exp_f32_e32 v121, v121
	v_pk_fma_f32 v[118:119], v[116:117], v[118:119], s[64:65] op_sel_hi:[1,1,0]
	v_pk_fma_f32 v[118:119], v[116:117], v[118:119], s[66:67] op_sel_hi:[1,1,0]
	v_pk_mul_f32 v[116:117], v[116:117], v[118:119]
	v_pk_mul_f32 v[102:103], v[102:103], v[116:117]
	v_max_f32_e32 v116, 0, v122
	v_max_f32_e32 v117, 0, v123
	v_fma_f32 v102, -|v122|, v102, v116
	v_fma_f32 v103, -|v123|, v103, v117
	s_nop 0
	v_fma_f32 v116, |v112|, s58, 1.0
	v_fma_f32 v117, |v113|, s58, 1.0
	v_rcp_f32_e32 v116, v116
	v_rcp_f32_e32 v117, v117
	v_pk_mul_f32 v[98:99], v[102:103], v[98:99]
	v_pk_fma_f32 v[118:119], v[116:117], s[60:61], v[128:129] op_sel_hi:[1,0,0]
	v_pk_fma_f32 v[118:119], v[116:117], v[118:119], s[62:63] op_sel_hi:[1,1,0]
	v_pk_fma_f32 v[118:119], v[116:117], v[118:119], s[64:65] op_sel_hi:[1,1,0]
	v_pk_fma_f32 v[118:119], v[116:117], v[118:119], s[66:67] op_sel_hi:[1,1,0]
	v_pk_mul_f32 v[116:117], v[116:117], v[118:119]
	v_pk_mul_f32 v[118:119], v[114:115], v[114:115]
	v_pk_mul_f32 v[116:117], v[120:121], v[116:117]
	v_pk_mul_f32 v[118:119], v[118:119], s[50:51] op_sel_hi:[1,0]
	v_max_f32_e32 v120, 0, v112
	v_max_f32_e32 v121, 0, v113
	v_exp_f32_e32 v118, v118
	v_fma_f32 v112, -|v112|, v116, v120
	v_fma_f32 v113, -|v113|, v117, v121
	v_exp_f32_e32 v119, v119
	v_fma_f32 v116, |v114|, s58, 1.0
	v_fma_f32 v117, |v115|, s58, 1.0
	v_rcp_f32_e32 v116, v116
	v_rcp_f32_e32 v117, v117
	s_nop 0
	v_pk_fma_f32 v[120:121], v[116:117], s[60:61], v[128:129] op_sel_hi:[1,0,0]
	v_pk_fma_f32 v[120:121], v[116:117], v[120:121], s[62:63] op_sel_hi:[1,1,0]
	v_pk_fma_f32 v[120:121], v[116:117], v[120:121], s[64:65] op_sel_hi:[1,1,0]
	v_pk_fma_f32 v[120:121], v[116:117], v[120:121], s[66:67] op_sel_hi:[1,1,0]
	v_pk_mul_f32 v[116:117], v[116:117], v[120:121]
	v_pk_mul_f32 v[116:117], v[118:119], v[116:117]
	v_max_f32_e32 v118, 0, v114
	v_max_f32_e32 v119, 0, v115
	v_fma_f32 v114, -|v114|, v116, v118
	v_fma_f32 v115, -|v115|, v117, v119
	s_nop 1
	v_pk_mul_f32 v[100:101], v[114:115], v[74:75]
	v_pk_mul_f32 v[74:75], v[112:113], v[72:73]
	v_cvt_pk_bf16_f32 v72, v96, v97
	v_mad_i64_i32 v[96:97], s[0:1], v124, s93, v[76:77]
	v_cvt_pk_bf16_f32 v73, v98, v99
	v_cvt_pk_bf16_f32 v74, v74, v75
	v_cvt_pk_bf16_f32 v75, v100, v101
	v_lshl_add_u64 v[96:97], v[96:97], 0, v[78:79]
	global_store_dwordx4 v[96:97], v[72:75], off nt
	s_nop 1
	v_fma_f32 v72, |v104|, s58, 1.0
	v_fma_f32 v73, |v105|, s58, 1.0
	v_pk_mul_f32 v[96:97], v[104:105], v[104:105]
	v_rcp_f32_e32 v72, v72
	v_rcp_f32_e32 v73, v73
	v_pk_mul_f32 v[96:97], v[96:97], s[50:51] op_sel_hi:[1,0]
	v_exp_f32_e32 v96, v96
	v_pk_fma_f32 v[74:75], v[72:73], s[60:61], v[128:129] op_sel_hi:[1,0,0]
	v_exp_f32_e32 v97, v97
	v_pk_fma_f32 v[74:75], v[72:73], v[74:75], s[62:63] op_sel_hi:[1,1,0]
	v_pk_mul_f32 v[100:101], v[108:109], v[108:109]
	v_pk_fma_f32 v[74:75], v[72:73], v[74:75], s[64:65] op_sel_hi:[1,1,0]
	v_pk_mul_f32 v[100:101], v[100:101], s[50:51] op_sel_hi:[1,0]
	v_pk_fma_f32 v[74:75], v[72:73], v[74:75], s[66:67] op_sel_hi:[1,1,0]
	v_exp_f32_e32 v100, v100
	v_pk_mul_f32 v[72:73], v[72:73], v[74:75]
	v_pk_mul_f32 v[74:75], v[106:107], v[106:107]
	v_pk_mul_f32 v[72:73], v[96:97], v[72:73]
	v_pk_mul_f32 v[74:75], v[74:75], s[50:51] op_sel_hi:[1,0]
	v_max_f32_e32 v96, 0, v104
	v_max_f32_e32 v97, 0, v105
	v_exp_f32_e32 v74, v74
	v_fma_f32 v72, -|v104|, v72, v96
	v_fma_f32 v73, -|v105|, v73, v97
	v_exp_f32_e32 v75, v75
	v_fma_f32 v96, |v106|, s58, 1.0
	v_fma_f32 v97, |v107|, s58, 1.0
	v_rcp_f32_e32 v96, v96
	v_rcp_f32_e32 v97, v97
	v_exp_f32_e32 v101, v101
	v_add_u32_e32 v112, 32, v179
	v_pk_mul_f32 v[72:73], v[72:73], v[88:89]
	v_pk_fma_f32 v[98:99], v[96:97], s[60:61], v[128:129] op_sel_hi:[1,0,0]
	v_pk_fma_f32 v[98:99], v[96:97], v[98:99], s[62:63] op_sel_hi:[1,1,0]
	v_pk_fma_f32 v[98:99], v[96:97], v[98:99], s[64:65] op_sel_hi:[1,1,0]
	v_pk_fma_f32 v[98:99], v[96:97], v[98:99], s[66:67] op_sel_hi:[1,1,0]
	v_pk_mul_f32 v[96:97], v[96:97], v[98:99]
	v_pk_mul_f32 v[74:75], v[74:75], v[96:97]
	v_max_f32_e32 v96, 0, v106
	v_max_f32_e32 v97, 0, v107
	v_fma_f32 v74, -|v106|, v74, v96
	v_fma_f32 v75, -|v107|, v75, v97
	s_nop 0
	v_fma_f32 v96, |v108|, s58, 1.0
	v_fma_f32 v97, |v109|, s58, 1.0
	v_rcp_f32_e32 v96, v96
	v_rcp_f32_e32 v97, v97
	v_pk_mul_f32 v[74:75], v[74:75], v[90:91]
	v_pk_fma_f32 v[98:99], v[96:97], s[60:61], v[128:129] op_sel_hi:[1,0,0]
	v_pk_fma_f32 v[98:99], v[96:97], v[98:99], s[62:63] op_sel_hi:[1,1,0]
	v_pk_fma_f32 v[98:99], v[96:97], v[98:99], s[64:65] op_sel_hi:[1,1,0]
	v_pk_fma_f32 v[98:99], v[96:97], v[98:99], s[66:67] op_sel_hi:[1,1,0]
	v_pk_mul_f32 v[96:97], v[96:97], v[98:99]
	v_pk_mul_f32 v[98:99], v[110:111], v[110:111]
	v_pk_mul_f32 v[96:97], v[100:101], v[96:97]
	v_pk_mul_f32 v[98:99], v[98:99], s[50:51] op_sel_hi:[1,0]
	v_max_f32_e32 v100, 0, v108
	v_max_f32_e32 v101, 0, v109
	v_exp_f32_e32 v98, v98
	v_fma_f32 v96, -|v108|, v96, v100
	v_fma_f32 v97, -|v109|, v97, v101
	v_exp_f32_e32 v99, v99
	v_fma_f32 v100, |v110|, s58, 1.0
	v_fma_f32 v101, |v111|, s58, 1.0
	v_rcp_f32_e32 v100, v100
	v_rcp_f32_e32 v101, v101
	s_nop 0
	v_pk_fma_f32 v[102:103], v[100:101], s[60:61], v[128:129] op_sel_hi:[1,0,0]
	v_pk_fma_f32 v[102:103], v[100:101], v[102:103], s[62:63] op_sel_hi:[1,1,0]
	v_pk_fma_f32 v[102:103], v[100:101], v[102:103], s[64:65] op_sel_hi:[1,1,0]
; #define PG8_LAS __attribute__((address_space(3)))
; __device__ __forceinline__ u32x4 pack8(f32x4 v0, f32x4 v1) { u32x4 w; w.x = cvt_pk_bf16(v0[0], v0[1]); w.y = cvt_pk_bf16(v0[2], v0[3]); w.z = cvt_pk_bf16(v1[0], v1[1]); w.w = cvt_pk_bf16(v1[2], v1[3]); return w; }
; __device__ __forceinline__ f32x4 gelu4(f32x4 v) { f32x2 a = gelu_pk((f32x2){v[0], v[1]}), b = gelu_pk((f32x2){v[2], v[3]}); return (f32x4){a.x, a.y, b.x, b.y}; }
;     __device__ __forceinline__ void operator()(f32x4 (&acc)[2][2][4][2], const Unit& u, int wr, int wc, int fr_, int fq_) const {
;     ...
;                     const int ct = bj * HALF + wc * 32 + 8 * fq + 4 * n;
;                     const int cidx = bj * 5632 + jcol + 4 * n;
;                     const f32x4 w0 = *(const f32x4*)(cw + cidx), w1 = *(const f32x4*)(cw + 11264 + cidx), w2 = *(const f32x4*)(cw + 22528 + cidx), b4 = *(const f32x4*)(cb + cidx);
;                     f32x4 pR1 = (f32x4){0.f, 0.f, 0.f, 0.f}, pR2 = pR1;
;                     if (blk) { const f32x4 h14 = *(const PG8_LAS f32x4*)(hal + ((blk - 1) * 2 + 0) * 256 + ct) * rs14, h15 = *(const PG8_LAS f32x4*)(hal + ((blk - 1) * 2 + 1) * 256 + ct) * rs15;
;                         pR1 = h15; pR2 = (fr == 0) ? h14 : h15; }
;     ...
;             for (int m = 0; m < 4; ++m) { const int row = u.pm * BM + blk * 64 + m * 16 + fr;
;                 const f32x4 g0 = gelu4(acc[ai][0][m][0]), g1 = gelu4(acc[ai][0][m][1]);
;                 *(u32x4*)(ACT + (size_t)row * 5632 + jcol) = pack8(g0 * acc[ai][1][m][0], g1 * acc[ai][1][m][1]); asm volatile("" ::: "memory"); __builtin_amdgcn_sched_barrier(0); }
	v_pk_fma_f32 v[102:103], v[100:101], v[102:103], s[66:67] op_sel_hi:[1,1,0]
	v_pk_mul_f32 v[100:101], v[100:101], v[102:103]
	v_pk_mul_f32 v[98:99], v[98:99], v[100:101]
	v_max_f32_e32 v100, 0, v110
	v_max_f32_e32 v101, 0, v111
	v_fma_f32 v98, -|v110|, v98, v100
	v_fma_f32 v99, -|v111|, v99, v101
	s_nop 1
	v_pk_mul_f32 v[88:89], v[98:99], v[70:71]
	v_pk_mul_f32 v[70:71], v[96:97], v[68:69]
	v_cvt_pk_bf16_f32 v68, v72, v73
	v_mad_i64_i32 v[72:73], s[0:1], v112, s93, v[76:77]
	v_cvt_pk_bf16_f32 v69, v74, v75
	v_cvt_pk_bf16_f32 v70, v70, v71
	v_cvt_pk_bf16_f32 v71, v88, v89
	v_lshl_add_u64 v[72:73], v[72:73], 0, v[78:79]
	global_store_dwordx4 v[72:73], v[68:71], off nt
	s_nop 1
	v_fma_f32 v68, |v80|, s58, 1.0
	v_fma_f32 v69, |v81|, s58, 1.0
	v_pk_mul_f32 v[72:73], v[80:81], v[80:81]
	v_rcp_f32_e32 v68, v68
	v_rcp_f32_e32 v69, v69
	v_pk_mul_f32 v[72:73], v[72:73], s[50:51] op_sel_hi:[1,0]
	v_exp_f32_e32 v72, v72
	v_pk_fma_f32 v[70:71], v[68:69], s[60:61], v[128:129] op_sel_hi:[1,0,0]
	v_exp_f32_e32 v73, v73
	v_pk_fma_f32 v[70:71], v[68:69], v[70:71], s[62:63] op_sel_hi:[1,1,0]
	v_add_u32_e32 v88, 48, v179
	v_pk_fma_f32 v[70:71], v[68:69], v[70:71], s[64:65] op_sel_hi:[1,1,0]
	v_pk_fma_f32 v[70:71], v[68:69], v[70:71], s[66:67] op_sel_hi:[1,1,0]
	v_pk_mul_f32 v[68:69], v[68:69], v[70:71]
	v_pk_mul_f32 v[70:71], v[82:83], v[82:83]
	v_pk_mul_f32 v[68:69], v[72:73], v[68:69]
	v_pk_mul_f32 v[70:71], v[70:71], s[50:51] op_sel_hi:[1,0]
	v_max_f32_e32 v72, 0, v80
	v_max_f32_e32 v73, 0, v81
	v_exp_f32_e32 v70, v70
	v_fma_f32 v68, -|v80|, v68, v72
	v_fma_f32 v69, -|v81|, v69, v73
	v_exp_f32_e32 v71, v71
	v_fma_f32 v72, |v82|, s58, 1.0
	v_fma_f32 v73, |v83|, s58, 1.0
	v_rcp_f32_e32 v72, v72
	v_rcp_f32_e32 v73, v73
	v_pk_mul_f32 v[80:81], v[92:93], v[92:93]
	v_pk_mul_f32 v[68:69], v[68:69], v[84:85]
	v_pk_mul_f32 v[80:81], v[80:81], s[50:51] op_sel_hi:[1,0]
	v_pk_fma_f32 v[74:75], v[72:73], s[60:61], v[128:129] op_sel_hi:[1,0,0]
	v_exp_f32_e32 v80, v80
	v_pk_fma_f32 v[74:75], v[72:73], v[74:75], s[62:63] op_sel_hi:[1,1,0]
	v_exp_f32_e32 v81, v81
	v_pk_fma_f32 v[74:75], v[72:73], v[74:75], s[64:65] op_sel_hi:[1,1,0]
	v_pk_fma_f32 v[74:75], v[72:73], v[74:75], s[66:67] op_sel_hi:[1,1,0]
	v_pk_mul_f32 v[72:73], v[72:73], v[74:75]
	v_pk_mul_f32 v[70:71], v[70:71], v[72:73]
	v_max_f32_e32 v72, 0, v82
	v_max_f32_e32 v73, 0, v83
	v_fma_f32 v70, -|v82|, v70, v72
	v_fma_f32 v71, -|v83|, v71, v73
	s_nop 0
	v_fma_f32 v72, |v92|, s58, 1.0
	v_fma_f32 v73, |v93|, s58, 1.0
	v_rcp_f32_e32 v72, v72
	v_rcp_f32_e32 v73, v73
	v_pk_mul_f32 v[70:71], v[70:71], v[86:87]
	v_pk_fma_f32 v[74:75], v[72:73], s[60:61], v[128:129] op_sel_hi:[1,0,0]
	v_pk_fma_f32 v[74:75], v[72:73], v[74:75], s[62:63] op_sel_hi:[1,1,0]
	v_pk_fma_f32 v[74:75], v[72:73], v[74:75], s[64:65] op_sel_hi:[1,1,0]
	v_pk_fma_f32 v[74:75], v[72:73], v[74:75], s[66:67] op_sel_hi:[1,1,0]
	v_pk_mul_f32 v[72:73], v[72:73], v[74:75]
	v_pk_mul_f32 v[74:75], v[94:95], v[94:95]
	v_pk_mul_f32 v[72:73], v[80:81], v[72:73]
	v_pk_mul_f32 v[74:75], v[74:75], s[50:51] op_sel_hi:[1,0]
	v_max_f32_e32 v80, 0, v92
	v_max_f32_e32 v81, 0, v93
	v_exp_f32_e32 v74, v74
	v_fma_f32 v72, -|v92|, v72, v80
	v_fma_f32 v73, -|v93|, v73, v81
	v_exp_f32_e32 v75, v75
	v_fma_f32 v80, |v94|, s58, 1.0
	v_fma_f32 v81, |v95|, s58, 1.0
	v_rcp_f32_e32 v80, v80
	v_rcp_f32_e32 v81, v81
	s_nop 0
	v_pk_fma_f32 v[82:83], v[80:81], s[60:61], v[128:129] op_sel_hi:[1,0,0]
	v_pk_fma_f32 v[82:83], v[80:81], v[82:83], s[62:63] op_sel_hi:[1,1,0]
	v_pk_fma_f32 v[82:83], v[80:81], v[82:83], s[64:65] op_sel_hi:[1,1,0]
	v_pk_fma_f32 v[82:83], v[80:81], v[82:83], s[66:67] op_sel_hi:[1,1,0]
	v_pk_mul_f32 v[80:81], v[80:81], v[82:83]
	v_pk_mul_f32 v[74:75], v[74:75], v[80:81]
	v_max_f32_e32 v80, 0, v94
	v_max_f32_e32 v81, 0, v95
	v_fma_f32 v74, -|v94|, v74, v80
	v_fma_f32 v75, -|v95|, v75, v81
	s_nop 1
	v_pk_mul_f32 v[74:75], v[74:75], v[66:67]
	v_pk_mul_f32 v[66:67], v[72:73], v[64:65]
	v_cvt_pk_bf16_f32 v64, v68, v69
	v_mad_i64_i32 v[68:69], s[0:1], v88, s93, v[76:77]
	v_cvt_pk_bf16_f32 v65, v70, v71
	v_cvt_pk_bf16_f32 v66, v66, v67
	v_cvt_pk_bf16_f32 v67, v74, v75
	v_lshl_add_u64 v[68:69], v[68:69], 0, v[78:79]
	global_store_dwordx4 v[68:69], v[64:67], off nt
	global_load_dwordx4 v[80:83], v[166:167], off
	global_load_dwordx4 v[84:87], v[164:165], off
	global_load_dwordx4 v[88:91], v[168:169], off
	global_load_dwordx4 v[92:95], v[170:171], off
	v_mov_b32_e32 v65, s96
	v_add_u32_e32 v71, s97, v154
	ds_read_b64 v[66:67], v65
	ds_read_b128 v[96:99], v71
	v_add_u32_e32 v64, s89, v225
	v_add_u32_e32 v73, s14, v154
	ds_read_b128 v[100:103], v73
	ds_read2_b32 v[68:69], v64 offset1:16
	ds_read2_b32 v[64:65], v64 offset0:32 offset1:48
	s_waitcnt lgkmcnt(3)
	v_pk_mul_f32 v[74:75], v[66:67], v[98:99] op_sel_hi:[0,1]
	v_pk_mul_f32 v[96:97], v[66:67], v[96:97] op_sel_hi:[0,1]
	s_waitcnt lgkmcnt(2)
	v_pk_mul_f32 v[98:99], v[66:67], v[102:103] op_sel:[1,0]
	v_pk_mul_f32 v[100:101], v[66:67], v[100:101] op_sel:[1,0]
	v_cndmask_b32_e64 v70, v99, v75, s[10:11]
	v_cndmask_b32_e64 v72, v98, v74, s[10:11]
	v_cndmask_b32_e64 v102, v101, v97, s[10:11]
	v_cndmask_b32_e64 v103, v100, v96, s[10:11]
	s_waitcnt lgkmcnt(1)
; #define PG8_LAS __attribute__((address_space(3)))
; __device__ __forceinline__ float dpp_ror1(float x) { float r; asm volatile("s_nop 1\n\tv_mov_b32_dpp %0, %1 row_ror:1 row_mask:0xf bank_mask:0xf" : "=&v"(r) : "v"(x)); return r; }
; __device__ __forceinline__ float dpp_ror2(float x) { float r; asm volatile("s_nop 1\n\tv_mov_b32_dpp %0, %1 row_ror:2 row_mask:0xf bank_mask:0xf" : "=&v"(r) : "v"(x)); return r; }
;     __device__ __forceinline__ void operator()(f32x4 (&acc)[2][2][4][2], const Unit& u, int wr, int wc, int fr_, int fq_) const {
;     ...
;                     const int ct = bj * HALF + wc * 32 + 8 * fq + 4 * n;
;                     const int cidx = bj * 5632 + jcol + 4 * n;
;                     const f32x4 w0 = *(const f32x4*)(cw + cidx), w1 = *(const f32x4*)(cw + 11264 + cidx), w2 = *(const f32x4*)(cw + 22528 + cidx), b4 = *(const f32x4*)(cb + cidx);
;                     f32x4 pR1 = (f32x4){0.f, 0.f, 0.f, 0.f}, pR2 = pR1;
;                     if (blk) { const f32x4 h14 = *(const PG8_LAS f32x4*)(hal + ((blk - 1) * 2 + 0) * 256 + ct) * rs14, h15 = *(const PG8_LAS f32x4*)(hal + ((blk - 1) * 2 + 1) * 256 + ct) * rs15;
;                         pR1 = h15; pR2 = (fr == 0) ? h14 : h15; }
; #pragma unroll
;                     for (int m = 0; m < 4; ++m) {
;                         const f32x4 U = acc[ai][bj][m][n] * rsr[m];
;                         f32x4 R1, R2;
; #pragma unroll
;                         for (int i = 0; i < 4; ++i) { R1[i] = dpp_ror1(U[i]); R2[i] = dpp_ror2(U[i]); }
;                         const f32x4 U1 = (fr >= 1) ? R1 : pR1, U2 = (fr >= 2) ? R2 : pR2;
;                         const f32x4 C = b4 + w0 * U2 + w1 * U1 + w2 * U;
;                         acc[ai][bj][m][n] = C; pR1 = R1; pR2 = R2;
;                         asm volatile("" : "+v"(acc[ai][bj][m][n]));
;                         __builtin_amdgcn_sched_barrier(0);
;                     }
	v_pk_mul_f32 v[62:63], v[62:63], v[68:69] op_sel_hi:[1,0]
	v_pk_mul_f32 v[60:61], v[60:61], v[68:69] op_sel_hi:[1,0]
	s_nop 0
	s_nop 1
	v_mov_b32_dpp v104, v60 row_ror:1 row_mask:0xf bank_mask:0xf
	v_mov_b32_dpp v105, v60 row_ror:2 row_mask:0xf bank_mask:0xf
	v_mov_b32_dpp v106, v61 row_ror:1 row_mask:0xf bank_mask:0xf
	v_mov_b32_dpp v107, v61 row_ror:2 row_mask:0xf bank_mask:0xf
	v_mov_b32_dpp v108, v62 row_ror:1 row_mask:0xf bank_mask:0xf
	v_mov_b32_dpp v109, v62 row_ror:2 row_mask:0xf bank_mask:0xf
	v_mov_b32_dpp v110, v63 row_ror:1 row_mask:0xf bank_mask:0xf
	v_mov_b32_dpp v111, v63 row_ror:2 row_mask:0xf bank_mask:0xf
	v_cndmask_b32_e64 v96, v100, v104, s[6:7]
	v_cndmask_b32_e64 v74, v98, v108, s[6:7]
	v_cndmask_b32_e64 v75, v99, v110, s[6:7]
	v_cndmask_b32_e64 v97, v101, v106, s[6:7]
	v_cndmask_b32_e64 v98, v72, v109, s[8:9]
	v_cndmask_b32_e64 v99, v70, v111, s[8:9]
	v_cndmask_b32_e64 v100, v103, v105, s[8:9]
	v_cndmask_b32_e64 v101, v102, v107, s[8:9]
	s_waitcnt vmcnt(2)
	v_pk_fma_f32 v[98:99], v[86:87], v[98:99], v[82:83]
	v_pk_fma_f32 v[100:101], v[84:85], v[100:101], v[80:81]
	s_waitcnt vmcnt(1)
	v_pk_fma_f32 v[74:75], v[90:91], v[74:75], v[98:99]
	v_pk_fma_f32 v[96:97], v[88:89], v[96:97], v[100:101]
	s_waitcnt vmcnt(0)
	v_pk_fma_f32 v[62:63], v[62:63], v[94:95], v[74:75]
	v_pk_fma_f32 v[60:61], v[60:61], v[92:93], v[96:97]
	v_mov_b32_e32 v70, v69
	v_pk_mul_f32 v[58:59], v[58:59], v[70:71] op_sel_hi:[1,0]
	v_pk_mul_f32 v[56:57], v[56:57], v[70:71] op_sel_hi:[1,0]
	s_nop 1
	v_mov_b32_dpp v69, v56 row_ror:1 row_mask:0xf bank_mask:0xf
	v_mov_b32_dpp v72, v56 row_ror:2 row_mask:0xf bank_mask:0xf
	v_mov_b32_dpp v102, v57 row_ror:1 row_mask:0xf bank_mask:0xf
	v_mov_b32_dpp v103, v57 row_ror:2 row_mask:0xf bank_mask:0xf
	v_mov_b32_dpp v112, v58 row_ror:1 row_mask:0xf bank_mask:0xf
	v_mov_b32_dpp v113, v58 row_ror:2 row_mask:0xf bank_mask:0xf
	v_mov_b32_dpp v114, v59 row_ror:1 row_mask:0xf bank_mask:0xf
	v_mov_b32_dpp v115, v59 row_ror:2 row_mask:0xf bank_mask:0xf
	v_cndmask_b32_e64 v100, v105, v72, s[8:9]
	v_cndmask_b32_e64 v98, v109, v113, s[8:9]
	v_cndmask_b32_e64 v99, v111, v115, s[8:9]
	v_cndmask_b32_e64 v101, v107, v103, s[8:9]
	v_cndmask_b32_e64 v74, v108, v112, s[6:7]
	v_cndmask_b32_e64 v75, v110, v114, s[6:7]
	v_cndmask_b32_e64 v96, v104, v69, s[6:7]
	v_cndmask_b32_e64 v97, v106, v102, s[6:7]
	v_pk_fma_f32 v[98:99], v[86:87], v[98:99], v[82:83]
	v_pk_fma_f32 v[100:101], v[84:85], v[100:101], v[80:81]
	v_pk_fma_f32 v[74:75], v[90:91], v[74:75], v[98:99]
	v_pk_fma_f32 v[96:97], v[88:89], v[96:97], v[100:101]
	v_pk_fma_f32 v[58:59], v[58:59], v[94:95], v[74:75]
	v_pk_fma_f32 v[56:57], v[56:57], v[92:93], v[96:97]
	s_nop 0
	s_waitcnt lgkmcnt(0)
	v_pk_mul_f32 v[54:55], v[54:55], v[64:65] op_sel_hi:[1,0]
	v_pk_mul_f32 v[52:53], v[52:53], v[64:65] op_sel_hi:[1,0]
	s_nop 0
	s_nop 1
	v_mov_b32_dpp v104, v52 row_ror:1 row_mask:0xf bank_mask:0xf
	v_mov_b32_dpp v105, v52 row_ror:2 row_mask:0xf bank_mask:0xf
	v_mov_b32_dpp v106, v53 row_ror:1 row_mask:0xf bank_mask:0xf
	v_mov_b32_dpp v107, v53 row_ror:2 row_mask:0xf bank_mask:0xf
	v_mov_b32_dpp v108, v54 row_ror:1 row_mask:0xf bank_mask:0xf
	v_mov_b32_dpp v109, v54 row_ror:2 row_mask:0xf bank_mask:0xf
	v_mov_b32_dpp v110, v55 row_ror:1 row_mask:0xf bank_mask:0xf
	v_mov_b32_dpp v111, v55 row_ror:2 row_mask:0xf bank_mask:0xf
	v_cndmask_b32_e64 v100, v72, v105, s[8:9]
	v_cndmask_b32_e64 v98, v113, v109, s[8:9]
	v_cndmask_b32_e64 v99, v115, v111, s[8:9]
	v_cndmask_b32_e64 v101, v103, v107, s[8:9]
	v_cndmask_b32_e64 v74, v112, v108, s[6:7]
	v_cndmask_b32_e64 v75, v114, v110, s[6:7]
	v_cndmask_b32_e64 v96, v69, v104, s[6:7]
	v_cndmask_b32_e64 v97, v102, v106, s[6:7]
	v_pk_fma_f32 v[98:99], v[86:87], v[98:99], v[82:83]
	v_pk_fma_f32 v[100:101], v[84:85], v[100:101], v[80:81]
	v_pk_fma_f32 v[74:75], v[90:91], v[74:75], v[98:99]
	v_pk_fma_f32 v[96:97], v[88:89], v[96:97], v[100:101]
	v_pk_fma_f32 v[54:55], v[54:55], v[94:95], v[74:75]
	v_pk_fma_f32 v[52:53], v[52:53], v[92:93], v[96:97]
	v_mov_b32_e32 v72, v65
	v_pk_mul_f32 v[50:51], v[50:51], v[72:73] op_sel_hi:[1,0]
	v_pk_mul_f32 v[48:49], v[48:49], v[72:73] op_sel_hi:[1,0]
	s_nop 1
	v_mov_b32_dpp v65, v48 row_ror:1 row_mask:0xf bank_mask:0xf
	v_mov_b32_dpp v69, v48 row_ror:2 row_mask:0xf bank_mask:0xf
	v_mov_b32_dpp v97, v49 row_ror:1 row_mask:0xf bank_mask:0xf
	v_mov_b32_dpp v101, v49 row_ror:2 row_mask:0xf bank_mask:0xf
	v_mov_b32_dpp v74, v50 row_ror:1 row_mask:0xf bank_mask:0xf
	v_mov_b32_dpp v98, v50 row_ror:2 row_mask:0xf bank_mask:0xf
	v_mov_b32_dpp v75, v51 row_ror:1 row_mask:0xf bank_mask:0xf
	v_mov_b32_dpp v99, v51 row_ror:2 row_mask:0xf bank_mask:0xf
	v_cndmask_b32_e64 v100, v105, v69, s[8:9]
	v_cndmask_b32_e64 v98, v109, v98, s[8:9]
	v_cndmask_b32_e64 v99, v111, v99, s[8:9]
	v_cndmask_b32_e64 v101, v107, v101, s[8:9]
	v_cndmask_b32_e64 v74, v108, v74, s[6:7]
	v_cndmask_b32_e64 v75, v110, v75, s[6:7]
	v_cndmask_b32_e64 v96, v104, v65, s[6:7]
	v_cndmask_b32_e64 v97, v106, v97, s[6:7]
	v_pk_fma_f32 v[82:83], v[86:87], v[98:99], v[82:83]
	v_pk_fma_f32 v[80:81], v[84:85], v[100:101], v[80:81]
	v_pk_fma_f32 v[74:75], v[90:91], v[74:75], v[82:83]
	v_pk_fma_f32 v[80:81], v[88:89], v[96:97], v[80:81]
	v_pk_fma_f32 v[50:51], v[50:51], v[94:95], v[74:75]
	v_pk_fma_f32 v[48:49], v[48:49], v[92:93], v[80:81]
	s_nop 0
	global_load_dwordx4 v[80:83], v[164:165], off offset:16
	global_load_dwordx4 v[84:87], v[166:167], off offset:16
	global_load_dwordx4 v[88:91], v[172:173], off
	global_load_dwordx4 v[92:95], v[174:175], off
	v_pk_mul_f32 v[74:75], v[46:47], v[68:69] op_sel_hi:[1,0]
	v_pk_mul_f32 v[100:101], v[44:45], v[68:69] op_sel_hi:[1,0]
	ds_read_b128 v[44:47], v71 offset:16
	ds_read_b128 v[96:99], v73 offset:16
	s_nop 1
	v_mov_b32_dpp v65, v100 row_ror:1 row_mask:0xf bank_mask:0xf
	v_mov_b32_dpp v69, v100 row_ror:2 row_mask:0xf bank_mask:0xf
	v_mov_b32_dpp v102, v101 row_ror:1 row_mask:0xf bank_mask:0xf
	s_waitcnt lgkmcnt(1)
; #define PG8_LAS __attribute__((address_space(3)))
; __device__ __forceinline__ float dpp_ror1(float x) { float r; asm volatile("s_nop 1\n\tv_mov_b32_dpp %0, %1 row_ror:1 row_mask:0xf bank_mask:0xf" : "=&v"(r) : "v"(x)); return r; }
; __device__ __forceinline__ float dpp_ror2(float x) { float r; asm volatile("s_nop 1\n\tv_mov_b32_dpp %0, %1 row_ror:2 row_mask:0xf bank_mask:0xf" : "=&v"(r) : "v"(x)); return r; }
;     __device__ __forceinline__ void operator()(f32x4 (&acc)[2][2][4][2], const Unit& u, int wr, int wc, int fr_, int fq_) const {
;     ...
;                     const int ct = bj * HALF + wc * 32 + 8 * fq + 4 * n;
;                     const int cidx = bj * 5632 + jcol + 4 * n;
;                     const f32x4 w0 = *(const f32x4*)(cw + cidx), w1 = *(const f32x4*)(cw + 11264 + cidx), w2 = *(const f32x4*)(cw + 22528 + cidx), b4 = *(const f32x4*)(cb + cidx);
;                     f32x4 pR1 = (f32x4){0.f, 0.f, 0.f, 0.f}, pR2 = pR1;
;                     if (blk) { const f32x4 h14 = *(const PG8_LAS f32x4*)(hal + ((blk - 1) * 2 + 0) * 256 + ct) * rs14, h15 = *(const PG8_LAS f32x4*)(hal + ((blk - 1) * 2 + 1) * 256 + ct) * rs15;
;                         pR1 = h15; pR2 = (fr == 0) ? h14 : h15; }
; #pragma unroll
;                     for (int m = 0; m < 4; ++m) {
;                         const f32x4 U = acc[ai][bj][m][n] * rsr[m];
;                         f32x4 R1, R2;
; #pragma unroll
;                         for (int i = 0; i < 4; ++i) { R1[i] = dpp_ror1(U[i]); R2[i] = dpp_ror2(U[i]); }
;                         const f32x4 U1 = (fr >= 1) ? R1 : pR1, U2 = (fr >= 2) ? R2 : pR2;
;                         const f32x4 C = b4 + w0 * U2 + w1 * U1 + w2 * U;
;                         acc[ai][bj][m][n] = C; pR1 = R1; pR2 = R2;
;                         asm volatile("" : "+v"(acc[ai][bj][m][n]));
;                         __builtin_amdgcn_sched_barrier(0);
;                     }
	v_pk_mul_f32 v[46:47], v[66:67], v[46:47] op_sel_hi:[0,1]
	v_pk_mul_f32 v[44:45], v[66:67], v[44:45] op_sel_hi:[0,1]
	s_waitcnt lgkmcnt(0)
	v_pk_mul_f32 v[98:99], v[66:67], v[98:99] op_sel:[1,0]
	v_pk_mul_f32 v[96:97], v[66:67], v[96:97] op_sel:[1,0]
	v_cndmask_b32_e64 v108, v99, v47, s[10:11]
	v_cndmask_b32_e64 v109, v98, v46, s[10:11]
	v_cndmask_b32_e64 v110, v96, v44, s[10:11]
	v_cndmask_b32_e64 v111, v97, v45, s[10:11]
	s_nop 1
	v_mov_b32_dpp v103, v101 row_ror:2 row_mask:0xf bank_mask:0xf
	v_mov_b32_dpp v104, v74 row_ror:1 row_mask:0xf bank_mask:0xf
	v_mov_b32_dpp v105, v74 row_ror:2 row_mask:0xf bank_mask:0xf
	v_mov_b32_dpp v106, v75 row_ror:1 row_mask:0xf bank_mask:0xf
	v_mov_b32_dpp v107, v75 row_ror:2 row_mask:0xf bank_mask:0xf
	v_cndmask_b32_e64 v47, v97, v102, s[6:7]
	v_cndmask_b32_e64 v44, v98, v104, s[6:7]
	v_cndmask_b32_e64 v45, v99, v106, s[6:7]
	v_cndmask_b32_e64 v46, v96, v65, s[6:7]
	v_cndmask_b32_e64 v96, v109, v105, s[8:9]
	v_cndmask_b32_e64 v97, v108, v107, s[8:9]
	v_cndmask_b32_e64 v99, v111, v103, s[8:9]
	v_cndmask_b32_e64 v98, v110, v69, s[8:9]
	s_waitcnt vmcnt(2)
	v_pk_fma_f32 v[96:97], v[82:83], v[96:97], v[86:87]
	v_pk_fma_f32 v[98:99], v[80:81], v[98:99], v[84:85]
	s_waitcnt vmcnt(1)
	v_pk_fma_f32 v[44:45], v[90:91], v[44:45], v[96:97]
	v_pk_fma_f32 v[96:97], v[88:89], v[46:47], v[98:99]
	s_waitcnt vmcnt(0)
	v_pk_fma_f32 v[46:47], v[74:75], v[94:95], v[44:45]
	v_pk_fma_f32 v[44:45], v[100:101], v[92:93], v[96:97]
	v_pk_mul_f32 v[42:43], v[42:43], v[70:71] op_sel_hi:[1,0]
	v_pk_mul_f32 v[40:41], v[40:41], v[70:71] op_sel_hi:[1,0]
	s_nop 1
	v_mov_b32_dpp v108, v40 row_ror:1 row_mask:0xf bank_mask:0xf
	v_mov_b32_dpp v109, v40 row_ror:2 row_mask:0xf bank_mask:0xf
	v_mov_b32_dpp v110, v41 row_ror:1 row_mask:0xf bank_mask:0xf
	v_mov_b32_dpp v111, v41 row_ror:2 row_mask:0xf bank_mask:0xf
	v_mov_b32_dpp v112, v42 row_ror:1 row_mask:0xf bank_mask:0xf
	v_mov_b32_dpp v113, v42 row_ror:2 row_mask:0xf bank_mask:0xf
	v_mov_b32_dpp v114, v43 row_ror:1 row_mask:0xf bank_mask:0xf
	v_mov_b32_dpp v115, v43 row_ror:2 row_mask:0xf bank_mask:0xf
	v_cndmask_b32_e64 v100, v69, v109, s[8:9]
	v_cndmask_b32_e64 v98, v105, v113, s[8:9]
	v_cndmask_b32_e64 v99, v107, v115, s[8:9]
	v_cndmask_b32_e64 v101, v103, v111, s[8:9]
	v_cndmask_b32_e64 v74, v104, v112, s[6:7]
	v_cndmask_b32_e64 v75, v106, v114, s[6:7]
	v_cndmask_b32_e64 v96, v65, v108, s[6:7]
	v_cndmask_b32_e64 v97, v102, v110, s[6:7]
	v_pk_fma_f32 v[98:99], v[82:83], v[98:99], v[86:87]
	v_pk_fma_f32 v[100:101], v[80:81], v[100:101], v[84:85]
	v_pk_fma_f32 v[74:75], v[90:91], v[74:75], v[98:99]
	v_pk_fma_f32 v[96:97], v[88:89], v[96:97], v[100:101]
	v_pk_fma_f32 v[42:43], v[42:43], v[94:95], v[74:75]
	v_pk_fma_f32 v[40:41], v[40:41], v[92:93], v[96:97]
	v_pk_mul_f32 v[38:39], v[38:39], v[64:65] op_sel_hi:[1,0]
	v_pk_mul_f32 v[36:37], v[36:37], v[64:65] op_sel_hi:[1,0]
	s_nop 1
	v_mov_b32_dpp v65, v36 row_ror:1 row_mask:0xf bank_mask:0xf
	v_mov_b32_dpp v69, v36 row_ror:2 row_mask:0xf bank_mask:0xf
	v_mov_b32_dpp v102, v37 row_ror:1 row_mask:0xf bank_mask:0xf
	v_mov_b32_dpp v103, v37 row_ror:2 row_mask:0xf bank_mask:0xf
	v_mov_b32_dpp v104, v38 row_ror:1 row_mask:0xf bank_mask:0xf
	v_mov_b32_dpp v105, v38 row_ror:2 row_mask:0xf bank_mask:0xf
	v_mov_b32_dpp v106, v39 row_ror:1 row_mask:0xf bank_mask:0xf
	v_mov_b32_dpp v107, v39 row_ror:2 row_mask:0xf bank_mask:0xf
	v_cndmask_b32_e64 v100, v109, v69, s[8:9]
	v_cndmask_b32_e64 v98, v113, v105, s[8:9]
	v_cndmask_b32_e64 v99, v115, v107, s[8:9]
	v_cndmask_b32_e64 v101, v111, v103, s[8:9]
	v_cndmask_b32_e64 v74, v112, v104, s[6:7]
	v_cndmask_b32_e64 v75, v114, v106, s[6:7]
	v_cndmask_b32_e64 v96, v108, v65, s[6:7]
	v_cndmask_b32_e64 v97, v110, v102, s[6:7]
	v_pk_fma_f32 v[98:99], v[82:83], v[98:99], v[86:87]
	v_pk_fma_f32 v[100:101], v[80:81], v[100:101], v[84:85]
	v_pk_fma_f32 v[74:75], v[90:91], v[74:75], v[98:99]
	v_pk_fma_f32 v[96:97], v[88:89], v[96:97], v[100:101]
	v_pk_fma_f32 v[38:39], v[38:39], v[94:95], v[74:75]
	v_pk_fma_f32 v[36:37], v[36:37], v[92:93], v[96:97]
	v_pk_mul_f32 v[34:35], v[34:35], v[72:73] op_sel_hi:[1,0]
	v_pk_mul_f32 v[32:33], v[32:33], v[72:73] op_sel_hi:[1,0]
	s_nop 1
	v_mov_b32_dpp v96, v32 row_ror:1 row_mask:0xf bank_mask:0xf
	v_mov_b32_dpp v100, v32 row_ror:2 row_mask:0xf bank_mask:0xf
	v_mov_b32_dpp v97, v33 row_ror:1 row_mask:0xf bank_mask:0xf
	v_mov_b32_dpp v101, v33 row_ror:2 row_mask:0xf bank_mask:0xf
	v_mov_b32_dpp v74, v34 row_ror:1 row_mask:0xf bank_mask:0xf
	v_mov_b32_dpp v98, v34 row_ror:2 row_mask:0xf bank_mask:0xf
	v_mov_b32_dpp v75, v35 row_ror:1 row_mask:0xf bank_mask:0xf
	v_mov_b32_dpp v99, v35 row_ror:2 row_mask:0xf bank_mask:0xf
	v_cndmask_b32_e64 v100, v69, v100, s[8:9]
	v_cndmask_b32_e64 v98, v105, v98, s[8:9]
	v_cndmask_b32_e64 v99, v107, v99, s[8:9]
	v_cndmask_b32_e64 v101, v103, v101, s[8:9]
	v_cndmask_b32_e64 v74, v104, v74, s[6:7]
	v_cndmask_b32_e64 v75, v106, v75, s[6:7]
	v_cndmask_b32_e64 v96, v65, v96, s[6:7]
	v_cndmask_b32_e64 v97, v102, v97, s[6:7]
	v_pk_fma_f32 v[82:83], v[82:83], v[98:99], v[86:87]
	v_pk_fma_f32 v[80:81], v[80:81], v[100:101], v[84:85]
	v_pk_fma_f32 v[74:75], v[90:91], v[74:75], v[82:83]
	v_pk_fma_f32 v[80:81], v[88:89], v[96:97], v[80:81]
	v_pk_fma_f32 v[34:35], v[34:35], v[94:95], v[74:75]
	v_pk_fma_f32 v[32:33], v[32:33], v[92:93], v[80:81]
	s_nop 0
	global_load_dwordx4 v[80:83], v[176:177], off
	global_load_dwordx4 v[84:87], v[138:139], off
	global_load_dwordx4 v[88:91], v[140:141], off
	global_load_dwordx4 v[92:95], v[142:143], off
	v_pk_mul_f32 v[74:75], v[30:31], v[68:69] op_sel_hi:[1,0]
	v_pk_mul_f32 v[100:101], v[28:29], v[68:69] op_sel_hi:[1,0]
	ds_read_b128 v[28:31], v71 offset:512
	ds_read_b128 v[96:99], v73 offset:512
	s_nop 1
	v_mov_b32_dpp v65, v100 row_ror:1 row_mask:0xf bank_mask:0xf
	v_mov_b32_dpp v69, v100 row_ror:2 row_mask:0xf bank_mask:0xf
	v_mov_b32_dpp v102, v101 row_ror:1 row_mask:0xf bank_mask:0xf
	s_waitcnt lgkmcnt(1)
; #define PG8_LAS __attribute__((address_space(3)))
; __device__ __forceinline__ float dpp_ror1(float x) { float r; asm volatile("s_nop 1\n\tv_mov_b32_dpp %0, %1 row_ror:1 row_mask:0xf bank_mask:0xf" : "=&v"(r) : "v"(x)); return r; }
; __device__ __forceinline__ float dpp_ror2(float x) { float r; asm volatile("s_nop 1\n\tv_mov_b32_dpp %0, %1 row_ror:2 row_mask:0xf bank_mask:0xf" : "=&v"(r) : "v"(x)); return r; }
;     __device__ __forceinline__ void operator()(f32x4 (&acc)[2][2][4][2], const Unit& u, int wr, int wc, int fr_, int fq_) const {
;     ...
;                     const int ct = bj * HALF + wc * 32 + 8 * fq + 4 * n;
;                     const int cidx = bj * 5632 + jcol + 4 * n;
;                     const f32x4 w0 = *(const f32x4*)(cw + cidx), w1 = *(const f32x4*)(cw + 11264 + cidx), w2 = *(const f32x4*)(cw + 22528 + cidx), b4 = *(const f32x4*)(cb + cidx);
;                     f32x4 pR1 = (f32x4){0.f, 0.f, 0.f, 0.f}, pR2 = pR1;
;                     if (blk) { const f32x4 h14 = *(const PG8_LAS f32x4*)(hal + ((blk - 1) * 2 + 0) * 256 + ct) * rs14, h15 = *(const PG8_LAS f32x4*)(hal + ((blk - 1) * 2 + 1) * 256 + ct) * rs15;
;                         pR1 = h15; pR2 = (fr == 0) ? h14 : h15; }
; #pragma unroll
;                     for (int m = 0; m < 4; ++m) {
;                         const f32x4 U = acc[ai][bj][m][n] * rsr[m];
;                         f32x4 R1, R2;
; #pragma unroll
;                         for (int i = 0; i < 4; ++i) { R1[i] = dpp_ror1(U[i]); R2[i] = dpp_ror2(U[i]); }
;                         const f32x4 U1 = (fr >= 1) ? R1 : pR1, U2 = (fr >= 2) ? R2 : pR2;
;                         const f32x4 C = b4 + w0 * U2 + w1 * U1 + w2 * U;
;                         acc[ai][bj][m][n] = C; pR1 = R1; pR2 = R2;
;                         asm volatile("" : "+v"(acc[ai][bj][m][n]));
;                         __builtin_amdgcn_sched_barrier(0);
;                     }
	v_pk_mul_f32 v[30:31], v[66:67], v[30:31] op_sel_hi:[0,1]
	v_pk_mul_f32 v[28:29], v[66:67], v[28:29] op_sel_hi:[0,1]
	s_waitcnt lgkmcnt(0)
	v_pk_mul_f32 v[98:99], v[66:67], v[98:99] op_sel:[1,0]
	v_pk_mul_f32 v[96:97], v[66:67], v[96:97] op_sel:[1,0]
	v_cndmask_b32_e64 v108, v99, v31, s[10:11]
	v_cndmask_b32_e64 v109, v98, v30, s[10:11]
	v_cndmask_b32_e64 v110, v96, v28, s[10:11]
	v_cndmask_b32_e64 v111, v97, v29, s[10:11]
	s_nop 1
	v_mov_b32_dpp v103, v101 row_ror:2 row_mask:0xf bank_mask:0xf
	v_mov_b32_dpp v104, v74 row_ror:1 row_mask:0xf bank_mask:0xf
	v_mov_b32_dpp v105, v74 row_ror:2 row_mask:0xf bank_mask:0xf
	v_mov_b32_dpp v106, v75 row_ror:1 row_mask:0xf bank_mask:0xf
	v_mov_b32_dpp v107, v75 row_ror:2 row_mask:0xf bank_mask:0xf
	v_cndmask_b32_e64 v31, v97, v102, s[6:7]
	v_cndmask_b32_e64 v28, v98, v104, s[6:7]
	v_cndmask_b32_e64 v29, v99, v106, s[6:7]
	v_cndmask_b32_e64 v30, v96, v65, s[6:7]
	v_cndmask_b32_e64 v96, v109, v105, s[8:9]
	v_cndmask_b32_e64 v97, v108, v107, s[8:9]
	v_cndmask_b32_e64 v99, v111, v103, s[8:9]
	v_cndmask_b32_e64 v98, v110, v69, s[8:9]
	s_waitcnt vmcnt(2)
	v_pk_fma_f32 v[96:97], v[86:87], v[96:97], v[82:83]
	v_pk_fma_f32 v[98:99], v[84:85], v[98:99], v[80:81]
	s_waitcnt vmcnt(1)
	v_pk_fma_f32 v[28:29], v[90:91], v[28:29], v[96:97]
	v_pk_fma_f32 v[96:97], v[88:89], v[30:31], v[98:99]
	s_waitcnt vmcnt(0)
	v_pk_fma_f32 v[30:31], v[74:75], v[94:95], v[28:29]
	v_pk_fma_f32 v[28:29], v[100:101], v[92:93], v[96:97]
	v_pk_mul_f32 v[26:27], v[26:27], v[70:71] op_sel_hi:[1,0]
	v_pk_mul_f32 v[24:25], v[24:25], v[70:71] op_sel_hi:[1,0]
	s_nop 1
	v_mov_b32_dpp v108, v24 row_ror:1 row_mask:0xf bank_mask:0xf
	v_mov_b32_dpp v109, v24 row_ror:2 row_mask:0xf bank_mask:0xf
	v_mov_b32_dpp v110, v25 row_ror:1 row_mask:0xf bank_mask:0xf
	v_mov_b32_dpp v111, v25 row_ror:2 row_mask:0xf bank_mask:0xf
	v_mov_b32_dpp v112, v26 row_ror:1 row_mask:0xf bank_mask:0xf
	v_mov_b32_dpp v113, v26 row_ror:2 row_mask:0xf bank_mask:0xf
	v_mov_b32_dpp v114, v27 row_ror:1 row_mask:0xf bank_mask:0xf
	v_mov_b32_dpp v115, v27 row_ror:2 row_mask:0xf bank_mask:0xf
	v_cndmask_b32_e64 v100, v69, v109, s[8:9]
	v_cndmask_b32_e64 v98, v105, v113, s[8:9]
	v_cndmask_b32_e64 v99, v107, v115, s[8:9]
	v_cndmask_b32_e64 v101, v103, v111, s[8:9]
	v_cndmask_b32_e64 v74, v104, v112, s[6:7]
	v_cndmask_b32_e64 v75, v106, v114, s[6:7]
	v_cndmask_b32_e64 v96, v65, v108, s[6:7]
	v_cndmask_b32_e64 v97, v102, v110, s[6:7]
	v_pk_fma_f32 v[98:99], v[86:87], v[98:99], v[82:83]
	v_pk_fma_f32 v[100:101], v[84:85], v[100:101], v[80:81]
	v_pk_fma_f32 v[74:75], v[90:91], v[74:75], v[98:99]
	v_pk_fma_f32 v[96:97], v[88:89], v[96:97], v[100:101]
	v_pk_fma_f32 v[26:27], v[26:27], v[94:95], v[74:75]
	v_pk_fma_f32 v[24:25], v[24:25], v[92:93], v[96:97]
	v_pk_mul_f32 v[22:23], v[22:23], v[64:65] op_sel_hi:[1,0]
	v_pk_mul_f32 v[20:21], v[20:21], v[64:65] op_sel_hi:[1,0]
	s_nop 1
	v_mov_b32_dpp v65, v20 row_ror:1 row_mask:0xf bank_mask:0xf
	v_mov_b32_dpp v69, v20 row_ror:2 row_mask:0xf bank_mask:0xf
	v_mov_b32_dpp v102, v21 row_ror:1 row_mask:0xf bank_mask:0xf
	v_mov_b32_dpp v103, v21 row_ror:2 row_mask:0xf bank_mask:0xf
	v_mov_b32_dpp v104, v22 row_ror:1 row_mask:0xf bank_mask:0xf
	v_mov_b32_dpp v105, v22 row_ror:2 row_mask:0xf bank_mask:0xf
	v_mov_b32_dpp v106, v23 row_ror:1 row_mask:0xf bank_mask:0xf
	v_mov_b32_dpp v107, v23 row_ror:2 row_mask:0xf bank_mask:0xf
	v_cndmask_b32_e64 v100, v109, v69, s[8:9]
	v_cndmask_b32_e64 v98, v113, v105, s[8:9]
	v_cndmask_b32_e64 v99, v115, v107, s[8:9]
	v_cndmask_b32_e64 v101, v111, v103, s[8:9]
	v_cndmask_b32_e64 v74, v112, v104, s[6:7]
	v_cndmask_b32_e64 v75, v114, v106, s[6:7]
	v_cndmask_b32_e64 v96, v108, v65, s[6:7]
	v_cndmask_b32_e64 v97, v110, v102, s[6:7]
	v_pk_fma_f32 v[98:99], v[86:87], v[98:99], v[82:83]
	v_pk_fma_f32 v[100:101], v[84:85], v[100:101], v[80:81]
	v_pk_fma_f32 v[74:75], v[90:91], v[74:75], v[98:99]
	v_pk_fma_f32 v[96:97], v[88:89], v[96:97], v[100:101]
	v_pk_fma_f32 v[22:23], v[22:23], v[94:95], v[74:75]
	v_pk_fma_f32 v[20:21], v[20:21], v[92:93], v[96:97]
	v_pk_mul_f32 v[18:19], v[18:19], v[72:73] op_sel_hi:[1,0]
	v_pk_mul_f32 v[16:17], v[16:17], v[72:73] op_sel_hi:[1,0]
	s_nop 1
	v_mov_b32_dpp v96, v16 row_ror:1 row_mask:0xf bank_mask:0xf
	v_mov_b32_dpp v100, v16 row_ror:2 row_mask:0xf bank_mask:0xf
	v_mov_b32_dpp v97, v17 row_ror:1 row_mask:0xf bank_mask:0xf
	v_mov_b32_dpp v101, v17 row_ror:2 row_mask:0xf bank_mask:0xf
	v_mov_b32_dpp v74, v18 row_ror:1 row_mask:0xf bank_mask:0xf
	v_mov_b32_dpp v98, v18 row_ror:2 row_mask:0xf bank_mask:0xf
	v_mov_b32_dpp v75, v19 row_ror:1 row_mask:0xf bank_mask:0xf
	v_mov_b32_dpp v99, v19 row_ror:2 row_mask:0xf bank_mask:0xf
	v_cndmask_b32_e64 v100, v69, v100, s[8:9]
	v_cndmask_b32_e64 v98, v105, v98, s[8:9]
	v_cndmask_b32_e64 v99, v107, v99, s[8:9]
	v_cndmask_b32_e64 v101, v103, v101, s[8:9]
	v_cndmask_b32_e64 v74, v104, v74, s[6:7]
	v_cndmask_b32_e64 v75, v106, v75, s[6:7]
	v_cndmask_b32_e64 v96, v65, v96, s[6:7]
	v_cndmask_b32_e64 v97, v102, v97, s[6:7]
	v_pk_fma_f32 v[82:83], v[86:87], v[98:99], v[82:83]
	v_pk_fma_f32 v[80:81], v[84:85], v[100:101], v[80:81]
	v_pk_fma_f32 v[74:75], v[90:91], v[74:75], v[82:83]
	v_pk_fma_f32 v[80:81], v[88:89], v[96:97], v[80:81]
	v_pk_fma_f32 v[18:19], v[18:19], v[94:95], v[74:75]
	v_pk_fma_f32 v[16:17], v[16:17], v[92:93], v[80:81]
	s_nop 0
	global_load_dwordx4 v[80:83], v[136:137], off
	global_load_dwordx4 v[84:87], v[130:131], off
	global_load_dwordx4 v[88:91], v[132:133], off
	global_load_dwordx4 v[92:95], v[134:135], off
	v_pk_mul_f32 v[74:75], v[14:15], v[68:69] op_sel_hi:[1,0]
	v_pk_mul_f32 v[68:69], v[12:13], v[68:69] op_sel_hi:[1,0]
	ds_read_b128 v[12:15], v71 offset:528
	ds_read_b128 v[96:99], v73 offset:528
	s_nop 1
	v_mov_b32_dpp v65, v68 row_ror:1 row_mask:0xf bank_mask:0xf
	v_mov_b32_dpp v73, v68 row_ror:2 row_mask:0xf bank_mask:0xf
	v_mov_b32_dpp v71, v69 row_ror:1 row_mask:0xf bank_mask:0xf
	s_waitcnt lgkmcnt(1)
; #define PG8_LAS __attribute__((address_space(3)))
; __device__ __forceinline__ u32x4 pack8(f32x4 v0, f32x4 v1) { u32x4 w; w.x = cvt_pk_bf16(v0[0], v0[1]); w.y = cvt_pk_bf16(v0[2], v0[3]); w.z = cvt_pk_bf16(v1[0], v1[1]); w.w = cvt_pk_bf16(v1[2], v1[3]); return w; }
; __device__ __forceinline__ f32x4 gelu4(f32x4 v) { f32x2 a = gelu_pk((f32x2){v[0], v[1]}), b = gelu_pk((f32x2){v[2], v[3]}); return (f32x4){a.x, a.y, b.x, b.y}; }
;     __device__ __forceinline__ void operator()(f32x4 (&acc)[2][2][4][2], const Unit& u, int wr, int wc, int fr_, int fq_) const {
;     ...
;                     const int ct = bj * HALF + wc * 32 + 8 * fq + 4 * n;
;                     const int cidx = bj * 5632 + jcol + 4 * n;
;                     const f32x4 w0 = *(const f32x4*)(cw + cidx), w1 = *(const f32x4*)(cw + 11264 + cidx), w2 = *(const f32x4*)(cw + 22528 + cidx), b4 = *(const f32x4*)(cb + cidx);
;                     f32x4 pR1 = (f32x4){0.f, 0.f, 0.f, 0.f}, pR2 = pR1;
;                     if (blk) { const f32x4 h14 = *(const PG8_LAS f32x4*)(hal + ((blk - 1) * 2 + 0) * 256 + ct) * rs14, h15 = *(const PG8_LAS f32x4*)(hal + ((blk - 1) * 2 + 1) * 256 + ct) * rs15;
;                         pR1 = h15; pR2 = (fr == 0) ? h14 : h15; }
; #pragma unroll
;                     for (int m = 0; m < 4; ++m) {
;                         const f32x4 U = acc[ai][bj][m][n] * rsr[m];
;                         f32x4 R1, R2;
; #pragma unroll
;                         for (int i = 0; i < 4; ++i) { R1[i] = dpp_ror1(U[i]); R2[i] = dpp_ror2(U[i]); }
;                         const f32x4 U1 = (fr >= 1) ? R1 : pR1, U2 = (fr >= 2) ? R2 : pR2;
;                         const f32x4 C = b4 + w0 * U2 + w1 * U1 + w2 * U;
;                         acc[ai][bj][m][n] = C; pR1 = R1; pR2 = R2;
;                         asm volatile("" : "+v"(acc[ai][bj][m][n]));
;                         __builtin_amdgcn_sched_barrier(0);
;                     }
;     ...
;             for (int m = 0; m < 4; ++m) { const int row = u.pm * BM + blk * 64 + m * 16 + fr;
;                 const f32x4 g0 = gelu4(acc[ai][0][m][0]), g1 = gelu4(acc[ai][0][m][1]);
;                 *(u32x4*)(ACT + (size_t)row * 5632 + jcol) = pack8(g0 * acc[ai][1][m][0], g1 * acc[ai][1][m][1]); asm volatile("" ::: "memory"); __builtin_amdgcn_sched_barrier(0); }
	v_pk_mul_f32 v[14:15], v[66:67], v[14:15] op_sel_hi:[0,1]
	v_pk_mul_f32 v[12:13], v[66:67], v[12:13] op_sel_hi:[0,1]
	s_waitcnt lgkmcnt(0)
	v_pk_mul_f32 v[98:99], v[66:67], v[98:99] op_sel:[1,0]
	v_pk_mul_f32 v[66:67], v[66:67], v[96:97] op_sel:[1,0]
	v_cndmask_b32_e64 v96, v99, v15, s[10:11]
	v_cndmask_b32_e64 v97, v98, v14, s[10:11]
	v_cndmask_b32_e64 v105, v66, v12, s[10:11]
	v_cndmask_b32_e64 v106, v67, v13, s[10:11]
	s_nop 1
	v_mov_b32_dpp v100, v69 row_ror:2 row_mask:0xf bank_mask:0xf
	v_mov_b32_dpp v101, v74 row_ror:1 row_mask:0xf bank_mask:0xf
	v_mov_b32_dpp v102, v74 row_ror:2 row_mask:0xf bank_mask:0xf
	v_mov_b32_dpp v103, v75 row_ror:1 row_mask:0xf bank_mask:0xf
	v_mov_b32_dpp v104, v75 row_ror:2 row_mask:0xf bank_mask:0xf
	v_cndmask_b32_e64 v15, v67, v71, s[6:7]
	v_cndmask_b32_e64 v14, v66, v65, s[6:7]
	v_cndmask_b32_e64 v66, v97, v102, s[8:9]
	v_cndmask_b32_e64 v67, v96, v104, s[8:9]
	v_cndmask_b32_e64 v97, v106, v100, s[8:9]
	v_cndmask_b32_e64 v96, v105, v73, s[8:9]
	v_cndmask_b32_e64 v12, v98, v101, s[6:7]
	v_cndmask_b32_e64 v13, v99, v103, s[6:7]
	s_waitcnt vmcnt(2)
	v_pk_fma_f32 v[66:67], v[86:87], v[66:67], v[82:83]
	v_pk_fma_f32 v[96:97], v[84:85], v[96:97], v[80:81]
	s_waitcnt vmcnt(1)
	v_pk_fma_f32 v[12:13], v[90:91], v[12:13], v[66:67]
	v_pk_fma_f32 v[66:67], v[88:89], v[14:15], v[96:97]
	s_waitcnt vmcnt(0)
	v_pk_fma_f32 v[14:15], v[74:75], v[94:95], v[12:13]
	v_pk_fma_f32 v[12:13], v[68:69], v[92:93], v[66:67]
	v_pk_mul_f32 v[10:11], v[10:11], v[70:71] op_sel_hi:[1,0]
	v_pk_mul_f32 v[8:9], v[8:9], v[70:71] op_sel_hi:[1,0]
	s_nop 1
	v_mov_b32_dpp v96, v8 row_ror:1 row_mask:0xf bank_mask:0xf
	v_mov_b32_dpp v97, v8 row_ror:2 row_mask:0xf bank_mask:0xf
	v_mov_b32_dpp v98, v9 row_ror:1 row_mask:0xf bank_mask:0xf
	v_mov_b32_dpp v99, v9 row_ror:2 row_mask:0xf bank_mask:0xf
	v_mov_b32_dpp v105, v10 row_ror:1 row_mask:0xf bank_mask:0xf
	v_mov_b32_dpp v106, v10 row_ror:2 row_mask:0xf bank_mask:0xf
	v_mov_b32_dpp v107, v11 row_ror:1 row_mask:0xf bank_mask:0xf
	v_mov_b32_dpp v108, v11 row_ror:2 row_mask:0xf bank_mask:0xf
	v_cndmask_b32_e64 v69, v71, v98, s[6:7]
	v_cndmask_b32_e64 v70, v102, v106, s[8:9]
	v_cndmask_b32_e64 v71, v104, v108, s[8:9]
	v_cndmask_b32_e64 v74, v73, v97, s[8:9]
	v_cndmask_b32_e64 v75, v100, v99, s[8:9]
	v_cndmask_b32_e64 v66, v101, v105, s[6:7]
	v_cndmask_b32_e64 v67, v103, v107, s[6:7]
	v_cndmask_b32_e64 v68, v65, v96, s[6:7]
	v_pk_fma_f32 v[70:71], v[86:87], v[70:71], v[82:83]
	v_pk_fma_f32 v[74:75], v[84:85], v[74:75], v[80:81]
	v_pk_fma_f32 v[66:67], v[90:91], v[66:67], v[70:71]
	v_pk_fma_f32 v[68:69], v[88:89], v[68:69], v[74:75]
	v_pk_fma_f32 v[10:11], v[10:11], v[94:95], v[66:67]
	v_pk_fma_f32 v[8:9], v[8:9], v[92:93], v[68:69]
	v_pk_mul_f32 v[6:7], v[6:7], v[64:65] op_sel_hi:[1,0]
	v_pk_mul_f32 v[4:5], v[4:5], v[64:65] op_sel_hi:[1,0]
	s_nop 1
	v_mov_b32_dpp v73, v4 row_ror:1 row_mask:0xf bank_mask:0xf
	v_mov_b32_dpp v74, v4 row_ror:2 row_mask:0xf bank_mask:0xf
	v_mov_b32_dpp v75, v5 row_ror:1 row_mask:0xf bank_mask:0xf
	v_mov_b32_dpp v100, v5 row_ror:2 row_mask:0xf bank_mask:0xf
	v_mov_b32_dpp v101, v6 row_ror:1 row_mask:0xf bank_mask:0xf
	v_mov_b32_dpp v102, v6 row_ror:2 row_mask:0xf bank_mask:0xf
	v_mov_b32_dpp v103, v7 row_ror:1 row_mask:0xf bank_mask:0xf
	v_mov_b32_dpp v104, v7 row_ror:2 row_mask:0xf bank_mask:0xf
	v_cndmask_b32_e64 v70, v97, v74, s[8:9]
	v_cndmask_b32_e64 v68, v106, v102, s[8:9]
	v_cndmask_b32_e64 v69, v108, v104, s[8:9]
	v_cndmask_b32_e64 v71, v99, v100, s[8:9]
	v_cndmask_b32_e64 v64, v105, v101, s[6:7]
	v_cndmask_b32_e64 v65, v107, v103, s[6:7]
	v_cndmask_b32_e64 v66, v96, v73, s[6:7]
	v_cndmask_b32_e64 v67, v98, v75, s[6:7]
	v_pk_fma_f32 v[68:69], v[86:87], v[68:69], v[82:83]
	v_pk_fma_f32 v[70:71], v[84:85], v[70:71], v[80:81]
	v_pk_fma_f32 v[64:65], v[90:91], v[64:65], v[68:69]
	v_pk_fma_f32 v[66:67], v[88:89], v[66:67], v[70:71]
	v_pk_fma_f32 v[6:7], v[6:7], v[94:95], v[64:65]
	v_pk_fma_f32 v[4:5], v[4:5], v[92:93], v[66:67]
	v_pk_mul_f32 v[2:3], v[2:3], v[72:73] op_sel_hi:[1,0]
	v_pk_mul_f32 v[0:1], v[0:1], v[72:73] op_sel_hi:[1,0]
	s_nop 1
	v_mov_b32_dpp v66, v0 row_ror:1 row_mask:0xf bank_mask:0xf
	v_mov_b32_dpp v70, v0 row_ror:2 row_mask:0xf bank_mask:0xf
	v_mov_b32_dpp v67, v1 row_ror:1 row_mask:0xf bank_mask:0xf
	v_mov_b32_dpp v71, v1 row_ror:2 row_mask:0xf bank_mask:0xf
	v_mov_b32_dpp v64, v2 row_ror:1 row_mask:0xf bank_mask:0xf
	v_mov_b32_dpp v68, v2 row_ror:2 row_mask:0xf bank_mask:0xf
	v_mov_b32_dpp v65, v3 row_ror:1 row_mask:0xf bank_mask:0xf
	v_mov_b32_dpp v69, v3 row_ror:2 row_mask:0xf bank_mask:0xf
	v_cndmask_b32_e64 v70, v74, v70, s[8:9]
	v_cndmask_b32_e64 v68, v102, v68, s[8:9]
	v_cndmask_b32_e64 v69, v104, v69, s[8:9]
	v_cndmask_b32_e64 v71, v100, v71, s[8:9]
	v_cndmask_b32_e64 v64, v101, v64, s[6:7]
	v_cndmask_b32_e64 v65, v103, v65, s[6:7]
	v_cndmask_b32_e64 v66, v73, v66, s[6:7]
	v_cndmask_b32_e64 v67, v75, v67, s[6:7]
	v_pk_fma_f32 v[68:69], v[86:87], v[68:69], v[82:83]
	v_pk_fma_f32 v[70:71], v[84:85], v[70:71], v[80:81]
	v_pk_fma_f32 v[64:65], v[90:91], v[64:65], v[68:69]
	v_pk_fma_f32 v[66:67], v[88:89], v[66:67], v[70:71]
	v_pk_fma_f32 v[2:3], v[2:3], v[94:95], v[64:65]
	v_pk_fma_f32 v[0:1], v[0:1], v[92:93], v[66:67]
	v_fma_f32 v66, |v60|, s58, 1.0
	v_fma_f32 v67, |v61|, s58, 1.0
	v_pk_mul_f32 v[70:71], v[60:61], v[60:61]
	v_rcp_f32_e32 v66, v66
	v_rcp_f32_e32 v67, v67
	v_pk_mul_f32 v[70:71], v[70:71], s[50:51] op_sel_hi:[1,0]
	v_exp_f32_e32 v70, v70
	v_pk_fma_f32 v[68:69], v[66:67], s[60:61], v[128:129] op_sel_hi:[1,0,0]
	v_exp_f32_e32 v71, v71
	v_pk_fma_f32 v[68:69], v[66:67], v[68:69], s[62:63] op_sel_hi:[1,1,0]
	v_readlane_b32 s0, v244, 59
; __device__ __forceinline__ u32x4 pack8(f32x4 v0, f32x4 v1) { u32x4 w; w.x = cvt_pk_bf16(v0[0], v0[1]); w.y = cvt_pk_bf16(v0[2], v0[3]); w.z = cvt_pk_bf16(v1[0], v1[1]); w.w = cvt_pk_bf16(v1[2], v1[3]); return w; }
; __device__ __forceinline__ f32x4 gelu4(f32x4 v) { f32x2 a = gelu_pk((f32x2){v[0], v[1]}), b = gelu_pk((f32x2){v[2], v[3]}); return (f32x4){a.x, a.y, b.x, b.y}; }
; __device__ __forceinline__ f32x2 gelu_pk(f32x2 v) {
;     const f32x2 av = __builtin_elementwise_abs(v), d = av * 0.2316418882f + 1.0f;
;     f32x2 t; t.x = __builtin_amdgcn_rcpf(d.x); t.y = __builtin_amdgcn_rcpf(d.y);
;     f32x2 q = t * 0.5307027145f + (-0.7265760135f); q = q * t + 0.7107068705f; q = q * t + (-0.142248368f); q = q * t + 0.127414796f; q = q * t;
;     const f32x2 s = (v * v) * (-0.72134752044f);
;     f32x2 e; e.x = __builtin_amdgcn_exp2f(s.x); e.y = __builtin_amdgcn_exp2f(s.y);
;     const f32x2 m = v * (q * e), r = v - m;
;     f32x2 o; o.x = v.x < 0.f ? m.x : r.x; o.y = v.y < 0.f ? m.y : r.y; return o;
; }
;     __device__ __forceinline__ void operator()(f32x4 (&acc)[2][2][4][2], const Unit& u, int wr, int wc, int fr_, int fq_) const {
;     ...
;             for (int m = 0; m < 4; ++m) { const int row = u.pm * BM + blk * 64 + m * 16 + fr;
;                 const f32x4 g0 = gelu4(acc[ai][0][m][0]), g1 = gelu4(acc[ai][0][m][1]);
;                 *(u32x4*)(ACT + (size_t)row * 5632 + jcol) = pack8(g0 * acc[ai][1][m][0], g1 * acc[ai][1][m][1]); asm volatile("" ::: "memory"); __builtin_amdgcn_sched_barrier(0); }
	v_pk_fma_f32 v[68:69], v[66:67], v[68:69], s[64:65] op_sel_hi:[1,1,0]
	s_nop 0
	v_pk_fma_f32 v[68:69], v[66:67], v[68:69], s[66:67] op_sel_hi:[1,1,0]
	v_add_u32_e32 v64, s0, v178
	v_pk_mul_f32 v[66:67], v[66:67], v[68:69]
	v_pk_mul_f32 v[68:69], v[62:63], v[62:63]
	v_pk_mul_f32 v[66:67], v[70:71], v[66:67]
	v_pk_mul_f32 v[68:69], v[68:69], s[50:51] op_sel_hi:[1,0]
	v_max_f32_e32 v70, 0, v60
	v_max_f32_e32 v71, 0, v61
	v_exp_f32_e32 v68, v68
	v_fma_f32 v60, -|v60|, v66, v70
	v_fma_f32 v61, -|v61|, v67, v71
	v_exp_f32_e32 v69, v69
	v_fma_f32 v66, |v62|, s58, 1.0
	v_fma_f32 v67, |v63|, s58, 1.0
	v_rcp_f32_e32 v66, v66
	v_rcp_f32_e32 v67, v67
	v_pk_mul_f32 v[28:29], v[60:61], v[28:29]
	v_pk_fma_f32 v[70:71], v[66:67], s[60:61], v[128:129] op_sel_hi:[1,0,0]
	v_pk_fma_f32 v[70:71], v[66:67], v[70:71], s[62:63] op_sel_hi:[1,1,0]
	v_pk_fma_f32 v[70:71], v[66:67], v[70:71], s[64:65] op_sel_hi:[1,1,0]
	v_pk_fma_f32 v[70:71], v[66:67], v[70:71], s[66:67] op_sel_hi:[1,1,0]
	v_pk_mul_f32 v[66:67], v[66:67], v[70:71]
	v_pk_mul_f32 v[70:71], v[44:45], v[44:45]
	v_pk_mul_f32 v[66:67], v[68:69], v[66:67]
	v_pk_mul_f32 v[70:71], v[70:71], s[50:51] op_sel_hi:[1,0]
	v_max_f32_e32 v68, 0, v62
	v_max_f32_e32 v69, 0, v63
	v_exp_f32_e32 v70, v70
	v_fma_f32 v62, -|v62|, v66, v68
	v_fma_f32 v63, -|v63|, v67, v69
	v_exp_f32_e32 v71, v71
	v_fma_f32 v66, |v44|, s58, 1.0
	v_fma_f32 v67, |v45|, s58, 1.0
	v_rcp_f32_e32 v66, v66
	v_rcp_f32_e32 v67, v67
	v_pk_mul_f32 v[30:31], v[62:63], v[30:31]
	v_pk_fma_f32 v[68:69], v[66:67], s[60:61], v[128:129] op_sel_hi:[1,0,0]
	v_pk_fma_f32 v[68:69], v[66:67], v[68:69], s[62:63] op_sel_hi:[1,1,0]
	v_pk_fma_f32 v[68:69], v[66:67], v[68:69], s[64:65] op_sel_hi:[1,1,0]
	v_pk_fma_f32 v[68:69], v[66:67], v[68:69], s[66:67] op_sel_hi:[1,1,0]
	v_pk_mul_f32 v[66:67], v[66:67], v[68:69]
	v_pk_mul_f32 v[68:69], v[46:47], v[46:47]
	v_pk_mul_f32 v[66:67], v[70:71], v[66:67]
	v_pk_mul_f32 v[68:69], v[68:69], s[50:51] op_sel_hi:[1,0]
	v_max_f32_e32 v70, 0, v44
	v_max_f32_e32 v71, 0, v45
	v_exp_f32_e32 v68, v68
	v_fma_f32 v44, -|v44|, v66, v70
	v_fma_f32 v45, -|v45|, v67, v71
	v_exp_f32_e32 v69, v69
	v_fma_f32 v66, |v46|, s58, 1.0
	v_fma_f32 v67, |v47|, s58, 1.0
	v_rcp_f32_e32 v66, v66
	v_rcp_f32_e32 v67, v67
	s_nop 0
	v_pk_fma_f32 v[70:71], v[66:67], s[60:61], v[128:129] op_sel_hi:[1,0,0]
	v_pk_fma_f32 v[70:71], v[66:67], v[70:71], s[62:63] op_sel_hi:[1,1,0]
	v_pk_fma_f32 v[70:71], v[66:67], v[70:71], s[64:65] op_sel_hi:[1,1,0]
	v_pk_fma_f32 v[70:71], v[66:67], v[70:71], s[66:67] op_sel_hi:[1,1,0]
	v_pk_mul_f32 v[66:67], v[66:67], v[70:71]
	v_pk_mul_f32 v[66:67], v[68:69], v[66:67]
	v_max_f32_e32 v68, 0, v46
	v_max_f32_e32 v69, 0, v47
	v_fma_f32 v46, -|v46|, v66, v68
	v_fma_f32 v47, -|v47|, v67, v69
	s_nop 1
	v_pk_mul_f32 v[46:47], v[46:47], v[14:15]
	v_pk_mul_f32 v[14:15], v[44:45], v[12:13]
	v_cvt_pk_bf16_f32 v12, v28, v29
	v_mad_i64_i32 v[28:29], s[0:1], v64, s93, v[76:77]
	v_cvt_pk_bf16_f32 v13, v30, v31
	v_cvt_pk_bf16_f32 v14, v14, v15
	v_cvt_pk_bf16_f32 v15, v46, v47
	v_lshl_add_u64 v[28:29], v[28:29], 0, v[78:79]
	global_store_dwordx4 v[28:29], v[12:15], off nt
	s_nop 1
	v_fma_f32 v12, |v56|, s58, 1.0
	v_fma_f32 v13, |v57|, s58, 1.0
	v_pk_mul_f32 v[28:29], v[56:57], v[56:57]
	v_rcp_f32_e32 v12, v12
	v_rcp_f32_e32 v13, v13
	v_pk_mul_f32 v[28:29], v[28:29], s[50:51] op_sel_hi:[1,0]
	v_exp_f32_e32 v28, v28
	v_pk_fma_f32 v[14:15], v[12:13], s[60:61], v[128:129] op_sel_hi:[1,0,0]
	v_exp_f32_e32 v29, v29
	v_pk_fma_f32 v[14:15], v[12:13], v[14:15], s[62:63] op_sel_hi:[1,1,0]
	v_pk_mul_f32 v[44:45], v[40:41], v[40:41]
	v_pk_fma_f32 v[14:15], v[12:13], v[14:15], s[64:65] op_sel_hi:[1,1,0]
	v_pk_mul_f32 v[44:45], v[44:45], s[50:51] op_sel_hi:[1,0]
	v_pk_fma_f32 v[14:15], v[12:13], v[14:15], s[66:67] op_sel_hi:[1,1,0]
	v_exp_f32_e32 v44, v44
	v_pk_mul_f32 v[12:13], v[12:13], v[14:15]
	v_pk_mul_f32 v[14:15], v[58:59], v[58:59]
	v_pk_mul_f32 v[12:13], v[28:29], v[12:13]
	v_pk_mul_f32 v[14:15], v[14:15], s[50:51] op_sel_hi:[1,0]
	v_max_f32_e32 v28, 0, v56
	v_max_f32_e32 v29, 0, v57
	v_exp_f32_e32 v14, v14
	v_fma_f32 v12, -|v56|, v12, v28
	v_fma_f32 v13, -|v57|, v13, v29
	v_exp_f32_e32 v15, v15
	v_fma_f32 v28, |v58|, s58, 1.0
	v_fma_f32 v29, |v59|, s58, 1.0
	v_rcp_f32_e32 v28, v28
	v_rcp_f32_e32 v29, v29
	v_exp_f32_e32 v45, v45
	v_add_u32_e32 v46, 16, v64
	v_pk_mul_f32 v[12:13], v[12:13], v[24:25]
	v_pk_fma_f32 v[30:31], v[28:29], s[60:61], v[128:129] op_sel_hi:[1,0,0]
	v_pk_fma_f32 v[30:31], v[28:29], v[30:31], s[62:63] op_sel_hi:[1,1,0]
	v_pk_fma_f32 v[30:31], v[28:29], v[30:31], s[64:65] op_sel_hi:[1,1,0]
	v_pk_fma_f32 v[30:31], v[28:29], v[30:31], s[66:67] op_sel_hi:[1,1,0]
	v_pk_mul_f32 v[28:29], v[28:29], v[30:31]
	v_pk_mul_f32 v[14:15], v[14:15], v[28:29]
	v_max_f32_e32 v28, 0, v58
	v_max_f32_e32 v29, 0, v59
	v_fma_f32 v14, -|v58|, v14, v28
	v_fma_f32 v15, -|v59|, v15, v29
	s_nop 0
	v_fma_f32 v28, |v40|, s58, 1.0
	v_fma_f32 v29, |v41|, s58, 1.0
	v_rcp_f32_e32 v28, v28
	v_rcp_f32_e32 v29, v29
	v_pk_mul_f32 v[14:15], v[14:15], v[26:27]
	v_pk_fma_f32 v[30:31], v[28:29], s[60:61], v[128:129] op_sel_hi:[1,0,0]
	v_pk_fma_f32 v[30:31], v[28:29], v[30:31], s[62:63] op_sel_hi:[1,1,0]
	v_pk_fma_f32 v[30:31], v[28:29], v[30:31], s[64:65] op_sel_hi:[1,1,0]
	v_pk_fma_f32 v[30:31], v[28:29], v[30:31], s[66:67] op_sel_hi:[1,1,0]
	v_pk_mul_f32 v[28:29], v[28:29], v[30:31]
	v_pk_mul_f32 v[30:31], v[42:43], v[42:43]
	v_pk_mul_f32 v[28:29], v[44:45], v[28:29]
	v_pk_mul_f32 v[30:31], v[30:31], s[50:51] op_sel_hi:[1,0]
	v_max_f32_e32 v44, 0, v40
	v_max_f32_e32 v45, 0, v41
	v_fma_f32 v28, -|v40|, v28, v44
	v_fma_f32 v29, -|v41|, v29, v45
	v_fma_f32 v40, |v42|, s58, 1.0
; __device__ __forceinline__ u32x4 pack8(f32x4 v0, f32x4 v1) { u32x4 w; w.x = cvt_pk_bf16(v0[0], v0[1]); w.y = cvt_pk_bf16(v0[2], v0[3]); w.z = cvt_pk_bf16(v1[0], v1[1]); w.w = cvt_pk_bf16(v1[2], v1[3]); return w; }
; __device__ __forceinline__ f32x4 gelu4(f32x4 v) { f32x2 a = gelu_pk((f32x2){v[0], v[1]}), b = gelu_pk((f32x2){v[2], v[3]}); return (f32x4){a.x, a.y, b.x, b.y}; }
; __device__ __forceinline__ f32x2 gelu_pk(f32x2 v) {
;     const f32x2 av = __builtin_elementwise_abs(v), d = av * 0.2316418882f + 1.0f;
;     f32x2 t; t.x = __builtin_amdgcn_rcpf(d.x); t.y = __builtin_amdgcn_rcpf(d.y);
;     f32x2 q = t * 0.5307027145f + (-0.7265760135f); q = q * t + 0.7107068705f; q = q * t + (-0.142248368f); q = q * t + 0.127414796f; q = q * t;
;     const f32x2 s = (v * v) * (-0.72134752044f);
;     f32x2 e; e.x = __builtin_amdgcn_exp2f(s.x); e.y = __builtin_amdgcn_exp2f(s.y);
;     const f32x2 m = v * (q * e), r = v - m;
;     f32x2 o; o.x = v.x < 0.f ? m.x : r.x; o.y = v.y < 0.f ? m.y : r.y; return o;
; }
;     __device__ __forceinline__ void operator()(f32x4 (&acc)[2][2][4][2], const Unit& u, int wr, int wc, int fr_, int fq_) const {
;     ...
;             for (int m = 0; m < 4; ++m) { const int row = u.pm * BM + blk * 64 + m * 16 + fr;
;                 const f32x4 g0 = gelu4(acc[ai][0][m][0]), g1 = gelu4(acc[ai][0][m][1]);
;                 *(u32x4*)(ACT + (size_t)row * 5632 + jcol) = pack8(g0 * acc[ai][1][m][0], g1 * acc[ai][1][m][1]); asm volatile("" ::: "memory"); __builtin_amdgcn_sched_barrier(0); }
	v_fma_f32 v41, |v43|, s58, 1.0
	v_rcp_f32_e32 v40, v40
	v_rcp_f32_e32 v41, v41
	v_exp_f32_e32 v30, v30
	v_exp_f32_e32 v31, v31
	v_pk_fma_f32 v[44:45], v[40:41], s[60:61], v[128:129] op_sel_hi:[1,0,0]
	s_nop 0
	v_pk_fma_f32 v[44:45], v[40:41], v[44:45], s[62:63] op_sel_hi:[1,1,0]
	s_nop 0
	v_pk_fma_f32 v[44:45], v[40:41], v[44:45], s[64:65] op_sel_hi:[1,1,0]
	v_pk_fma_f32 v[44:45], v[40:41], v[44:45], s[66:67] op_sel_hi:[1,1,0]
	v_pk_mul_f32 v[40:41], v[40:41], v[44:45]
	v_pk_mul_f32 v[30:31], v[30:31], v[40:41]
	v_max_f32_e32 v40, 0, v42
	v_max_f32_e32 v41, 0, v43
	v_fma_f32 v30, -|v42|, v30, v40
	v_fma_f32 v31, -|v43|, v31, v41
	s_nop 1
	v_pk_mul_f32 v[24:25], v[30:31], v[10:11]
	v_pk_mul_f32 v[10:11], v[28:29], v[8:9]
	v_cvt_pk_bf16_f32 v8, v12, v13
	v_mad_i64_i32 v[12:13], s[0:1], v46, s93, v[76:77]
	v_cvt_pk_bf16_f32 v9, v14, v15
	v_cvt_pk_bf16_f32 v10, v10, v11
	v_cvt_pk_bf16_f32 v11, v24, v25
	v_lshl_add_u64 v[12:13], v[12:13], 0, v[78:79]
	global_store_dwordx4 v[12:13], v[8:11], off nt
	s_nop 1
	v_fma_f32 v8, |v52|, s58, 1.0
	v_fma_f32 v9, |v53|, s58, 1.0
	v_pk_mul_f32 v[12:13], v[52:53], v[52:53]
	v_rcp_f32_e32 v8, v8
	v_rcp_f32_e32 v9, v9
	v_pk_mul_f32 v[12:13], v[12:13], s[50:51] op_sel_hi:[1,0]
	v_exp_f32_e32 v12, v12
	v_pk_fma_f32 v[10:11], v[8:9], s[60:61], v[128:129] op_sel_hi:[1,0,0]
	v_exp_f32_e32 v13, v13
	v_pk_fma_f32 v[10:11], v[8:9], v[10:11], s[62:63] op_sel_hi:[1,1,0]
	v_pk_mul_f32 v[24:25], v[36:37], v[36:37]
	v_pk_fma_f32 v[10:11], v[8:9], v[10:11], s[64:65] op_sel_hi:[1,1,0]
	v_pk_mul_f32 v[24:25], v[24:25], s[50:51] op_sel_hi:[1,0]
	v_pk_fma_f32 v[10:11], v[8:9], v[10:11], s[66:67] op_sel_hi:[1,1,0]
	v_exp_f32_e32 v24, v24
	v_pk_mul_f32 v[8:9], v[8:9], v[10:11]
	v_pk_mul_f32 v[10:11], v[54:55], v[54:55]
	v_pk_mul_f32 v[8:9], v[12:13], v[8:9]
	v_pk_mul_f32 v[10:11], v[10:11], s[50:51] op_sel_hi:[1,0]
	v_max_f32_e32 v12, 0, v52
	v_max_f32_e32 v13, 0, v53
	v_exp_f32_e32 v10, v10
	v_fma_f32 v8, -|v52|, v8, v12
	v_fma_f32 v9, -|v53|, v9, v13
	v_exp_f32_e32 v11, v11
	v_fma_f32 v12, |v54|, s58, 1.0
	v_fma_f32 v13, |v55|, s58, 1.0
	v_rcp_f32_e32 v12, v12
	v_rcp_f32_e32 v13, v13
	v_exp_f32_e32 v25, v25
	v_add_u32_e32 v28, 32, v64
	v_pk_mul_f32 v[8:9], v[8:9], v[20:21]
	v_pk_fma_f32 v[14:15], v[12:13], s[60:61], v[128:129] op_sel_hi:[1,0,0]
	v_pk_fma_f32 v[14:15], v[12:13], v[14:15], s[62:63] op_sel_hi:[1,1,0]
	v_pk_fma_f32 v[14:15], v[12:13], v[14:15], s[64:65] op_sel_hi:[1,1,0]
	v_pk_fma_f32 v[14:15], v[12:13], v[14:15], s[66:67] op_sel_hi:[1,1,0]
	v_pk_mul_f32 v[12:13], v[12:13], v[14:15]
	v_pk_mul_f32 v[10:11], v[10:11], v[12:13]
	v_max_f32_e32 v12, 0, v54
	v_max_f32_e32 v13, 0, v55
	v_fma_f32 v10, -|v54|, v10, v12
	v_fma_f32 v11, -|v55|, v11, v13
	s_nop 0
	v_fma_f32 v12, |v36|, s58, 1.0
	v_fma_f32 v13, |v37|, s58, 1.0
	v_rcp_f32_e32 v12, v12
	v_rcp_f32_e32 v13, v13
	v_pk_mul_f32 v[10:11], v[10:11], v[22:23]
	v_pk_fma_f32 v[14:15], v[12:13], s[60:61], v[128:129] op_sel_hi:[1,0,0]
	v_pk_fma_f32 v[14:15], v[12:13], v[14:15], s[62:63] op_sel_hi:[1,1,0]
	v_pk_fma_f32 v[14:15], v[12:13], v[14:15], s[64:65] op_sel_hi:[1,1,0]
	v_pk_fma_f32 v[14:15], v[12:13], v[14:15], s[66:67] op_sel_hi:[1,1,0]
	v_pk_mul_f32 v[12:13], v[12:13], v[14:15]
	v_pk_mul_f32 v[14:15], v[38:39], v[38:39]
	v_pk_mul_f32 v[12:13], v[24:25], v[12:13]
	v_pk_mul_f32 v[14:15], v[14:15], s[50:51] op_sel_hi:[1,0]
	v_max_f32_e32 v24, 0, v36
	v_max_f32_e32 v25, 0, v37
	v_exp_f32_e32 v14, v14
	v_fma_f32 v12, -|v36|, v12, v24
	v_fma_f32 v13, -|v37|, v13, v25
	v_exp_f32_e32 v15, v15
	v_fma_f32 v24, |v38|, s58, 1.0
	v_fma_f32 v25, |v39|, s58, 1.0
	v_rcp_f32_e32 v24, v24
	v_rcp_f32_e32 v25, v25
	s_nop 0
	v_pk_fma_f32 v[26:27], v[24:25], s[60:61], v[128:129] op_sel_hi:[1,0,0]
	v_pk_fma_f32 v[26:27], v[24:25], v[26:27], s[62:63] op_sel_hi:[1,1,0]
	v_pk_fma_f32 v[26:27], v[24:25], v[26:27], s[64:65] op_sel_hi:[1,1,0]
	v_pk_fma_f32 v[26:27], v[24:25], v[26:27], s[66:67] op_sel_hi:[1,1,0]
	v_pk_mul_f32 v[24:25], v[24:25], v[26:27]
	v_pk_mul_f32 v[14:15], v[14:15], v[24:25]
; __device__ __forceinline__ u32x4 pack8(f32x4 v0, f32x4 v1) { u32x4 w; w.x = cvt_pk_bf16(v0[0], v0[1]); w.y = cvt_pk_bf16(v0[2], v0[3]); w.z = cvt_pk_bf16(v1[0], v1[1]); w.w = cvt_pk_bf16(v1[2], v1[3]); return w; }
; __device__ __forceinline__ f32x4 gelu4(f32x4 v) { f32x2 a = gelu_pk((f32x2){v[0], v[1]}), b = gelu_pk((f32x2){v[2], v[3]}); return (f32x4){a.x, a.y, b.x, b.y}; }
; #define PG8_BAR __builtin_amdgcn_s_barrier()
;     __device__ __forceinline__ void operator()(f32x4 (&acc)[2][2][4][2], const Unit& u, int wr, int wc, int fr_, int fq_) const {
;     ...
;             for (int m = 0; m < 4; ++m) { const int row = u.pm * BM + blk * 64 + m * 16 + fr;
;                 const f32x4 g0 = gelu4(acc[ai][0][m][0]), g1 = gelu4(acc[ai][0][m][1]);
;                 *(u32x4*)(ACT + (size_t)row * 5632 + jcol) = pack8(g0 * acc[ai][1][m][0], g1 * acc[ai][1][m][1]); asm volatile("" ::: "memory"); __builtin_amdgcn_sched_barrier(0); }
; template <class Epi, class Sched, bool ALIGN_EPI = false, bool SP2 = false>
; __device__ __forceinline__ void gemm_phase(PG8_LAS unsigned char* lds, const Gemm g, const Sched& S, const Epi& E) {
;     ...
;         if constexpr (!Epi::AFTER_DRAIN) { E(acc, cur, wr, wc, fr, fq); S.done(cur); }
;         if (!has_next) break;
; #pragma unroll
;         for (int a = 0; a < 2; ++a)
; #pragma unroll
;             for (int b = 0; b < 2; ++b)
; #pragma unroll
;                 for (int m = 0; m < 4; ++m)
; #pragma unroll
;                     for (int n = 0; n < 2; ++n) acc[a][b][m][n] = (f32x4){0.f, 0.f, 0.f, 0.f};
;         cur = nxt; cA = nA; cB = nB; ++ui;
;         if constexpr (ALIGN_EPI) { if (wr == 1) PG8_BAR; }
	v_max_f32_e32 v24, 0, v38
	v_max_f32_e32 v25, 0, v39
	v_fma_f32 v14, -|v38|, v14, v24
	v_fma_f32 v15, -|v39|, v15, v25
	s_nop 1
	v_pk_mul_f32 v[14:15], v[14:15], v[6:7]
	v_pk_mul_f32 v[6:7], v[12:13], v[4:5]
	v_cvt_pk_bf16_f32 v4, v8, v9
	v_mad_i64_i32 v[8:9], s[0:1], v28, s93, v[76:77]
	v_cvt_pk_bf16_f32 v5, v10, v11
	v_cvt_pk_bf16_f32 v6, v6, v7
	v_cvt_pk_bf16_f32 v7, v14, v15
	v_lshl_add_u64 v[8:9], v[8:9], 0, v[78:79]
	global_store_dwordx4 v[8:9], v[4:7], off nt
	s_nop 1
	v_fma_f32 v4, |v48|, s58, 1.0
	v_fma_f32 v5, |v49|, s58, 1.0
	v_pk_mul_f32 v[8:9], v[48:49], v[48:49]
	v_rcp_f32_e32 v4, v4
	v_rcp_f32_e32 v5, v5
	v_pk_mul_f32 v[8:9], v[8:9], s[50:51] op_sel_hi:[1,0]
	v_exp_f32_e32 v8, v8
	v_pk_fma_f32 v[6:7], v[4:5], s[60:61], v[128:129] op_sel_hi:[1,0,0]
	v_exp_f32_e32 v9, v9
	v_pk_fma_f32 v[6:7], v[4:5], v[6:7], s[62:63] op_sel_hi:[1,1,0]
	v_pk_mul_f32 v[12:13], v[32:33], v[32:33]
	v_pk_fma_f32 v[6:7], v[4:5], v[6:7], s[64:65] op_sel_hi:[1,1,0]
	v_pk_mul_f32 v[12:13], v[12:13], s[50:51] op_sel_hi:[1,0]
	v_pk_fma_f32 v[6:7], v[4:5], v[6:7], s[66:67] op_sel_hi:[1,1,0]
	v_exp_f32_e32 v12, v12
	v_pk_mul_f32 v[4:5], v[4:5], v[6:7]
	v_pk_mul_f32 v[6:7], v[50:51], v[50:51]
	v_pk_mul_f32 v[4:5], v[8:9], v[4:5]
	v_pk_mul_f32 v[6:7], v[6:7], s[50:51] op_sel_hi:[1,0]
	v_max_f32_e32 v8, 0, v48
	v_max_f32_e32 v9, 0, v49
	v_exp_f32_e32 v6, v6
	v_fma_f32 v4, -|v48|, v4, v8
	v_fma_f32 v5, -|v49|, v5, v9
	v_exp_f32_e32 v7, v7
	v_fma_f32 v8, |v50|, s58, 1.0
	v_fma_f32 v9, |v51|, s58, 1.0
	v_rcp_f32_e32 v8, v8
	v_rcp_f32_e32 v9, v9
	v_exp_f32_e32 v13, v13
	v_add_u32_e32 v20, 48, v64
	v_pk_mul_f32 v[4:5], v[4:5], v[16:17]
	v_pk_fma_f32 v[10:11], v[8:9], s[60:61], v[128:129] op_sel_hi:[1,0,0]
	v_pk_fma_f32 v[10:11], v[8:9], v[10:11], s[62:63] op_sel_hi:[1,1,0]
	v_pk_fma_f32 v[10:11], v[8:9], v[10:11], s[64:65] op_sel_hi:[1,1,0]
	v_pk_fma_f32 v[10:11], v[8:9], v[10:11], s[66:67] op_sel_hi:[1,1,0]
	v_pk_mul_f32 v[8:9], v[8:9], v[10:11]
	v_pk_mul_f32 v[6:7], v[6:7], v[8:9]
	v_max_f32_e32 v8, 0, v50
	v_max_f32_e32 v9, 0, v51
	v_fma_f32 v6, -|v50|, v6, v8
	v_fma_f32 v7, -|v51|, v7, v9
	s_nop 0
	v_fma_f32 v8, |v32|, s58, 1.0
	v_fma_f32 v9, |v33|, s58, 1.0
	v_rcp_f32_e32 v8, v8
	v_rcp_f32_e32 v9, v9
	v_pk_mul_f32 v[6:7], v[6:7], v[18:19]
	v_pk_fma_f32 v[10:11], v[8:9], s[60:61], v[128:129] op_sel_hi:[1,0,0]
	v_pk_fma_f32 v[10:11], v[8:9], v[10:11], s[62:63] op_sel_hi:[1,1,0]
	v_pk_fma_f32 v[10:11], v[8:9], v[10:11], s[64:65] op_sel_hi:[1,1,0]
	v_pk_fma_f32 v[10:11], v[8:9], v[10:11], s[66:67] op_sel_hi:[1,1,0]
	v_pk_mul_f32 v[8:9], v[8:9], v[10:11]
	v_pk_mul_f32 v[10:11], v[34:35], v[34:35]
	v_pk_mul_f32 v[8:9], v[12:13], v[8:9]
	v_pk_mul_f32 v[10:11], v[10:11], s[50:51] op_sel_hi:[1,0]
	v_max_f32_e32 v12, 0, v32
	v_max_f32_e32 v13, 0, v33
	v_exp_f32_e32 v10, v10
	v_fma_f32 v8, -|v32|, v8, v12
	v_fma_f32 v9, -|v33|, v9, v13
	v_exp_f32_e32 v11, v11
	v_fma_f32 v12, |v34|, s58, 1.0
	v_fma_f32 v13, |v35|, s58, 1.0
	v_rcp_f32_e32 v12, v12
	v_rcp_f32_e32 v13, v13
	s_nop 0
	v_pk_fma_f32 v[14:15], v[12:13], s[60:61], v[128:129] op_sel_hi:[1,0,0]
	v_pk_fma_f32 v[14:15], v[12:13], v[14:15], s[62:63] op_sel_hi:[1,1,0]
	v_pk_fma_f32 v[14:15], v[12:13], v[14:15], s[64:65] op_sel_hi:[1,1,0]
	v_pk_fma_f32 v[14:15], v[12:13], v[14:15], s[66:67] op_sel_hi:[1,1,0]
	v_pk_mul_f32 v[12:13], v[12:13], v[14:15]
	v_pk_mul_f32 v[10:11], v[10:11], v[12:13]
	v_max_f32_e32 v12, 0, v34
	v_max_f32_e32 v13, 0, v35
	v_fma_f32 v10, -|v34|, v10, v12
	v_fma_f32 v11, -|v35|, v11, v13
	s_nop 1
	v_pk_mul_f32 v[10:11], v[10:11], v[2:3]
	v_pk_mul_f32 v[2:3], v[8:9], v[0:1]
	v_cvt_pk_bf16_f32 v0, v4, v5
	v_mad_i64_i32 v[4:5], s[0:1], v20, s93, v[76:77]
	v_cvt_pk_bf16_f32 v1, v6, v7
	v_cvt_pk_bf16_f32 v2, v2, v3
	v_cvt_pk_bf16_f32 v3, v10, v11
	v_lshl_add_u64 v[4:5], v[4:5], 0, v[78:79]
	global_store_dwordx4 v[4:5], v[0:3], off nt
	s_andn2_b64 vcc, exec, s[4:5]
	s_mov_b64 s[0:1], -1
	s_cbranch_vccnz .LBB0_1697
	s_andn2_b64 vcc, exec, s[18:19]
	s_cbranch_vccnz .LBB0_1696
	s_barrier
	s_branch .LBB0_1696

; __device__ __forceinline__ u32x4 pack8(f32x4 v0, f32x4 v1) { u32x4 w; w.x = cvt_pk_bf16(v0[0], v0[1]); w.y = cvt_pk_bf16(v0[2], v0[3]); w.z = cvt_pk_bf16(v1[0], v1[1]); w.w = cvt_pk_bf16(v1[2], v1[3]); return w; }
; __device__ __forceinline__ void unpack8(u32x4 w, f32x4& v0, f32x4& v1) {
;     v0[0] = __uint_as_float(w.x << 16); v0[1] = __uint_as_float(w.x & 0xffff0000u); v0[2] = __uint_as_float(w.y << 16); v0[3] = __uint_as_float(w.y & 0xffff0000u);
;     v1[0] = __uint_as_float(w.z << 16); v1[1] = __uint_as_float(w.z & 0xffff0000u); v1[2] = __uint_as_float(w.w << 16); v1[3] = __uint_as_float(w.w & 0xffff0000u); }
;     __device__ __forceinline__ void operator()(f32x4 (&acc)[2][2][4][2], const Unit& u, int wr, int wc, int fr_, int fq_) const {
;     ...
;             for (int m = 0; m < 4; ++m) { const int row = row0 + ai * HALF + m * 16; float s = 0.f;
; #pragma unroll
;                 for (int bj = 0; bj < 2; ++bj) { const size_t off = (size_t)row * 2048 + col0 + bj * HALF;
;                     f32x4 b0, b1; unpack8(*(const u32x4*)(base + off), b0, b1);
;                     const f32x4 x0 = b0 + acc[ai][bj][m][0], x1 = b1 + acc[ai][bj][m][1];
;                     if (OUTF) { *(f32x4*)(out + off) = x0; *(f32x4*)(out + off + 4) = x1; }
;                     else *(u32x4*)(ob + off) = pack8(x0, x1);
;                     s += (x0[0] * x0[0] + x0[1] * x0[1]) + (x0[2] * x0[2] + x0[3] * x0[3]) + (x1[0] * x1[0] + x1[1] * x1[1]) + (x1[2] * x1[2] + x1[3] * x1[3]); }
;                 s += __shfl_xor(s, 16); s += __shfl_xor(s, 32);
;                 if (fq == 0) ssq[(size_t)row * 32 + u.pn * 4 + wc] = s; }
.LBB0_1927:
	s_lshl_b32 s22, s60, 8
	v_mov_b32_e32 v157, v151
	v_mov_b32_e32 v146, v150
	s_add_i32 s22, s22, s50
	s_nop 0
	v_add_u32_e32 v148, s22, v146
	s_lshl_b32 s22, s8, 8
	s_or_b32 s22, s22, s51
	v_lshl_add_u32 v146, v157, 3, s22
	v_ashrrev_i32_e32 v149, 31, v148
	v_ashrrev_i32_e32 v147, 31, v146
	v_lshlrev_b64 v[158:159], 11, v[148:149]
	v_lshl_add_u64 v[162:163], v[158:159], 0, v[146:147]
	v_lshl_add_u64 v[164:165], v[162:163], 1, s[12:13]
	global_load_dwordx4 v[158:161], v[164:165], off
	v_lshl_add_u64 v[166:167], v[162:163], 2, s[26:27]
	s_lshl_b32 s22, s8, 2
	s_ashr_i32 s23, s22, 31
	s_waitcnt vmcnt(0)
	v_lshlrev_b32_e32 v162, 16, v158
	v_and_b32_e32 v163, 0xffff0000, v158
	v_lshlrev_b32_e32 v158, 16, v159
	v_and_b32_e32 v159, 0xffff0000, v159
	v_lshlrev_b32_e32 v168, 16, v160
	v_and_b32_e32 v169, 0xffff0000, v160
	v_lshlrev_b32_e32 v160, 16, v161
	v_and_b32_e32 v161, 0xffff0000, v161
	v_pk_add_f32 v[126:127], v[126:127], v[158:159]
	v_pk_add_f32 v[124:125], v[124:125], v[162:163]
	v_pk_add_f32 v[160:161], v[122:123], v[160:161]
	v_pk_add_f32 v[158:159], v[120:121], v[168:169]
	global_store_dwordx4 v[166:167], v[124:127], off nt
	global_store_dwordx4 v[166:167], v[158:161], off offset:16 nt
	global_load_dwordx4 v[162:165], v[164:165], off offset:256
	v_mul_f32_e32 v122, v125, v125
	v_mul_f32_e32 v123, v127, v127
	v_mul_f32_e32 v125, v159, v159
	v_fmac_f32_e32 v122, v124, v124
	v_fmac_f32_e32 v123, v126, v126
	v_mul_f32_e32 v127, v161, v161
	v_fmac_f32_e32 v125, v158, v158
	v_add_f32_e32 v122, v122, v123
	v_fmac_f32_e32 v127, v160, v160
	v_add_f32_e32 v122, v125, v122
	v_add_f32_e32 v160, v127, v122
	v_and_b32_e32 v121, 64, v156
	v_xor_b32_e32 v120, 16, v156
	v_add_u32_e32 v121, 64, v121
	v_cmp_lt_i32_e32 vcc, v120, v121
	v_xor_b32_e32 v168, 32, v156
	s_waitcnt vmcnt(0)
	v_lshlrev_b32_e32 v122, 16, v162
	v_and_b32_e32 v123, 0xffff0000, v162
	v_lshlrev_b32_e32 v124, 16, v163
	v_and_b32_e32 v125, 0xffff0000, v163
	v_lshlrev_b32_e32 v126, 16, v164
	v_and_b32_e32 v127, 0xffff0000, v164
	v_pk_add_f32 v[118:119], v[118:119], v[124:125]
	v_pk_add_f32 v[116:117], v[116:117], v[122:123]
	v_lshlrev_b32_e32 v158, 16, v165
	v_and_b32_e32 v159, 0xffff0000, v165
	v_pk_add_f32 v[122:123], v[112:113], v[126:127]
	v_mul_f32_e32 v112, v117, v117
	v_mul_f32_e32 v113, v119, v119
	v_pk_add_f32 v[124:125], v[114:115], v[158:159]
	v_mul_f32_e32 v114, v123, v123
	v_fmac_f32_e32 v112, v116, v116
	v_fmac_f32_e32 v113, v118, v118
	v_mul_f32_e32 v115, v125, v125
	v_fmac_f32_e32 v114, v122, v122
	v_add_f32_e32 v112, v112, v113
	v_add_f32_e32 v112, v114, v112
	v_fmac_f32_e32 v115, v124, v124
	v_cndmask_b32_e32 v120, v156, v120, vcc
	v_add_f32_e32 v112, v115, v112
	v_lshlrev_b32_e32 v120, 2, v120
	v_add_f32_e32 v112, v160, v112
	ds_bpermute_b32 v113, v120, v112
	v_cmp_lt_i32_e32 vcc, v168, v121
	global_store_dwordx4 v[166:167], v[116:119], off offset:512 nt
	global_store_dwordx4 v[166:167], v[122:125], off offset:528 nt
	v_cndmask_b32_e32 v114, v156, v168, vcc
	v_lshlrev_b32_e32 v114, 2, v114
	s_waitcnt lgkmcnt(0)
	v_add_f32_e32 v112, v112, v113
	ds_bpermute_b32 v113, v114, v112
	v_cmp_eq_u32_e32 vcc, 0, v157
	s_and_saveexec_b64 s[36:37], vcc
	s_cbranch_execz .LBB0_1929
	v_lshlrev_b64 v[116:117], 7, v[148:149]
	v_lshl_add_u64 v[116:117], s[14:15], 0, v[116:117]
	v_lshl_add_u64 v[116:117], s[22:23], 2, v[116:117]
	s_lshl_b32 s8, s49, 2
	v_lshl_add_u64 v[116:117], v[116:117], 0, s[8:9]
	s_waitcnt lgkmcnt(0)
	v_add_f32_e32 v112, v112, v113
	global_store_dword v[116:117], v112, off
.LBB0_1929:
	s_or_b64 exec, exec, s[36:37]
	v_add_u32_e32 v112, 16, v148
	s_waitcnt lgkmcnt(0)
	v_ashrrev_i32_e32 v113, 31, v112
	v_lshlrev_b64 v[116:117], 11, v[112:113]
	v_lshl_add_u64 v[122:123], v[116:117], 0, v[146:147]
	v_lshl_add_u64 v[124:125], v[122:123], 1, s[12:13]
	global_load_dwordx4 v[116:119], v[124:125], off
	v_lshl_add_u64 v[122:123], v[122:123], 2, s[26:27]
	s_waitcnt vmcnt(0)
	v_lshlrev_b32_e32 v126, 16, v116
	v_and_b32_e32 v127, 0xffff0000, v116
	v_lshlrev_b32_e32 v116, 16, v117
	v_and_b32_e32 v117, 0xffff0000, v117
	v_lshlrev_b32_e32 v158, 16, v118
	v_and_b32_e32 v159, 0xffff0000, v118
	v_lshlrev_b32_e32 v118, 16, v119
	v_and_b32_e32 v119, 0xffff0000, v119
	v_pk_add_f32 v[110:111], v[110:111], v[116:117]
	v_pk_add_f32 v[108:109], v[108:109], v[126:127]
	v_pk_add_f32 v[106:107], v[106:107], v[118:119]
	v_pk_add_f32 v[104:105], v[104:105], v[158:159]
	global_store_dwordx4 v[122:123], v[108:111], off nt
	global_store_dwordx4 v[122:123], v[104:107], off offset:16 nt
	global_load_dwordx4 v[116:119], v[124:125], off offset:256
	v_mul_f32_e32 v109, v109, v109
	v_mul_f32_e32 v111, v111, v111
	v_mul_f32_e32 v105, v105, v105
	v_fmac_f32_e32 v109, v108, v108
	v_fmac_f32_e32 v111, v110, v110
	v_mul_f32_e32 v107, v107, v107
	v_fmac_f32_e32 v105, v104, v104
	v_add_f32_e32 v104, v109, v111
	v_fmac_f32_e32 v107, v106, v106
	v_add_f32_e32 v104, v105, v104
	v_add_f32_e32 v115, v107, v104
	s_waitcnt vmcnt(0)
	v_lshlrev_b32_e32 v104, 16, v116
	v_and_b32_e32 v105, 0xffff0000, v116
	v_lshlrev_b32_e32 v106, 16, v117
	v_and_b32_e32 v107, 0xffff0000, v117
	v_lshlrev_b32_e32 v108, 16, v118
	v_and_b32_e32 v109, 0xffff0000, v118
	v_pk_add_f32 v[102:103], v[102:103], v[106:107]
	v_pk_add_f32 v[100:101], v[100:101], v[104:105]
	v_lshlrev_b32_e32 v110, 16, v119
	v_and_b32_e32 v111, 0xffff0000, v119
	v_pk_add_f32 v[104:105], v[96:97], v[108:109]
	v_mul_f32_e32 v96, v101, v101
	v_mul_f32_e32 v97, v103, v103
	v_pk_add_f32 v[106:107], v[98:99], v[110:111]
	v_mul_f32_e32 v98, v105, v105
	v_fmac_f32_e32 v96, v100, v100
	v_fmac_f32_e32 v97, v102, v102
	v_mul_f32_e32 v99, v107, v107
	v_fmac_f32_e32 v98, v104, v104
	v_add_f32_e32 v96, v96, v97
	v_add_f32_e32 v96, v98, v96
	v_fmac_f32_e32 v99, v106, v106
	v_add_f32_e32 v96, v99, v96
	v_add_f32_e32 v96, v115, v96
	ds_bpermute_b32 v97, v120, v96
	global_store_dwordx4 v[122:123], v[100:103], off offset:512 nt
	global_store_dwordx4 v[122:123], v[104:107], off offset:528 nt
	s_waitcnt lgkmcnt(0)
	v_add_f32_e32 v96, v96, v97
	ds_bpermute_b32 v97, v114, v96
	s_and_saveexec_b64 s[36:37], vcc
	s_cbranch_execz .LBB0_1931
	v_lshlrev_b64 v[98:99], 7, v[112:113]
	v_lshl_add_u64 v[98:99], s[14:15], 0, v[98:99]
	v_lshl_add_u64 v[98:99], s[22:23], 2, v[98:99]
	s_lshl_b32 s8, s49, 2
	v_lshl_add_u64 v[98:99], v[98:99], 0, s[8:9]
	s_waitcnt lgkmcnt(0)
	v_add_f32_e32 v96, v96, v97
	global_store_dword v[98:99], v96, off
; __device__ __forceinline__ u32x4 pack8(f32x4 v0, f32x4 v1) { u32x4 w; w.x = cvt_pk_bf16(v0[0], v0[1]); w.y = cvt_pk_bf16(v0[2], v0[3]); w.z = cvt_pk_bf16(v1[0], v1[1]); w.w = cvt_pk_bf16(v1[2], v1[3]); return w; }
; __device__ __forceinline__ void unpack8(u32x4 w, f32x4& v0, f32x4& v1) {
;     v0[0] = __uint_as_float(w.x << 16); v0[1] = __uint_as_float(w.x & 0xffff0000u); v0[2] = __uint_as_float(w.y << 16); v0[3] = __uint_as_float(w.y & 0xffff0000u);
;     v1[0] = __uint_as_float(w.z << 16); v1[1] = __uint_as_float(w.z & 0xffff0000u); v1[2] = __uint_as_float(w.w << 16); v1[3] = __uint_as_float(w.w & 0xffff0000u); }
;     __device__ __forceinline__ void operator()(f32x4 (&acc)[2][2][4][2], const Unit& u, int wr, int wc, int fr_, int fq_) const {
;     ...
;             for (int m = 0; m < 4; ++m) { const int row = row0 + ai * HALF + m * 16; float s = 0.f;
; #pragma unroll
;                 for (int bj = 0; bj < 2; ++bj) { const size_t off = (size_t)row * 2048 + col0 + bj * HALF;
;                     f32x4 b0, b1; unpack8(*(const u32x4*)(base + off), b0, b1);
;                     const f32x4 x0 = b0 + acc[ai][bj][m][0], x1 = b1 + acc[ai][bj][m][1];
;                     if (OUTF) { *(f32x4*)(out + off) = x0; *(f32x4*)(out + off + 4) = x1; }
;                     else *(u32x4*)(ob + off) = pack8(x0, x1);
;                     s += (x0[0] * x0[0] + x0[1] * x0[1]) + (x0[2] * x0[2] + x0[3] * x0[3]) + (x1[0] * x1[0] + x1[1] * x1[1]) + (x1[2] * x1[2] + x1[3] * x1[3]); }
;                 s += __shfl_xor(s, 16); s += __shfl_xor(s, 32);
;                 if (fq == 0) ssq[(size_t)row * 32 + u.pn * 4 + wc] = s; }
.LBB0_1931:
	s_or_b64 exec, exec, s[36:37]
	v_add_u32_e32 v96, 32, v148
	s_waitcnt lgkmcnt(0)
	v_ashrrev_i32_e32 v97, 31, v96
	v_lshlrev_b64 v[98:99], 11, v[96:97]
	v_lshl_add_u64 v[102:103], v[98:99], 0, v[146:147]
	v_lshl_add_u64 v[104:105], v[102:103], 1, s[12:13]
	global_load_dwordx4 v[98:101], v[104:105], off
	v_lshl_add_u64 v[102:103], v[102:103], 2, s[26:27]
	s_waitcnt vmcnt(0)
	v_lshlrev_b32_e32 v106, 16, v98
	v_and_b32_e32 v107, 0xffff0000, v98
	v_lshlrev_b32_e32 v98, 16, v99
	v_and_b32_e32 v99, 0xffff0000, v99
	v_lshlrev_b32_e32 v108, 16, v100
	v_and_b32_e32 v109, 0xffff0000, v100
	v_lshlrev_b32_e32 v100, 16, v101
	v_and_b32_e32 v101, 0xffff0000, v101
	v_pk_add_f32 v[94:95], v[94:95], v[98:99]
	v_pk_add_f32 v[92:93], v[92:93], v[106:107]
	v_pk_add_f32 v[90:91], v[90:91], v[100:101]
	v_pk_add_f32 v[88:89], v[88:89], v[108:109]
	global_store_dwordx4 v[102:103], v[92:95], off nt
	global_store_dwordx4 v[102:103], v[88:91], off offset:16 nt
	global_load_dwordx4 v[98:101], v[104:105], off offset:256
	v_mul_f32_e32 v93, v93, v93
	v_mul_f32_e32 v95, v95, v95
	v_mul_f32_e32 v89, v89, v89
	v_fmac_f32_e32 v93, v92, v92
	v_fmac_f32_e32 v95, v94, v94
	v_mul_f32_e32 v91, v91, v91
	v_fmac_f32_e32 v89, v88, v88
	v_add_f32_e32 v88, v93, v95
	v_fmac_f32_e32 v91, v90, v90
	v_add_f32_e32 v88, v89, v88
	v_add_f32_e32 v104, v91, v88
	s_waitcnt vmcnt(0)
	v_lshlrev_b32_e32 v88, 16, v98
	v_and_b32_e32 v89, 0xffff0000, v98
	v_lshlrev_b32_e32 v90, 16, v99
	v_and_b32_e32 v91, 0xffff0000, v99
	v_lshlrev_b32_e32 v92, 16, v100
	v_and_b32_e32 v93, 0xffff0000, v100
	v_pk_add_f32 v[86:87], v[86:87], v[90:91]
	v_pk_add_f32 v[84:85], v[84:85], v[88:89]
	v_lshlrev_b32_e32 v94, 16, v101
	v_and_b32_e32 v95, 0xffff0000, v101
	v_pk_add_f32 v[88:89], v[80:81], v[92:93]
	v_mul_f32_e32 v80, v85, v85
	v_mul_f32_e32 v81, v87, v87
	v_pk_add_f32 v[90:91], v[82:83], v[94:95]
	v_mul_f32_e32 v82, v89, v89
	v_fmac_f32_e32 v80, v84, v84
	v_fmac_f32_e32 v81, v86, v86
	v_mul_f32_e32 v83, v91, v91
	v_fmac_f32_e32 v82, v88, v88
	v_add_f32_e32 v80, v80, v81
	v_add_f32_e32 v80, v82, v80
	v_fmac_f32_e32 v83, v90, v90
	v_add_f32_e32 v80, v83, v80
	v_add_f32_e32 v80, v104, v80
	ds_bpermute_b32 v81, v120, v80
	global_store_dwordx4 v[102:103], v[84:87], off offset:512 nt
	global_store_dwordx4 v[102:103], v[88:91], off offset:528 nt
	s_waitcnt lgkmcnt(0)
	v_add_f32_e32 v80, v80, v81
	ds_bpermute_b32 v81, v114, v80
	s_and_saveexec_b64 s[36:37], vcc
	s_cbranch_execz .LBB0_1933
	v_lshlrev_b64 v[82:83], 7, v[96:97]
	v_lshl_add_u64 v[82:83], s[14:15], 0, v[82:83]
	v_lshl_add_u64 v[82:83], s[22:23], 2, v[82:83]
	s_lshl_b32 s8, s49, 2
	v_lshl_add_u64 v[82:83], v[82:83], 0, s[8:9]
	s_waitcnt lgkmcnt(0)
	v_add_f32_e32 v80, v80, v81
	global_store_dword v[82:83], v80, off
.LBB0_1933:
	s_or_b64 exec, exec, s[36:37]
	v_add_u32_e32 v80, 48, v148
	s_waitcnt lgkmcnt(0)
	v_ashrrev_i32_e32 v81, 31, v80
	v_lshlrev_b64 v[82:83], 11, v[80:81]
	v_lshl_add_u64 v[86:87], v[82:83], 0, v[146:147]
	v_lshl_add_u64 v[88:89], v[86:87], 1, s[12:13]
	global_load_dwordx4 v[82:85], v[88:89], off
	v_lshl_add_u64 v[86:87], v[86:87], 2, s[26:27]
	s_waitcnt vmcnt(0)
	v_lshlrev_b32_e32 v90, 16, v82
	v_and_b32_e32 v91, 0xffff0000, v82
	v_lshlrev_b32_e32 v82, 16, v83
	v_and_b32_e32 v83, 0xffff0000, v83
	v_lshlrev_b32_e32 v92, 16, v84
	v_and_b32_e32 v93, 0xffff0000, v84
	v_lshlrev_b32_e32 v84, 16, v85
	v_and_b32_e32 v85, 0xffff0000, v85
	v_pk_add_f32 v[78:79], v[78:79], v[82:83]
	v_pk_add_f32 v[76:77], v[76:77], v[90:91]
	v_pk_add_f32 v[74:75], v[74:75], v[84:85]
	v_pk_add_f32 v[72:73], v[72:73], v[92:93]
	global_store_dwordx4 v[86:87], v[76:79], off nt
	global_store_dwordx4 v[86:87], v[72:75], off offset:16 nt
	global_load_dwordx4 v[82:85], v[88:89], off offset:256
	v_mul_f32_e32 v77, v77, v77
	v_mul_f32_e32 v79, v79, v79
	v_mul_f32_e32 v73, v73, v73
	v_fmac_f32_e32 v77, v76, v76
	v_fmac_f32_e32 v79, v78, v78
	v_mul_f32_e32 v75, v75, v75
	v_fmac_f32_e32 v73, v72, v72
	v_add_f32_e32 v72, v77, v79
	v_fmac_f32_e32 v75, v74, v74
	v_add_f32_e32 v72, v73, v72
	v_add_f32_e32 v88, v75, v72
	s_waitcnt vmcnt(0)
	v_lshlrev_b32_e32 v72, 16, v82
	v_and_b32_e32 v73, 0xffff0000, v82
	v_lshlrev_b32_e32 v74, 16, v83
	v_and_b32_e32 v75, 0xffff0000, v83
	v_lshlrev_b32_e32 v76, 16, v84
	v_and_b32_e32 v77, 0xffff0000, v84
	v_pk_add_f32 v[70:71], v[70:71], v[74:75]
	v_pk_add_f32 v[68:69], v[68:69], v[72:73]
	v_lshlrev_b32_e32 v78, 16, v85
	v_and_b32_e32 v79, 0xffff0000, v85
	v_pk_add_f32 v[72:73], v[64:65], v[76:77]
	v_mul_f32_e32 v64, v69, v69
	v_mul_f32_e32 v65, v71, v71
	v_pk_add_f32 v[74:75], v[66:67], v[78:79]
	v_mul_f32_e32 v66, v73, v73
	v_fmac_f32_e32 v64, v68, v68
	v_fmac_f32_e32 v65, v70, v70
	v_mul_f32_e32 v67, v75, v75
	v_fmac_f32_e32 v66, v72, v72
	v_add_f32_e32 v64, v64, v65
	v_add_f32_e32 v64, v66, v64
	v_fmac_f32_e32 v67, v74, v74
	v_add_f32_e32 v64, v67, v64
	v_add_f32_e32 v64, v88, v64
	ds_bpermute_b32 v65, v120, v64
	global_store_dwordx4 v[86:87], v[68:71], off offset:512 nt
	global_store_dwordx4 v[86:87], v[72:75], off offset:528 nt
	s_waitcnt lgkmcnt(0)
	v_add_f32_e32 v64, v64, v65
	ds_bpermute_b32 v65, v114, v64
	s_and_saveexec_b64 s[36:37], vcc
	s_cbranch_execz .LBB0_1935
	v_lshlrev_b64 v[66:67], 7, v[80:81]
	v_lshl_add_u64 v[66:67], s[14:15], 0, v[66:67]
	v_lshl_add_u64 v[66:67], s[22:23], 2, v[66:67]
	s_lshl_b32 s8, s49, 2
	v_lshl_add_u64 v[66:67], v[66:67], 0, s[8:9]
	s_waitcnt lgkmcnt(0)
	v_add_f32_e32 v64, v64, v65
	global_store_dword v[66:67], v64, off
; __device__ __forceinline__ u32x4 pack8(f32x4 v0, f32x4 v1) { u32x4 w; w.x = cvt_pk_bf16(v0[0], v0[1]); w.y = cvt_pk_bf16(v0[2], v0[3]); w.z = cvt_pk_bf16(v1[0], v1[1]); w.w = cvt_pk_bf16(v1[2], v1[3]); return w; }
; __device__ __forceinline__ void unpack8(u32x4 w, f32x4& v0, f32x4& v1) {
;     v0[0] = __uint_as_float(w.x << 16); v0[1] = __uint_as_float(w.x & 0xffff0000u); v0[2] = __uint_as_float(w.y << 16); v0[3] = __uint_as_float(w.y & 0xffff0000u);
;     v1[0] = __uint_as_float(w.z << 16); v1[1] = __uint_as_float(w.z & 0xffff0000u); v1[2] = __uint_as_float(w.w << 16); v1[3] = __uint_as_float(w.w & 0xffff0000u); }
;     __device__ __forceinline__ void operator()(f32x4 (&acc)[2][2][4][2], const Unit& u, int wr, int wc, int fr_, int fq_) const {
;     ...
;             for (int m = 0; m < 4; ++m) { const int row = row0 + ai * HALF + m * 16; float s = 0.f;
; #pragma unroll
;                 for (int bj = 0; bj < 2; ++bj) { const size_t off = (size_t)row * 2048 + col0 + bj * HALF;
;                     f32x4 b0, b1; unpack8(*(const u32x4*)(base + off), b0, b1);
;                     const f32x4 x0 = b0 + acc[ai][bj][m][0], x1 = b1 + acc[ai][bj][m][1];
;                     if (OUTF) { *(f32x4*)(out + off) = x0; *(f32x4*)(out + off + 4) = x1; }
;                     else *(u32x4*)(ob + off) = pack8(x0, x1);
;                     s += (x0[0] * x0[0] + x0[1] * x0[1]) + (x0[2] * x0[2] + x0[3] * x0[3]) + (x1[0] * x1[0] + x1[1] * x1[1]) + (x1[2] * x1[2] + x1[3] * x1[3]); }
;                 s += __shfl_xor(s, 16); s += __shfl_xor(s, 32);
;                 if (fq == 0) ssq[(size_t)row * 32 + u.pn * 4 + wc] = s; }
.LBB0_1935:
	s_or_b64 exec, exec, s[36:37]
	v_add_u32_e32 v64, 0x80, v148
	s_waitcnt lgkmcnt(0)
	v_ashrrev_i32_e32 v65, 31, v64
	v_lshlrev_b64 v[66:67], 11, v[64:65]
	v_lshl_add_u64 v[70:71], v[66:67], 0, v[146:147]
	v_lshl_add_u64 v[72:73], v[70:71], 1, s[12:13]
	global_load_dwordx4 v[66:69], v[72:73], off
	v_lshl_add_u64 v[70:71], v[70:71], 2, s[26:27]
	s_waitcnt vmcnt(0)
	v_lshlrev_b32_e32 v74, 16, v66
	v_and_b32_e32 v75, 0xffff0000, v66
	v_lshlrev_b32_e32 v66, 16, v67
	v_and_b32_e32 v67, 0xffff0000, v67
	v_lshlrev_b32_e32 v76, 16, v68
	v_and_b32_e32 v77, 0xffff0000, v68
	v_lshlrev_b32_e32 v68, 16, v69
	v_and_b32_e32 v69, 0xffff0000, v69
	v_pk_add_f32 v[62:63], v[62:63], v[66:67]
	v_pk_add_f32 v[60:61], v[60:61], v[74:75]
	v_pk_add_f32 v[58:59], v[58:59], v[68:69]
	v_pk_add_f32 v[56:57], v[56:57], v[76:77]
	global_store_dwordx4 v[70:71], v[60:63], off nt
	global_store_dwordx4 v[70:71], v[56:59], off offset:16 nt
	global_load_dwordx4 v[66:69], v[72:73], off offset:256
	v_mul_f32_e32 v61, v61, v61
	v_mul_f32_e32 v63, v63, v63
	v_mul_f32_e32 v57, v57, v57
	v_fmac_f32_e32 v61, v60, v60
	v_fmac_f32_e32 v63, v62, v62
	v_mul_f32_e32 v59, v59, v59
	v_fmac_f32_e32 v57, v56, v56
	v_add_f32_e32 v56, v61, v63
	v_fmac_f32_e32 v59, v58, v58
	v_add_f32_e32 v56, v57, v56
	v_add_f32_e32 v72, v59, v56
	s_waitcnt vmcnt(0)
	v_lshlrev_b32_e32 v56, 16, v66
	v_and_b32_e32 v57, 0xffff0000, v66
	v_lshlrev_b32_e32 v58, 16, v67
	v_and_b32_e32 v59, 0xffff0000, v67
	v_lshlrev_b32_e32 v60, 16, v68
	v_and_b32_e32 v61, 0xffff0000, v68
	v_pk_add_f32 v[54:55], v[54:55], v[58:59]
	v_pk_add_f32 v[52:53], v[52:53], v[56:57]
	v_lshlrev_b32_e32 v62, 16, v69
	v_and_b32_e32 v63, 0xffff0000, v69
	v_pk_add_f32 v[56:57], v[48:49], v[60:61]
	v_mul_f32_e32 v48, v53, v53
	v_mul_f32_e32 v49, v55, v55
	v_pk_add_f32 v[58:59], v[50:51], v[62:63]
	v_mul_f32_e32 v50, v57, v57
	v_fmac_f32_e32 v48, v52, v52
	v_fmac_f32_e32 v49, v54, v54
	v_mul_f32_e32 v51, v59, v59
	v_fmac_f32_e32 v50, v56, v56
	v_add_f32_e32 v48, v48, v49
	v_add_f32_e32 v48, v50, v48
	v_fmac_f32_e32 v51, v58, v58
	v_add_f32_e32 v48, v51, v48
	v_add_f32_e32 v48, v72, v48
	ds_bpermute_b32 v49, v120, v48
	global_store_dwordx4 v[70:71], v[52:55], off offset:512 nt
	global_store_dwordx4 v[70:71], v[56:59], off offset:528 nt
	s_waitcnt lgkmcnt(0)
	v_add_f32_e32 v48, v48, v49
	ds_bpermute_b32 v49, v114, v48
	s_and_saveexec_b64 s[36:37], vcc
	s_cbranch_execz .LBB0_1937
	v_lshlrev_b64 v[50:51], 7, v[64:65]
	v_lshl_add_u64 v[50:51], s[14:15], 0, v[50:51]
	v_lshl_add_u64 v[50:51], s[22:23], 2, v[50:51]
	s_lshl_b32 s8, s49, 2
	v_lshl_add_u64 v[50:51], v[50:51], 0, s[8:9]
	s_waitcnt lgkmcnt(0)
	v_add_f32_e32 v48, v48, v49
	global_store_dword v[50:51], v48, off
.LBB0_1937:
	s_or_b64 exec, exec, s[36:37]
	v_add_u32_e32 v48, 0x90, v148
	s_waitcnt lgkmcnt(0)
	v_ashrrev_i32_e32 v49, 31, v48
	v_lshlrev_b64 v[50:51], 11, v[48:49]
	v_lshl_add_u64 v[54:55], v[50:51], 0, v[146:147]
	v_lshl_add_u64 v[56:57], v[54:55], 1, s[12:13]
	global_load_dwordx4 v[50:53], v[56:57], off
	v_lshl_add_u64 v[54:55], v[54:55], 2, s[26:27]
	s_waitcnt vmcnt(0)
	v_lshlrev_b32_e32 v58, 16, v50
	v_and_b32_e32 v59, 0xffff0000, v50
	v_lshlrev_b32_e32 v50, 16, v51
	v_and_b32_e32 v51, 0xffff0000, v51
	v_lshlrev_b32_e32 v60, 16, v52
	v_and_b32_e32 v61, 0xffff0000, v52
	v_lshlrev_b32_e32 v52, 16, v53
	v_and_b32_e32 v53, 0xffff0000, v53
	v_pk_add_f32 v[46:47], v[46:47], v[50:51]
	v_pk_add_f32 v[44:45], v[44:45], v[58:59]
	v_pk_add_f32 v[42:43], v[42:43], v[52:53]
	v_pk_add_f32 v[40:41], v[40:41], v[60:61]
	global_store_dwordx4 v[54:55], v[44:47], off nt
	global_store_dwordx4 v[54:55], v[40:43], off offset:16 nt
	global_load_dwordx4 v[50:53], v[56:57], off offset:256
	v_mul_f32_e32 v45, v45, v45
	v_mul_f32_e32 v47, v47, v47
	v_mul_f32_e32 v41, v41, v41
	v_fmac_f32_e32 v45, v44, v44
	v_fmac_f32_e32 v47, v46, v46
	v_mul_f32_e32 v43, v43, v43
	v_fmac_f32_e32 v41, v40, v40
	v_add_f32_e32 v40, v45, v47
	v_fmac_f32_e32 v43, v42, v42
	v_add_f32_e32 v40, v41, v40
	v_add_f32_e32 v56, v43, v40
	s_waitcnt vmcnt(0)
	v_lshlrev_b32_e32 v40, 16, v50
	v_and_b32_e32 v41, 0xffff0000, v50
	v_lshlrev_b32_e32 v42, 16, v51
	v_and_b32_e32 v43, 0xffff0000, v51
	v_lshlrev_b32_e32 v44, 16, v52
	v_and_b32_e32 v45, 0xffff0000, v52
	v_pk_add_f32 v[38:39], v[38:39], v[42:43]
	v_pk_add_f32 v[36:37], v[36:37], v[40:41]
	v_lshlrev_b32_e32 v46, 16, v53
	v_and_b32_e32 v47, 0xffff0000, v53
	v_pk_add_f32 v[40:41], v[32:33], v[44:45]
	v_mul_f32_e32 v32, v37, v37
	v_mul_f32_e32 v33, v39, v39
	v_pk_add_f32 v[42:43], v[34:35], v[46:47]
	v_mul_f32_e32 v34, v41, v41
	v_fmac_f32_e32 v32, v36, v36
	v_fmac_f32_e32 v33, v38, v38
	v_mul_f32_e32 v35, v43, v43
	v_fmac_f32_e32 v34, v40, v40
	v_add_f32_e32 v32, v32, v33
	v_add_f32_e32 v32, v34, v32
	v_fmac_f32_e32 v35, v42, v42
	v_add_f32_e32 v32, v35, v32
	v_add_f32_e32 v32, v56, v32
	ds_bpermute_b32 v33, v120, v32
	global_store_dwordx4 v[54:55], v[36:39], off offset:512 nt
	global_store_dwordx4 v[54:55], v[40:43], off offset:528 nt
	s_waitcnt lgkmcnt(0)
	v_add_f32_e32 v32, v32, v33
	ds_bpermute_b32 v33, v114, v32
	s_and_saveexec_b64 s[36:37], vcc
	s_cbranch_execz .LBB0_1939
	v_lshlrev_b64 v[34:35], 7, v[48:49]
	v_lshl_add_u64 v[34:35], s[14:15], 0, v[34:35]
	v_lshl_add_u64 v[34:35], s[22:23], 2, v[34:35]
	s_lshl_b32 s8, s49, 2
	v_lshl_add_u64 v[34:35], v[34:35], 0, s[8:9]
	s_waitcnt lgkmcnt(0)
	v_add_f32_e32 v32, v32, v33
	global_store_dword v[34:35], v32, off
; __device__ __forceinline__ u32x4 pack8(f32x4 v0, f32x4 v1) { u32x4 w; w.x = cvt_pk_bf16(v0[0], v0[1]); w.y = cvt_pk_bf16(v0[2], v0[3]); w.z = cvt_pk_bf16(v1[0], v1[1]); w.w = cvt_pk_bf16(v1[2], v1[3]); return w; }
; __device__ __forceinline__ void unpack8(u32x4 w, f32x4& v0, f32x4& v1) {
;     v0[0] = __uint_as_float(w.x << 16); v0[1] = __uint_as_float(w.x & 0xffff0000u); v0[2] = __uint_as_float(w.y << 16); v0[3] = __uint_as_float(w.y & 0xffff0000u);
;     v1[0] = __uint_as_float(w.z << 16); v1[1] = __uint_as_float(w.z & 0xffff0000u); v1[2] = __uint_as_float(w.w << 16); v1[3] = __uint_as_float(w.w & 0xffff0000u); }
;     __device__ __forceinline__ void operator()(f32x4 (&acc)[2][2][4][2], const Unit& u, int wr, int wc, int fr_, int fq_) const {
;     ...
;             for (int m = 0; m < 4; ++m) { const int row = row0 + ai * HALF + m * 16; float s = 0.f;
; #pragma unroll
;                 for (int bj = 0; bj < 2; ++bj) { const size_t off = (size_t)row * 2048 + col0 + bj * HALF;
;                     f32x4 b0, b1; unpack8(*(const u32x4*)(base + off), b0, b1);
;                     const f32x4 x0 = b0 + acc[ai][bj][m][0], x1 = b1 + acc[ai][bj][m][1];
;                     if (OUTF) { *(f32x4*)(out + off) = x0; *(f32x4*)(out + off + 4) = x1; }
;                     else *(u32x4*)(ob + off) = pack8(x0, x1);
;                     s += (x0[0] * x0[0] + x0[1] * x0[1]) + (x0[2] * x0[2] + x0[3] * x0[3]) + (x1[0] * x1[0] + x1[1] * x1[1]) + (x1[2] * x1[2] + x1[3] * x1[3]); }
;                 s += __shfl_xor(s, 16); s += __shfl_xor(s, 32);
;                 if (fq == 0) ssq[(size_t)row * 32 + u.pn * 4 + wc] = s; }
.LBB0_1939:
	s_or_b64 exec, exec, s[36:37]
	v_add_u32_e32 v32, 0xa0, v148
	s_waitcnt lgkmcnt(0)
	v_ashrrev_i32_e32 v33, 31, v32
	v_lshlrev_b64 v[34:35], 11, v[32:33]
	v_lshl_add_u64 v[38:39], v[34:35], 0, v[146:147]
	v_lshl_add_u64 v[40:41], v[38:39], 1, s[12:13]
	global_load_dwordx4 v[34:37], v[40:41], off
	v_lshl_add_u64 v[38:39], v[38:39], 2, s[26:27]
	s_waitcnt vmcnt(0)
	v_lshlrev_b32_e32 v42, 16, v34
	v_and_b32_e32 v43, 0xffff0000, v34
	v_lshlrev_b32_e32 v34, 16, v35
	v_and_b32_e32 v35, 0xffff0000, v35
	v_lshlrev_b32_e32 v44, 16, v36
	v_and_b32_e32 v45, 0xffff0000, v36
	v_lshlrev_b32_e32 v36, 16, v37
	v_and_b32_e32 v37, 0xffff0000, v37
	v_pk_add_f32 v[30:31], v[30:31], v[34:35]
	v_pk_add_f32 v[28:29], v[28:29], v[42:43]
	v_pk_add_f32 v[26:27], v[26:27], v[36:37]
	v_pk_add_f32 v[24:25], v[24:25], v[44:45]
	global_store_dwordx4 v[38:39], v[28:31], off nt
	global_store_dwordx4 v[38:39], v[24:27], off offset:16 nt
	global_load_dwordx4 v[34:37], v[40:41], off offset:256
	v_mul_f32_e32 v29, v29, v29
	v_mul_f32_e32 v31, v31, v31
	v_mul_f32_e32 v25, v25, v25
	v_fmac_f32_e32 v29, v28, v28
	v_fmac_f32_e32 v31, v30, v30
	v_mul_f32_e32 v27, v27, v27
	v_fmac_f32_e32 v25, v24, v24
	v_add_f32_e32 v24, v29, v31
	v_fmac_f32_e32 v27, v26, v26
	v_add_f32_e32 v24, v25, v24
	v_add_f32_e32 v40, v27, v24
	s_waitcnt vmcnt(0)
	v_lshlrev_b32_e32 v24, 16, v34
	v_and_b32_e32 v25, 0xffff0000, v34
	v_lshlrev_b32_e32 v26, 16, v35
	v_and_b32_e32 v27, 0xffff0000, v35
	v_lshlrev_b32_e32 v28, 16, v36
	v_and_b32_e32 v29, 0xffff0000, v36
	v_pk_add_f32 v[22:23], v[22:23], v[26:27]
	v_pk_add_f32 v[20:21], v[20:21], v[24:25]
	v_lshlrev_b32_e32 v30, 16, v37
	v_and_b32_e32 v31, 0xffff0000, v37
	v_pk_add_f32 v[24:25], v[16:17], v[28:29]
	v_mul_f32_e32 v16, v21, v21
	v_mul_f32_e32 v17, v23, v23
	v_pk_add_f32 v[26:27], v[18:19], v[30:31]
	v_mul_f32_e32 v18, v25, v25
	v_fmac_f32_e32 v16, v20, v20
	v_fmac_f32_e32 v17, v22, v22
	v_mul_f32_e32 v19, v27, v27
	v_fmac_f32_e32 v18, v24, v24
	v_add_f32_e32 v16, v16, v17
	v_add_f32_e32 v16, v18, v16
	v_fmac_f32_e32 v19, v26, v26
	v_add_f32_e32 v16, v19, v16
	v_add_f32_e32 v16, v40, v16
	ds_bpermute_b32 v17, v120, v16
	global_store_dwordx4 v[38:39], v[20:23], off offset:512 nt
	global_store_dwordx4 v[38:39], v[24:27], off offset:528 nt
	s_waitcnt lgkmcnt(0)
	v_add_f32_e32 v16, v16, v17
	ds_bpermute_b32 v17, v114, v16
	s_and_saveexec_b64 s[36:37], vcc
	s_cbranch_execz .LBB0_1941
	v_lshlrev_b64 v[18:19], 7, v[32:33]
	v_lshl_add_u64 v[18:19], s[14:15], 0, v[18:19]
	v_lshl_add_u64 v[18:19], s[22:23], 2, v[18:19]
	s_lshl_b32 s8, s49, 2
	v_lshl_add_u64 v[18:19], v[18:19], 0, s[8:9]
	s_waitcnt lgkmcnt(0)
	v_add_f32_e32 v16, v16, v17
	global_store_dword v[18:19], v16, off
.LBB0_1941:
	s_or_b64 exec, exec, s[36:37]
	v_add_u32_e32 v16, 0xb0, v148
	s_waitcnt lgkmcnt(0)
	v_ashrrev_i32_e32 v17, 31, v16
	v_lshlrev_b64 v[18:19], 11, v[16:17]
	v_lshl_add_u64 v[22:23], v[18:19], 0, v[146:147]
	v_lshl_add_u64 v[24:25], v[22:23], 1, s[12:13]
	global_load_dwordx4 v[18:21], v[24:25], off
	v_lshl_add_u64 v[22:23], v[22:23], 2, s[26:27]
	s_waitcnt vmcnt(0)
	v_lshlrev_b32_e32 v26, 16, v18
	v_and_b32_e32 v27, 0xffff0000, v18
	v_lshlrev_b32_e32 v18, 16, v19
	v_and_b32_e32 v19, 0xffff0000, v19
	v_lshlrev_b32_e32 v28, 16, v20
	v_and_b32_e32 v29, 0xffff0000, v20
	v_lshlrev_b32_e32 v20, 16, v21
	v_and_b32_e32 v21, 0xffff0000, v21
	v_pk_add_f32 v[14:15], v[14:15], v[18:19]
	v_pk_add_f32 v[12:13], v[12:13], v[26:27]
	v_pk_add_f32 v[10:11], v[10:11], v[20:21]
	v_pk_add_f32 v[8:9], v[8:9], v[28:29]
	global_store_dwordx4 v[22:23], v[12:15], off nt
	global_store_dwordx4 v[22:23], v[8:11], off offset:16 nt
	global_load_dwordx4 v[18:21], v[24:25], off offset:256
	v_mul_f32_e32 v13, v13, v13
	v_mul_f32_e32 v15, v15, v15
	v_mul_f32_e32 v9, v9, v9
	v_fmac_f32_e32 v13, v12, v12
	v_fmac_f32_e32 v15, v14, v14
	v_mul_f32_e32 v11, v11, v11
	v_fmac_f32_e32 v9, v8, v8
	v_add_f32_e32 v8, v13, v15
	v_fmac_f32_e32 v11, v10, v10
	v_add_f32_e32 v8, v9, v8
	v_add_f32_e32 v24, v11, v8
	s_waitcnt vmcnt(0)
	v_lshlrev_b32_e32 v8, 16, v18
	v_and_b32_e32 v9, 0xffff0000, v18
	v_lshlrev_b32_e32 v10, 16, v19
	v_and_b32_e32 v11, 0xffff0000, v19
	v_lshlrev_b32_e32 v12, 16, v20
	v_and_b32_e32 v13, 0xffff0000, v20
	v_pk_add_f32 v[6:7], v[6:7], v[10:11]
	v_pk_add_f32 v[4:5], v[4:5], v[8:9]
	v_lshlrev_b32_e32 v14, 16, v21
	v_and_b32_e32 v15, 0xffff0000, v21
	v_pk_add_f32 v[8:9], v[0:1], v[12:13]
	v_mul_f32_e32 v0, v5, v5
	v_mul_f32_e32 v1, v7, v7
	v_pk_add_f32 v[10:11], v[2:3], v[14:15]
	v_mul_f32_e32 v2, v9, v9
	v_fmac_f32_e32 v0, v4, v4
	v_fmac_f32_e32 v1, v6, v6
	v_mul_f32_e32 v3, v11, v11
	v_fmac_f32_e32 v2, v8, v8
	v_add_f32_e32 v0, v0, v1
	v_add_f32_e32 v0, v2, v0
	v_fmac_f32_e32 v3, v10, v10
	v_add_f32_e32 v0, v3, v0
	v_add_f32_e32 v0, v24, v0
	ds_bpermute_b32 v1, v120, v0
	global_store_dwordx4 v[22:23], v[4:7], off offset:512 nt
	global_store_dwordx4 v[22:23], v[8:11], off offset:528 nt
	s_waitcnt lgkmcnt(0)
	v_add_f32_e32 v0, v0, v1
	ds_bpermute_b32 v1, v114, v0
	s_and_saveexec_b64 s[36:37], vcc
	s_cbranch_execz .LBB0_1943
	v_lshlrev_b64 v[2:3], 7, v[16:17]
	v_lshl_add_u64 v[2:3], s[14:15], 0, v[2:3]
	v_lshl_add_u64 v[2:3], s[22:23], 2, v[2:3]
	s_lshl_b32 s8, s49, 2
	v_lshl_add_u64 v[2:3], v[2:3], 0, s[8:9]
	s_waitcnt lgkmcnt(0)
	v_add_f32_e32 v0, v0, v1
	global_store_dword v[2:3], v0, off
